# v024 without the tile-transition barrier change (epilogues of the two halves aligned as in the baseline)
# baseline (speedup 1.0000x reference)
.LBB0_208:
	s_add_i32 s84, s84, 1
	s_mul_i32 s4, s84, s56
	s_mul_hi_u32 s5, s84, s57
	s_add_i32 s5, s5, s4
	s_mul_i32 s4, s84, s57
	s_add_u32 s42, s4, s2
	s_addc_u32 s43, s5, s3
	v_cmp_gt_i64_e32 vcc, s[42:43], v[150:151]
	v_cmp_lt_i64_e64 s[4:5], s[42:43], v[148:149]
	s_cbranch_vccnz .LBB0_210
	s_and_b32 s100, s42, 7
	s_mul_i32 s100, s100, 0xc0
	s_lshr_b32 s101, s42, 3
	s_add_i32 s100, s100, s101
	s_mul_hi_u32 s101, s100, 0x2aaaaab
	s_mul_i32 s28, s101, 0x60
	s_sub_i32 s28, s100, s28
	s_and_b32 s100, s28, 7
	s_lshl_b32 s40, s101, 3
	s_add_i32 s40, s40, s100
	s_lshr_b32 s28, s28, 3
	s_mov_b32 s85, s84
.LBB0_210:
	s_ashr_i32 s41, s40, 31
	s_lshl_b64 s[12:13], s[40:41], 19
	s_add_u32 s42, s14, s12
	s_addc_u32 s43, s15, s13
	s_and_b64 s[12:13], s[4:5], exec
	s_cselect_b32 s7, s43, s51
	s_cselect_b32 s8, s42, s50
	s_ashr_i32 s29, s28, 31
	s_lshl_b64 s[12:13], s[28:29], 19
	s_add_u32 s48, s59, s12
	s_addc_u32 s49, s62, s13
	s_and_b64 s[12:13], s[4:5], exec
	s_cselect_b32 s12, s49, s53
	s_cselect_b32 s13, s48, s52
	s_add_u32 s50, s50, 0x40080
	s_addc_u32 s51, s51, 0
	s_add_u32 s29, s52, 0x100
	s_addc_u32 s41, s53, 0
	s_mov_b32 s86, -2
	s_waitcnt lgkmcnt(0)
	ds_read_b128 v[152:155], v157
	ds_read_b128 v[160:163], v157 offset:1024
	ds_read_b128 v[164:167], v157 offset:2048
	ds_read_b128 v[168:171], v157 offset:3072
	ds_read_b128 v[172:175], v158
	ds_read_b128 v[176:179], v158 offset:1024
	ds_read_b128 v[180:183], v158 offset:2048
	ds_read_b128 v[184:187], v158 offset:3072
	s_add_u32 s34, s50, 0xfffc0080
	s_addc_u32 s35, s51, -1
	s_cmp_eq_u32 s86, 12
	s_cselect_b32 s55, s7, s35
	s_cselect_b32 s54, s8, s34
	s_cselect_b32 s53, s12, s41
	s_cselect_b32 s52, s13, s29
	v_lshl_add_u64 v[220:221], s[50:51], 0, v[144:145]
	s_add_i32 m0, s63, 0xc000
	ds_read_b128 v[188:191], v159
	ds_read_b128 v[192:195], v159 offset:1024
	ds_read_b128 v[196:199], v159 offset:2048
	ds_read_b128 v[200:203], v159 offset:3072
	ds_read_b128 v[204:207], v159 offset:4096
	ds_read_b128 v[208:211], v159 offset:5120
	ds_read_b128 v[212:215], v159 offset:6144
	ds_read_b128 v[216:219], v159 offset:7168
	global_load_lds_dwordx4 v[220:221], off
	v_lshl_add_u64 v[220:221], s[50:51], 0, v[146:147]
	s_add_i32 m0, s63, 0xe000
	s_nop 0
	global_load_lds_dwordx4 v[220:221], off
	s_waitcnt vmcnt(8)
	s_waitcnt lgkmcnt(0)
	s_barrier
	s_setprio 1
	s_waitcnt lgkmcnt(0)
	v_mfma_f32_16x16x32_bf16 v[124:127], v[152:155], v[188:191], 0
	v_mfma_f32_16x16x32_bf16 v[120:123], v[164:167], v[188:191], 0
	v_mfma_f32_16x16x32_bf16 v[108:111], v[152:155], v[196:199], 0
	v_mfma_f32_16x16x32_bf16 v[104:107], v[164:167], v[196:199], 0
	v_mfma_f32_16x16x32_bf16 v[92:95], v[152:155], v[204:207], 0
	v_mfma_f32_16x16x32_bf16 v[88:91], v[164:167], v[204:207], 0
	v_mfma_f32_16x16x32_bf16 v[76:79], v[152:155], v[212:215], 0
	v_mfma_f32_16x16x32_bf16 v[72:75], v[164:167], v[212:215], 0
	v_mfma_f32_16x16x32_bf16 v[124:127], v[160:163], v[192:195], v[124:127]
	v_mfma_f32_16x16x32_bf16 v[120:123], v[168:171], v[192:195], v[120:123]
	v_mfma_f32_16x16x32_bf16 v[108:111], v[160:163], v[200:203], v[108:111]
	v_mfma_f32_16x16x32_bf16 v[104:107], v[168:171], v[200:203], v[104:107]
	v_mfma_f32_16x16x32_bf16 v[92:95], v[160:163], v[208:211], v[92:95]
	v_mfma_f32_16x16x32_bf16 v[88:91], v[168:171], v[208:211], v[88:91]
	v_mfma_f32_16x16x32_bf16 v[76:79], v[160:163], v[216:219], v[76:79]
	v_mfma_f32_16x16x32_bf16 v[72:75], v[168:171], v[216:219], v[72:75]
	s_setprio 0
	s_setprio 1
	v_mfma_f32_16x16x32_bf16 v[116:119], v[172:175], v[188:191], 0
	v_mfma_f32_16x16x32_bf16 v[112:115], v[180:183], v[188:191], 0
	v_mfma_f32_16x16x32_bf16 v[100:103], v[172:175], v[196:199], 0
	v_mfma_f32_16x16x32_bf16 v[96:99], v[180:183], v[196:199], 0
	v_mfma_f32_16x16x32_bf16 v[84:87], v[172:175], v[204:207], 0
	v_mfma_f32_16x16x32_bf16 v[80:83], v[180:183], v[204:207], 0
	v_mfma_f32_16x16x32_bf16 v[68:71], v[172:175], v[212:215], 0
	v_mfma_f32_16x16x32_bf16 v[64:67], v[180:183], v[212:215], 0
	v_mfma_f32_16x16x32_bf16 v[116:119], v[176:179], v[192:195], v[116:119]
	v_mfma_f32_16x16x32_bf16 v[112:115], v[184:187], v[192:195], v[112:115]
	v_mfma_f32_16x16x32_bf16 v[100:103], v[176:179], v[200:203], v[100:103]
	v_mfma_f32_16x16x32_bf16 v[96:99], v[184:187], v[200:203], v[96:99]
	v_mfma_f32_16x16x32_bf16 v[84:87], v[176:179], v[208:211], v[84:87]
	v_mfma_f32_16x16x32_bf16 v[80:83], v[184:187], v[208:211], v[80:83]
	v_mfma_f32_16x16x32_bf16 v[68:71], v[176:179], v[216:219], v[68:71]
	v_mfma_f32_16x16x32_bf16 v[64:67], v[184:187], v[216:219], v[64:67]
	s_setprio 0
	s_barrier
	s_add_i32 s34, s82, s58
	v_lshl_add_u64 v[220:221], s[52:53], 0, v[136:137]
	s_mov_b32 m0, s34
	ds_read_b128 v[188:191], v159 offset:16384
	ds_read_b128 v[192:195], v159 offset:17408
	ds_read_b128 v[196:199], v159 offset:18432
	ds_read_b128 v[200:203], v159 offset:19456
	ds_read_b128 v[204:207], v159 offset:20480
	ds_read_b128 v[208:211], v159 offset:21504
	ds_read_b128 v[212:215], v159 offset:22528
	ds_read_b128 v[216:219], v159 offset:23552
	global_load_lds_dwordx4 v[220:221], off
	s_add_i32 m0, s34, 0x2000
	s_add_u32 s34, s52, 0x40000
	v_lshl_add_u64 v[222:223], s[52:53], 0, v[140:141]
	s_addc_u32 s35, s53, 0
	s_add_i32 s87, s83, s58
	global_load_lds_dwordx4 v[222:223], off
	v_lshl_add_u64 v[224:225], s[34:35], 0, v[136:137]
	s_mov_b32 m0, s87
	v_lshl_add_u64 v[226:227], s[54:55], 0, v[138:139]
	global_load_lds_dwordx4 v[224:225], off
	v_lshl_add_u64 v[224:225], s[34:35], 0, v[140:141]
	s_add_i32 m0, s87, 0x2000
	s_nop 0
	global_load_lds_dwordx4 v[224:225], off
	v_lshl_add_u64 v[224:225], s[54:55], 0, v[134:135]
	s_mov_b32 m0, s63
	s_nop 0
	global_load_lds_dwordx4 v[224:225], off
	s_mov_b32 m0, s64
	s_nop 0
	global_load_lds_dwordx4 v[226:227], off
	s_waitcnt vmcnt(8)
	s_waitcnt lgkmcnt(0)
	s_barrier
	s_setprio 1
	s_waitcnt lgkmcnt(0)
	v_mfma_f32_16x16x32_bf16 v[60:63], v[152:155], v[188:191], 0
	v_mfma_f32_16x16x32_bf16 v[56:59], v[164:167], v[188:191], 0
	v_mfma_f32_16x16x32_bf16 v[44:47], v[152:155], v[196:199], 0
	v_mfma_f32_16x16x32_bf16 v[40:43], v[164:167], v[196:199], 0
	v_mfma_f32_16x16x32_bf16 v[28:31], v[152:155], v[204:207], 0
	v_mfma_f32_16x16x32_bf16 v[24:27], v[164:167], v[204:207], 0
	v_mfma_f32_16x16x32_bf16 v[12:15], v[152:155], v[212:215], 0
	v_mfma_f32_16x16x32_bf16 v[8:11], v[164:167], v[212:215], 0
	v_mfma_f32_16x16x32_bf16 v[60:63], v[160:163], v[192:195], v[60:63]
	v_mfma_f32_16x16x32_bf16 v[56:59], v[168:171], v[192:195], v[56:59]
	v_mfma_f32_16x16x32_bf16 v[44:47], v[160:163], v[200:203], v[44:47]
	v_mfma_f32_16x16x32_bf16 v[40:43], v[168:171], v[200:203], v[40:43]
	v_mfma_f32_16x16x32_bf16 v[28:31], v[160:163], v[208:211], v[28:31]
	v_mfma_f32_16x16x32_bf16 v[24:27], v[168:171], v[208:211], v[24:27]
	v_mfma_f32_16x16x32_bf16 v[12:15], v[160:163], v[216:219], v[12:15]
	v_mfma_f32_16x16x32_bf16 v[8:11], v[168:171], v[216:219], v[8:11]
	s_setprio 0
	s_setprio 1
	v_mfma_f32_16x16x32_bf16 v[52:55], v[172:175], v[188:191], 0
	v_mfma_f32_16x16x32_bf16 v[48:51], v[180:183], v[188:191], 0
	v_mfma_f32_16x16x32_bf16 v[36:39], v[172:175], v[196:199], 0
	v_mfma_f32_16x16x32_bf16 v[32:35], v[180:183], v[196:199], 0
	v_mfma_f32_16x16x32_bf16 v[20:23], v[172:175], v[204:207], 0
	v_mfma_f32_16x16x32_bf16 v[16:19], v[180:183], v[204:207], 0
	v_mfma_f32_16x16x32_bf16 v[4:7], v[172:175], v[212:215], 0
	v_mfma_f32_16x16x32_bf16 v[0:3], v[180:183], v[212:215], 0
	v_mfma_f32_16x16x32_bf16 v[52:55], v[176:179], v[192:195], v[52:55]
	v_mfma_f32_16x16x32_bf16 v[48:51], v[184:187], v[192:195], v[48:51]
	v_mfma_f32_16x16x32_bf16 v[36:39], v[176:179], v[200:203], v[36:39]
	v_mfma_f32_16x16x32_bf16 v[32:35], v[184:187], v[200:203], v[32:35]
	v_mfma_f32_16x16x32_bf16 v[20:23], v[176:179], v[208:211], v[20:23]
	v_mfma_f32_16x16x32_bf16 v[16:19], v[184:187], v[208:211], v[16:19]
	v_mfma_f32_16x16x32_bf16 v[4:7], v[176:179], v[216:219], v[4:7]
	v_mfma_f32_16x16x32_bf16 v[0:3], v[184:187], v[216:219], v[0:3]
	s_setprio 0
	s_barrier
	s_add_i32 s87, 0, 0x18000
	v_add_u32_e32 v142, s87, v133
	s_add_i32 s88, 0, 0x1c000
	ds_read_b128 v[152:155], v142
	ds_read_b128 v[160:163], v142 offset:1024
	ds_read_b128 v[164:167], v142 offset:2048
	ds_read_b128 v[168:171], v142 offset:3072
	v_add_u32_e32 v142, s88, v133
	ds_read_b128 v[172:175], v142
	ds_read_b128 v[176:179], v142 offset:1024
	ds_read_b128 v[180:183], v142 offset:2048
	ds_read_b128 v[184:187], v142 offset:3072
	s_add_u32 s34, s54, 0x40000
	s_addc_u32 s35, s55, 0
	s_mov_b32 m0, s65
	v_lshl_add_u64 v[228:229], s[34:35], 0, v[134:135]
	ds_read_b128 v[188:191], v159 offset:32768
	ds_read_b128 v[192:195], v159 offset:33792
	ds_read_b128 v[196:199], v159 offset:34816
	ds_read_b128 v[200:203], v159 offset:35840
	ds_read_b128 v[204:207], v159 offset:36864
	ds_read_b128 v[208:211], v159 offset:37888
	ds_read_b128 v[212:215], v159 offset:38912
	ds_read_b128 v[216:219], v159 offset:39936
	global_load_lds_dwordx4 v[228:229], off
	v_lshl_add_u64 v[228:229], s[34:35], 0, v[138:139]
	s_mov_b32 m0, s66
	s_nop 0
	global_load_lds_dwordx4 v[228:229], off
	s_waitcnt vmcnt(8)
	s_waitcnt lgkmcnt(0)
	s_barrier
	s_setprio 1
	s_waitcnt lgkmcnt(0)
	v_mfma_f32_16x16x32_bf16 v[124:127], v[152:155], v[188:191], v[124:127]
	v_mfma_f32_16x16x32_bf16 v[120:123], v[164:167], v[188:191], v[120:123]
	v_mfma_f32_16x16x32_bf16 v[108:111], v[152:155], v[196:199], v[108:111]
	v_mfma_f32_16x16x32_bf16 v[104:107], v[164:167], v[196:199], v[104:107]
	v_mfma_f32_16x16x32_bf16 v[92:95], v[152:155], v[204:207], v[92:95]
	v_mfma_f32_16x16x32_bf16 v[88:91], v[164:167], v[204:207], v[88:91]
	v_mfma_f32_16x16x32_bf16 v[76:79], v[152:155], v[212:215], v[76:79]
	v_mfma_f32_16x16x32_bf16 v[72:75], v[164:167], v[212:215], v[72:75]
	v_mfma_f32_16x16x32_bf16 v[124:127], v[160:163], v[192:195], v[124:127]
	v_mfma_f32_16x16x32_bf16 v[120:123], v[168:171], v[192:195], v[120:123]
	v_mfma_f32_16x16x32_bf16 v[108:111], v[160:163], v[200:203], v[108:111]
	v_mfma_f32_16x16x32_bf16 v[104:107], v[168:171], v[200:203], v[104:107]
	v_mfma_f32_16x16x32_bf16 v[92:95], v[160:163], v[208:211], v[92:95]
	v_mfma_f32_16x16x32_bf16 v[88:91], v[168:171], v[208:211], v[88:91]
	v_mfma_f32_16x16x32_bf16 v[76:79], v[160:163], v[216:219], v[76:79]
	v_mfma_f32_16x16x32_bf16 v[72:75], v[168:171], v[216:219], v[72:75]
	s_setprio 0
	s_setprio 1
	v_mfma_f32_16x16x32_bf16 v[116:119], v[172:175], v[188:191], v[116:119]
	v_mfma_f32_16x16x32_bf16 v[112:115], v[180:183], v[188:191], v[112:115]
	v_mfma_f32_16x16x32_bf16 v[100:103], v[172:175], v[196:199], v[100:103]
	v_mfma_f32_16x16x32_bf16 v[96:99], v[180:183], v[196:199], v[96:99]
	v_mfma_f32_16x16x32_bf16 v[84:87], v[172:175], v[204:207], v[84:87]
	v_mfma_f32_16x16x32_bf16 v[80:83], v[180:183], v[204:207], v[80:83]
	v_mfma_f32_16x16x32_bf16 v[68:71], v[172:175], v[212:215], v[68:71]
	v_mfma_f32_16x16x32_bf16 v[64:67], v[180:183], v[212:215], v[64:67]
	v_mfma_f32_16x16x32_bf16 v[116:119], v[176:179], v[192:195], v[116:119]
	v_mfma_f32_16x16x32_bf16 v[112:115], v[184:187], v[192:195], v[112:115]
	v_mfma_f32_16x16x32_bf16 v[100:103], v[176:179], v[200:203], v[100:103]
	v_mfma_f32_16x16x32_bf16 v[96:99], v[184:187], v[200:203], v[96:99]
	v_mfma_f32_16x16x32_bf16 v[84:87], v[176:179], v[208:211], v[84:87]
	v_mfma_f32_16x16x32_bf16 v[80:83], v[184:187], v[208:211], v[80:83]
	v_mfma_f32_16x16x32_bf16 v[68:71], v[176:179], v[216:219], v[68:71]
	v_mfma_f32_16x16x32_bf16 v[64:67], v[184:187], v[216:219], v[64:67]
	s_setprio 0
	s_barrier
	s_add_i32 s34, s87, s58
	v_lshl_add_u64 v[220:221], v[220:221], 0, s[22:23]
	s_mov_b32 m0, s34
	ds_read_b128 v[188:191], v159 offset:49152
	ds_read_b128 v[192:195], v159 offset:50176
	ds_read_b128 v[196:199], v159 offset:51200
	ds_read_b128 v[200:203], v159 offset:52224
	ds_read_b128 v[204:207], v159 offset:53248
	ds_read_b128 v[208:211], v159 offset:54272
	ds_read_b128 v[212:215], v159 offset:55296
	ds_read_b128 v[216:219], v159 offset:56320
	global_load_lds_dwordx4 v[220:221], off
	s_add_i32 m0, s34, 0x2000
	s_add_u32 s34, s52, 0x40080
	v_lshl_add_u64 v[220:221], v[222:223], 0, s[22:23]
	s_addc_u32 s35, s53, 0
	s_add_i32 s52, s88, s58
	global_load_lds_dwordx4 v[220:221], off
	v_lshl_add_u64 v[220:221], s[34:35], 0, v[136:137]
	s_mov_b32 m0, s52
	s_nop 0
	global_load_lds_dwordx4 v[220:221], off
	v_lshl_add_u64 v[220:221], s[34:35], 0, v[140:141]
	s_add_i32 m0, s52, 0x2000
	s_nop 0
	global_load_lds_dwordx4 v[220:221], off
	v_lshl_add_u64 v[220:221], v[224:225], 0, s[22:23]
	s_mov_b32 m0, s79
	s_nop 0
	global_load_lds_dwordx4 v[220:221], off
	v_lshl_add_u64 v[220:221], v[226:227], 0, s[22:23]
	s_mov_b32 m0, s81
	s_nop 0
	global_load_lds_dwordx4 v[220:221], off
	s_waitcnt vmcnt(8)
	s_waitcnt lgkmcnt(0)
	s_barrier
	s_setprio 1
	s_waitcnt lgkmcnt(0)
	v_mfma_f32_16x16x32_bf16 v[60:63], v[152:155], v[188:191], v[60:63]
	v_mfma_f32_16x16x32_bf16 v[56:59], v[164:167], v[188:191], v[56:59]
	v_mfma_f32_16x16x32_bf16 v[44:47], v[152:155], v[196:199], v[44:47]
	v_mfma_f32_16x16x32_bf16 v[40:43], v[164:167], v[196:199], v[40:43]
	v_mfma_f32_16x16x32_bf16 v[28:31], v[152:155], v[204:207], v[28:31]
	v_mfma_f32_16x16x32_bf16 v[24:27], v[164:167], v[204:207], v[24:27]
	v_mfma_f32_16x16x32_bf16 v[12:15], v[152:155], v[212:215], v[12:15]
	v_mfma_f32_16x16x32_bf16 v[8:11], v[164:167], v[212:215], v[8:11]
	v_mfma_f32_16x16x32_bf16 v[60:63], v[160:163], v[192:195], v[60:63]
	v_mfma_f32_16x16x32_bf16 v[56:59], v[168:171], v[192:195], v[56:59]
	v_mfma_f32_16x16x32_bf16 v[44:47], v[160:163], v[200:203], v[44:47]
	v_mfma_f32_16x16x32_bf16 v[40:43], v[168:171], v[200:203], v[40:43]
	v_mfma_f32_16x16x32_bf16 v[28:31], v[160:163], v[208:211], v[28:31]
	v_mfma_f32_16x16x32_bf16 v[24:27], v[168:171], v[208:211], v[24:27]
	v_mfma_f32_16x16x32_bf16 v[12:15], v[160:163], v[216:219], v[12:15]
	v_mfma_f32_16x16x32_bf16 v[8:11], v[168:171], v[216:219], v[8:11]
	s_setprio 0
	s_setprio 1
	v_mfma_f32_16x16x32_bf16 v[52:55], v[172:175], v[188:191], v[52:55]
	v_mfma_f32_16x16x32_bf16 v[48:51], v[180:183], v[188:191], v[48:51]
	v_mfma_f32_16x16x32_bf16 v[36:39], v[172:175], v[196:199], v[36:39]
	v_mfma_f32_16x16x32_bf16 v[32:35], v[180:183], v[196:199], v[32:35]
	v_mfma_f32_16x16x32_bf16 v[20:23], v[172:175], v[204:207], v[20:23]
	v_mfma_f32_16x16x32_bf16 v[16:19], v[180:183], v[204:207], v[16:19]
	v_mfma_f32_16x16x32_bf16 v[4:7], v[172:175], v[212:215], v[4:7]
	v_mfma_f32_16x16x32_bf16 v[0:3], v[180:183], v[212:215], v[0:3]
	v_mfma_f32_16x16x32_bf16 v[52:55], v[176:179], v[192:195], v[52:55]
	v_mfma_f32_16x16x32_bf16 v[48:51], v[184:187], v[192:195], v[48:51]
	v_mfma_f32_16x16x32_bf16 v[36:39], v[176:179], v[200:203], v[36:39]
	v_mfma_f32_16x16x32_bf16 v[32:35], v[184:187], v[200:203], v[32:35]
	v_mfma_f32_16x16x32_bf16 v[20:23], v[176:179], v[208:211], v[20:23]
	v_mfma_f32_16x16x32_bf16 v[16:19], v[184:187], v[208:211], v[16:19]
	v_mfma_f32_16x16x32_bf16 v[4:7], v[176:179], v[216:219], v[4:7]
	v_mfma_f32_16x16x32_bf16 v[0:3], v[184:187], v[216:219], v[0:3]
	s_setprio 0
	s_barrier
	s_add_i32 s86, s86, 2
	s_add_u32 s50, s50, 0x100
	s_addc_u32 s51, s51, 0
	s_add_u32 s29, s29, 0x100
	s_addc_u32 s41, s41, 0

.LBB0_379:
	s_add_i32 s84, s84, 1
	s_mul_i32 s6, s84, s67
	s_mul_hi_u32 s7, s84, s79
	s_add_i32 s7, s7, s6
	s_mul_i32 s6, s84, s79
	s_add_u32 s40, s6, s2
	s_addc_u32 s41, s7, s81
	v_cmp_gt_i64_e32 vcc, s[40:41], v[146:147]
	v_cmp_lt_i64_e64 s[6:7], s[40:41], v[144:145]
	s_cbranch_vccnz .LBB0_385
	s_and_b32 s100, s40, 7
	s_mul_i32 s100, s100, 0x40
	s_lshr_b32 s101, s40, 3
	s_add_i32 s100, s100, s101
	s_mul_hi_u32 s101, s100, 0x8000000
	s_mul_i32 s26, s101, 0x20
	s_sub_i32 s26, s100, s26
	s_and_b32 s100, s26, 7
	s_lshl_b32 s28, s101, 3
	s_add_i32 s28, s28, s100
	s_lshr_b32 s26, s26, 3
.LBB0_385:
	s_ashr_i32 s29, s28, 31
	s_lshl_b64 s[12:13], s[28:29], 19
	s_add_u32 s40, s20, s12
	s_addc_u32 s41, s21, s13
	s_and_b64 s[12:13], s[6:7], exec
	s_cselect_b32 s12, s41, s51
	s_cselect_b32 s13, s40, s50
	s_ashr_i32 s27, s26, 31
	s_lshl_b64 s[34:35], s[26:27], 19
	s_add_u32 s42, s3, s34
	s_addc_u32 s43, s56, s35
	s_and_b64 s[34:35], s[6:7], exec
	s_cselect_b32 s27, s43, s53
	s_cselect_b32 s29, s42, s52
	s_add_u32 s50, s50, 0x40080
	s_addc_u32 s51, s51, 0
	s_add_u32 s49, s52, 0x100
	s_addc_u32 s77, s53, 0
	s_mov_b32 s85, -2
	s_waitcnt lgkmcnt(0)
	ds_read_b128 v[148:151], v154
	ds_read_b128 v[160:163], v154 offset:1024
	ds_read_b128 v[164:167], v154 offset:2048
	ds_read_b128 v[168:171], v154 offset:3072
	ds_read_b128 v[172:175], v155
	ds_read_b128 v[176:179], v155 offset:1024
	ds_read_b128 v[180:183], v155 offset:2048
	ds_read_b128 v[184:187], v155 offset:3072
	s_add_u32 s34, s50, 0xfffc0080
	s_addc_u32 s35, s51, -1
	s_cmp_eq_u32 s85, 12
	s_cselect_b32 s55, s12, s35
	s_cselect_b32 s54, s13, s34
	s_cselect_b32 s53, s27, s77
	s_cselect_b32 s52, s29, s49
	v_lshl_add_u64 v[220:221], s[50:51], 0, v[140:141]
	s_add_i32 m0, s58, 0xc000
	ds_read_b128 v[188:191], v157
	ds_read_b128 v[192:195], v157 offset:1024
	ds_read_b128 v[196:199], v157 offset:2048
	ds_read_b128 v[200:203], v157 offset:3072
	ds_read_b128 v[204:207], v157 offset:4096
	ds_read_b128 v[208:211], v157 offset:5120
	ds_read_b128 v[212:215], v157 offset:6144
	ds_read_b128 v[216:219], v157 offset:7168
	global_load_lds_dwordx4 v[220:221], off
	v_lshl_add_u64 v[220:221], s[50:51], 0, v[142:143]
	s_add_i32 m0, s58, 0xe000
	s_nop 0
	global_load_lds_dwordx4 v[220:221], off
	s_waitcnt vmcnt(8)
	s_waitcnt lgkmcnt(0)
	s_barrier
	s_setprio 1
	s_waitcnt lgkmcnt(0)
	v_mfma_f32_16x16x32_bf16 v[124:127], v[148:151], v[188:191], 0
	v_mfma_f32_16x16x32_bf16 v[120:123], v[164:167], v[188:191], 0
	v_mfma_f32_16x16x32_bf16 v[108:111], v[148:151], v[196:199], 0
	v_mfma_f32_16x16x32_bf16 v[104:107], v[164:167], v[196:199], 0
	v_mfma_f32_16x16x32_bf16 v[92:95], v[148:151], v[204:207], 0
	v_mfma_f32_16x16x32_bf16 v[88:91], v[164:167], v[204:207], 0
	v_mfma_f32_16x16x32_bf16 v[76:79], v[148:151], v[212:215], 0
	v_mfma_f32_16x16x32_bf16 v[72:75], v[164:167], v[212:215], 0
	v_mfma_f32_16x16x32_bf16 v[124:127], v[160:163], v[192:195], v[124:127]
	v_mfma_f32_16x16x32_bf16 v[120:123], v[168:171], v[192:195], v[120:123]
	v_mfma_f32_16x16x32_bf16 v[108:111], v[160:163], v[200:203], v[108:111]
	v_mfma_f32_16x16x32_bf16 v[104:107], v[168:171], v[200:203], v[104:107]
	v_mfma_f32_16x16x32_bf16 v[92:95], v[160:163], v[208:211], v[92:95]
	v_mfma_f32_16x16x32_bf16 v[88:91], v[168:171], v[208:211], v[88:91]
	v_mfma_f32_16x16x32_bf16 v[76:79], v[160:163], v[216:219], v[76:79]
	v_mfma_f32_16x16x32_bf16 v[72:75], v[168:171], v[216:219], v[72:75]
	s_setprio 0
	s_setprio 1
	v_mfma_f32_16x16x32_bf16 v[116:119], v[172:175], v[188:191], 0
	v_mfma_f32_16x16x32_bf16 v[112:115], v[180:183], v[188:191], 0
	v_mfma_f32_16x16x32_bf16 v[100:103], v[172:175], v[196:199], 0
	v_mfma_f32_16x16x32_bf16 v[96:99], v[180:183], v[196:199], 0
	v_mfma_f32_16x16x32_bf16 v[84:87], v[172:175], v[204:207], 0
	v_mfma_f32_16x16x32_bf16 v[80:83], v[180:183], v[204:207], 0
	v_mfma_f32_16x16x32_bf16 v[68:71], v[172:175], v[212:215], 0
	v_mfma_f32_16x16x32_bf16 v[64:67], v[180:183], v[212:215], 0
	v_mfma_f32_16x16x32_bf16 v[116:119], v[176:179], v[192:195], v[116:119]
	v_mfma_f32_16x16x32_bf16 v[112:115], v[184:187], v[192:195], v[112:115]
	v_mfma_f32_16x16x32_bf16 v[100:103], v[176:179], v[200:203], v[100:103]
	v_mfma_f32_16x16x32_bf16 v[96:99], v[184:187], v[200:203], v[96:99]
	v_mfma_f32_16x16x32_bf16 v[84:87], v[176:179], v[208:211], v[84:87]
	v_mfma_f32_16x16x32_bf16 v[80:83], v[184:187], v[208:211], v[80:83]
	v_mfma_f32_16x16x32_bf16 v[68:71], v[176:179], v[216:219], v[68:71]
	v_mfma_f32_16x16x32_bf16 v[64:67], v[184:187], v[216:219], v[64:67]
	s_setprio 0
	s_barrier
	s_add_i32 s34, s82, s57
	v_lshl_add_u64 v[220:221], s[52:53], 0, v[134:135]
	s_mov_b32 m0, s34
	ds_read_b128 v[188:191], v157 offset:16384
	ds_read_b128 v[192:195], v157 offset:17408
	ds_read_b128 v[196:199], v157 offset:18432
	ds_read_b128 v[200:203], v157 offset:19456
	ds_read_b128 v[204:207], v157 offset:20480
	ds_read_b128 v[208:211], v157 offset:21504
	ds_read_b128 v[212:215], v157 offset:22528
	ds_read_b128 v[216:219], v157 offset:23552
	global_load_lds_dwordx4 v[220:221], off
	s_add_i32 m0, s34, 0x2000
	s_add_u32 s34, s52, 0x40000
	v_lshl_add_u64 v[222:223], s[52:53], 0, v[138:139]
	s_addc_u32 s35, s53, 0
	s_add_i32 s86, s83, s57
	global_load_lds_dwordx4 v[222:223], off
	v_lshl_add_u64 v[224:225], s[34:35], 0, v[134:135]
	s_mov_b32 m0, s86
	v_lshl_add_u64 v[226:227], s[54:55], 0, v[136:137]
	global_load_lds_dwordx4 v[224:225], off
	v_lshl_add_u64 v[224:225], s[34:35], 0, v[138:139]
	s_add_i32 m0, s86, 0x2000
	s_nop 0
	global_load_lds_dwordx4 v[224:225], off
	v_lshl_add_u64 v[224:225], s[54:55], 0, v[132:133]
	s_mov_b32 m0, s58
	s_nop 0
	global_load_lds_dwordx4 v[224:225], off
	s_mov_b32 m0, s59
	s_nop 0
	global_load_lds_dwordx4 v[226:227], off
	s_waitcnt vmcnt(8)
	s_waitcnt lgkmcnt(0)
	s_barrier
	s_setprio 1
	s_waitcnt lgkmcnt(0)
	v_mfma_f32_16x16x32_bf16 v[60:63], v[148:151], v[188:191], 0
	v_mfma_f32_16x16x32_bf16 v[56:59], v[164:167], v[188:191], 0
	v_mfma_f32_16x16x32_bf16 v[44:47], v[148:151], v[196:199], 0
	v_mfma_f32_16x16x32_bf16 v[40:43], v[164:167], v[196:199], 0
	v_mfma_f32_16x16x32_bf16 v[28:31], v[148:151], v[204:207], 0
	v_mfma_f32_16x16x32_bf16 v[24:27], v[164:167], v[204:207], 0
	v_mfma_f32_16x16x32_bf16 v[12:15], v[148:151], v[212:215], 0
	v_mfma_f32_16x16x32_bf16 v[8:11], v[164:167], v[212:215], 0
	v_mfma_f32_16x16x32_bf16 v[60:63], v[160:163], v[192:195], v[60:63]
	v_mfma_f32_16x16x32_bf16 v[56:59], v[168:171], v[192:195], v[56:59]
	v_mfma_f32_16x16x32_bf16 v[44:47], v[160:163], v[200:203], v[44:47]
	v_mfma_f32_16x16x32_bf16 v[40:43], v[168:171], v[200:203], v[40:43]
	v_mfma_f32_16x16x32_bf16 v[28:31], v[160:163], v[208:211], v[28:31]
	v_mfma_f32_16x16x32_bf16 v[24:27], v[168:171], v[208:211], v[24:27]
	v_mfma_f32_16x16x32_bf16 v[12:15], v[160:163], v[216:219], v[12:15]
	v_mfma_f32_16x16x32_bf16 v[8:11], v[168:171], v[216:219], v[8:11]
	s_setprio 0
	s_setprio 1
	v_mfma_f32_16x16x32_bf16 v[52:55], v[172:175], v[188:191], 0
	v_mfma_f32_16x16x32_bf16 v[48:51], v[180:183], v[188:191], 0
	v_mfma_f32_16x16x32_bf16 v[36:39], v[172:175], v[196:199], 0
	v_mfma_f32_16x16x32_bf16 v[32:35], v[180:183], v[196:199], 0
	v_mfma_f32_16x16x32_bf16 v[20:23], v[172:175], v[204:207], 0
	v_mfma_f32_16x16x32_bf16 v[16:19], v[180:183], v[204:207], 0
	v_mfma_f32_16x16x32_bf16 v[4:7], v[172:175], v[212:215], 0
	v_mfma_f32_16x16x32_bf16 v[0:3], v[180:183], v[212:215], 0
	v_mfma_f32_16x16x32_bf16 v[52:55], v[176:179], v[192:195], v[52:55]
	v_mfma_f32_16x16x32_bf16 v[48:51], v[184:187], v[192:195], v[48:51]
	v_mfma_f32_16x16x32_bf16 v[36:39], v[176:179], v[200:203], v[36:39]
	v_mfma_f32_16x16x32_bf16 v[32:35], v[184:187], v[200:203], v[32:35]
	v_mfma_f32_16x16x32_bf16 v[20:23], v[176:179], v[208:211], v[20:23]
	v_mfma_f32_16x16x32_bf16 v[16:19], v[184:187], v[208:211], v[16:19]
	v_mfma_f32_16x16x32_bf16 v[4:7], v[176:179], v[216:219], v[4:7]
	v_mfma_f32_16x16x32_bf16 v[0:3], v[184:187], v[216:219], v[0:3]
	s_setprio 0
	s_barrier
	s_add_i32 s86, 0, 0x18000
	v_add_u32_e32 v159, s86, v152
	s_add_i32 s87, 0, 0x1c000
	ds_read_b128 v[148:151], v159
	ds_read_b128 v[160:163], v159 offset:1024
	ds_read_b128 v[164:167], v159 offset:2048
	ds_read_b128 v[168:171], v159 offset:3072
	v_add_u32_e32 v159, s87, v152
	ds_read_b128 v[172:175], v159
	ds_read_b128 v[176:179], v159 offset:1024
	ds_read_b128 v[180:183], v159 offset:2048
	ds_read_b128 v[184:187], v159 offset:3072
	s_add_u32 s34, s54, 0x40000
	s_addc_u32 s35, s55, 0
	s_mov_b32 m0, s62
	v_lshl_add_u64 v[228:229], s[34:35], 0, v[132:133]
	ds_read_b128 v[188:191], v157 offset:32768
	ds_read_b128 v[192:195], v157 offset:33792
	ds_read_b128 v[196:199], v157 offset:34816
	ds_read_b128 v[200:203], v157 offset:35840
	ds_read_b128 v[204:207], v157 offset:36864
	ds_read_b128 v[208:211], v157 offset:37888
	ds_read_b128 v[212:215], v157 offset:38912
	ds_read_b128 v[216:219], v157 offset:39936
	global_load_lds_dwordx4 v[228:229], off
	v_lshl_add_u64 v[228:229], s[34:35], 0, v[136:137]
	s_mov_b32 m0, s63
	s_nop 0
	global_load_lds_dwordx4 v[228:229], off
	s_waitcnt vmcnt(8)
	s_waitcnt lgkmcnt(0)
	s_barrier
	s_setprio 1
	s_waitcnt lgkmcnt(0)
	v_mfma_f32_16x16x32_bf16 v[124:127], v[148:151], v[188:191], v[124:127]
	v_mfma_f32_16x16x32_bf16 v[120:123], v[164:167], v[188:191], v[120:123]
	v_mfma_f32_16x16x32_bf16 v[108:111], v[148:151], v[196:199], v[108:111]
	v_mfma_f32_16x16x32_bf16 v[104:107], v[164:167], v[196:199], v[104:107]
	v_mfma_f32_16x16x32_bf16 v[92:95], v[148:151], v[204:207], v[92:95]
	v_mfma_f32_16x16x32_bf16 v[88:91], v[164:167], v[204:207], v[88:91]
	v_mfma_f32_16x16x32_bf16 v[76:79], v[148:151], v[212:215], v[76:79]
	v_mfma_f32_16x16x32_bf16 v[72:75], v[164:167], v[212:215], v[72:75]
	v_mfma_f32_16x16x32_bf16 v[124:127], v[160:163], v[192:195], v[124:127]
	v_mfma_f32_16x16x32_bf16 v[120:123], v[168:171], v[192:195], v[120:123]
	v_mfma_f32_16x16x32_bf16 v[108:111], v[160:163], v[200:203], v[108:111]
	v_mfma_f32_16x16x32_bf16 v[104:107], v[168:171], v[200:203], v[104:107]
	v_mfma_f32_16x16x32_bf16 v[92:95], v[160:163], v[208:211], v[92:95]
	v_mfma_f32_16x16x32_bf16 v[88:91], v[168:171], v[208:211], v[88:91]
	v_mfma_f32_16x16x32_bf16 v[76:79], v[160:163], v[216:219], v[76:79]
	v_mfma_f32_16x16x32_bf16 v[72:75], v[168:171], v[216:219], v[72:75]
	s_setprio 0
	s_setprio 1
	v_mfma_f32_16x16x32_bf16 v[116:119], v[172:175], v[188:191], v[116:119]
	v_mfma_f32_16x16x32_bf16 v[112:115], v[180:183], v[188:191], v[112:115]
	v_mfma_f32_16x16x32_bf16 v[100:103], v[172:175], v[196:199], v[100:103]
	v_mfma_f32_16x16x32_bf16 v[96:99], v[180:183], v[196:199], v[96:99]
	v_mfma_f32_16x16x32_bf16 v[84:87], v[172:175], v[204:207], v[84:87]
	v_mfma_f32_16x16x32_bf16 v[80:83], v[180:183], v[204:207], v[80:83]
	v_mfma_f32_16x16x32_bf16 v[68:71], v[172:175], v[212:215], v[68:71]
	v_mfma_f32_16x16x32_bf16 v[64:67], v[180:183], v[212:215], v[64:67]
	v_mfma_f32_16x16x32_bf16 v[116:119], v[176:179], v[192:195], v[116:119]
	v_mfma_f32_16x16x32_bf16 v[112:115], v[184:187], v[192:195], v[112:115]
	v_mfma_f32_16x16x32_bf16 v[100:103], v[176:179], v[200:203], v[100:103]
	v_mfma_f32_16x16x32_bf16 v[96:99], v[184:187], v[200:203], v[96:99]
	v_mfma_f32_16x16x32_bf16 v[84:87], v[176:179], v[208:211], v[84:87]
	v_mfma_f32_16x16x32_bf16 v[80:83], v[184:187], v[208:211], v[80:83]
	v_mfma_f32_16x16x32_bf16 v[68:71], v[176:179], v[216:219], v[68:71]
	v_mfma_f32_16x16x32_bf16 v[64:67], v[184:187], v[216:219], v[64:67]
	s_setprio 0
	s_barrier
	s_add_i32 s34, s86, s57
	v_lshl_add_u64 v[220:221], v[220:221], 0, s[10:11]
	s_mov_b32 m0, s34
	ds_read_b128 v[188:191], v157 offset:49152
	ds_read_b128 v[192:195], v157 offset:50176
	ds_read_b128 v[196:199], v157 offset:51200
	ds_read_b128 v[200:203], v157 offset:52224
	ds_read_b128 v[204:207], v157 offset:53248
	ds_read_b128 v[208:211], v157 offset:54272
	ds_read_b128 v[212:215], v157 offset:55296
	ds_read_b128 v[216:219], v157 offset:56320
	global_load_lds_dwordx4 v[220:221], off
	s_add_i32 m0, s34, 0x2000
	s_add_u32 s34, s52, 0x40080
	v_lshl_add_u64 v[220:221], v[222:223], 0, s[10:11]
	s_addc_u32 s35, s53, 0
	s_add_i32 s52, s87, s57
	global_load_lds_dwordx4 v[220:221], off
	v_lshl_add_u64 v[220:221], s[34:35], 0, v[134:135]
	s_mov_b32 m0, s52
	s_nop 0
	global_load_lds_dwordx4 v[220:221], off
	v_lshl_add_u64 v[220:221], s[34:35], 0, v[138:139]
	s_add_i32 m0, s52, 0x2000
	s_nop 0
	global_load_lds_dwordx4 v[220:221], off
	v_lshl_add_u64 v[220:221], v[224:225], 0, s[10:11]
	s_mov_b32 m0, s65
	s_nop 0
	global_load_lds_dwordx4 v[220:221], off
	v_lshl_add_u64 v[220:221], v[226:227], 0, s[10:11]
	s_mov_b32 m0, s66
	s_nop 0
	global_load_lds_dwordx4 v[220:221], off
	s_waitcnt vmcnt(8)
	s_waitcnt lgkmcnt(0)
	s_barrier
	s_setprio 1
	s_waitcnt lgkmcnt(0)
	v_mfma_f32_16x16x32_bf16 v[60:63], v[148:151], v[188:191], v[60:63]
	v_mfma_f32_16x16x32_bf16 v[56:59], v[164:167], v[188:191], v[56:59]
	v_mfma_f32_16x16x32_bf16 v[44:47], v[148:151], v[196:199], v[44:47]
	v_mfma_f32_16x16x32_bf16 v[40:43], v[164:167], v[196:199], v[40:43]
	v_mfma_f32_16x16x32_bf16 v[28:31], v[148:151], v[204:207], v[28:31]
	v_mfma_f32_16x16x32_bf16 v[24:27], v[164:167], v[204:207], v[24:27]
	v_mfma_f32_16x16x32_bf16 v[12:15], v[148:151], v[212:215], v[12:15]
	v_mfma_f32_16x16x32_bf16 v[8:11], v[164:167], v[212:215], v[8:11]
	v_mfma_f32_16x16x32_bf16 v[60:63], v[160:163], v[192:195], v[60:63]
	v_mfma_f32_16x16x32_bf16 v[56:59], v[168:171], v[192:195], v[56:59]
	v_mfma_f32_16x16x32_bf16 v[44:47], v[160:163], v[200:203], v[44:47]
	v_mfma_f32_16x16x32_bf16 v[40:43], v[168:171], v[200:203], v[40:43]
	v_mfma_f32_16x16x32_bf16 v[28:31], v[160:163], v[208:211], v[28:31]
	v_mfma_f32_16x16x32_bf16 v[24:27], v[168:171], v[208:211], v[24:27]
	v_mfma_f32_16x16x32_bf16 v[12:15], v[160:163], v[216:219], v[12:15]
	v_mfma_f32_16x16x32_bf16 v[8:11], v[168:171], v[216:219], v[8:11]
	s_setprio 0
	s_setprio 1
	v_mfma_f32_16x16x32_bf16 v[52:55], v[172:175], v[188:191], v[52:55]
	v_mfma_f32_16x16x32_bf16 v[48:51], v[180:183], v[188:191], v[48:51]
	v_mfma_f32_16x16x32_bf16 v[36:39], v[172:175], v[196:199], v[36:39]
	v_mfma_f32_16x16x32_bf16 v[32:35], v[180:183], v[196:199], v[32:35]
	v_mfma_f32_16x16x32_bf16 v[20:23], v[172:175], v[204:207], v[20:23]
	v_mfma_f32_16x16x32_bf16 v[16:19], v[180:183], v[204:207], v[16:19]
	v_mfma_f32_16x16x32_bf16 v[4:7], v[172:175], v[212:215], v[4:7]
	v_mfma_f32_16x16x32_bf16 v[0:3], v[180:183], v[212:215], v[0:3]
	v_mfma_f32_16x16x32_bf16 v[52:55], v[176:179], v[192:195], v[52:55]
	v_mfma_f32_16x16x32_bf16 v[48:51], v[184:187], v[192:195], v[48:51]
	v_mfma_f32_16x16x32_bf16 v[36:39], v[176:179], v[200:203], v[36:39]
	v_mfma_f32_16x16x32_bf16 v[32:35], v[184:187], v[200:203], v[32:35]
	v_mfma_f32_16x16x32_bf16 v[20:23], v[176:179], v[208:211], v[20:23]
	v_mfma_f32_16x16x32_bf16 v[16:19], v[184:187], v[208:211], v[16:19]
	v_mfma_f32_16x16x32_bf16 v[4:7], v[176:179], v[216:219], v[4:7]
	v_mfma_f32_16x16x32_bf16 v[0:3], v[184:187], v[216:219], v[0:3]
	s_setprio 0
	s_barrier
	s_add_i32 s85, s85, 2
	s_add_u32 s50, s50, 0x100
	s_addc_u32 s51, s51, 0
	s_add_u32 s49, s49, 0x100
	s_addc_u32 s77, s77, 0

.LBB0_473:
	s_add_i32 s77, s77, 1
	s_mul_i32 s4, s77, s52
	s_mul_hi_u32 s5, s77, s53
	s_add_i32 s5, s5, s4
	s_mul_i32 s4, s77, s53
	s_add_u32 s26, s4, s2
	s_addc_u32 s27, s5, s3
	v_cmp_gt_i64_e32 vcc, s[26:27], v[146:147]
	v_cmp_lt_i64_e64 s[4:5], s[26:27], v[144:145]
	s_cbranch_vccnz .LBB0_475
	s_and_b32 s100, s26, 7
	s_mul_i32 s100, s100, 0x160
	s_lshr_b32 s101, s26, 3
	s_add_i32 s100, s100, s101
	s_mul_hi_u32 s101, s100, 0x1745d18
	s_mul_i32 s10, s101, 0xb0
	s_sub_i32 s10, s100, s10
	s_and_b32 s100, s10, 7
	s_lshl_b32 s22, s101, 3
	s_add_i32 s22, s22, s100
	s_lshr_b32 s10, s10, 3
	s_mov_b32 s79, s77
.LBB0_475:
	s_ashr_i32 s23, s22, 31
	s_lshl_b64 s[26:27], s[22:23], 19
	s_add_u32 s26, s14, s26
	s_addc_u32 s27, s15, s27
	s_and_b64 s[28:29], s[4:5], exec
	s_cselect_b32 s23, s27, s43
	s_cselect_b32 s81, s26, s42
	s_ashr_i32 s11, s10, 31
	s_lshl_b64 s[28:29], s[10:11], 19
	s_add_u32 s28, s55, s28
	s_addc_u32 s29, s56, s29
	s_and_b64 s[34:35], s[4:5], exec
	s_cselect_b32 s11, s29, s49
	s_cselect_b32 s82, s28, s48
	s_add_u32 s42, s42, 0x40080
	s_addc_u32 s43, s43, 0
	s_add_u32 s83, s48, 0x100
	s_addc_u32 s84, s49, 0
	s_mov_b32 s85, -2
	ds_read_b128 v[148:151], v155
	ds_read_b128 v[160:163], v155 offset:1024
	ds_read_b128 v[164:167], v155 offset:2048
	ds_read_b128 v[168:171], v155 offset:3072
	ds_read_b128 v[172:175], v157
	ds_read_b128 v[176:179], v157 offset:1024
	ds_read_b128 v[180:183], v157 offset:2048
	ds_read_b128 v[184:187], v157 offset:3072
	s_add_u32 s34, s42, 0xfffc0080
	s_addc_u32 s35, s43, -1
	s_cmp_eq_u32 s85, 12
	s_cselect_b32 s51, s23, s35
	s_cselect_b32 s50, s81, s34
	s_cselect_b32 s49, s11, s84
	s_cselect_b32 s48, s82, s83
	v_lshl_add_u64 v[220:221], s[42:43], 0, v[140:141]
	s_add_i32 m0, s41, 0xc000
	ds_read_b128 v[188:191], v158
	ds_read_b128 v[192:195], v158 offset:1024
	ds_read_b128 v[196:199], v158 offset:2048
	ds_read_b128 v[200:203], v158 offset:3072
	ds_read_b128 v[204:207], v158 offset:4096
	ds_read_b128 v[208:211], v158 offset:5120
	ds_read_b128 v[212:215], v158 offset:6144
	ds_read_b128 v[216:219], v158 offset:7168
	global_load_lds_dwordx4 v[220:221], off
	v_lshl_add_u64 v[220:221], s[42:43], 0, v[142:143]
	s_add_i32 m0, s41, 0xe000
	s_nop 0
	global_load_lds_dwordx4 v[220:221], off
	s_waitcnt vmcnt(8)
	s_waitcnt lgkmcnt(0)
	s_barrier
	s_setprio 1
	s_waitcnt lgkmcnt(0)
	v_mfma_f32_16x16x32_bf16 v[124:127], v[148:151], v[188:191], 0
	v_mfma_f32_16x16x32_bf16 v[120:123], v[164:167], v[188:191], 0
	v_mfma_f32_16x16x32_bf16 v[108:111], v[148:151], v[196:199], 0
	v_mfma_f32_16x16x32_bf16 v[104:107], v[164:167], v[196:199], 0
	v_mfma_f32_16x16x32_bf16 v[92:95], v[148:151], v[204:207], 0
	v_mfma_f32_16x16x32_bf16 v[88:91], v[164:167], v[204:207], 0
	v_mfma_f32_16x16x32_bf16 v[76:79], v[148:151], v[212:215], 0
	v_mfma_f32_16x16x32_bf16 v[72:75], v[164:167], v[212:215], 0
	v_mfma_f32_16x16x32_bf16 v[124:127], v[160:163], v[192:195], v[124:127]
	v_mfma_f32_16x16x32_bf16 v[120:123], v[168:171], v[192:195], v[120:123]
	v_mfma_f32_16x16x32_bf16 v[108:111], v[160:163], v[200:203], v[108:111]
	v_mfma_f32_16x16x32_bf16 v[104:107], v[168:171], v[200:203], v[104:107]
	v_mfma_f32_16x16x32_bf16 v[92:95], v[160:163], v[208:211], v[92:95]
	v_mfma_f32_16x16x32_bf16 v[88:91], v[168:171], v[208:211], v[88:91]
	v_mfma_f32_16x16x32_bf16 v[76:79], v[160:163], v[216:219], v[76:79]
	v_mfma_f32_16x16x32_bf16 v[72:75], v[168:171], v[216:219], v[72:75]
	s_setprio 0
	s_setprio 1
	v_mfma_f32_16x16x32_bf16 v[116:119], v[172:175], v[188:191], 0
	v_mfma_f32_16x16x32_bf16 v[112:115], v[180:183], v[188:191], 0
	v_mfma_f32_16x16x32_bf16 v[100:103], v[172:175], v[196:199], 0
	v_mfma_f32_16x16x32_bf16 v[96:99], v[180:183], v[196:199], 0
	v_mfma_f32_16x16x32_bf16 v[84:87], v[172:175], v[204:207], 0
	v_mfma_f32_16x16x32_bf16 v[80:83], v[180:183], v[204:207], 0
	v_mfma_f32_16x16x32_bf16 v[68:71], v[172:175], v[212:215], 0
	v_mfma_f32_16x16x32_bf16 v[64:67], v[180:183], v[212:215], 0
	v_mfma_f32_16x16x32_bf16 v[116:119], v[176:179], v[192:195], v[116:119]
	v_mfma_f32_16x16x32_bf16 v[112:115], v[184:187], v[192:195], v[112:115]
	v_mfma_f32_16x16x32_bf16 v[100:103], v[176:179], v[200:203], v[100:103]
	v_mfma_f32_16x16x32_bf16 v[96:99], v[184:187], v[200:203], v[96:99]
	v_mfma_f32_16x16x32_bf16 v[84:87], v[176:179], v[208:211], v[84:87]
	v_mfma_f32_16x16x32_bf16 v[80:83], v[184:187], v[208:211], v[80:83]
	v_mfma_f32_16x16x32_bf16 v[68:71], v[176:179], v[216:219], v[68:71]
	v_mfma_f32_16x16x32_bf16 v[64:67], v[184:187], v[216:219], v[64:67]
	s_setprio 0
	s_barrier
	s_add_i32 s34, s65, s54
	v_lshl_add_u64 v[220:221], s[48:49], 0, v[136:137]
	s_mov_b32 m0, s34
	ds_read_b128 v[188:191], v158 offset:16384
	ds_read_b128 v[192:195], v158 offset:17408
	ds_read_b128 v[196:199], v158 offset:18432
	ds_read_b128 v[200:203], v158 offset:19456
	ds_read_b128 v[204:207], v158 offset:20480
	ds_read_b128 v[208:211], v158 offset:21504
	ds_read_b128 v[212:215], v158 offset:22528
	ds_read_b128 v[216:219], v158 offset:23552
	global_load_lds_dwordx4 v[220:221], off
	s_add_i32 m0, s34, 0x2000
	s_add_u32 s34, s48, 0x40000
	v_lshl_add_u64 v[222:223], s[48:49], 0, v[132:133]
	s_addc_u32 s35, s49, 0
	s_add_i32 s86, s66, s54
	global_load_lds_dwordx4 v[222:223], off
	v_lshl_add_u64 v[224:225], s[34:35], 0, v[136:137]
	s_mov_b32 m0, s86
	v_lshl_add_u64 v[226:227], s[50:51], 0, v[134:135]
	global_load_lds_dwordx4 v[224:225], off
	v_lshl_add_u64 v[224:225], s[34:35], 0, v[132:133]
	s_add_i32 m0, s86, 0x2000
	s_nop 0
	global_load_lds_dwordx4 v[224:225], off
	v_lshl_add_u64 v[224:225], s[50:51], 0, v[138:139]
	s_mov_b32 m0, s41
	s_nop 0
	global_load_lds_dwordx4 v[224:225], off
	s_mov_b32 m0, s58
	s_nop 0
	global_load_lds_dwordx4 v[226:227], off
	s_waitcnt vmcnt(8)
	s_waitcnt lgkmcnt(0)
	s_barrier
	s_setprio 1
	s_waitcnt lgkmcnt(0)
	v_mfma_f32_16x16x32_bf16 v[60:63], v[148:151], v[188:191], 0
	v_mfma_f32_16x16x32_bf16 v[56:59], v[164:167], v[188:191], 0
	v_mfma_f32_16x16x32_bf16 v[44:47], v[148:151], v[196:199], 0
	v_mfma_f32_16x16x32_bf16 v[40:43], v[164:167], v[196:199], 0
	v_mfma_f32_16x16x32_bf16 v[28:31], v[148:151], v[204:207], 0
	v_mfma_f32_16x16x32_bf16 v[24:27], v[164:167], v[204:207], 0
	v_mfma_f32_16x16x32_bf16 v[12:15], v[148:151], v[212:215], 0
	v_mfma_f32_16x16x32_bf16 v[8:11], v[164:167], v[212:215], 0
	v_mfma_f32_16x16x32_bf16 v[60:63], v[160:163], v[192:195], v[60:63]
	v_mfma_f32_16x16x32_bf16 v[56:59], v[168:171], v[192:195], v[56:59]
	v_mfma_f32_16x16x32_bf16 v[44:47], v[160:163], v[200:203], v[44:47]
	v_mfma_f32_16x16x32_bf16 v[40:43], v[168:171], v[200:203], v[40:43]
	v_mfma_f32_16x16x32_bf16 v[28:31], v[160:163], v[208:211], v[28:31]
	v_mfma_f32_16x16x32_bf16 v[24:27], v[168:171], v[208:211], v[24:27]
	v_mfma_f32_16x16x32_bf16 v[12:15], v[160:163], v[216:219], v[12:15]
	v_mfma_f32_16x16x32_bf16 v[8:11], v[168:171], v[216:219], v[8:11]
	s_setprio 0
	s_setprio 1
	v_mfma_f32_16x16x32_bf16 v[52:55], v[172:175], v[188:191], 0
	v_mfma_f32_16x16x32_bf16 v[48:51], v[180:183], v[188:191], 0
	v_mfma_f32_16x16x32_bf16 v[36:39], v[172:175], v[196:199], 0
	v_mfma_f32_16x16x32_bf16 v[32:35], v[180:183], v[196:199], 0
	v_mfma_f32_16x16x32_bf16 v[20:23], v[172:175], v[204:207], 0
	v_mfma_f32_16x16x32_bf16 v[16:19], v[180:183], v[204:207], 0
	v_mfma_f32_16x16x32_bf16 v[4:7], v[172:175], v[212:215], 0
	v_mfma_f32_16x16x32_bf16 v[0:3], v[180:183], v[212:215], 0
	v_mfma_f32_16x16x32_bf16 v[52:55], v[176:179], v[192:195], v[52:55]
	v_mfma_f32_16x16x32_bf16 v[48:51], v[184:187], v[192:195], v[48:51]
	v_mfma_f32_16x16x32_bf16 v[36:39], v[176:179], v[200:203], v[36:39]
	v_mfma_f32_16x16x32_bf16 v[32:35], v[184:187], v[200:203], v[32:35]
	v_mfma_f32_16x16x32_bf16 v[20:23], v[176:179], v[208:211], v[20:23]
	v_mfma_f32_16x16x32_bf16 v[16:19], v[184:187], v[208:211], v[16:19]
	v_mfma_f32_16x16x32_bf16 v[4:7], v[176:179], v[216:219], v[4:7]
	v_mfma_f32_16x16x32_bf16 v[0:3], v[184:187], v[216:219], v[0:3]
	s_setprio 0
	s_barrier
	s_add_i32 s86, 0, 0x18000
	v_add_u32_e32 v159, s86, v152
	s_add_i32 s87, 0, 0x1c000
	ds_read_b128 v[148:151], v159
	ds_read_b128 v[160:163], v159 offset:1024
	ds_read_b128 v[164:167], v159 offset:2048
	ds_read_b128 v[168:171], v159 offset:3072
	v_add_u32_e32 v159, s87, v152
	ds_read_b128 v[172:175], v159
	ds_read_b128 v[176:179], v159 offset:1024
	ds_read_b128 v[180:183], v159 offset:2048
	ds_read_b128 v[184:187], v159 offset:3072
	s_add_u32 s34, s50, 0x40000
	s_addc_u32 s35, s51, 0
	s_mov_b32 m0, s59
	v_lshl_add_u64 v[228:229], s[34:35], 0, v[138:139]
	ds_read_b128 v[188:191], v158 offset:32768
	ds_read_b128 v[192:195], v158 offset:33792
	ds_read_b128 v[196:199], v158 offset:34816
	ds_read_b128 v[200:203], v158 offset:35840
	ds_read_b128 v[204:207], v158 offset:36864
	ds_read_b128 v[208:211], v158 offset:37888
	ds_read_b128 v[212:215], v158 offset:38912
	ds_read_b128 v[216:219], v158 offset:39936
	global_load_lds_dwordx4 v[228:229], off
	v_lshl_add_u64 v[228:229], s[34:35], 0, v[134:135]
	s_mov_b32 m0, s62
	s_nop 0
	global_load_lds_dwordx4 v[228:229], off
	s_waitcnt vmcnt(8)
	s_waitcnt lgkmcnt(0)
	s_barrier
	s_setprio 1
	s_waitcnt lgkmcnt(0)
	v_mfma_f32_16x16x32_bf16 v[124:127], v[148:151], v[188:191], v[124:127]
	v_mfma_f32_16x16x32_bf16 v[120:123], v[164:167], v[188:191], v[120:123]
	v_mfma_f32_16x16x32_bf16 v[108:111], v[148:151], v[196:199], v[108:111]
	v_mfma_f32_16x16x32_bf16 v[104:107], v[164:167], v[196:199], v[104:107]
	v_mfma_f32_16x16x32_bf16 v[92:95], v[148:151], v[204:207], v[92:95]
	v_mfma_f32_16x16x32_bf16 v[88:91], v[164:167], v[204:207], v[88:91]
	v_mfma_f32_16x16x32_bf16 v[76:79], v[148:151], v[212:215], v[76:79]
	v_mfma_f32_16x16x32_bf16 v[72:75], v[164:167], v[212:215], v[72:75]
	v_mfma_f32_16x16x32_bf16 v[124:127], v[160:163], v[192:195], v[124:127]
	v_mfma_f32_16x16x32_bf16 v[120:123], v[168:171], v[192:195], v[120:123]
	v_mfma_f32_16x16x32_bf16 v[108:111], v[160:163], v[200:203], v[108:111]
	v_mfma_f32_16x16x32_bf16 v[104:107], v[168:171], v[200:203], v[104:107]
	v_mfma_f32_16x16x32_bf16 v[92:95], v[160:163], v[208:211], v[92:95]
	v_mfma_f32_16x16x32_bf16 v[88:91], v[168:171], v[208:211], v[88:91]
	v_mfma_f32_16x16x32_bf16 v[76:79], v[160:163], v[216:219], v[76:79]
	v_mfma_f32_16x16x32_bf16 v[72:75], v[168:171], v[216:219], v[72:75]
	s_setprio 0
	s_setprio 1
	v_mfma_f32_16x16x32_bf16 v[116:119], v[172:175], v[188:191], v[116:119]
	v_mfma_f32_16x16x32_bf16 v[112:115], v[180:183], v[188:191], v[112:115]
	v_mfma_f32_16x16x32_bf16 v[100:103], v[172:175], v[196:199], v[100:103]
	v_mfma_f32_16x16x32_bf16 v[96:99], v[180:183], v[196:199], v[96:99]
	v_mfma_f32_16x16x32_bf16 v[84:87], v[172:175], v[204:207], v[84:87]
	v_mfma_f32_16x16x32_bf16 v[80:83], v[180:183], v[204:207], v[80:83]
	v_mfma_f32_16x16x32_bf16 v[68:71], v[172:175], v[212:215], v[68:71]
	v_mfma_f32_16x16x32_bf16 v[64:67], v[180:183], v[212:215], v[64:67]
	v_mfma_f32_16x16x32_bf16 v[116:119], v[176:179], v[192:195], v[116:119]
	v_mfma_f32_16x16x32_bf16 v[112:115], v[184:187], v[192:195], v[112:115]
	v_mfma_f32_16x16x32_bf16 v[100:103], v[176:179], v[200:203], v[100:103]
	v_mfma_f32_16x16x32_bf16 v[96:99], v[184:187], v[200:203], v[96:99]
	v_mfma_f32_16x16x32_bf16 v[84:87], v[176:179], v[208:211], v[84:87]
	v_mfma_f32_16x16x32_bf16 v[80:83], v[184:187], v[208:211], v[80:83]
	v_mfma_f32_16x16x32_bf16 v[68:71], v[176:179], v[216:219], v[68:71]
	v_mfma_f32_16x16x32_bf16 v[64:67], v[184:187], v[216:219], v[64:67]
	s_setprio 0
	s_barrier
	s_add_i32 s34, s86, s54
	v_lshl_add_u64 v[220:221], v[220:221], 0, s[6:7]
	s_mov_b32 m0, s34
	ds_read_b128 v[188:191], v158 offset:49152
	ds_read_b128 v[192:195], v158 offset:50176
	ds_read_b128 v[196:199], v158 offset:51200
	ds_read_b128 v[200:203], v158 offset:52224
	ds_read_b128 v[204:207], v158 offset:53248
	ds_read_b128 v[208:211], v158 offset:54272
	ds_read_b128 v[212:215], v158 offset:55296
	ds_read_b128 v[216:219], v158 offset:56320
	global_load_lds_dwordx4 v[220:221], off
	s_add_i32 m0, s34, 0x2000
	s_add_u32 s34, s48, 0x40080
	v_lshl_add_u64 v[220:221], v[222:223], 0, s[6:7]
	s_addc_u32 s35, s49, 0
	s_add_i32 s48, s87, s54
	global_load_lds_dwordx4 v[220:221], off
	v_lshl_add_u64 v[220:221], s[34:35], 0, v[136:137]
	s_mov_b32 m0, s48
	s_nop 0
	global_load_lds_dwordx4 v[220:221], off
	v_lshl_add_u64 v[220:221], s[34:35], 0, v[132:133]
	s_add_i32 m0, s48, 0x2000
	s_nop 0
	global_load_lds_dwordx4 v[220:221], off
	v_lshl_add_u64 v[220:221], v[224:225], 0, s[6:7]
	s_mov_b32 m0, s63
	s_nop 0
	global_load_lds_dwordx4 v[220:221], off
	v_lshl_add_u64 v[220:221], v[226:227], 0, s[6:7]
	s_mov_b32 m0, s64
	s_nop 0
	global_load_lds_dwordx4 v[220:221], off
	s_waitcnt vmcnt(8)
	s_waitcnt lgkmcnt(0)
	s_barrier
	s_setprio 1
	s_waitcnt lgkmcnt(0)
	v_mfma_f32_16x16x32_bf16 v[60:63], v[148:151], v[188:191], v[60:63]
	v_mfma_f32_16x16x32_bf16 v[56:59], v[164:167], v[188:191], v[56:59]
	v_mfma_f32_16x16x32_bf16 v[44:47], v[148:151], v[196:199], v[44:47]
	v_mfma_f32_16x16x32_bf16 v[40:43], v[164:167], v[196:199], v[40:43]
	v_mfma_f32_16x16x32_bf16 v[28:31], v[148:151], v[204:207], v[28:31]
	v_mfma_f32_16x16x32_bf16 v[24:27], v[164:167], v[204:207], v[24:27]
	v_mfma_f32_16x16x32_bf16 v[12:15], v[148:151], v[212:215], v[12:15]
	v_mfma_f32_16x16x32_bf16 v[8:11], v[164:167], v[212:215], v[8:11]
	v_mfma_f32_16x16x32_bf16 v[60:63], v[160:163], v[192:195], v[60:63]
	v_mfma_f32_16x16x32_bf16 v[56:59], v[168:171], v[192:195], v[56:59]
	v_mfma_f32_16x16x32_bf16 v[44:47], v[160:163], v[200:203], v[44:47]
	v_mfma_f32_16x16x32_bf16 v[40:43], v[168:171], v[200:203], v[40:43]
	v_mfma_f32_16x16x32_bf16 v[28:31], v[160:163], v[208:211], v[28:31]
	v_mfma_f32_16x16x32_bf16 v[24:27], v[168:171], v[208:211], v[24:27]
	v_mfma_f32_16x16x32_bf16 v[12:15], v[160:163], v[216:219], v[12:15]
	v_mfma_f32_16x16x32_bf16 v[8:11], v[168:171], v[216:219], v[8:11]
	s_setprio 0
	s_setprio 1
	v_mfma_f32_16x16x32_bf16 v[52:55], v[172:175], v[188:191], v[52:55]
	v_mfma_f32_16x16x32_bf16 v[48:51], v[180:183], v[188:191], v[48:51]
	v_mfma_f32_16x16x32_bf16 v[36:39], v[172:175], v[196:199], v[36:39]
	v_mfma_f32_16x16x32_bf16 v[32:35], v[180:183], v[196:199], v[32:35]
	v_mfma_f32_16x16x32_bf16 v[20:23], v[172:175], v[204:207], v[20:23]
	v_mfma_f32_16x16x32_bf16 v[16:19], v[180:183], v[204:207], v[16:19]
	v_mfma_f32_16x16x32_bf16 v[4:7], v[172:175], v[212:215], v[4:7]
	v_mfma_f32_16x16x32_bf16 v[0:3], v[180:183], v[212:215], v[0:3]
	v_mfma_f32_16x16x32_bf16 v[52:55], v[176:179], v[192:195], v[52:55]
	v_mfma_f32_16x16x32_bf16 v[48:51], v[184:187], v[192:195], v[48:51]
	v_mfma_f32_16x16x32_bf16 v[36:39], v[176:179], v[200:203], v[36:39]
	v_mfma_f32_16x16x32_bf16 v[32:35], v[184:187], v[200:203], v[32:35]
	v_mfma_f32_16x16x32_bf16 v[20:23], v[176:179], v[208:211], v[20:23]
	v_mfma_f32_16x16x32_bf16 v[16:19], v[184:187], v[208:211], v[16:19]
	v_mfma_f32_16x16x32_bf16 v[4:7], v[176:179], v[216:219], v[4:7]
	v_mfma_f32_16x16x32_bf16 v[0:3], v[184:187], v[216:219], v[0:3]
	s_setprio 0
	s_barrier
	s_add_i32 s85, s85, 2
	s_add_u32 s42, s42, 0x100
	s_addc_u32 s43, s43, 0
	s_add_u32 s83, s83, 0x100
	s_addc_u32 s84, s84, 0

.LBB0_479:
	v_lshl_add_u32 v160, s12, 10, v153
	v_lshl_or_b32 v150, s13, 7, v154
	v_lshl_add_u32 v159, s40, 8, v131
	v_ashrrev_i32_e32 v151, 31, v150
	v_mov_b64_e32 v[148:149], s[16:17]
	v_mad_i64_i32 v[164:165], s[12:13], v159, s67, v[148:149]
	v_lshlrev_b64 v[150:151], 1, v[150:151]
	v_lshl_add_u64 v[164:165], v[164:165], 0, v[150:151]
	v_mov_b32_e32 v232, v164
	v_mov_b32_e32 v233, v165
	ds_read_b32 v172, v160
	ds_read_b32 v174, v160 offset:64
	ds_read_b32 v176, v160 offset:128
	ds_read_b32 v178, v160 offset:192
	ds_read_b32 v180, v160 offset:512
	ds_read_b32 v182, v160 offset:576
	ds_read_b32 v184, v160 offset:640
	ds_read_b32 v186, v160 offset:704
	v_mov_b32_e32 v188, 0xbfb8aa3b
	s_waitcnt lgkmcnt(7)
	v_pk_mul_f32 v[124:125], v[124:125], v[172:173] op_sel_hi:[1,0]
	v_pk_mul_f32 v[126:127], v[126:127], v[172:173] op_sel_hi:[1,0]
	v_pk_mul_f32 v[120:121], v[120:121], v[172:173] op_sel_hi:[1,0]
	v_pk_mul_f32 v[122:123], v[122:123], v[172:173] op_sel_hi:[1,0]
	v_pk_mul_f32 v[116:117], v[116:117], v[172:173] op_sel_hi:[1,0]
	v_pk_mul_f32 v[118:119], v[118:119], v[172:173] op_sel_hi:[1,0]
	v_pk_mul_f32 v[112:113], v[112:113], v[172:173] op_sel_hi:[1,0]
	v_pk_mul_f32 v[114:115], v[114:115], v[172:173] op_sel_hi:[1,0]
	v_pk_mul_f32 v[192:193], v[124:125], v[188:189] op_sel_hi:[1,0]
	v_pk_mul_f32 v[194:195], v[126:127], v[188:189] op_sel_hi:[1,0]
	v_pk_mul_f32 v[196:197], v[120:121], v[188:189] op_sel_hi:[1,0]
	v_pk_mul_f32 v[198:199], v[122:123], v[188:189] op_sel_hi:[1,0]
	v_exp_f32_e32 v192, v192
	v_exp_f32_e32 v193, v193
	v_exp_f32_e32 v194, v194
	v_exp_f32_e32 v195, v195
	v_exp_f32_e32 v196, v196
	v_exp_f32_e32 v197, v197
	v_exp_f32_e32 v198, v198
	v_exp_f32_e32 v199, v199
	v_add_f32_e32 v192, 1.0, v192
	v_add_f32_e32 v193, 1.0, v193
	v_add_f32_e32 v194, 1.0, v194
	v_add_f32_e32 v195, 1.0, v195
	v_add_f32_e32 v196, 1.0, v196
	v_add_f32_e32 v197, 1.0, v197
	v_add_f32_e32 v198, 1.0, v198
	v_add_f32_e32 v199, 1.0, v199
	v_rcp_f32_e32 v192, v192
	v_rcp_f32_e32 v193, v193
	v_rcp_f32_e32 v194, v194
	v_rcp_f32_e32 v195, v195
	v_rcp_f32_e32 v196, v196
	v_rcp_f32_e32 v197, v197
	v_rcp_f32_e32 v198, v198
	v_rcp_f32_e32 v199, v199
	v_pk_mul_f32 v[124:125], v[124:125], v[192:193]
	v_pk_mul_f32 v[126:127], v[126:127], v[194:195]
	v_pk_mul_f32 v[120:121], v[120:121], v[196:197]
	v_pk_mul_f32 v[122:123], v[122:123], v[198:199]
	v_pk_mul_f32 v[124:125], v[116:117], v[124:125]
	v_pk_mul_f32 v[126:127], v[118:119], v[126:127]
	v_pk_mul_f32 v[120:121], v[112:113], v[120:121]
	v_pk_mul_f32 v[122:123], v[114:115], v[122:123]
	v_cvt_pk_bf16_f32 v208, v124, v125
	v_cvt_pk_bf16_f32 v209, v126, v127
	v_cvt_pk_bf16_f32 v210, v120, v121
	v_cvt_pk_bf16_f32 v211, v122, v123
	global_store_dwordx4 v[232:233], v[208:211], off
	s_waitcnt lgkmcnt(6)
	v_pk_mul_f32 v[108:109], v[108:109], v[174:175] op_sel_hi:[1,0]
	v_pk_mul_f32 v[110:111], v[110:111], v[174:175] op_sel_hi:[1,0]
	v_pk_mul_f32 v[104:105], v[104:105], v[174:175] op_sel_hi:[1,0]
	v_pk_mul_f32 v[106:107], v[106:107], v[174:175] op_sel_hi:[1,0]
	v_pk_mul_f32 v[100:101], v[100:101], v[174:175] op_sel_hi:[1,0]
	v_pk_mul_f32 v[102:103], v[102:103], v[174:175] op_sel_hi:[1,0]
	v_pk_mul_f32 v[96:97], v[96:97], v[174:175] op_sel_hi:[1,0]
	v_pk_mul_f32 v[98:99], v[98:99], v[174:175] op_sel_hi:[1,0]
	v_pk_mul_f32 v[200:201], v[108:109], v[188:189] op_sel_hi:[1,0]
	v_pk_mul_f32 v[202:203], v[110:111], v[188:189] op_sel_hi:[1,0]
	v_pk_mul_f32 v[204:205], v[104:105], v[188:189] op_sel_hi:[1,0]
	v_pk_mul_f32 v[206:207], v[106:107], v[188:189] op_sel_hi:[1,0]
	v_exp_f32_e32 v200, v200
	v_exp_f32_e32 v201, v201
	v_exp_f32_e32 v202, v202
	v_exp_f32_e32 v203, v203
	v_exp_f32_e32 v204, v204
	v_exp_f32_e32 v205, v205
	v_exp_f32_e32 v206, v206
	v_exp_f32_e32 v207, v207
	v_add_f32_e32 v200, 1.0, v200
	v_add_f32_e32 v201, 1.0, v201
	v_add_f32_e32 v202, 1.0, v202
	v_add_f32_e32 v203, 1.0, v203
	v_add_f32_e32 v204, 1.0, v204
	v_add_f32_e32 v205, 1.0, v205
	v_add_f32_e32 v206, 1.0, v206
	v_add_f32_e32 v207, 1.0, v207
	v_rcp_f32_e32 v200, v200
	v_rcp_f32_e32 v201, v201
	v_rcp_f32_e32 v202, v202
	v_rcp_f32_e32 v203, v203
	v_rcp_f32_e32 v204, v204
	v_rcp_f32_e32 v205, v205
	v_rcp_f32_e32 v206, v206
	v_rcp_f32_e32 v207, v207
	v_pk_mul_f32 v[108:109], v[108:109], v[200:201]
	v_pk_mul_f32 v[110:111], v[110:111], v[202:203]
	v_pk_mul_f32 v[104:105], v[104:105], v[204:205]
	v_pk_mul_f32 v[106:107], v[106:107], v[206:207]
	v_pk_mul_f32 v[108:109], v[100:101], v[108:109]
	v_pk_mul_f32 v[110:111], v[102:103], v[110:111]
	v_pk_mul_f32 v[104:105], v[96:97], v[104:105]
	v_pk_mul_f32 v[106:107], v[98:99], v[106:107]
	v_cvt_pk_bf16_f32 v212, v108, v109
	v_cvt_pk_bf16_f32 v213, v110, v111
	v_cvt_pk_bf16_f32 v214, v104, v105
	v_cvt_pk_bf16_f32 v215, v106, v107
	s_mov_b64 s[100:101], 0x16000
	v_lshl_add_u64 v[216:217], v[232:233], 0, s[100:101]
	global_store_dwordx4 v[216:217], v[212:215], off
	s_waitcnt lgkmcnt(5)
	v_pk_mul_f32 v[92:93], v[92:93], v[176:177] op_sel_hi:[1,0]
	v_pk_mul_f32 v[94:95], v[94:95], v[176:177] op_sel_hi:[1,0]
	v_pk_mul_f32 v[88:89], v[88:89], v[176:177] op_sel_hi:[1,0]
	v_pk_mul_f32 v[90:91], v[90:91], v[176:177] op_sel_hi:[1,0]
	v_pk_mul_f32 v[84:85], v[84:85], v[176:177] op_sel_hi:[1,0]
	v_pk_mul_f32 v[86:87], v[86:87], v[176:177] op_sel_hi:[1,0]
	v_pk_mul_f32 v[80:81], v[80:81], v[176:177] op_sel_hi:[1,0]
	v_pk_mul_f32 v[82:83], v[82:83], v[176:177] op_sel_hi:[1,0]
	v_pk_mul_f32 v[192:193], v[92:93], v[188:189] op_sel_hi:[1,0]
	v_pk_mul_f32 v[194:195], v[94:95], v[188:189] op_sel_hi:[1,0]
	v_pk_mul_f32 v[196:197], v[88:89], v[188:189] op_sel_hi:[1,0]
	v_pk_mul_f32 v[198:199], v[90:91], v[188:189] op_sel_hi:[1,0]
	v_exp_f32_e32 v192, v192
	v_exp_f32_e32 v193, v193
	v_exp_f32_e32 v194, v194
	v_exp_f32_e32 v195, v195
	v_exp_f32_e32 v196, v196
	v_exp_f32_e32 v197, v197
	v_exp_f32_e32 v198, v198
	v_exp_f32_e32 v199, v199
	v_add_f32_e32 v192, 1.0, v192
	v_add_f32_e32 v193, 1.0, v193
	v_add_f32_e32 v194, 1.0, v194
	v_add_f32_e32 v195, 1.0, v195
	v_add_f32_e32 v196, 1.0, v196
	v_add_f32_e32 v197, 1.0, v197
	v_add_f32_e32 v198, 1.0, v198
	v_add_f32_e32 v199, 1.0, v199
	v_rcp_f32_e32 v192, v192
	v_rcp_f32_e32 v193, v193
	v_rcp_f32_e32 v194, v194
	v_rcp_f32_e32 v195, v195
	v_rcp_f32_e32 v196, v196
	v_rcp_f32_e32 v197, v197
	v_rcp_f32_e32 v198, v198
	v_rcp_f32_e32 v199, v199
	v_pk_mul_f32 v[92:93], v[92:93], v[192:193]
	v_pk_mul_f32 v[94:95], v[94:95], v[194:195]
	v_pk_mul_f32 v[88:89], v[88:89], v[196:197]
	v_pk_mul_f32 v[90:91], v[90:91], v[198:199]
	v_pk_mul_f32 v[92:93], v[84:85], v[92:93]
	v_pk_mul_f32 v[94:95], v[86:87], v[94:95]
	v_pk_mul_f32 v[88:89], v[80:81], v[88:89]
	v_pk_mul_f32 v[90:91], v[82:83], v[90:91]
	v_cvt_pk_bf16_f32 v208, v92, v93
	v_cvt_pk_bf16_f32 v209, v94, v95
	v_cvt_pk_bf16_f32 v210, v88, v89
	v_cvt_pk_bf16_f32 v211, v90, v91
	s_mov_b64 s[100:101], 0x2c000
	v_lshl_add_u64 v[216:217], v[232:233], 0, s[100:101]
	global_store_dwordx4 v[216:217], v[208:211], off
	s_waitcnt lgkmcnt(4)
	v_pk_mul_f32 v[76:77], v[76:77], v[178:179] op_sel_hi:[1,0]
	v_pk_mul_f32 v[78:79], v[78:79], v[178:179] op_sel_hi:[1,0]
	v_pk_mul_f32 v[72:73], v[72:73], v[178:179] op_sel_hi:[1,0]
	v_pk_mul_f32 v[74:75], v[74:75], v[178:179] op_sel_hi:[1,0]
	v_pk_mul_f32 v[68:69], v[68:69], v[178:179] op_sel_hi:[1,0]
	v_pk_mul_f32 v[70:71], v[70:71], v[178:179] op_sel_hi:[1,0]
	v_pk_mul_f32 v[64:65], v[64:65], v[178:179] op_sel_hi:[1,0]
	v_pk_mul_f32 v[66:67], v[66:67], v[178:179] op_sel_hi:[1,0]
	v_pk_mul_f32 v[200:201], v[76:77], v[188:189] op_sel_hi:[1,0]
	v_pk_mul_f32 v[202:203], v[78:79], v[188:189] op_sel_hi:[1,0]
	v_pk_mul_f32 v[204:205], v[72:73], v[188:189] op_sel_hi:[1,0]
	v_pk_mul_f32 v[206:207], v[74:75], v[188:189] op_sel_hi:[1,0]
	v_exp_f32_e32 v200, v200
	v_exp_f32_e32 v201, v201
	v_exp_f32_e32 v202, v202
	v_exp_f32_e32 v203, v203
	v_exp_f32_e32 v204, v204
	v_exp_f32_e32 v205, v205
	v_exp_f32_e32 v206, v206
	v_exp_f32_e32 v207, v207
	v_add_f32_e32 v200, 1.0, v200
	v_add_f32_e32 v201, 1.0, v201
	v_add_f32_e32 v202, 1.0, v202
	v_add_f32_e32 v203, 1.0, v203
	v_add_f32_e32 v204, 1.0, v204
	v_add_f32_e32 v205, 1.0, v205
	v_add_f32_e32 v206, 1.0, v206
	v_add_f32_e32 v207, 1.0, v207
	v_rcp_f32_e32 v200, v200
	v_rcp_f32_e32 v201, v201
	v_rcp_f32_e32 v202, v202
	v_rcp_f32_e32 v203, v203
	v_rcp_f32_e32 v204, v204
	v_rcp_f32_e32 v205, v205
	v_rcp_f32_e32 v206, v206
	v_rcp_f32_e32 v207, v207
	v_pk_mul_f32 v[76:77], v[76:77], v[200:201]
	v_pk_mul_f32 v[78:79], v[78:79], v[202:203]
	v_pk_mul_f32 v[72:73], v[72:73], v[204:205]
	v_pk_mul_f32 v[74:75], v[74:75], v[206:207]
	v_pk_mul_f32 v[76:77], v[68:69], v[76:77]
	v_pk_mul_f32 v[78:79], v[70:71], v[78:79]
	v_pk_mul_f32 v[72:73], v[64:65], v[72:73]
	v_pk_mul_f32 v[74:75], v[66:67], v[74:75]
	v_cvt_pk_bf16_f32 v212, v76, v77
	v_cvt_pk_bf16_f32 v213, v78, v79
	v_cvt_pk_bf16_f32 v214, v72, v73
	v_cvt_pk_bf16_f32 v215, v74, v75
	s_mov_b64 s[100:101], 0x42000
	v_lshl_add_u64 v[216:217], v[232:233], 0, s[100:101]
	global_store_dwordx4 v[216:217], v[212:215], off
	s_waitcnt lgkmcnt(3)
	v_pk_mul_f32 v[60:61], v[60:61], v[180:181] op_sel_hi:[1,0]
	v_pk_mul_f32 v[62:63], v[62:63], v[180:181] op_sel_hi:[1,0]
	v_pk_mul_f32 v[56:57], v[56:57], v[180:181] op_sel_hi:[1,0]
	v_pk_mul_f32 v[58:59], v[58:59], v[180:181] op_sel_hi:[1,0]
	v_pk_mul_f32 v[52:53], v[52:53], v[180:181] op_sel_hi:[1,0]
	v_pk_mul_f32 v[54:55], v[54:55], v[180:181] op_sel_hi:[1,0]
	v_pk_mul_f32 v[48:49], v[48:49], v[180:181] op_sel_hi:[1,0]
	v_pk_mul_f32 v[50:51], v[50:51], v[180:181] op_sel_hi:[1,0]
	v_pk_mul_f32 v[192:193], v[60:61], v[188:189] op_sel_hi:[1,0]
	v_pk_mul_f32 v[194:195], v[62:63], v[188:189] op_sel_hi:[1,0]
	v_pk_mul_f32 v[196:197], v[56:57], v[188:189] op_sel_hi:[1,0]
	v_pk_mul_f32 v[198:199], v[58:59], v[188:189] op_sel_hi:[1,0]
	v_exp_f32_e32 v192, v192
	v_exp_f32_e32 v193, v193
	v_exp_f32_e32 v194, v194
	v_exp_f32_e32 v195, v195
	v_exp_f32_e32 v196, v196
	v_exp_f32_e32 v197, v197
	v_exp_f32_e32 v198, v198
	v_exp_f32_e32 v199, v199
	v_add_f32_e32 v192, 1.0, v192
	v_add_f32_e32 v193, 1.0, v193
	v_add_f32_e32 v194, 1.0, v194
	v_add_f32_e32 v195, 1.0, v195
	v_add_f32_e32 v196, 1.0, v196
	v_add_f32_e32 v197, 1.0, v197
	v_add_f32_e32 v198, 1.0, v198
	v_add_f32_e32 v199, 1.0, v199
	v_rcp_f32_e32 v192, v192
	v_rcp_f32_e32 v193, v193
	v_rcp_f32_e32 v194, v194
	v_rcp_f32_e32 v195, v195
	v_rcp_f32_e32 v196, v196
	v_rcp_f32_e32 v197, v197
	v_rcp_f32_e32 v198, v198
	v_rcp_f32_e32 v199, v199
	v_pk_mul_f32 v[60:61], v[60:61], v[192:193]
	v_pk_mul_f32 v[62:63], v[62:63], v[194:195]
	v_pk_mul_f32 v[56:57], v[56:57], v[196:197]
	v_pk_mul_f32 v[58:59], v[58:59], v[198:199]
	v_pk_mul_f32 v[60:61], v[52:53], v[60:61]
	v_pk_mul_f32 v[62:63], v[54:55], v[62:63]
	v_pk_mul_f32 v[56:57], v[48:49], v[56:57]
	v_pk_mul_f32 v[58:59], v[50:51], v[58:59]
	v_cvt_pk_bf16_f32 v208, v60, v61
	v_cvt_pk_bf16_f32 v209, v62, v63
	v_cvt_pk_bf16_f32 v210, v56, v57
	v_cvt_pk_bf16_f32 v211, v58, v59
	s_mov_b64 s[100:101], 0xb0000
	v_lshl_add_u64 v[216:217], v[232:233], 0, s[100:101]
	global_store_dwordx4 v[216:217], v[208:211], off
	s_waitcnt lgkmcnt(2)
	v_pk_mul_f32 v[44:45], v[44:45], v[182:183] op_sel_hi:[1,0]
	v_pk_mul_f32 v[46:47], v[46:47], v[182:183] op_sel_hi:[1,0]
	v_pk_mul_f32 v[40:41], v[40:41], v[182:183] op_sel_hi:[1,0]
	v_pk_mul_f32 v[42:43], v[42:43], v[182:183] op_sel_hi:[1,0]
	v_pk_mul_f32 v[36:37], v[36:37], v[182:183] op_sel_hi:[1,0]
	v_pk_mul_f32 v[38:39], v[38:39], v[182:183] op_sel_hi:[1,0]
	v_pk_mul_f32 v[32:33], v[32:33], v[182:183] op_sel_hi:[1,0]
	v_pk_mul_f32 v[34:35], v[34:35], v[182:183] op_sel_hi:[1,0]
	v_pk_mul_f32 v[200:201], v[44:45], v[188:189] op_sel_hi:[1,0]
	v_pk_mul_f32 v[202:203], v[46:47], v[188:189] op_sel_hi:[1,0]
	v_pk_mul_f32 v[204:205], v[40:41], v[188:189] op_sel_hi:[1,0]
	v_pk_mul_f32 v[206:207], v[42:43], v[188:189] op_sel_hi:[1,0]
	v_exp_f32_e32 v200, v200
	v_exp_f32_e32 v201, v201
	v_exp_f32_e32 v202, v202
	v_exp_f32_e32 v203, v203
	v_exp_f32_e32 v204, v204
	v_exp_f32_e32 v205, v205
	v_exp_f32_e32 v206, v206
	v_exp_f32_e32 v207, v207
	v_add_f32_e32 v200, 1.0, v200
	v_add_f32_e32 v201, 1.0, v201
	v_add_f32_e32 v202, 1.0, v202
	v_add_f32_e32 v203, 1.0, v203
	v_add_f32_e32 v204, 1.0, v204
	v_add_f32_e32 v205, 1.0, v205
	v_add_f32_e32 v206, 1.0, v206
	v_add_f32_e32 v207, 1.0, v207
	v_rcp_f32_e32 v200, v200
	v_rcp_f32_e32 v201, v201
	v_rcp_f32_e32 v202, v202
	v_rcp_f32_e32 v203, v203
	v_rcp_f32_e32 v204, v204
	v_rcp_f32_e32 v205, v205
	v_rcp_f32_e32 v206, v206
	v_rcp_f32_e32 v207, v207
	v_pk_mul_f32 v[44:45], v[44:45], v[200:201]
	v_pk_mul_f32 v[46:47], v[46:47], v[202:203]
	v_pk_mul_f32 v[40:41], v[40:41], v[204:205]
	v_pk_mul_f32 v[42:43], v[42:43], v[206:207]
	v_pk_mul_f32 v[44:45], v[36:37], v[44:45]
	v_pk_mul_f32 v[46:47], v[38:39], v[46:47]
	v_pk_mul_f32 v[40:41], v[32:33], v[40:41]
	v_pk_mul_f32 v[42:43], v[34:35], v[42:43]
	v_cvt_pk_bf16_f32 v212, v44, v45
	v_cvt_pk_bf16_f32 v213, v46, v47
	v_cvt_pk_bf16_f32 v214, v40, v41
	v_cvt_pk_bf16_f32 v215, v42, v43
	s_mov_b64 s[100:101], 0xc6000
	v_lshl_add_u64 v[216:217], v[232:233], 0, s[100:101]
	global_store_dwordx4 v[216:217], v[212:215], off
	s_waitcnt lgkmcnt(1)
	v_pk_mul_f32 v[28:29], v[28:29], v[184:185] op_sel_hi:[1,0]
	v_pk_mul_f32 v[30:31], v[30:31], v[184:185] op_sel_hi:[1,0]
	v_pk_mul_f32 v[24:25], v[24:25], v[184:185] op_sel_hi:[1,0]
	v_pk_mul_f32 v[26:27], v[26:27], v[184:185] op_sel_hi:[1,0]
	v_pk_mul_f32 v[20:21], v[20:21], v[184:185] op_sel_hi:[1,0]
	v_pk_mul_f32 v[22:23], v[22:23], v[184:185] op_sel_hi:[1,0]
	v_pk_mul_f32 v[16:17], v[16:17], v[184:185] op_sel_hi:[1,0]
	v_pk_mul_f32 v[18:19], v[18:19], v[184:185] op_sel_hi:[1,0]
	v_pk_mul_f32 v[192:193], v[28:29], v[188:189] op_sel_hi:[1,0]
	v_pk_mul_f32 v[194:195], v[30:31], v[188:189] op_sel_hi:[1,0]
	v_pk_mul_f32 v[196:197], v[24:25], v[188:189] op_sel_hi:[1,0]
	v_pk_mul_f32 v[198:199], v[26:27], v[188:189] op_sel_hi:[1,0]
	v_exp_f32_e32 v192, v192
	v_exp_f32_e32 v193, v193
	v_exp_f32_e32 v194, v194
	v_exp_f32_e32 v195, v195
	v_exp_f32_e32 v196, v196
	v_exp_f32_e32 v197, v197
	v_exp_f32_e32 v198, v198
	v_exp_f32_e32 v199, v199
	v_add_f32_e32 v192, 1.0, v192
	v_add_f32_e32 v193, 1.0, v193
	v_add_f32_e32 v194, 1.0, v194
	v_add_f32_e32 v195, 1.0, v195
	v_add_f32_e32 v196, 1.0, v196
	v_add_f32_e32 v197, 1.0, v197
	v_add_f32_e32 v198, 1.0, v198
	v_add_f32_e32 v199, 1.0, v199
	v_rcp_f32_e32 v192, v192
	v_rcp_f32_e32 v193, v193
	v_rcp_f32_e32 v194, v194
	v_rcp_f32_e32 v195, v195
	v_rcp_f32_e32 v196, v196
	v_rcp_f32_e32 v197, v197
	v_rcp_f32_e32 v198, v198
	v_rcp_f32_e32 v199, v199
	v_pk_mul_f32 v[28:29], v[28:29], v[192:193]
	v_pk_mul_f32 v[30:31], v[30:31], v[194:195]
	v_pk_mul_f32 v[24:25], v[24:25], v[196:197]
	v_pk_mul_f32 v[26:27], v[26:27], v[198:199]
	v_pk_mul_f32 v[28:29], v[20:21], v[28:29]
	v_pk_mul_f32 v[30:31], v[22:23], v[30:31]
	v_pk_mul_f32 v[24:25], v[16:17], v[24:25]
	v_pk_mul_f32 v[26:27], v[18:19], v[26:27]
	v_cvt_pk_bf16_f32 v208, v28, v29
	v_cvt_pk_bf16_f32 v209, v30, v31
	v_cvt_pk_bf16_f32 v210, v24, v25
	v_cvt_pk_bf16_f32 v211, v26, v27
	s_mov_b64 s[100:101], 0xdc000
	v_lshl_add_u64 v[216:217], v[232:233], 0, s[100:101]
	global_store_dwordx4 v[216:217], v[208:211], off
	s_waitcnt lgkmcnt(0)
	v_pk_mul_f32 v[12:13], v[12:13], v[186:187] op_sel_hi:[1,0]
	v_pk_mul_f32 v[14:15], v[14:15], v[186:187] op_sel_hi:[1,0]
	v_pk_mul_f32 v[8:9], v[8:9], v[186:187] op_sel_hi:[1,0]
	v_pk_mul_f32 v[10:11], v[10:11], v[186:187] op_sel_hi:[1,0]
	v_pk_mul_f32 v[4:5], v[4:5], v[186:187] op_sel_hi:[1,0]
	v_pk_mul_f32 v[6:7], v[6:7], v[186:187] op_sel_hi:[1,0]
	v_pk_mul_f32 v[0:1], v[0:1], v[186:187] op_sel_hi:[1,0]
	v_pk_mul_f32 v[2:3], v[2:3], v[186:187] op_sel_hi:[1,0]
	v_pk_mul_f32 v[200:201], v[12:13], v[188:189] op_sel_hi:[1,0]
	v_pk_mul_f32 v[202:203], v[14:15], v[188:189] op_sel_hi:[1,0]
	v_pk_mul_f32 v[204:205], v[8:9], v[188:189] op_sel_hi:[1,0]
	v_pk_mul_f32 v[206:207], v[10:11], v[188:189] op_sel_hi:[1,0]
	v_exp_f32_e32 v200, v200
	v_exp_f32_e32 v201, v201
	v_exp_f32_e32 v202, v202
	v_exp_f32_e32 v203, v203
	v_exp_f32_e32 v204, v204
	v_exp_f32_e32 v205, v205
	v_exp_f32_e32 v206, v206
	v_exp_f32_e32 v207, v207
	v_add_f32_e32 v200, 1.0, v200
	v_add_f32_e32 v201, 1.0, v201
	v_add_f32_e32 v202, 1.0, v202
	v_add_f32_e32 v203, 1.0, v203
	v_add_f32_e32 v204, 1.0, v204
	v_add_f32_e32 v205, 1.0, v205
	v_add_f32_e32 v206, 1.0, v206
	v_add_f32_e32 v207, 1.0, v207
	v_rcp_f32_e32 v200, v200
	v_rcp_f32_e32 v201, v201
	v_rcp_f32_e32 v202, v202
	v_rcp_f32_e32 v203, v203
	v_rcp_f32_e32 v204, v204
	v_rcp_f32_e32 v205, v205
	v_rcp_f32_e32 v206, v206
	v_rcp_f32_e32 v207, v207
	v_pk_mul_f32 v[12:13], v[12:13], v[200:201]
	v_pk_mul_f32 v[14:15], v[14:15], v[202:203]
	v_pk_mul_f32 v[8:9], v[8:9], v[204:205]
	v_pk_mul_f32 v[10:11], v[10:11], v[206:207]
	v_pk_mul_f32 v[12:13], v[4:5], v[12:13]
	v_pk_mul_f32 v[14:15], v[6:7], v[14:15]
	v_pk_mul_f32 v[8:9], v[0:1], v[8:9]
	v_pk_mul_f32 v[10:11], v[2:3], v[10:11]
	v_cvt_pk_bf16_f32 v212, v12, v13
	v_cvt_pk_bf16_f32 v213, v14, v15
	v_cvt_pk_bf16_f32 v214, v8, v9
	v_cvt_pk_bf16_f32 v215, v10, v11
	s_mov_b64 s[100:101], 0xf2000
	v_lshl_add_u64 v[216:217], v[232:233], 0, s[100:101]
	global_store_dwordx4 v[216:217], v[212:215], off
	s_andn2_b64 vcc, exec, s[4:5]
	s_mov_b64 s[4:5], -1
	s_cbranch_vccnz .LBB0_472
	s_andn2_b64 vcc, exec, s[0:1]
	s_cbranch_vccnz .LBB0_471
	s_barrier
	s_branch .LBB0_471

.LBB0_551:
	s_add_i32 s66, s66, 1
	s_mul_i32 s0, s66, s59
	s_mul_hi_u32 s1, s66, s62
	s_add_i32 s1, s1, s0
	s_mul_i32 s0, s66, s62
	s_add_u32 s6, s0, s2
	s_addc_u32 s7, s1, s63
	v_cmp_gt_i64_e32 vcc, s[6:7], v[146:147]
	v_cmp_lt_i64_e64 s[0:1], s[6:7], v[144:145]
	s_cbranch_vccnz .LBB0_557
	s_and_b32 s100, s6, 7
	s_mul_i32 s100, s100, 0x40
	s_lshr_b32 s101, s6, 3
	s_add_i32 s100, s100, s101
	s_mul_hi_u32 s101, s100, 0x8000000
	s_mul_i32 s67, s101, 0x20
	s_sub_i32 s67, s100, s67
	s_and_b32 s100, s67, 7
	s_lshl_b32 s79, s101, 3
	s_add_i32 s79, s79, s100
	s_lshr_b32 s67, s67, 3

.LBB0_561:
	s_add_u32 s40, s40, 0xb0080
	s_addc_u32 s41, s41, 0
	s_add_u32 s13, s42, 0x100
	s_addc_u32 s77, s43, 0
	s_mov_b32 s81, -2
	s_waitcnt lgkmcnt(0)
	ds_read_b128 v[148:151], v154
	ds_read_b128 v[160:163], v154 offset:1024
	ds_read_b128 v[164:167], v154 offset:2048
	ds_read_b128 v[168:171], v154 offset:3072
	ds_read_b128 v[172:175], v155
	ds_read_b128 v[176:179], v155 offset:1024
	ds_read_b128 v[180:183], v155 offset:2048
	ds_read_b128 v[184:187], v155 offset:3072
	s_add_u32 s34, s40, 0xfff50080
	s_addc_u32 s35, s41, -1
	s_cmp_eq_u32 s81, 40
	s_cselect_b32 s49, s1, s35
	s_cselect_b32 s48, s0, s34
	s_cselect_b32 s43, s29, s77
	s_cselect_b32 s42, s28, s13
	v_lshl_add_u64 v[220:221], s[40:41], 0, v[140:141]
	s_add_i32 m0, s52, 0xc000
	ds_read_b128 v[188:191], v157
	ds_read_b128 v[192:195], v157 offset:1024
	ds_read_b128 v[196:199], v157 offset:2048
	ds_read_b128 v[200:203], v157 offset:3072
	ds_read_b128 v[204:207], v157 offset:4096
	ds_read_b128 v[208:211], v157 offset:5120
	ds_read_b128 v[212:215], v157 offset:6144
	ds_read_b128 v[216:219], v157 offset:7168
	global_load_lds_dwordx4 v[220:221], off
	v_lshl_add_u64 v[220:221], s[40:41], 0, v[142:143]
	s_add_i32 m0, s52, 0xe000
	s_nop 0
	global_load_lds_dwordx4 v[220:221], off
	s_waitcnt vmcnt(8)
	s_waitcnt lgkmcnt(0)
	s_barrier
	s_setprio 1
	s_waitcnt lgkmcnt(0)
	v_mfma_f32_16x16x32_bf16 v[124:127], v[148:151], v[188:191], 0
	v_mfma_f32_16x16x32_bf16 v[120:123], v[164:167], v[188:191], 0
	v_mfma_f32_16x16x32_bf16 v[108:111], v[148:151], v[196:199], 0
	v_mfma_f32_16x16x32_bf16 v[104:107], v[164:167], v[196:199], 0
	v_mfma_f32_16x16x32_bf16 v[92:95], v[148:151], v[204:207], 0
	v_mfma_f32_16x16x32_bf16 v[88:91], v[164:167], v[204:207], 0
	v_mfma_f32_16x16x32_bf16 v[76:79], v[148:151], v[212:215], 0
	v_mfma_f32_16x16x32_bf16 v[72:75], v[164:167], v[212:215], 0
	v_mfma_f32_16x16x32_bf16 v[124:127], v[160:163], v[192:195], v[124:127]
	v_mfma_f32_16x16x32_bf16 v[120:123], v[168:171], v[192:195], v[120:123]
	v_mfma_f32_16x16x32_bf16 v[108:111], v[160:163], v[200:203], v[108:111]
	v_mfma_f32_16x16x32_bf16 v[104:107], v[168:171], v[200:203], v[104:107]
	v_mfma_f32_16x16x32_bf16 v[92:95], v[160:163], v[208:211], v[92:95]
	v_mfma_f32_16x16x32_bf16 v[88:91], v[168:171], v[208:211], v[88:91]
	v_mfma_f32_16x16x32_bf16 v[76:79], v[160:163], v[216:219], v[76:79]
	v_mfma_f32_16x16x32_bf16 v[72:75], v[168:171], v[216:219], v[72:75]
	s_setprio 0
	s_setprio 1
	v_mfma_f32_16x16x32_bf16 v[116:119], v[172:175], v[188:191], 0
	v_mfma_f32_16x16x32_bf16 v[112:115], v[180:183], v[188:191], 0
	v_mfma_f32_16x16x32_bf16 v[100:103], v[172:175], v[196:199], 0
	v_mfma_f32_16x16x32_bf16 v[96:99], v[180:183], v[196:199], 0
	v_mfma_f32_16x16x32_bf16 v[84:87], v[172:175], v[204:207], 0
	v_mfma_f32_16x16x32_bf16 v[80:83], v[180:183], v[204:207], 0
	v_mfma_f32_16x16x32_bf16 v[68:71], v[172:175], v[212:215], 0
	v_mfma_f32_16x16x32_bf16 v[64:67], v[180:183], v[212:215], 0
	v_mfma_f32_16x16x32_bf16 v[116:119], v[176:179], v[192:195], v[116:119]
	v_mfma_f32_16x16x32_bf16 v[112:115], v[184:187], v[192:195], v[112:115]
	v_mfma_f32_16x16x32_bf16 v[100:103], v[176:179], v[200:203], v[100:103]
	v_mfma_f32_16x16x32_bf16 v[96:99], v[184:187], v[200:203], v[96:99]
	v_mfma_f32_16x16x32_bf16 v[84:87], v[176:179], v[208:211], v[84:87]
	v_mfma_f32_16x16x32_bf16 v[80:83], v[184:187], v[208:211], v[80:83]
	v_mfma_f32_16x16x32_bf16 v[68:71], v[176:179], v[216:219], v[68:71]
	v_mfma_f32_16x16x32_bf16 v[64:67], v[184:187], v[216:219], v[64:67]
	s_setprio 0
	s_barrier
	s_add_i32 s34, s64, s51
	v_lshl_add_u64 v[220:221], s[42:43], 0, v[134:135]
	s_mov_b32 m0, s34
	ds_read_b128 v[188:191], v157 offset:16384
	ds_read_b128 v[192:195], v157 offset:17408
	ds_read_b128 v[196:199], v157 offset:18432
	ds_read_b128 v[200:203], v157 offset:19456
	ds_read_b128 v[204:207], v157 offset:20480
	ds_read_b128 v[208:211], v157 offset:21504
	ds_read_b128 v[212:215], v157 offset:22528
	ds_read_b128 v[216:219], v157 offset:23552
	global_load_lds_dwordx4 v[220:221], off
	s_add_i32 m0, s34, 0x2000
	s_add_u32 s34, s42, 0xb0000
	v_lshl_add_u64 v[222:223], s[42:43], 0, v[138:139]
	s_addc_u32 s35, s43, 0
	s_add_i32 s82, s65, s51
	global_load_lds_dwordx4 v[222:223], off
	v_lshl_add_u64 v[224:225], s[34:35], 0, v[134:135]
	s_mov_b32 m0, s82
	v_lshl_add_u64 v[226:227], s[48:49], 0, v[136:137]
	global_load_lds_dwordx4 v[224:225], off
	v_lshl_add_u64 v[224:225], s[34:35], 0, v[138:139]
	s_add_i32 m0, s82, 0x2000
	s_nop 0
	global_load_lds_dwordx4 v[224:225], off
	v_lshl_add_u64 v[224:225], s[48:49], 0, v[132:133]
	s_mov_b32 m0, s52
	s_nop 0
	global_load_lds_dwordx4 v[224:225], off
	s_mov_b32 m0, s53
	s_nop 0
	global_load_lds_dwordx4 v[226:227], off
	s_waitcnt vmcnt(8)
	s_waitcnt lgkmcnt(0)
	s_barrier
	s_setprio 1
	s_waitcnt lgkmcnt(0)
	v_mfma_f32_16x16x32_bf16 v[60:63], v[148:151], v[188:191], 0
	v_mfma_f32_16x16x32_bf16 v[56:59], v[164:167], v[188:191], 0
	v_mfma_f32_16x16x32_bf16 v[44:47], v[148:151], v[196:199], 0
	v_mfma_f32_16x16x32_bf16 v[40:43], v[164:167], v[196:199], 0
	v_mfma_f32_16x16x32_bf16 v[28:31], v[148:151], v[204:207], 0
	v_mfma_f32_16x16x32_bf16 v[24:27], v[164:167], v[204:207], 0
	v_mfma_f32_16x16x32_bf16 v[12:15], v[148:151], v[212:215], 0
	v_mfma_f32_16x16x32_bf16 v[8:11], v[164:167], v[212:215], 0
	v_mfma_f32_16x16x32_bf16 v[60:63], v[160:163], v[192:195], v[60:63]
	v_mfma_f32_16x16x32_bf16 v[56:59], v[168:171], v[192:195], v[56:59]
	v_mfma_f32_16x16x32_bf16 v[44:47], v[160:163], v[200:203], v[44:47]
	v_mfma_f32_16x16x32_bf16 v[40:43], v[168:171], v[200:203], v[40:43]
	v_mfma_f32_16x16x32_bf16 v[28:31], v[160:163], v[208:211], v[28:31]
	v_mfma_f32_16x16x32_bf16 v[24:27], v[168:171], v[208:211], v[24:27]
	v_mfma_f32_16x16x32_bf16 v[12:15], v[160:163], v[216:219], v[12:15]
	v_mfma_f32_16x16x32_bf16 v[8:11], v[168:171], v[216:219], v[8:11]
	s_setprio 0
	s_setprio 1
	v_mfma_f32_16x16x32_bf16 v[52:55], v[172:175], v[188:191], 0
	v_mfma_f32_16x16x32_bf16 v[48:51], v[180:183], v[188:191], 0
	v_mfma_f32_16x16x32_bf16 v[36:39], v[172:175], v[196:199], 0
	v_mfma_f32_16x16x32_bf16 v[32:35], v[180:183], v[196:199], 0
	v_mfma_f32_16x16x32_bf16 v[20:23], v[172:175], v[204:207], 0
	v_mfma_f32_16x16x32_bf16 v[16:19], v[180:183], v[204:207], 0
	v_mfma_f32_16x16x32_bf16 v[4:7], v[172:175], v[212:215], 0
	v_mfma_f32_16x16x32_bf16 v[0:3], v[180:183], v[212:215], 0
	v_mfma_f32_16x16x32_bf16 v[52:55], v[176:179], v[192:195], v[52:55]
	v_mfma_f32_16x16x32_bf16 v[48:51], v[184:187], v[192:195], v[48:51]
	v_mfma_f32_16x16x32_bf16 v[36:39], v[176:179], v[200:203], v[36:39]
	v_mfma_f32_16x16x32_bf16 v[32:35], v[184:187], v[200:203], v[32:35]
	v_mfma_f32_16x16x32_bf16 v[20:23], v[176:179], v[208:211], v[20:23]
	v_mfma_f32_16x16x32_bf16 v[16:19], v[184:187], v[208:211], v[16:19]
	v_mfma_f32_16x16x32_bf16 v[4:7], v[176:179], v[216:219], v[4:7]
	v_mfma_f32_16x16x32_bf16 v[0:3], v[184:187], v[216:219], v[0:3]
	s_setprio 0
	s_barrier
	s_add_i32 s82, 0, 0x18000
	v_add_u32_e32 v159, s82, v152
	s_add_i32 s83, 0, 0x1c000
	ds_read_b128 v[148:151], v159
	ds_read_b128 v[160:163], v159 offset:1024
	ds_read_b128 v[164:167], v159 offset:2048
	ds_read_b128 v[168:171], v159 offset:3072
	v_add_u32_e32 v159, s83, v152
	ds_read_b128 v[172:175], v159
	ds_read_b128 v[176:179], v159 offset:1024
	ds_read_b128 v[180:183], v159 offset:2048
	ds_read_b128 v[184:187], v159 offset:3072
	s_add_u32 s34, s48, 0xb0000
	s_addc_u32 s35, s49, 0
	s_mov_b32 m0, s54
	v_lshl_add_u64 v[228:229], s[34:35], 0, v[132:133]
	ds_read_b128 v[188:191], v157 offset:32768
	ds_read_b128 v[192:195], v157 offset:33792
	ds_read_b128 v[196:199], v157 offset:34816
	ds_read_b128 v[200:203], v157 offset:35840
	ds_read_b128 v[204:207], v157 offset:36864
	ds_read_b128 v[208:211], v157 offset:37888
	ds_read_b128 v[212:215], v157 offset:38912
	ds_read_b128 v[216:219], v157 offset:39936
	global_load_lds_dwordx4 v[228:229], off
	v_lshl_add_u64 v[228:229], s[34:35], 0, v[136:137]
	s_mov_b32 m0, s55
	s_nop 0
	global_load_lds_dwordx4 v[228:229], off
	s_waitcnt vmcnt(8)
	s_waitcnt lgkmcnt(0)
	s_barrier
	s_setprio 1
	s_waitcnt lgkmcnt(0)
	v_mfma_f32_16x16x32_bf16 v[124:127], v[148:151], v[188:191], v[124:127]
	v_mfma_f32_16x16x32_bf16 v[120:123], v[164:167], v[188:191], v[120:123]
	v_mfma_f32_16x16x32_bf16 v[108:111], v[148:151], v[196:199], v[108:111]
	v_mfma_f32_16x16x32_bf16 v[104:107], v[164:167], v[196:199], v[104:107]
	v_mfma_f32_16x16x32_bf16 v[92:95], v[148:151], v[204:207], v[92:95]
	v_mfma_f32_16x16x32_bf16 v[88:91], v[164:167], v[204:207], v[88:91]
	v_mfma_f32_16x16x32_bf16 v[76:79], v[148:151], v[212:215], v[76:79]
	v_mfma_f32_16x16x32_bf16 v[72:75], v[164:167], v[212:215], v[72:75]
	v_mfma_f32_16x16x32_bf16 v[124:127], v[160:163], v[192:195], v[124:127]
	v_mfma_f32_16x16x32_bf16 v[120:123], v[168:171], v[192:195], v[120:123]
	v_mfma_f32_16x16x32_bf16 v[108:111], v[160:163], v[200:203], v[108:111]
	v_mfma_f32_16x16x32_bf16 v[104:107], v[168:171], v[200:203], v[104:107]
	v_mfma_f32_16x16x32_bf16 v[92:95], v[160:163], v[208:211], v[92:95]
	v_mfma_f32_16x16x32_bf16 v[88:91], v[168:171], v[208:211], v[88:91]
	v_mfma_f32_16x16x32_bf16 v[76:79], v[160:163], v[216:219], v[76:79]
	v_mfma_f32_16x16x32_bf16 v[72:75], v[168:171], v[216:219], v[72:75]
	s_setprio 0
	s_setprio 1
	v_mfma_f32_16x16x32_bf16 v[116:119], v[172:175], v[188:191], v[116:119]
	v_mfma_f32_16x16x32_bf16 v[112:115], v[180:183], v[188:191], v[112:115]
	v_mfma_f32_16x16x32_bf16 v[100:103], v[172:175], v[196:199], v[100:103]
	v_mfma_f32_16x16x32_bf16 v[96:99], v[180:183], v[196:199], v[96:99]
	v_mfma_f32_16x16x32_bf16 v[84:87], v[172:175], v[204:207], v[84:87]
	v_mfma_f32_16x16x32_bf16 v[80:83], v[180:183], v[204:207], v[80:83]
	v_mfma_f32_16x16x32_bf16 v[68:71], v[172:175], v[212:215], v[68:71]
	v_mfma_f32_16x16x32_bf16 v[64:67], v[180:183], v[212:215], v[64:67]
	v_mfma_f32_16x16x32_bf16 v[116:119], v[176:179], v[192:195], v[116:119]
	v_mfma_f32_16x16x32_bf16 v[112:115], v[184:187], v[192:195], v[112:115]
	v_mfma_f32_16x16x32_bf16 v[100:103], v[176:179], v[200:203], v[100:103]
	v_mfma_f32_16x16x32_bf16 v[96:99], v[184:187], v[200:203], v[96:99]
	v_mfma_f32_16x16x32_bf16 v[84:87], v[176:179], v[208:211], v[84:87]
	v_mfma_f32_16x16x32_bf16 v[80:83], v[184:187], v[208:211], v[80:83]
	v_mfma_f32_16x16x32_bf16 v[68:71], v[176:179], v[216:219], v[68:71]
	v_mfma_f32_16x16x32_bf16 v[64:67], v[184:187], v[216:219], v[64:67]
	s_setprio 0
	s_barrier
	s_add_i32 s34, s82, s51
	v_lshl_add_u64 v[220:221], v[220:221], 0, s[22:23]
	s_mov_b32 m0, s34
	ds_read_b128 v[188:191], v157 offset:49152
	ds_read_b128 v[192:195], v157 offset:50176
	ds_read_b128 v[196:199], v157 offset:51200
	ds_read_b128 v[200:203], v157 offset:52224
	ds_read_b128 v[204:207], v157 offset:53248
	ds_read_b128 v[208:211], v157 offset:54272
	ds_read_b128 v[212:215], v157 offset:55296
	ds_read_b128 v[216:219], v157 offset:56320
	global_load_lds_dwordx4 v[220:221], off
	s_add_i32 m0, s34, 0x2000
	s_add_u32 s34, s42, 0xb0080
	v_lshl_add_u64 v[220:221], v[222:223], 0, s[22:23]
	s_addc_u32 s35, s43, 0
	s_add_i32 s42, s83, s51
	global_load_lds_dwordx4 v[220:221], off
	v_lshl_add_u64 v[220:221], s[34:35], 0, v[134:135]
	s_mov_b32 m0, s42
	s_nop 0
	global_load_lds_dwordx4 v[220:221], off
	v_lshl_add_u64 v[220:221], s[34:35], 0, v[138:139]
	s_add_i32 m0, s42, 0x2000
	s_nop 0
	global_load_lds_dwordx4 v[220:221], off
	v_lshl_add_u64 v[220:221], v[224:225], 0, s[22:23]
	s_mov_b32 m0, s57
	s_nop 0
	global_load_lds_dwordx4 v[220:221], off
	v_lshl_add_u64 v[220:221], v[226:227], 0, s[22:23]
	s_mov_b32 m0, s58
	s_nop 0
	global_load_lds_dwordx4 v[220:221], off
	s_waitcnt vmcnt(8)
	s_waitcnt lgkmcnt(0)
	s_barrier
	s_setprio 1
	s_waitcnt lgkmcnt(0)
	v_mfma_f32_16x16x32_bf16 v[60:63], v[148:151], v[188:191], v[60:63]
	v_mfma_f32_16x16x32_bf16 v[56:59], v[164:167], v[188:191], v[56:59]
	v_mfma_f32_16x16x32_bf16 v[44:47], v[148:151], v[196:199], v[44:47]
	v_mfma_f32_16x16x32_bf16 v[40:43], v[164:167], v[196:199], v[40:43]
	v_mfma_f32_16x16x32_bf16 v[28:31], v[148:151], v[204:207], v[28:31]
	v_mfma_f32_16x16x32_bf16 v[24:27], v[164:167], v[204:207], v[24:27]
	v_mfma_f32_16x16x32_bf16 v[12:15], v[148:151], v[212:215], v[12:15]
	v_mfma_f32_16x16x32_bf16 v[8:11], v[164:167], v[212:215], v[8:11]
	v_mfma_f32_16x16x32_bf16 v[60:63], v[160:163], v[192:195], v[60:63]
	v_mfma_f32_16x16x32_bf16 v[56:59], v[168:171], v[192:195], v[56:59]
	v_mfma_f32_16x16x32_bf16 v[44:47], v[160:163], v[200:203], v[44:47]
	v_mfma_f32_16x16x32_bf16 v[40:43], v[168:171], v[200:203], v[40:43]
	v_mfma_f32_16x16x32_bf16 v[28:31], v[160:163], v[208:211], v[28:31]
	v_mfma_f32_16x16x32_bf16 v[24:27], v[168:171], v[208:211], v[24:27]
	v_mfma_f32_16x16x32_bf16 v[12:15], v[160:163], v[216:219], v[12:15]
	v_mfma_f32_16x16x32_bf16 v[8:11], v[168:171], v[216:219], v[8:11]
	s_setprio 0
	s_setprio 1
	v_mfma_f32_16x16x32_bf16 v[52:55], v[172:175], v[188:191], v[52:55]
	v_mfma_f32_16x16x32_bf16 v[48:51], v[180:183], v[188:191], v[48:51]
	v_mfma_f32_16x16x32_bf16 v[36:39], v[172:175], v[196:199], v[36:39]
	v_mfma_f32_16x16x32_bf16 v[32:35], v[180:183], v[196:199], v[32:35]
	v_mfma_f32_16x16x32_bf16 v[20:23], v[172:175], v[204:207], v[20:23]
	v_mfma_f32_16x16x32_bf16 v[16:19], v[180:183], v[204:207], v[16:19]
	v_mfma_f32_16x16x32_bf16 v[4:7], v[172:175], v[212:215], v[4:7]
	v_mfma_f32_16x16x32_bf16 v[0:3], v[180:183], v[212:215], v[0:3]
	v_mfma_f32_16x16x32_bf16 v[52:55], v[176:179], v[192:195], v[52:55]
	v_mfma_f32_16x16x32_bf16 v[48:51], v[184:187], v[192:195], v[48:51]
	v_mfma_f32_16x16x32_bf16 v[36:39], v[176:179], v[200:203], v[36:39]
	v_mfma_f32_16x16x32_bf16 v[32:35], v[184:187], v[200:203], v[32:35]
	v_mfma_f32_16x16x32_bf16 v[20:23], v[176:179], v[208:211], v[20:23]
	v_mfma_f32_16x16x32_bf16 v[16:19], v[184:187], v[208:211], v[16:19]
	v_mfma_f32_16x16x32_bf16 v[4:7], v[176:179], v[216:219], v[4:7]
	v_mfma_f32_16x16x32_bf16 v[0:3], v[184:187], v[216:219], v[0:3]
	s_setprio 0
	s_barrier
	s_add_i32 s81, s81, 2
	s_add_u32 s40, s40, 0x100
	s_addc_u32 s41, s41, 0
	s_add_u32 s13, s13, 0x100
	s_addc_u32 s77, s77, 0

.LBB0_652:
	s_add_i32 s93, s93, 1
	s_mul_i32 s6, s93, s58
	s_mul_hi_u32 s7, s93, s59
	s_add_i32 s7, s7, s6
	s_mul_i32 s6, s93, s59
	s_add_u32 s48, s6, s2
	s_addc_u32 s49, s7, s3
	v_cmp_gt_i64_e32 vcc, s[48:49], v[146:147]
	v_cmp_lt_i64_e64 s[6:7], s[48:49], v[144:145]
	s_cbranch_vccnz .LBB0_654
	s_and_b32 s100, s48, 7
	s_mul_i32 s100, s100, 0xc0
	s_lshr_b32 s101, s48, 3
	s_add_i32 s100, s100, s101
	s_mul_hi_u32 s101, s100, 0x2aaaaab
	s_mul_i32 s40, s101, 0x60
	s_sub_i32 s40, s100, s40
	s_and_b32 s100, s40, 7
	s_lshl_b32 s42, s101, 3
	s_add_i32 s42, s42, s100
	s_lshr_b32 s40, s40, 3
	s_mov_b32 s94, s93
.LBB0_654:
	s_ashr_i32 s43, s42, 31
	s_lshl_b64 s[12:13], s[42:43], 19
	s_add_u32 s48, s14, s12
	s_addc_u32 s49, s15, s13
	s_and_b64 s[12:13], s[6:7], exec
	s_cselect_b32 s9, s49, s53
	s_cselect_b32 s10, s48, s52
	s_ashr_i32 s41, s40, 31
	s_lshl_b64 s[12:13], s[40:41], 19
	s_add_u32 s50, s63, s12
	s_addc_u32 s51, s64, s13
	s_and_b64 s[12:13], s[6:7], exec
	s_cselect_b32 s12, s51, s55
	s_cselect_b32 s13, s50, s54
	s_add_u32 s52, s52, 0x40080
	s_addc_u32 s53, s53, 0
	s_add_u32 s41, s54, 0x100
	s_addc_u32 s43, s55, 0
	s_mov_b32 s77, -2
	s_waitcnt lgkmcnt(0)
	ds_read_b128 v[148:151], v160
	ds_read_b128 v[152:155], v160 offset:1024
	ds_read_b128 v[164:167], v160 offset:2048
	ds_read_b128 v[168:171], v160 offset:3072
	ds_read_b128 v[172:175], v161
	ds_read_b128 v[176:179], v161 offset:1024
	ds_read_b128 v[180:183], v161 offset:2048
	ds_read_b128 v[184:187], v161 offset:3072
	s_add_u32 s34, s52, 0xfffc0080
	s_addc_u32 s35, s53, -1
	s_cmp_eq_u32 s77, 12
	s_cselect_b32 s57, s9, s35
	s_cselect_b32 s56, s10, s34
	s_cselect_b32 s55, s12, s43
	s_cselect_b32 s54, s13, s41
	v_lshl_add_u64 v[220:221], s[52:53], 0, v[140:141]
	s_add_i32 m0, s65, 0xc000
	ds_read_b128 v[188:191], v162
	ds_read_b128 v[192:195], v162 offset:1024
	ds_read_b128 v[196:199], v162 offset:2048
	ds_read_b128 v[200:203], v162 offset:3072
	ds_read_b128 v[204:207], v162 offset:4096
	ds_read_b128 v[208:211], v162 offset:5120
	ds_read_b128 v[212:215], v162 offset:6144
	ds_read_b128 v[216:219], v162 offset:7168
	global_load_lds_dwordx4 v[220:221], off
	v_lshl_add_u64 v[220:221], s[52:53], 0, v[142:143]
	s_add_i32 m0, s65, 0xe000
	s_nop 0
	global_load_lds_dwordx4 v[220:221], off
	s_waitcnt vmcnt(8)
	s_waitcnt lgkmcnt(0)
	s_barrier
	s_setprio 1
	s_waitcnt lgkmcnt(0)
	v_mfma_f32_16x16x32_bf16 v[124:127], v[148:151], v[188:191], 0
	v_mfma_f32_16x16x32_bf16 v[120:123], v[164:167], v[188:191], 0
	v_mfma_f32_16x16x32_bf16 v[108:111], v[148:151], v[196:199], 0
	v_mfma_f32_16x16x32_bf16 v[104:107], v[164:167], v[196:199], 0
	v_mfma_f32_16x16x32_bf16 v[92:95], v[148:151], v[204:207], 0
	v_mfma_f32_16x16x32_bf16 v[88:91], v[164:167], v[204:207], 0
	v_mfma_f32_16x16x32_bf16 v[76:79], v[148:151], v[212:215], 0
	v_mfma_f32_16x16x32_bf16 v[72:75], v[164:167], v[212:215], 0
	v_mfma_f32_16x16x32_bf16 v[124:127], v[152:155], v[192:195], v[124:127]
	v_mfma_f32_16x16x32_bf16 v[120:123], v[168:171], v[192:195], v[120:123]
	v_mfma_f32_16x16x32_bf16 v[108:111], v[152:155], v[200:203], v[108:111]
	v_mfma_f32_16x16x32_bf16 v[104:107], v[168:171], v[200:203], v[104:107]
	v_mfma_f32_16x16x32_bf16 v[92:95], v[152:155], v[208:211], v[92:95]
	v_mfma_f32_16x16x32_bf16 v[88:91], v[168:171], v[208:211], v[88:91]
	v_mfma_f32_16x16x32_bf16 v[76:79], v[152:155], v[216:219], v[76:79]
	v_mfma_f32_16x16x32_bf16 v[72:75], v[168:171], v[216:219], v[72:75]
	s_setprio 0
	s_setprio 1
	v_mfma_f32_16x16x32_bf16 v[116:119], v[172:175], v[188:191], 0
	v_mfma_f32_16x16x32_bf16 v[112:115], v[180:183], v[188:191], 0
	v_mfma_f32_16x16x32_bf16 v[100:103], v[172:175], v[196:199], 0
	v_mfma_f32_16x16x32_bf16 v[96:99], v[180:183], v[196:199], 0
	v_mfma_f32_16x16x32_bf16 v[84:87], v[172:175], v[204:207], 0
	v_mfma_f32_16x16x32_bf16 v[80:83], v[180:183], v[204:207], 0
	v_mfma_f32_16x16x32_bf16 v[68:71], v[172:175], v[212:215], 0
	v_mfma_f32_16x16x32_bf16 v[64:67], v[180:183], v[212:215], 0
	v_mfma_f32_16x16x32_bf16 v[116:119], v[176:179], v[192:195], v[116:119]
	v_mfma_f32_16x16x32_bf16 v[112:115], v[184:187], v[192:195], v[112:115]
	v_mfma_f32_16x16x32_bf16 v[100:103], v[176:179], v[200:203], v[100:103]
	v_mfma_f32_16x16x32_bf16 v[96:99], v[184:187], v[200:203], v[96:99]
	v_mfma_f32_16x16x32_bf16 v[84:87], v[176:179], v[208:211], v[84:87]
	v_mfma_f32_16x16x32_bf16 v[80:83], v[184:187], v[208:211], v[80:83]
	v_mfma_f32_16x16x32_bf16 v[68:71], v[176:179], v[216:219], v[68:71]
	v_mfma_f32_16x16x32_bf16 v[64:67], v[184:187], v[216:219], v[64:67]
	s_setprio 0
	s_barrier
	s_add_i32 s34, s88, s62
	v_lshl_add_u64 v[220:221], s[54:55], 0, v[134:135]
	s_mov_b32 m0, s34
	ds_read_b128 v[188:191], v162 offset:16384
	ds_read_b128 v[192:195], v162 offset:17408
	ds_read_b128 v[196:199], v162 offset:18432
	ds_read_b128 v[200:203], v162 offset:19456
	ds_read_b128 v[204:207], v162 offset:20480
	ds_read_b128 v[208:211], v162 offset:21504
	ds_read_b128 v[212:215], v162 offset:22528
	ds_read_b128 v[216:219], v162 offset:23552
	global_load_lds_dwordx4 v[220:221], off
	s_add_i32 m0, s34, 0x2000
	s_add_u32 s34, s54, 0x40000
	v_lshl_add_u64 v[222:223], s[54:55], 0, v[138:139]
	s_addc_u32 s35, s55, 0
	s_add_i32 s90, s89, s62
	global_load_lds_dwordx4 v[222:223], off
	v_lshl_add_u64 v[224:225], s[34:35], 0, v[134:135]
	s_mov_b32 m0, s90
	v_lshl_add_u64 v[226:227], s[56:57], 0, v[136:137]
	global_load_lds_dwordx4 v[224:225], off
	v_lshl_add_u64 v[224:225], s[34:35], 0, v[138:139]
	s_add_i32 m0, s90, 0x2000
	s_nop 0
	global_load_lds_dwordx4 v[224:225], off
	v_lshl_add_u64 v[224:225], s[56:57], 0, v[132:133]
	s_mov_b32 m0, s65
	s_nop 0
	global_load_lds_dwordx4 v[224:225], off
	s_mov_b32 m0, s66
	s_nop 0
	global_load_lds_dwordx4 v[226:227], off
	s_waitcnt vmcnt(8)
	s_waitcnt lgkmcnt(0)
	s_barrier
	s_setprio 1
	s_waitcnt lgkmcnt(0)
	v_mfma_f32_16x16x32_bf16 v[60:63], v[148:151], v[188:191], 0
	v_mfma_f32_16x16x32_bf16 v[56:59], v[164:167], v[188:191], 0
	v_mfma_f32_16x16x32_bf16 v[44:47], v[148:151], v[196:199], 0
	v_mfma_f32_16x16x32_bf16 v[40:43], v[164:167], v[196:199], 0
	v_mfma_f32_16x16x32_bf16 v[28:31], v[148:151], v[204:207], 0
	v_mfma_f32_16x16x32_bf16 v[24:27], v[164:167], v[204:207], 0
	v_mfma_f32_16x16x32_bf16 v[12:15], v[148:151], v[212:215], 0
	v_mfma_f32_16x16x32_bf16 v[8:11], v[164:167], v[212:215], 0
	v_mfma_f32_16x16x32_bf16 v[60:63], v[152:155], v[192:195], v[60:63]
	v_mfma_f32_16x16x32_bf16 v[56:59], v[168:171], v[192:195], v[56:59]
	v_mfma_f32_16x16x32_bf16 v[44:47], v[152:155], v[200:203], v[44:47]
	v_mfma_f32_16x16x32_bf16 v[40:43], v[168:171], v[200:203], v[40:43]
	v_mfma_f32_16x16x32_bf16 v[28:31], v[152:155], v[208:211], v[28:31]
	v_mfma_f32_16x16x32_bf16 v[24:27], v[168:171], v[208:211], v[24:27]
	v_mfma_f32_16x16x32_bf16 v[12:15], v[152:155], v[216:219], v[12:15]
	v_mfma_f32_16x16x32_bf16 v[8:11], v[168:171], v[216:219], v[8:11]
	s_setprio 0
	s_setprio 1
	v_mfma_f32_16x16x32_bf16 v[52:55], v[172:175], v[188:191], 0
	v_mfma_f32_16x16x32_bf16 v[48:51], v[180:183], v[188:191], 0
	v_mfma_f32_16x16x32_bf16 v[36:39], v[172:175], v[196:199], 0
	v_mfma_f32_16x16x32_bf16 v[32:35], v[180:183], v[196:199], 0
	v_mfma_f32_16x16x32_bf16 v[20:23], v[172:175], v[204:207], 0
	v_mfma_f32_16x16x32_bf16 v[16:19], v[180:183], v[204:207], 0
	v_mfma_f32_16x16x32_bf16 v[4:7], v[172:175], v[212:215], 0
	v_mfma_f32_16x16x32_bf16 v[0:3], v[180:183], v[212:215], 0
	v_mfma_f32_16x16x32_bf16 v[52:55], v[176:179], v[192:195], v[52:55]
	v_mfma_f32_16x16x32_bf16 v[48:51], v[184:187], v[192:195], v[48:51]
	v_mfma_f32_16x16x32_bf16 v[36:39], v[176:179], v[200:203], v[36:39]
	v_mfma_f32_16x16x32_bf16 v[32:35], v[184:187], v[200:203], v[32:35]
	v_mfma_f32_16x16x32_bf16 v[20:23], v[176:179], v[208:211], v[20:23]
	v_mfma_f32_16x16x32_bf16 v[16:19], v[184:187], v[208:211], v[16:19]
	v_mfma_f32_16x16x32_bf16 v[4:7], v[176:179], v[216:219], v[4:7]
	v_mfma_f32_16x16x32_bf16 v[0:3], v[184:187], v[216:219], v[0:3]
	s_setprio 0
	s_barrier
	s_add_i32 s90, 0, 0x18000
	s_add_i32 s95, 0, 0x1c000
	v_add_u32_e32 v168, s90, v157
	v_add_u32_e32 v184, s95, v157
	ds_read_b128 v[148:151], v168
	ds_read_b128 v[152:155], v168 offset:1024
	ds_read_b128 v[164:167], v168 offset:2048
	ds_read_b128 v[168:171], v168 offset:3072
	ds_read_b128 v[172:175], v184
	ds_read_b128 v[176:179], v184 offset:1024
	ds_read_b128 v[180:183], v184 offset:2048
	ds_read_b128 v[184:187], v184 offset:3072
	s_add_u32 s34, s56, 0x40000
	s_addc_u32 s35, s57, 0
	s_mov_b32 m0, s67
	v_lshl_add_u64 v[228:229], s[34:35], 0, v[132:133]
	ds_read_b128 v[188:191], v162 offset:32768
	ds_read_b128 v[192:195], v162 offset:33792
	ds_read_b128 v[196:199], v162 offset:34816
	ds_read_b128 v[200:203], v162 offset:35840
	ds_read_b128 v[204:207], v162 offset:36864
	ds_read_b128 v[208:211], v162 offset:37888
	ds_read_b128 v[212:215], v162 offset:38912
	ds_read_b128 v[216:219], v162 offset:39936
	global_load_lds_dwordx4 v[228:229], off
	v_lshl_add_u64 v[228:229], s[34:35], 0, v[136:137]
	s_mov_b32 m0, s79
	s_nop 0
	global_load_lds_dwordx4 v[228:229], off
	s_waitcnt vmcnt(8)
	s_waitcnt lgkmcnt(0)
	s_barrier
	s_setprio 1
	s_waitcnt lgkmcnt(0)
	v_mfma_f32_16x16x32_bf16 v[124:127], v[148:151], v[188:191], v[124:127]
	v_mfma_f32_16x16x32_bf16 v[120:123], v[164:167], v[188:191], v[120:123]
	v_mfma_f32_16x16x32_bf16 v[108:111], v[148:151], v[196:199], v[108:111]
	v_mfma_f32_16x16x32_bf16 v[104:107], v[164:167], v[196:199], v[104:107]
	v_mfma_f32_16x16x32_bf16 v[92:95], v[148:151], v[204:207], v[92:95]
	v_mfma_f32_16x16x32_bf16 v[88:91], v[164:167], v[204:207], v[88:91]
	v_mfma_f32_16x16x32_bf16 v[76:79], v[148:151], v[212:215], v[76:79]
	v_mfma_f32_16x16x32_bf16 v[72:75], v[164:167], v[212:215], v[72:75]
	v_mfma_f32_16x16x32_bf16 v[124:127], v[152:155], v[192:195], v[124:127]
	v_mfma_f32_16x16x32_bf16 v[120:123], v[168:171], v[192:195], v[120:123]
	v_mfma_f32_16x16x32_bf16 v[108:111], v[152:155], v[200:203], v[108:111]
	v_mfma_f32_16x16x32_bf16 v[104:107], v[168:171], v[200:203], v[104:107]
	v_mfma_f32_16x16x32_bf16 v[92:95], v[152:155], v[208:211], v[92:95]
	v_mfma_f32_16x16x32_bf16 v[88:91], v[168:171], v[208:211], v[88:91]
	v_mfma_f32_16x16x32_bf16 v[76:79], v[152:155], v[216:219], v[76:79]
	v_mfma_f32_16x16x32_bf16 v[72:75], v[168:171], v[216:219], v[72:75]
	s_setprio 0
	s_setprio 1
	v_mfma_f32_16x16x32_bf16 v[116:119], v[172:175], v[188:191], v[116:119]
	v_mfma_f32_16x16x32_bf16 v[112:115], v[180:183], v[188:191], v[112:115]
	v_mfma_f32_16x16x32_bf16 v[100:103], v[172:175], v[196:199], v[100:103]
	v_mfma_f32_16x16x32_bf16 v[96:99], v[180:183], v[196:199], v[96:99]
	v_mfma_f32_16x16x32_bf16 v[84:87], v[172:175], v[204:207], v[84:87]
	v_mfma_f32_16x16x32_bf16 v[80:83], v[180:183], v[204:207], v[80:83]
	v_mfma_f32_16x16x32_bf16 v[68:71], v[172:175], v[212:215], v[68:71]
	v_mfma_f32_16x16x32_bf16 v[64:67], v[180:183], v[212:215], v[64:67]
	v_mfma_f32_16x16x32_bf16 v[116:119], v[176:179], v[192:195], v[116:119]
	v_mfma_f32_16x16x32_bf16 v[112:115], v[184:187], v[192:195], v[112:115]
	v_mfma_f32_16x16x32_bf16 v[100:103], v[176:179], v[200:203], v[100:103]
	v_mfma_f32_16x16x32_bf16 v[96:99], v[184:187], v[200:203], v[96:99]
	v_mfma_f32_16x16x32_bf16 v[84:87], v[176:179], v[208:211], v[84:87]
	v_mfma_f32_16x16x32_bf16 v[80:83], v[184:187], v[208:211], v[80:83]
	v_mfma_f32_16x16x32_bf16 v[68:71], v[176:179], v[216:219], v[68:71]
	v_mfma_f32_16x16x32_bf16 v[64:67], v[184:187], v[216:219], v[64:67]
	s_setprio 0
	s_barrier
	s_add_i32 s34, s90, s62
	v_lshl_add_u64 v[220:221], v[220:221], 0, s[26:27]
	s_mov_b32 m0, s34
	ds_read_b128 v[188:191], v162 offset:49152
	ds_read_b128 v[192:195], v162 offset:50176
	ds_read_b128 v[196:199], v162 offset:51200
	ds_read_b128 v[200:203], v162 offset:52224
	ds_read_b128 v[204:207], v162 offset:53248
	ds_read_b128 v[208:211], v162 offset:54272
	ds_read_b128 v[212:215], v162 offset:55296
	ds_read_b128 v[216:219], v162 offset:56320
	global_load_lds_dwordx4 v[220:221], off
	s_add_i32 m0, s34, 0x2000
	s_add_u32 s34, s54, 0x40080
	v_lshl_add_u64 v[220:221], v[222:223], 0, s[26:27]
	s_addc_u32 s35, s55, 0
	s_add_i32 s54, s95, s62
	global_load_lds_dwordx4 v[220:221], off
	v_lshl_add_u64 v[220:221], s[34:35], 0, v[134:135]
	s_mov_b32 m0, s54
	s_nop 0
	global_load_lds_dwordx4 v[220:221], off
	v_lshl_add_u64 v[220:221], s[34:35], 0, v[138:139]
	s_add_i32 m0, s54, 0x2000
	s_nop 0
	global_load_lds_dwordx4 v[220:221], off
	v_lshl_add_u64 v[220:221], v[224:225], 0, s[26:27]
	s_mov_b32 m0, s83
	s_nop 0
	global_load_lds_dwordx4 v[220:221], off
	v_lshl_add_u64 v[220:221], v[226:227], 0, s[26:27]
	s_mov_b32 m0, s84
	s_nop 0
	global_load_lds_dwordx4 v[220:221], off
	s_waitcnt vmcnt(8)
	s_waitcnt lgkmcnt(0)
	s_barrier
	s_setprio 1
	s_waitcnt lgkmcnt(0)
	v_mfma_f32_16x16x32_bf16 v[60:63], v[148:151], v[188:191], v[60:63]
	v_mfma_f32_16x16x32_bf16 v[56:59], v[164:167], v[188:191], v[56:59]
	v_mfma_f32_16x16x32_bf16 v[44:47], v[148:151], v[196:199], v[44:47]
	v_mfma_f32_16x16x32_bf16 v[40:43], v[164:167], v[196:199], v[40:43]
	v_mfma_f32_16x16x32_bf16 v[28:31], v[148:151], v[204:207], v[28:31]
	v_mfma_f32_16x16x32_bf16 v[24:27], v[164:167], v[204:207], v[24:27]
	v_mfma_f32_16x16x32_bf16 v[12:15], v[148:151], v[212:215], v[12:15]
	v_mfma_f32_16x16x32_bf16 v[8:11], v[164:167], v[212:215], v[8:11]
	v_mfma_f32_16x16x32_bf16 v[60:63], v[152:155], v[192:195], v[60:63]
	v_mfma_f32_16x16x32_bf16 v[56:59], v[168:171], v[192:195], v[56:59]
	v_mfma_f32_16x16x32_bf16 v[44:47], v[152:155], v[200:203], v[44:47]
	v_mfma_f32_16x16x32_bf16 v[40:43], v[168:171], v[200:203], v[40:43]
	v_mfma_f32_16x16x32_bf16 v[28:31], v[152:155], v[208:211], v[28:31]
	v_mfma_f32_16x16x32_bf16 v[24:27], v[168:171], v[208:211], v[24:27]
	v_mfma_f32_16x16x32_bf16 v[12:15], v[152:155], v[216:219], v[12:15]
	v_mfma_f32_16x16x32_bf16 v[8:11], v[168:171], v[216:219], v[8:11]
	s_setprio 0
	s_setprio 1
	v_mfma_f32_16x16x32_bf16 v[52:55], v[172:175], v[188:191], v[52:55]
	v_mfma_f32_16x16x32_bf16 v[48:51], v[180:183], v[188:191], v[48:51]
	v_mfma_f32_16x16x32_bf16 v[36:39], v[172:175], v[196:199], v[36:39]
	v_mfma_f32_16x16x32_bf16 v[32:35], v[180:183], v[196:199], v[32:35]
	v_mfma_f32_16x16x32_bf16 v[20:23], v[172:175], v[204:207], v[20:23]
	v_mfma_f32_16x16x32_bf16 v[16:19], v[180:183], v[204:207], v[16:19]
	v_mfma_f32_16x16x32_bf16 v[4:7], v[172:175], v[212:215], v[4:7]
	v_mfma_f32_16x16x32_bf16 v[0:3], v[180:183], v[212:215], v[0:3]
	v_mfma_f32_16x16x32_bf16 v[52:55], v[176:179], v[192:195], v[52:55]
	v_mfma_f32_16x16x32_bf16 v[48:51], v[184:187], v[192:195], v[48:51]
	v_mfma_f32_16x16x32_bf16 v[36:39], v[176:179], v[200:203], v[36:39]
	v_mfma_f32_16x16x32_bf16 v[32:35], v[184:187], v[200:203], v[32:35]
	v_mfma_f32_16x16x32_bf16 v[20:23], v[176:179], v[208:211], v[20:23]
	v_mfma_f32_16x16x32_bf16 v[16:19], v[184:187], v[208:211], v[16:19]
	v_mfma_f32_16x16x32_bf16 v[4:7], v[176:179], v[216:219], v[4:7]
	v_mfma_f32_16x16x32_bf16 v[0:3], v[184:187], v[216:219], v[0:3]
	s_setprio 0
	s_barrier
	s_add_i32 s77, s77, 2
	s_add_u32 s52, s52, 0x100
	s_addc_u32 s53, s53, 0
	s_add_u32 s41, s41, 0x100
	s_addc_u32 s43, s43, 0

.LBB0_962:
	s_add_i32 s66, s66, 1
	s_mul_i32 s6, s66, s59
	s_mul_hi_u32 s7, s66, s62
	s_add_i32 s7, s7, s6
	s_mul_i32 s6, s66, s62
	s_add_u32 s30, s6, s2
	s_addc_u32 s31, s7, s63
	v_cmp_gt_i64_e32 vcc, s[30:31], v[146:147]
	v_cmp_lt_i64_e64 s[6:7], s[30:31], v[144:145]
	s_cbranch_vccnz .LBB0_968
	s_and_b32 s100, s30, 7
	s_mul_i32 s100, s100, 0x40
	s_lshr_b32 s101, s30, 3
	s_add_i32 s100, s100, s101
	s_mul_hi_u32 s101, s100, 0x8000000
	s_mul_i32 s26, s101, 0x20
	s_sub_i32 s26, s100, s26
	s_and_b32 s100, s26, 7
	s_lshl_b32 s28, s101, 3
	s_add_i32 s28, s28, s100
	s_lshr_b32 s26, s26, 3
.LBB0_968:
	s_ashr_i32 s29, s28, 31
	s_lshl_b64 s[12:13], s[28:29], 19
	s_add_u32 s30, s20, s12
	s_addc_u32 s31, s21, s13
	s_and_b64 s[12:13], s[6:7], exec
	s_cselect_b32 s12, s31, s41
	s_cselect_b32 s13, s30, s40
	s_ashr_i32 s27, s26, 31
	s_lshl_b64 s[34:35], s[26:27], 19
	s_add_u32 s36, s3, s34
	s_addc_u32 s37, s50, s35
	s_and_b64 s[34:35], s[6:7], exec
	s_cselect_b32 s27, s37, s43
	s_cselect_b32 s29, s36, s42
	s_add_u32 s40, s40, 0x40080
	s_addc_u32 s41, s41, 0
	s_add_u32 s39, s42, 0x100
	s_addc_u32 s67, s43, 0
	s_mov_b32 s77, -2
	s_waitcnt lgkmcnt(0)
	ds_read_b128 v[148:151], v154
	ds_read_b128 v[160:163], v154 offset:1024
	ds_read_b128 v[164:167], v154 offset:2048
	ds_read_b128 v[168:171], v154 offset:3072
	ds_read_b128 v[172:175], v155
	ds_read_b128 v[176:179], v155 offset:1024
	ds_read_b128 v[180:183], v155 offset:2048
	ds_read_b128 v[184:187], v155 offset:3072
	s_add_u32 s34, s40, 0xfffc0080
	s_addc_u32 s35, s41, -1
	s_cmp_eq_u32 s77, 12
	s_cselect_b32 s49, s12, s35
	s_cselect_b32 s48, s13, s34
	s_cselect_b32 s43, s27, s67
	s_cselect_b32 s42, s29, s39
	v_lshl_add_u64 v[220:221], s[40:41], 0, v[140:141]
	s_add_i32 m0, s52, 0xc000
	ds_read_b128 v[188:191], v157
	ds_read_b128 v[192:195], v157 offset:1024
	ds_read_b128 v[196:199], v157 offset:2048
	ds_read_b128 v[200:203], v157 offset:3072
	ds_read_b128 v[204:207], v157 offset:4096
	ds_read_b128 v[208:211], v157 offset:5120
	ds_read_b128 v[212:215], v157 offset:6144
	ds_read_b128 v[216:219], v157 offset:7168
	global_load_lds_dwordx4 v[220:221], off
	v_lshl_add_u64 v[220:221], s[40:41], 0, v[142:143]
	s_add_i32 m0, s52, 0xe000
	s_nop 0
	global_load_lds_dwordx4 v[220:221], off
	s_waitcnt vmcnt(8)
	s_waitcnt lgkmcnt(0)
	s_barrier
	s_setprio 1
	s_waitcnt lgkmcnt(0)
	v_mfma_f32_16x16x32_bf16 v[124:127], v[148:151], v[188:191], 0
	v_mfma_f32_16x16x32_bf16 v[120:123], v[164:167], v[188:191], 0
	v_mfma_f32_16x16x32_bf16 v[108:111], v[148:151], v[196:199], 0
	v_mfma_f32_16x16x32_bf16 v[104:107], v[164:167], v[196:199], 0
	v_mfma_f32_16x16x32_bf16 v[92:95], v[148:151], v[204:207], 0
	v_mfma_f32_16x16x32_bf16 v[88:91], v[164:167], v[204:207], 0
	v_mfma_f32_16x16x32_bf16 v[76:79], v[148:151], v[212:215], 0
	v_mfma_f32_16x16x32_bf16 v[72:75], v[164:167], v[212:215], 0
	v_mfma_f32_16x16x32_bf16 v[124:127], v[160:163], v[192:195], v[124:127]
	v_mfma_f32_16x16x32_bf16 v[120:123], v[168:171], v[192:195], v[120:123]
	v_mfma_f32_16x16x32_bf16 v[108:111], v[160:163], v[200:203], v[108:111]
	v_mfma_f32_16x16x32_bf16 v[104:107], v[168:171], v[200:203], v[104:107]
	v_mfma_f32_16x16x32_bf16 v[92:95], v[160:163], v[208:211], v[92:95]
	v_mfma_f32_16x16x32_bf16 v[88:91], v[168:171], v[208:211], v[88:91]
	v_mfma_f32_16x16x32_bf16 v[76:79], v[160:163], v[216:219], v[76:79]
	v_mfma_f32_16x16x32_bf16 v[72:75], v[168:171], v[216:219], v[72:75]
	s_setprio 0
	s_setprio 1
	v_mfma_f32_16x16x32_bf16 v[116:119], v[172:175], v[188:191], 0
	v_mfma_f32_16x16x32_bf16 v[112:115], v[180:183], v[188:191], 0
	v_mfma_f32_16x16x32_bf16 v[100:103], v[172:175], v[196:199], 0
	v_mfma_f32_16x16x32_bf16 v[96:99], v[180:183], v[196:199], 0
	v_mfma_f32_16x16x32_bf16 v[84:87], v[172:175], v[204:207], 0
	v_mfma_f32_16x16x32_bf16 v[80:83], v[180:183], v[204:207], 0
	v_mfma_f32_16x16x32_bf16 v[68:71], v[172:175], v[212:215], 0
	v_mfma_f32_16x16x32_bf16 v[64:67], v[180:183], v[212:215], 0
	v_mfma_f32_16x16x32_bf16 v[116:119], v[176:179], v[192:195], v[116:119]
	v_mfma_f32_16x16x32_bf16 v[112:115], v[184:187], v[192:195], v[112:115]
	v_mfma_f32_16x16x32_bf16 v[100:103], v[176:179], v[200:203], v[100:103]
	v_mfma_f32_16x16x32_bf16 v[96:99], v[184:187], v[200:203], v[96:99]
	v_mfma_f32_16x16x32_bf16 v[84:87], v[176:179], v[208:211], v[84:87]
	v_mfma_f32_16x16x32_bf16 v[80:83], v[184:187], v[208:211], v[80:83]
	v_mfma_f32_16x16x32_bf16 v[68:71], v[176:179], v[216:219], v[68:71]
	v_mfma_f32_16x16x32_bf16 v[64:67], v[184:187], v[216:219], v[64:67]
	s_setprio 0
	s_barrier
	s_add_i32 s34, s64, s51
	v_lshl_add_u64 v[220:221], s[42:43], 0, v[134:135]
	s_mov_b32 m0, s34
	ds_read_b128 v[188:191], v157 offset:16384
	ds_read_b128 v[192:195], v157 offset:17408
	ds_read_b128 v[196:199], v157 offset:18432
	ds_read_b128 v[200:203], v157 offset:19456
	ds_read_b128 v[204:207], v157 offset:20480
	ds_read_b128 v[208:211], v157 offset:21504
	ds_read_b128 v[212:215], v157 offset:22528
	ds_read_b128 v[216:219], v157 offset:23552
	global_load_lds_dwordx4 v[220:221], off
	s_add_i32 m0, s34, 0x2000
	s_add_u32 s34, s42, 0x40000
	v_lshl_add_u64 v[222:223], s[42:43], 0, v[138:139]
	s_addc_u32 s35, s43, 0
	s_add_i32 s79, s65, s51
	global_load_lds_dwordx4 v[222:223], off
	v_lshl_add_u64 v[224:225], s[34:35], 0, v[134:135]
	s_mov_b32 m0, s79
	v_lshl_add_u64 v[226:227], s[48:49], 0, v[136:137]
	global_load_lds_dwordx4 v[224:225], off
	v_lshl_add_u64 v[224:225], s[34:35], 0, v[138:139]
	s_add_i32 m0, s79, 0x2000
	s_nop 0
	global_load_lds_dwordx4 v[224:225], off
	v_lshl_add_u64 v[224:225], s[48:49], 0, v[132:133]
	s_mov_b32 m0, s52
	s_nop 0
	global_load_lds_dwordx4 v[224:225], off
	s_mov_b32 m0, s53
	s_nop 0
	global_load_lds_dwordx4 v[226:227], off
	s_waitcnt vmcnt(8)
	s_waitcnt lgkmcnt(0)
	s_barrier
	s_setprio 1
	s_waitcnt lgkmcnt(0)
	v_mfma_f32_16x16x32_bf16 v[60:63], v[148:151], v[188:191], 0
	v_mfma_f32_16x16x32_bf16 v[56:59], v[164:167], v[188:191], 0
	v_mfma_f32_16x16x32_bf16 v[44:47], v[148:151], v[196:199], 0
	v_mfma_f32_16x16x32_bf16 v[40:43], v[164:167], v[196:199], 0
	v_mfma_f32_16x16x32_bf16 v[28:31], v[148:151], v[204:207], 0
	v_mfma_f32_16x16x32_bf16 v[24:27], v[164:167], v[204:207], 0
	v_mfma_f32_16x16x32_bf16 v[12:15], v[148:151], v[212:215], 0
	v_mfma_f32_16x16x32_bf16 v[8:11], v[164:167], v[212:215], 0
	v_mfma_f32_16x16x32_bf16 v[60:63], v[160:163], v[192:195], v[60:63]
	v_mfma_f32_16x16x32_bf16 v[56:59], v[168:171], v[192:195], v[56:59]
	v_mfma_f32_16x16x32_bf16 v[44:47], v[160:163], v[200:203], v[44:47]
	v_mfma_f32_16x16x32_bf16 v[40:43], v[168:171], v[200:203], v[40:43]
	v_mfma_f32_16x16x32_bf16 v[28:31], v[160:163], v[208:211], v[28:31]
	v_mfma_f32_16x16x32_bf16 v[24:27], v[168:171], v[208:211], v[24:27]
	v_mfma_f32_16x16x32_bf16 v[12:15], v[160:163], v[216:219], v[12:15]
	v_mfma_f32_16x16x32_bf16 v[8:11], v[168:171], v[216:219], v[8:11]
	s_setprio 0
	s_setprio 1
	v_mfma_f32_16x16x32_bf16 v[52:55], v[172:175], v[188:191], 0
	v_mfma_f32_16x16x32_bf16 v[48:51], v[180:183], v[188:191], 0
	v_mfma_f32_16x16x32_bf16 v[36:39], v[172:175], v[196:199], 0
	v_mfma_f32_16x16x32_bf16 v[32:35], v[180:183], v[196:199], 0
	v_mfma_f32_16x16x32_bf16 v[20:23], v[172:175], v[204:207], 0
	v_mfma_f32_16x16x32_bf16 v[16:19], v[180:183], v[204:207], 0
	v_mfma_f32_16x16x32_bf16 v[4:7], v[172:175], v[212:215], 0
	v_mfma_f32_16x16x32_bf16 v[0:3], v[180:183], v[212:215], 0
	v_mfma_f32_16x16x32_bf16 v[52:55], v[176:179], v[192:195], v[52:55]
	v_mfma_f32_16x16x32_bf16 v[48:51], v[184:187], v[192:195], v[48:51]
	v_mfma_f32_16x16x32_bf16 v[36:39], v[176:179], v[200:203], v[36:39]
	v_mfma_f32_16x16x32_bf16 v[32:35], v[184:187], v[200:203], v[32:35]
	v_mfma_f32_16x16x32_bf16 v[20:23], v[176:179], v[208:211], v[20:23]
	v_mfma_f32_16x16x32_bf16 v[16:19], v[184:187], v[208:211], v[16:19]
	v_mfma_f32_16x16x32_bf16 v[4:7], v[176:179], v[216:219], v[4:7]
	v_mfma_f32_16x16x32_bf16 v[0:3], v[184:187], v[216:219], v[0:3]
	s_setprio 0
	s_barrier
	s_add_i32 s79, 0, 0x18000
	v_add_u32_e32 v159, s79, v152
	s_add_i32 s81, 0, 0x1c000
	ds_read_b128 v[148:151], v159
	ds_read_b128 v[160:163], v159 offset:1024
	ds_read_b128 v[164:167], v159 offset:2048
	ds_read_b128 v[168:171], v159 offset:3072
	v_add_u32_e32 v159, s81, v152
	ds_read_b128 v[172:175], v159
	ds_read_b128 v[176:179], v159 offset:1024
	ds_read_b128 v[180:183], v159 offset:2048
	ds_read_b128 v[184:187], v159 offset:3072
	s_add_u32 s34, s48, 0x40000
	s_addc_u32 s35, s49, 0
	s_mov_b32 m0, s54
	v_lshl_add_u64 v[228:229], s[34:35], 0, v[132:133]
	ds_read_b128 v[188:191], v157 offset:32768
	ds_read_b128 v[192:195], v157 offset:33792
	ds_read_b128 v[196:199], v157 offset:34816
	ds_read_b128 v[200:203], v157 offset:35840
	ds_read_b128 v[204:207], v157 offset:36864
	ds_read_b128 v[208:211], v157 offset:37888
	ds_read_b128 v[212:215], v157 offset:38912
	ds_read_b128 v[216:219], v157 offset:39936
	global_load_lds_dwordx4 v[228:229], off
	v_lshl_add_u64 v[228:229], s[34:35], 0, v[136:137]
	s_mov_b32 m0, s55
	s_nop 0
	global_load_lds_dwordx4 v[228:229], off
	s_waitcnt vmcnt(8)
	s_waitcnt lgkmcnt(0)
	s_barrier
	s_setprio 1
	s_waitcnt lgkmcnt(0)
	v_mfma_f32_16x16x32_bf16 v[124:127], v[148:151], v[188:191], v[124:127]
	v_mfma_f32_16x16x32_bf16 v[120:123], v[164:167], v[188:191], v[120:123]
	v_mfma_f32_16x16x32_bf16 v[108:111], v[148:151], v[196:199], v[108:111]
	v_mfma_f32_16x16x32_bf16 v[104:107], v[164:167], v[196:199], v[104:107]
	v_mfma_f32_16x16x32_bf16 v[92:95], v[148:151], v[204:207], v[92:95]
	v_mfma_f32_16x16x32_bf16 v[88:91], v[164:167], v[204:207], v[88:91]
	v_mfma_f32_16x16x32_bf16 v[76:79], v[148:151], v[212:215], v[76:79]
	v_mfma_f32_16x16x32_bf16 v[72:75], v[164:167], v[212:215], v[72:75]
	v_mfma_f32_16x16x32_bf16 v[124:127], v[160:163], v[192:195], v[124:127]
	v_mfma_f32_16x16x32_bf16 v[120:123], v[168:171], v[192:195], v[120:123]
	v_mfma_f32_16x16x32_bf16 v[108:111], v[160:163], v[200:203], v[108:111]
	v_mfma_f32_16x16x32_bf16 v[104:107], v[168:171], v[200:203], v[104:107]
	v_mfma_f32_16x16x32_bf16 v[92:95], v[160:163], v[208:211], v[92:95]
	v_mfma_f32_16x16x32_bf16 v[88:91], v[168:171], v[208:211], v[88:91]
	v_mfma_f32_16x16x32_bf16 v[76:79], v[160:163], v[216:219], v[76:79]
	v_mfma_f32_16x16x32_bf16 v[72:75], v[168:171], v[216:219], v[72:75]
	s_setprio 0
	s_setprio 1
	v_mfma_f32_16x16x32_bf16 v[116:119], v[172:175], v[188:191], v[116:119]
	v_mfma_f32_16x16x32_bf16 v[112:115], v[180:183], v[188:191], v[112:115]
	v_mfma_f32_16x16x32_bf16 v[100:103], v[172:175], v[196:199], v[100:103]
	v_mfma_f32_16x16x32_bf16 v[96:99], v[180:183], v[196:199], v[96:99]
	v_mfma_f32_16x16x32_bf16 v[84:87], v[172:175], v[204:207], v[84:87]
	v_mfma_f32_16x16x32_bf16 v[80:83], v[180:183], v[204:207], v[80:83]
	v_mfma_f32_16x16x32_bf16 v[68:71], v[172:175], v[212:215], v[68:71]
	v_mfma_f32_16x16x32_bf16 v[64:67], v[180:183], v[212:215], v[64:67]
	v_mfma_f32_16x16x32_bf16 v[116:119], v[176:179], v[192:195], v[116:119]
	v_mfma_f32_16x16x32_bf16 v[112:115], v[184:187], v[192:195], v[112:115]
	v_mfma_f32_16x16x32_bf16 v[100:103], v[176:179], v[200:203], v[100:103]
	v_mfma_f32_16x16x32_bf16 v[96:99], v[184:187], v[200:203], v[96:99]
	v_mfma_f32_16x16x32_bf16 v[84:87], v[176:179], v[208:211], v[84:87]
	v_mfma_f32_16x16x32_bf16 v[80:83], v[184:187], v[208:211], v[80:83]
	v_mfma_f32_16x16x32_bf16 v[68:71], v[176:179], v[216:219], v[68:71]
	v_mfma_f32_16x16x32_bf16 v[64:67], v[184:187], v[216:219], v[64:67]
	s_setprio 0
	s_barrier
	s_add_i32 s34, s79, s51
	v_lshl_add_u64 v[220:221], v[220:221], 0, s[10:11]
	s_mov_b32 m0, s34
	ds_read_b128 v[188:191], v157 offset:49152
	ds_read_b128 v[192:195], v157 offset:50176
	ds_read_b128 v[196:199], v157 offset:51200
	ds_read_b128 v[200:203], v157 offset:52224
	ds_read_b128 v[204:207], v157 offset:53248
	ds_read_b128 v[208:211], v157 offset:54272
	ds_read_b128 v[212:215], v157 offset:55296
	ds_read_b128 v[216:219], v157 offset:56320
	global_load_lds_dwordx4 v[220:221], off
	s_add_i32 m0, s34, 0x2000
	s_add_u32 s34, s42, 0x40080
	v_lshl_add_u64 v[220:221], v[222:223], 0, s[10:11]
	s_addc_u32 s35, s43, 0
	s_add_i32 s42, s81, s51
	global_load_lds_dwordx4 v[220:221], off
	v_lshl_add_u64 v[220:221], s[34:35], 0, v[134:135]
	s_mov_b32 m0, s42
	s_nop 0
	global_load_lds_dwordx4 v[220:221], off
	v_lshl_add_u64 v[220:221], s[34:35], 0, v[138:139]
	s_add_i32 m0, s42, 0x2000
	s_nop 0
	global_load_lds_dwordx4 v[220:221], off
	v_lshl_add_u64 v[220:221], v[224:225], 0, s[10:11]
	s_mov_b32 m0, s57
	s_nop 0
	global_load_lds_dwordx4 v[220:221], off
	v_lshl_add_u64 v[220:221], v[226:227], 0, s[10:11]
	s_mov_b32 m0, s58
	s_nop 0
	global_load_lds_dwordx4 v[220:221], off
	s_waitcnt vmcnt(8)
	s_waitcnt lgkmcnt(0)
	s_barrier
	s_setprio 1
	s_waitcnt lgkmcnt(0)
	v_mfma_f32_16x16x32_bf16 v[60:63], v[148:151], v[188:191], v[60:63]
	v_mfma_f32_16x16x32_bf16 v[56:59], v[164:167], v[188:191], v[56:59]
	v_mfma_f32_16x16x32_bf16 v[44:47], v[148:151], v[196:199], v[44:47]
	v_mfma_f32_16x16x32_bf16 v[40:43], v[164:167], v[196:199], v[40:43]
	v_mfma_f32_16x16x32_bf16 v[28:31], v[148:151], v[204:207], v[28:31]
	v_mfma_f32_16x16x32_bf16 v[24:27], v[164:167], v[204:207], v[24:27]
	v_mfma_f32_16x16x32_bf16 v[12:15], v[148:151], v[212:215], v[12:15]
	v_mfma_f32_16x16x32_bf16 v[8:11], v[164:167], v[212:215], v[8:11]
	v_mfma_f32_16x16x32_bf16 v[60:63], v[160:163], v[192:195], v[60:63]
	v_mfma_f32_16x16x32_bf16 v[56:59], v[168:171], v[192:195], v[56:59]
	v_mfma_f32_16x16x32_bf16 v[44:47], v[160:163], v[200:203], v[44:47]
	v_mfma_f32_16x16x32_bf16 v[40:43], v[168:171], v[200:203], v[40:43]
	v_mfma_f32_16x16x32_bf16 v[28:31], v[160:163], v[208:211], v[28:31]
	v_mfma_f32_16x16x32_bf16 v[24:27], v[168:171], v[208:211], v[24:27]
	v_mfma_f32_16x16x32_bf16 v[12:15], v[160:163], v[216:219], v[12:15]
	v_mfma_f32_16x16x32_bf16 v[8:11], v[168:171], v[216:219], v[8:11]
	s_setprio 0
	s_setprio 1
	v_mfma_f32_16x16x32_bf16 v[52:55], v[172:175], v[188:191], v[52:55]
	v_mfma_f32_16x16x32_bf16 v[48:51], v[180:183], v[188:191], v[48:51]
	v_mfma_f32_16x16x32_bf16 v[36:39], v[172:175], v[196:199], v[36:39]
	v_mfma_f32_16x16x32_bf16 v[32:35], v[180:183], v[196:199], v[32:35]
	v_mfma_f32_16x16x32_bf16 v[20:23], v[172:175], v[204:207], v[20:23]
	v_mfma_f32_16x16x32_bf16 v[16:19], v[180:183], v[204:207], v[16:19]
	v_mfma_f32_16x16x32_bf16 v[4:7], v[172:175], v[212:215], v[4:7]
	v_mfma_f32_16x16x32_bf16 v[0:3], v[180:183], v[212:215], v[0:3]
	v_mfma_f32_16x16x32_bf16 v[52:55], v[176:179], v[192:195], v[52:55]
	v_mfma_f32_16x16x32_bf16 v[48:51], v[184:187], v[192:195], v[48:51]
	v_mfma_f32_16x16x32_bf16 v[36:39], v[176:179], v[200:203], v[36:39]
	v_mfma_f32_16x16x32_bf16 v[32:35], v[184:187], v[200:203], v[32:35]
	v_mfma_f32_16x16x32_bf16 v[20:23], v[176:179], v[208:211], v[20:23]
	v_mfma_f32_16x16x32_bf16 v[16:19], v[184:187], v[208:211], v[16:19]
	v_mfma_f32_16x16x32_bf16 v[4:7], v[176:179], v[216:219], v[4:7]
	v_mfma_f32_16x16x32_bf16 v[0:3], v[184:187], v[216:219], v[0:3]
	s_setprio 0
	s_barrier
	s_add_i32 s77, s77, 2
	s_add_u32 s40, s40, 0x100
	s_addc_u32 s41, s41, 0
	s_add_u32 s39, s39, 0x100
	s_addc_u32 s67, s67, 0

.LBB0_1056:
	s_add_i32 s62, s62, 1
	s_mul_i32 s4, s62, s42
	s_mul_hi_u32 s5, s62, s43
	s_add_i32 s5, s5, s4
	s_mul_i32 s4, s62, s43
	s_add_u32 s26, s4, s2
	s_addc_u32 s27, s5, s3
	v_cmp_gt_i64_e32 vcc, s[26:27], v[146:147]
	v_cmp_lt_i64_e64 s[4:5], s[26:27], v[144:145]
	s_cbranch_vccnz .LBB0_1058
	s_and_b32 s100, s26, 7
	s_mul_i32 s100, s100, 0x160
	s_lshr_b32 s101, s26, 3
	s_add_i32 s100, s100, s101
	s_mul_hi_u32 s101, s100, 0x1745d18
	s_mul_i32 s10, s101, 0xb0
	s_sub_i32 s10, s100, s10
	s_and_b32 s100, s10, 7
	s_lshl_b32 s22, s101, 3
	s_add_i32 s22, s22, s100
	s_lshr_b32 s10, s10, 3
	s_mov_b32 s63, s62
.LBB0_1058:
	s_ashr_i32 s23, s22, 31
	s_lshl_b64 s[26:27], s[22:23], 19
	s_add_u32 s26, s14, s26
	s_addc_u32 s27, s15, s27
	s_and_b64 s[28:29], s[4:5], exec
	s_cselect_b32 s23, s27, s37
	s_cselect_b32 s64, s26, s36
	s_ashr_i32 s11, s10, 31
	s_lshl_b64 s[28:29], s[10:11], 19
	s_add_u32 s28, s49, s28
	s_addc_u32 s29, s50, s29
	s_and_b64 s[34:35], s[4:5], exec
	s_cselect_b32 s11, s29, s39
	s_cselect_b32 s65, s28, s38
	s_add_u32 s36, s36, 0x40080
	s_addc_u32 s37, s37, 0
	s_add_u32 s66, s38, 0x100
	s_addc_u32 s67, s39, 0
	s_mov_b32 s77, -2
	ds_read_b128 v[148:151], v155
	ds_read_b128 v[160:163], v155 offset:1024
	ds_read_b128 v[164:167], v155 offset:2048
	ds_read_b128 v[168:171], v155 offset:3072
	ds_read_b128 v[172:175], v157
	ds_read_b128 v[176:179], v157 offset:1024
	ds_read_b128 v[180:183], v157 offset:2048
	ds_read_b128 v[184:187], v157 offset:3072
	s_add_u32 s34, s36, 0xfffc0080
	s_addc_u32 s35, s37, -1
	s_cmp_eq_u32 s77, 12
	s_cselect_b32 s41, s23, s35
	s_cselect_b32 s40, s64, s34
	s_cselect_b32 s39, s11, s67
	s_cselect_b32 s38, s65, s66
	v_lshl_add_u64 v[220:221], s[36:37], 0, v[140:141]
	s_add_i32 m0, s31, 0xc000
	ds_read_b128 v[188:191], v158
	ds_read_b128 v[192:195], v158 offset:1024
	ds_read_b128 v[196:199], v158 offset:2048
	ds_read_b128 v[200:203], v158 offset:3072
	ds_read_b128 v[204:207], v158 offset:4096
	ds_read_b128 v[208:211], v158 offset:5120
	ds_read_b128 v[212:215], v158 offset:6144
	ds_read_b128 v[216:219], v158 offset:7168
	global_load_lds_dwordx4 v[220:221], off
	v_lshl_add_u64 v[220:221], s[36:37], 0, v[142:143]
	s_add_i32 m0, s31, 0xe000
	s_nop 0
	global_load_lds_dwordx4 v[220:221], off
	s_waitcnt vmcnt(8)
	s_waitcnt lgkmcnt(0)
	s_barrier
	s_setprio 1
	s_waitcnt lgkmcnt(0)
	v_mfma_f32_16x16x32_bf16 v[124:127], v[148:151], v[188:191], 0
	v_mfma_f32_16x16x32_bf16 v[120:123], v[164:167], v[188:191], 0
	v_mfma_f32_16x16x32_bf16 v[108:111], v[148:151], v[196:199], 0
	v_mfma_f32_16x16x32_bf16 v[104:107], v[164:167], v[196:199], 0
	v_mfma_f32_16x16x32_bf16 v[92:95], v[148:151], v[204:207], 0
	v_mfma_f32_16x16x32_bf16 v[88:91], v[164:167], v[204:207], 0
	v_mfma_f32_16x16x32_bf16 v[76:79], v[148:151], v[212:215], 0
	v_mfma_f32_16x16x32_bf16 v[72:75], v[164:167], v[212:215], 0
	v_mfma_f32_16x16x32_bf16 v[124:127], v[160:163], v[192:195], v[124:127]
	v_mfma_f32_16x16x32_bf16 v[120:123], v[168:171], v[192:195], v[120:123]
	v_mfma_f32_16x16x32_bf16 v[108:111], v[160:163], v[200:203], v[108:111]
	v_mfma_f32_16x16x32_bf16 v[104:107], v[168:171], v[200:203], v[104:107]
	v_mfma_f32_16x16x32_bf16 v[92:95], v[160:163], v[208:211], v[92:95]
	v_mfma_f32_16x16x32_bf16 v[88:91], v[168:171], v[208:211], v[88:91]
	v_mfma_f32_16x16x32_bf16 v[76:79], v[160:163], v[216:219], v[76:79]
	v_mfma_f32_16x16x32_bf16 v[72:75], v[168:171], v[216:219], v[72:75]
	s_setprio 0
	s_setprio 1
	v_mfma_f32_16x16x32_bf16 v[116:119], v[172:175], v[188:191], 0
	v_mfma_f32_16x16x32_bf16 v[112:115], v[180:183], v[188:191], 0
	v_mfma_f32_16x16x32_bf16 v[100:103], v[172:175], v[196:199], 0
	v_mfma_f32_16x16x32_bf16 v[96:99], v[180:183], v[196:199], 0
	v_mfma_f32_16x16x32_bf16 v[84:87], v[172:175], v[204:207], 0
	v_mfma_f32_16x16x32_bf16 v[80:83], v[180:183], v[204:207], 0
	v_mfma_f32_16x16x32_bf16 v[68:71], v[172:175], v[212:215], 0
	v_mfma_f32_16x16x32_bf16 v[64:67], v[180:183], v[212:215], 0
	v_mfma_f32_16x16x32_bf16 v[116:119], v[176:179], v[192:195], v[116:119]
	v_mfma_f32_16x16x32_bf16 v[112:115], v[184:187], v[192:195], v[112:115]
	v_mfma_f32_16x16x32_bf16 v[100:103], v[176:179], v[200:203], v[100:103]
	v_mfma_f32_16x16x32_bf16 v[96:99], v[184:187], v[200:203], v[96:99]
	v_mfma_f32_16x16x32_bf16 v[84:87], v[176:179], v[208:211], v[84:87]
	v_mfma_f32_16x16x32_bf16 v[80:83], v[184:187], v[208:211], v[80:83]
	v_mfma_f32_16x16x32_bf16 v[68:71], v[176:179], v[216:219], v[68:71]
	v_mfma_f32_16x16x32_bf16 v[64:67], v[184:187], v[216:219], v[64:67]
	s_setprio 0
	s_barrier
	s_add_i32 s34, s57, s48
	v_lshl_add_u64 v[220:221], s[38:39], 0, v[136:137]
	s_mov_b32 m0, s34
	ds_read_b128 v[188:191], v158 offset:16384
	ds_read_b128 v[192:195], v158 offset:17408
	ds_read_b128 v[196:199], v158 offset:18432
	ds_read_b128 v[200:203], v158 offset:19456
	ds_read_b128 v[204:207], v158 offset:20480
	ds_read_b128 v[208:211], v158 offset:21504
	ds_read_b128 v[212:215], v158 offset:22528
	ds_read_b128 v[216:219], v158 offset:23552
	global_load_lds_dwordx4 v[220:221], off
	s_add_i32 m0, s34, 0x2000
	s_add_u32 s34, s38, 0x40000
	v_lshl_add_u64 v[222:223], s[38:39], 0, v[132:133]
	s_addc_u32 s35, s39, 0
	s_add_i32 s79, s58, s48
	global_load_lds_dwordx4 v[222:223], off
	v_lshl_add_u64 v[224:225], s[34:35], 0, v[136:137]
	s_mov_b32 m0, s79
	v_lshl_add_u64 v[226:227], s[40:41], 0, v[134:135]
	global_load_lds_dwordx4 v[224:225], off
	v_lshl_add_u64 v[224:225], s[34:35], 0, v[132:133]
	s_add_i32 m0, s79, 0x2000
	s_nop 0
	global_load_lds_dwordx4 v[224:225], off
	v_lshl_add_u64 v[224:225], s[40:41], 0, v[138:139]
	s_mov_b32 m0, s31
	s_nop 0
	global_load_lds_dwordx4 v[224:225], off
	s_mov_b32 m0, s52
	s_nop 0
	global_load_lds_dwordx4 v[226:227], off
	s_waitcnt vmcnt(8)
	s_waitcnt lgkmcnt(0)
	s_barrier
	s_setprio 1
	s_waitcnt lgkmcnt(0)
	v_mfma_f32_16x16x32_bf16 v[60:63], v[148:151], v[188:191], 0
	v_mfma_f32_16x16x32_bf16 v[56:59], v[164:167], v[188:191], 0
	v_mfma_f32_16x16x32_bf16 v[44:47], v[148:151], v[196:199], 0
	v_mfma_f32_16x16x32_bf16 v[40:43], v[164:167], v[196:199], 0
	v_mfma_f32_16x16x32_bf16 v[28:31], v[148:151], v[204:207], 0
	v_mfma_f32_16x16x32_bf16 v[24:27], v[164:167], v[204:207], 0
	v_mfma_f32_16x16x32_bf16 v[12:15], v[148:151], v[212:215], 0
	v_mfma_f32_16x16x32_bf16 v[8:11], v[164:167], v[212:215], 0
	v_mfma_f32_16x16x32_bf16 v[60:63], v[160:163], v[192:195], v[60:63]
	v_mfma_f32_16x16x32_bf16 v[56:59], v[168:171], v[192:195], v[56:59]
	v_mfma_f32_16x16x32_bf16 v[44:47], v[160:163], v[200:203], v[44:47]
	v_mfma_f32_16x16x32_bf16 v[40:43], v[168:171], v[200:203], v[40:43]
	v_mfma_f32_16x16x32_bf16 v[28:31], v[160:163], v[208:211], v[28:31]
	v_mfma_f32_16x16x32_bf16 v[24:27], v[168:171], v[208:211], v[24:27]
	v_mfma_f32_16x16x32_bf16 v[12:15], v[160:163], v[216:219], v[12:15]
	v_mfma_f32_16x16x32_bf16 v[8:11], v[168:171], v[216:219], v[8:11]
	s_setprio 0
	s_setprio 1
	v_mfma_f32_16x16x32_bf16 v[52:55], v[172:175], v[188:191], 0
	v_mfma_f32_16x16x32_bf16 v[48:51], v[180:183], v[188:191], 0
	v_mfma_f32_16x16x32_bf16 v[36:39], v[172:175], v[196:199], 0
	v_mfma_f32_16x16x32_bf16 v[32:35], v[180:183], v[196:199], 0
	v_mfma_f32_16x16x32_bf16 v[20:23], v[172:175], v[204:207], 0
	v_mfma_f32_16x16x32_bf16 v[16:19], v[180:183], v[204:207], 0
	v_mfma_f32_16x16x32_bf16 v[4:7], v[172:175], v[212:215], 0
	v_mfma_f32_16x16x32_bf16 v[0:3], v[180:183], v[212:215], 0
	v_mfma_f32_16x16x32_bf16 v[52:55], v[176:179], v[192:195], v[52:55]
	v_mfma_f32_16x16x32_bf16 v[48:51], v[184:187], v[192:195], v[48:51]
	v_mfma_f32_16x16x32_bf16 v[36:39], v[176:179], v[200:203], v[36:39]
	v_mfma_f32_16x16x32_bf16 v[32:35], v[184:187], v[200:203], v[32:35]
	v_mfma_f32_16x16x32_bf16 v[20:23], v[176:179], v[208:211], v[20:23]
	v_mfma_f32_16x16x32_bf16 v[16:19], v[184:187], v[208:211], v[16:19]
	v_mfma_f32_16x16x32_bf16 v[4:7], v[176:179], v[216:219], v[4:7]
	v_mfma_f32_16x16x32_bf16 v[0:3], v[184:187], v[216:219], v[0:3]
	s_setprio 0
	s_barrier
	s_add_i32 s79, 0, 0x18000
	v_add_u32_e32 v159, s79, v152
	s_add_i32 s81, 0, 0x1c000
	ds_read_b128 v[148:151], v159
	ds_read_b128 v[160:163], v159 offset:1024
	ds_read_b128 v[164:167], v159 offset:2048
	ds_read_b128 v[168:171], v159 offset:3072
	v_add_u32_e32 v159, s81, v152
	ds_read_b128 v[172:175], v159
	ds_read_b128 v[176:179], v159 offset:1024
	ds_read_b128 v[180:183], v159 offset:2048
	ds_read_b128 v[184:187], v159 offset:3072
	s_add_u32 s34, s40, 0x40000
	s_addc_u32 s35, s41, 0
	s_mov_b32 m0, s53
	v_lshl_add_u64 v[228:229], s[34:35], 0, v[138:139]
	ds_read_b128 v[188:191], v158 offset:32768
	ds_read_b128 v[192:195], v158 offset:33792
	ds_read_b128 v[196:199], v158 offset:34816
	ds_read_b128 v[200:203], v158 offset:35840
	ds_read_b128 v[204:207], v158 offset:36864
	ds_read_b128 v[208:211], v158 offset:37888
	ds_read_b128 v[212:215], v158 offset:38912
	ds_read_b128 v[216:219], v158 offset:39936
	global_load_lds_dwordx4 v[228:229], off
	v_lshl_add_u64 v[228:229], s[34:35], 0, v[134:135]
	s_mov_b32 m0, s54
	s_nop 0
	global_load_lds_dwordx4 v[228:229], off
	s_waitcnt vmcnt(8)
	s_waitcnt lgkmcnt(0)
	s_barrier
	s_setprio 1
	s_waitcnt lgkmcnt(0)
	v_mfma_f32_16x16x32_bf16 v[124:127], v[148:151], v[188:191], v[124:127]
	v_mfma_f32_16x16x32_bf16 v[120:123], v[164:167], v[188:191], v[120:123]
	v_mfma_f32_16x16x32_bf16 v[108:111], v[148:151], v[196:199], v[108:111]
	v_mfma_f32_16x16x32_bf16 v[104:107], v[164:167], v[196:199], v[104:107]
	v_mfma_f32_16x16x32_bf16 v[92:95], v[148:151], v[204:207], v[92:95]
	v_mfma_f32_16x16x32_bf16 v[88:91], v[164:167], v[204:207], v[88:91]
	v_mfma_f32_16x16x32_bf16 v[76:79], v[148:151], v[212:215], v[76:79]
	v_mfma_f32_16x16x32_bf16 v[72:75], v[164:167], v[212:215], v[72:75]
	v_mfma_f32_16x16x32_bf16 v[124:127], v[160:163], v[192:195], v[124:127]
	v_mfma_f32_16x16x32_bf16 v[120:123], v[168:171], v[192:195], v[120:123]
	v_mfma_f32_16x16x32_bf16 v[108:111], v[160:163], v[200:203], v[108:111]
	v_mfma_f32_16x16x32_bf16 v[104:107], v[168:171], v[200:203], v[104:107]
	v_mfma_f32_16x16x32_bf16 v[92:95], v[160:163], v[208:211], v[92:95]
	v_mfma_f32_16x16x32_bf16 v[88:91], v[168:171], v[208:211], v[88:91]
	v_mfma_f32_16x16x32_bf16 v[76:79], v[160:163], v[216:219], v[76:79]
	v_mfma_f32_16x16x32_bf16 v[72:75], v[168:171], v[216:219], v[72:75]
	s_setprio 0
	s_setprio 1
	v_mfma_f32_16x16x32_bf16 v[116:119], v[172:175], v[188:191], v[116:119]
	v_mfma_f32_16x16x32_bf16 v[112:115], v[180:183], v[188:191], v[112:115]
	v_mfma_f32_16x16x32_bf16 v[100:103], v[172:175], v[196:199], v[100:103]
	v_mfma_f32_16x16x32_bf16 v[96:99], v[180:183], v[196:199], v[96:99]
	v_mfma_f32_16x16x32_bf16 v[84:87], v[172:175], v[204:207], v[84:87]
	v_mfma_f32_16x16x32_bf16 v[80:83], v[180:183], v[204:207], v[80:83]
	v_mfma_f32_16x16x32_bf16 v[68:71], v[172:175], v[212:215], v[68:71]
	v_mfma_f32_16x16x32_bf16 v[64:67], v[180:183], v[212:215], v[64:67]
	v_mfma_f32_16x16x32_bf16 v[116:119], v[176:179], v[192:195], v[116:119]
	v_mfma_f32_16x16x32_bf16 v[112:115], v[184:187], v[192:195], v[112:115]
	v_mfma_f32_16x16x32_bf16 v[100:103], v[176:179], v[200:203], v[100:103]
	v_mfma_f32_16x16x32_bf16 v[96:99], v[184:187], v[200:203], v[96:99]
	v_mfma_f32_16x16x32_bf16 v[84:87], v[176:179], v[208:211], v[84:87]
	v_mfma_f32_16x16x32_bf16 v[80:83], v[184:187], v[208:211], v[80:83]
	v_mfma_f32_16x16x32_bf16 v[68:71], v[176:179], v[216:219], v[68:71]
	v_mfma_f32_16x16x32_bf16 v[64:67], v[184:187], v[216:219], v[64:67]
	s_setprio 0
	s_barrier
	s_add_i32 s34, s79, s48
	v_lshl_add_u64 v[220:221], v[220:221], 0, s[6:7]
	s_mov_b32 m0, s34
	ds_read_b128 v[188:191], v158 offset:49152
	ds_read_b128 v[192:195], v158 offset:50176
	ds_read_b128 v[196:199], v158 offset:51200
	ds_read_b128 v[200:203], v158 offset:52224
	ds_read_b128 v[204:207], v158 offset:53248
	ds_read_b128 v[208:211], v158 offset:54272
	ds_read_b128 v[212:215], v158 offset:55296
	ds_read_b128 v[216:219], v158 offset:56320
	global_load_lds_dwordx4 v[220:221], off
	s_add_i32 m0, s34, 0x2000
	s_add_u32 s34, s38, 0x40080
	v_lshl_add_u64 v[220:221], v[222:223], 0, s[6:7]
	s_addc_u32 s35, s39, 0
	s_add_i32 s38, s81, s48
	global_load_lds_dwordx4 v[220:221], off
	v_lshl_add_u64 v[220:221], s[34:35], 0, v[136:137]
	s_mov_b32 m0, s38
	s_nop 0
	global_load_lds_dwordx4 v[220:221], off
	v_lshl_add_u64 v[220:221], s[34:35], 0, v[132:133]
	s_add_i32 m0, s38, 0x2000
	s_nop 0
	global_load_lds_dwordx4 v[220:221], off
	v_lshl_add_u64 v[220:221], v[224:225], 0, s[6:7]
	s_mov_b32 m0, s55
	s_nop 0
	global_load_lds_dwordx4 v[220:221], off
	v_lshl_add_u64 v[220:221], v[226:227], 0, s[6:7]
	s_mov_b32 m0, s56
	s_nop 0
	global_load_lds_dwordx4 v[220:221], off
	s_waitcnt vmcnt(8)
	s_waitcnt lgkmcnt(0)
	s_barrier
	s_setprio 1
	s_waitcnt lgkmcnt(0)
	v_mfma_f32_16x16x32_bf16 v[60:63], v[148:151], v[188:191], v[60:63]
	v_mfma_f32_16x16x32_bf16 v[56:59], v[164:167], v[188:191], v[56:59]
	v_mfma_f32_16x16x32_bf16 v[44:47], v[148:151], v[196:199], v[44:47]
	v_mfma_f32_16x16x32_bf16 v[40:43], v[164:167], v[196:199], v[40:43]
	v_mfma_f32_16x16x32_bf16 v[28:31], v[148:151], v[204:207], v[28:31]
	v_mfma_f32_16x16x32_bf16 v[24:27], v[164:167], v[204:207], v[24:27]
	v_mfma_f32_16x16x32_bf16 v[12:15], v[148:151], v[212:215], v[12:15]
	v_mfma_f32_16x16x32_bf16 v[8:11], v[164:167], v[212:215], v[8:11]
	v_mfma_f32_16x16x32_bf16 v[60:63], v[160:163], v[192:195], v[60:63]
	v_mfma_f32_16x16x32_bf16 v[56:59], v[168:171], v[192:195], v[56:59]
	v_mfma_f32_16x16x32_bf16 v[44:47], v[160:163], v[200:203], v[44:47]
	v_mfma_f32_16x16x32_bf16 v[40:43], v[168:171], v[200:203], v[40:43]
	v_mfma_f32_16x16x32_bf16 v[28:31], v[160:163], v[208:211], v[28:31]
	v_mfma_f32_16x16x32_bf16 v[24:27], v[168:171], v[208:211], v[24:27]
	v_mfma_f32_16x16x32_bf16 v[12:15], v[160:163], v[216:219], v[12:15]
	v_mfma_f32_16x16x32_bf16 v[8:11], v[168:171], v[216:219], v[8:11]
	s_setprio 0
	s_setprio 1
	v_mfma_f32_16x16x32_bf16 v[52:55], v[172:175], v[188:191], v[52:55]
	v_mfma_f32_16x16x32_bf16 v[48:51], v[180:183], v[188:191], v[48:51]
	v_mfma_f32_16x16x32_bf16 v[36:39], v[172:175], v[196:199], v[36:39]
	v_mfma_f32_16x16x32_bf16 v[32:35], v[180:183], v[196:199], v[32:35]
	v_mfma_f32_16x16x32_bf16 v[20:23], v[172:175], v[204:207], v[20:23]
	v_mfma_f32_16x16x32_bf16 v[16:19], v[180:183], v[204:207], v[16:19]
	v_mfma_f32_16x16x32_bf16 v[4:7], v[172:175], v[212:215], v[4:7]
	v_mfma_f32_16x16x32_bf16 v[0:3], v[180:183], v[212:215], v[0:3]
	v_mfma_f32_16x16x32_bf16 v[52:55], v[176:179], v[192:195], v[52:55]
	v_mfma_f32_16x16x32_bf16 v[48:51], v[184:187], v[192:195], v[48:51]
	v_mfma_f32_16x16x32_bf16 v[36:39], v[176:179], v[200:203], v[36:39]
	v_mfma_f32_16x16x32_bf16 v[32:35], v[184:187], v[200:203], v[32:35]
	v_mfma_f32_16x16x32_bf16 v[20:23], v[176:179], v[208:211], v[20:23]
	v_mfma_f32_16x16x32_bf16 v[16:19], v[184:187], v[208:211], v[16:19]
	v_mfma_f32_16x16x32_bf16 v[4:7], v[176:179], v[216:219], v[4:7]
	v_mfma_f32_16x16x32_bf16 v[0:3], v[184:187], v[216:219], v[0:3]
	s_setprio 0
	s_barrier
	s_add_i32 s77, s77, 2
	s_add_u32 s36, s36, 0x100
	s_addc_u32 s37, s37, 0
	s_add_u32 s66, s66, 0x100
	s_addc_u32 s67, s67, 0

.LBB0_1062:
	v_lshl_add_u32 v160, s12, 10, v153
	v_lshl_or_b32 v150, s13, 7, v154
	v_lshl_add_u32 v159, s30, 8, v131
	v_ashrrev_i32_e32 v151, 31, v150
	v_mov_b64_e32 v[148:149], s[16:17]
	v_mad_i64_i32 v[164:165], s[12:13], v159, s59, v[148:149]
	v_lshlrev_b64 v[150:151], 1, v[150:151]
	v_lshl_add_u64 v[164:165], v[164:165], 0, v[150:151]
	v_mov_b32_e32 v232, v164
	v_mov_b32_e32 v233, v165
	ds_read_b32 v172, v160
	ds_read_b32 v174, v160 offset:64
	ds_read_b32 v176, v160 offset:128
	ds_read_b32 v178, v160 offset:192
	ds_read_b32 v180, v160 offset:512
	ds_read_b32 v182, v160 offset:576
	ds_read_b32 v184, v160 offset:640
	ds_read_b32 v186, v160 offset:704
	v_mov_b32_e32 v188, 0xbfb8aa3b
	s_waitcnt lgkmcnt(7)
	v_pk_mul_f32 v[124:125], v[124:125], v[172:173] op_sel_hi:[1,0]
	v_pk_mul_f32 v[126:127], v[126:127], v[172:173] op_sel_hi:[1,0]
	v_pk_mul_f32 v[120:121], v[120:121], v[172:173] op_sel_hi:[1,0]
	v_pk_mul_f32 v[122:123], v[122:123], v[172:173] op_sel_hi:[1,0]
	v_pk_mul_f32 v[116:117], v[116:117], v[172:173] op_sel_hi:[1,0]
	v_pk_mul_f32 v[118:119], v[118:119], v[172:173] op_sel_hi:[1,0]
	v_pk_mul_f32 v[112:113], v[112:113], v[172:173] op_sel_hi:[1,0]
	v_pk_mul_f32 v[114:115], v[114:115], v[172:173] op_sel_hi:[1,0]
	v_pk_mul_f32 v[192:193], v[124:125], v[188:189] op_sel_hi:[1,0]
	v_pk_mul_f32 v[194:195], v[126:127], v[188:189] op_sel_hi:[1,0]
	v_pk_mul_f32 v[196:197], v[120:121], v[188:189] op_sel_hi:[1,0]
	v_pk_mul_f32 v[198:199], v[122:123], v[188:189] op_sel_hi:[1,0]
	v_exp_f32_e32 v192, v192
	v_exp_f32_e32 v193, v193
	v_exp_f32_e32 v194, v194
	v_exp_f32_e32 v195, v195
	v_exp_f32_e32 v196, v196
	v_exp_f32_e32 v197, v197
	v_exp_f32_e32 v198, v198
	v_exp_f32_e32 v199, v199
	v_add_f32_e32 v192, 1.0, v192
	v_add_f32_e32 v193, 1.0, v193
	v_add_f32_e32 v194, 1.0, v194
	v_add_f32_e32 v195, 1.0, v195
	v_add_f32_e32 v196, 1.0, v196
	v_add_f32_e32 v197, 1.0, v197
	v_add_f32_e32 v198, 1.0, v198
	v_add_f32_e32 v199, 1.0, v199
	v_rcp_f32_e32 v192, v192
	v_rcp_f32_e32 v193, v193
	v_rcp_f32_e32 v194, v194
	v_rcp_f32_e32 v195, v195
	v_rcp_f32_e32 v196, v196
	v_rcp_f32_e32 v197, v197
	v_rcp_f32_e32 v198, v198
	v_rcp_f32_e32 v199, v199
	v_pk_mul_f32 v[124:125], v[124:125], v[192:193]
	v_pk_mul_f32 v[126:127], v[126:127], v[194:195]
	v_pk_mul_f32 v[120:121], v[120:121], v[196:197]
	v_pk_mul_f32 v[122:123], v[122:123], v[198:199]
	v_pk_mul_f32 v[124:125], v[116:117], v[124:125]
	v_pk_mul_f32 v[126:127], v[118:119], v[126:127]
	v_pk_mul_f32 v[120:121], v[112:113], v[120:121]
	v_pk_mul_f32 v[122:123], v[114:115], v[122:123]
	v_cvt_pk_bf16_f32 v208, v124, v125
	v_cvt_pk_bf16_f32 v209, v126, v127
	v_cvt_pk_bf16_f32 v210, v120, v121
	v_cvt_pk_bf16_f32 v211, v122, v123
	global_store_dwordx4 v[232:233], v[208:211], off
	s_waitcnt lgkmcnt(6)
	v_pk_mul_f32 v[108:109], v[108:109], v[174:175] op_sel_hi:[1,0]
	v_pk_mul_f32 v[110:111], v[110:111], v[174:175] op_sel_hi:[1,0]
	v_pk_mul_f32 v[104:105], v[104:105], v[174:175] op_sel_hi:[1,0]
	v_pk_mul_f32 v[106:107], v[106:107], v[174:175] op_sel_hi:[1,0]
	v_pk_mul_f32 v[100:101], v[100:101], v[174:175] op_sel_hi:[1,0]
	v_pk_mul_f32 v[102:103], v[102:103], v[174:175] op_sel_hi:[1,0]
	v_pk_mul_f32 v[96:97], v[96:97], v[174:175] op_sel_hi:[1,0]
	v_pk_mul_f32 v[98:99], v[98:99], v[174:175] op_sel_hi:[1,0]
	v_pk_mul_f32 v[200:201], v[108:109], v[188:189] op_sel_hi:[1,0]
	v_pk_mul_f32 v[202:203], v[110:111], v[188:189] op_sel_hi:[1,0]
	v_pk_mul_f32 v[204:205], v[104:105], v[188:189] op_sel_hi:[1,0]
	v_pk_mul_f32 v[206:207], v[106:107], v[188:189] op_sel_hi:[1,0]
	v_exp_f32_e32 v200, v200
	v_exp_f32_e32 v201, v201
	v_exp_f32_e32 v202, v202
	v_exp_f32_e32 v203, v203
	v_exp_f32_e32 v204, v204
	v_exp_f32_e32 v205, v205
	v_exp_f32_e32 v206, v206
	v_exp_f32_e32 v207, v207
	v_add_f32_e32 v200, 1.0, v200
	v_add_f32_e32 v201, 1.0, v201
	v_add_f32_e32 v202, 1.0, v202
	v_add_f32_e32 v203, 1.0, v203
	v_add_f32_e32 v204, 1.0, v204
	v_add_f32_e32 v205, 1.0, v205
	v_add_f32_e32 v206, 1.0, v206
	v_add_f32_e32 v207, 1.0, v207
	v_rcp_f32_e32 v200, v200
	v_rcp_f32_e32 v201, v201
	v_rcp_f32_e32 v202, v202
	v_rcp_f32_e32 v203, v203
	v_rcp_f32_e32 v204, v204
	v_rcp_f32_e32 v205, v205
	v_rcp_f32_e32 v206, v206
	v_rcp_f32_e32 v207, v207
	v_pk_mul_f32 v[108:109], v[108:109], v[200:201]
	v_pk_mul_f32 v[110:111], v[110:111], v[202:203]
	v_pk_mul_f32 v[104:105], v[104:105], v[204:205]
	v_pk_mul_f32 v[106:107], v[106:107], v[206:207]
	v_pk_mul_f32 v[108:109], v[100:101], v[108:109]
	v_pk_mul_f32 v[110:111], v[102:103], v[110:111]
	v_pk_mul_f32 v[104:105], v[96:97], v[104:105]
	v_pk_mul_f32 v[106:107], v[98:99], v[106:107]
	v_cvt_pk_bf16_f32 v212, v108, v109
	v_cvt_pk_bf16_f32 v213, v110, v111
	v_cvt_pk_bf16_f32 v214, v104, v105
	v_cvt_pk_bf16_f32 v215, v106, v107
	s_mov_b64 s[100:101], 0x16000
	v_lshl_add_u64 v[216:217], v[232:233], 0, s[100:101]
	global_store_dwordx4 v[216:217], v[212:215], off
	s_waitcnt lgkmcnt(5)
	v_pk_mul_f32 v[92:93], v[92:93], v[176:177] op_sel_hi:[1,0]
	v_pk_mul_f32 v[94:95], v[94:95], v[176:177] op_sel_hi:[1,0]
	v_pk_mul_f32 v[88:89], v[88:89], v[176:177] op_sel_hi:[1,0]
	v_pk_mul_f32 v[90:91], v[90:91], v[176:177] op_sel_hi:[1,0]
	v_pk_mul_f32 v[84:85], v[84:85], v[176:177] op_sel_hi:[1,0]
	v_pk_mul_f32 v[86:87], v[86:87], v[176:177] op_sel_hi:[1,0]
	v_pk_mul_f32 v[80:81], v[80:81], v[176:177] op_sel_hi:[1,0]
	v_pk_mul_f32 v[82:83], v[82:83], v[176:177] op_sel_hi:[1,0]
	v_pk_mul_f32 v[192:193], v[92:93], v[188:189] op_sel_hi:[1,0]
	v_pk_mul_f32 v[194:195], v[94:95], v[188:189] op_sel_hi:[1,0]
	v_pk_mul_f32 v[196:197], v[88:89], v[188:189] op_sel_hi:[1,0]
	v_pk_mul_f32 v[198:199], v[90:91], v[188:189] op_sel_hi:[1,0]
	v_exp_f32_e32 v192, v192
	v_exp_f32_e32 v193, v193
	v_exp_f32_e32 v194, v194
	v_exp_f32_e32 v195, v195
	v_exp_f32_e32 v196, v196
	v_exp_f32_e32 v197, v197
	v_exp_f32_e32 v198, v198
	v_exp_f32_e32 v199, v199
	v_add_f32_e32 v192, 1.0, v192
	v_add_f32_e32 v193, 1.0, v193
	v_add_f32_e32 v194, 1.0, v194
	v_add_f32_e32 v195, 1.0, v195
	v_add_f32_e32 v196, 1.0, v196
	v_add_f32_e32 v197, 1.0, v197
	v_add_f32_e32 v198, 1.0, v198
	v_add_f32_e32 v199, 1.0, v199
	v_rcp_f32_e32 v192, v192
	v_rcp_f32_e32 v193, v193
	v_rcp_f32_e32 v194, v194
	v_rcp_f32_e32 v195, v195
	v_rcp_f32_e32 v196, v196
	v_rcp_f32_e32 v197, v197
	v_rcp_f32_e32 v198, v198
	v_rcp_f32_e32 v199, v199
	v_pk_mul_f32 v[92:93], v[92:93], v[192:193]
	v_pk_mul_f32 v[94:95], v[94:95], v[194:195]
	v_pk_mul_f32 v[88:89], v[88:89], v[196:197]
	v_pk_mul_f32 v[90:91], v[90:91], v[198:199]
	v_pk_mul_f32 v[92:93], v[84:85], v[92:93]
	v_pk_mul_f32 v[94:95], v[86:87], v[94:95]
	v_pk_mul_f32 v[88:89], v[80:81], v[88:89]
	v_pk_mul_f32 v[90:91], v[82:83], v[90:91]
	v_cvt_pk_bf16_f32 v208, v92, v93
	v_cvt_pk_bf16_f32 v209, v94, v95
	v_cvt_pk_bf16_f32 v210, v88, v89
	v_cvt_pk_bf16_f32 v211, v90, v91
	s_mov_b64 s[100:101], 0x2c000
	v_lshl_add_u64 v[216:217], v[232:233], 0, s[100:101]
	global_store_dwordx4 v[216:217], v[208:211], off
	s_waitcnt lgkmcnt(4)
	v_pk_mul_f32 v[76:77], v[76:77], v[178:179] op_sel_hi:[1,0]
	v_pk_mul_f32 v[78:79], v[78:79], v[178:179] op_sel_hi:[1,0]
	v_pk_mul_f32 v[72:73], v[72:73], v[178:179] op_sel_hi:[1,0]
	v_pk_mul_f32 v[74:75], v[74:75], v[178:179] op_sel_hi:[1,0]
	v_pk_mul_f32 v[68:69], v[68:69], v[178:179] op_sel_hi:[1,0]
	v_pk_mul_f32 v[70:71], v[70:71], v[178:179] op_sel_hi:[1,0]
	v_pk_mul_f32 v[64:65], v[64:65], v[178:179] op_sel_hi:[1,0]
	v_pk_mul_f32 v[66:67], v[66:67], v[178:179] op_sel_hi:[1,0]
	v_pk_mul_f32 v[200:201], v[76:77], v[188:189] op_sel_hi:[1,0]
	v_pk_mul_f32 v[202:203], v[78:79], v[188:189] op_sel_hi:[1,0]
	v_pk_mul_f32 v[204:205], v[72:73], v[188:189] op_sel_hi:[1,0]
	v_pk_mul_f32 v[206:207], v[74:75], v[188:189] op_sel_hi:[1,0]
	v_exp_f32_e32 v200, v200
	v_exp_f32_e32 v201, v201
	v_exp_f32_e32 v202, v202
	v_exp_f32_e32 v203, v203
	v_exp_f32_e32 v204, v204
	v_exp_f32_e32 v205, v205
	v_exp_f32_e32 v206, v206
	v_exp_f32_e32 v207, v207
	v_add_f32_e32 v200, 1.0, v200
	v_add_f32_e32 v201, 1.0, v201
	v_add_f32_e32 v202, 1.0, v202
	v_add_f32_e32 v203, 1.0, v203
	v_add_f32_e32 v204, 1.0, v204
	v_add_f32_e32 v205, 1.0, v205
	v_add_f32_e32 v206, 1.0, v206
	v_add_f32_e32 v207, 1.0, v207
	v_rcp_f32_e32 v200, v200
	v_rcp_f32_e32 v201, v201
	v_rcp_f32_e32 v202, v202
	v_rcp_f32_e32 v203, v203
	v_rcp_f32_e32 v204, v204
	v_rcp_f32_e32 v205, v205
	v_rcp_f32_e32 v206, v206
	v_rcp_f32_e32 v207, v207
	v_pk_mul_f32 v[76:77], v[76:77], v[200:201]
	v_pk_mul_f32 v[78:79], v[78:79], v[202:203]
	v_pk_mul_f32 v[72:73], v[72:73], v[204:205]
	v_pk_mul_f32 v[74:75], v[74:75], v[206:207]
	v_pk_mul_f32 v[76:77], v[68:69], v[76:77]
	v_pk_mul_f32 v[78:79], v[70:71], v[78:79]
	v_pk_mul_f32 v[72:73], v[64:65], v[72:73]
	v_pk_mul_f32 v[74:75], v[66:67], v[74:75]
	v_cvt_pk_bf16_f32 v212, v76, v77
	v_cvt_pk_bf16_f32 v213, v78, v79
	v_cvt_pk_bf16_f32 v214, v72, v73
	v_cvt_pk_bf16_f32 v215, v74, v75
	s_mov_b64 s[100:101], 0x42000
	v_lshl_add_u64 v[216:217], v[232:233], 0, s[100:101]
	global_store_dwordx4 v[216:217], v[212:215], off
	s_waitcnt lgkmcnt(3)
	v_pk_mul_f32 v[60:61], v[60:61], v[180:181] op_sel_hi:[1,0]
	v_pk_mul_f32 v[62:63], v[62:63], v[180:181] op_sel_hi:[1,0]
	v_pk_mul_f32 v[56:57], v[56:57], v[180:181] op_sel_hi:[1,0]
	v_pk_mul_f32 v[58:59], v[58:59], v[180:181] op_sel_hi:[1,0]
	v_pk_mul_f32 v[52:53], v[52:53], v[180:181] op_sel_hi:[1,0]
	v_pk_mul_f32 v[54:55], v[54:55], v[180:181] op_sel_hi:[1,0]
	v_pk_mul_f32 v[48:49], v[48:49], v[180:181] op_sel_hi:[1,0]
	v_pk_mul_f32 v[50:51], v[50:51], v[180:181] op_sel_hi:[1,0]
	v_pk_mul_f32 v[192:193], v[60:61], v[188:189] op_sel_hi:[1,0]
	v_pk_mul_f32 v[194:195], v[62:63], v[188:189] op_sel_hi:[1,0]
	v_pk_mul_f32 v[196:197], v[56:57], v[188:189] op_sel_hi:[1,0]
	v_pk_mul_f32 v[198:199], v[58:59], v[188:189] op_sel_hi:[1,0]
	v_exp_f32_e32 v192, v192
	v_exp_f32_e32 v193, v193
	v_exp_f32_e32 v194, v194
	v_exp_f32_e32 v195, v195
	v_exp_f32_e32 v196, v196
	v_exp_f32_e32 v197, v197
	v_exp_f32_e32 v198, v198
	v_exp_f32_e32 v199, v199
	v_add_f32_e32 v192, 1.0, v192
	v_add_f32_e32 v193, 1.0, v193
	v_add_f32_e32 v194, 1.0, v194
	v_add_f32_e32 v195, 1.0, v195
	v_add_f32_e32 v196, 1.0, v196
	v_add_f32_e32 v197, 1.0, v197
	v_add_f32_e32 v198, 1.0, v198
	v_add_f32_e32 v199, 1.0, v199
	v_rcp_f32_e32 v192, v192
	v_rcp_f32_e32 v193, v193
	v_rcp_f32_e32 v194, v194
	v_rcp_f32_e32 v195, v195
	v_rcp_f32_e32 v196, v196
	v_rcp_f32_e32 v197, v197
	v_rcp_f32_e32 v198, v198
	v_rcp_f32_e32 v199, v199
	v_pk_mul_f32 v[60:61], v[60:61], v[192:193]
	v_pk_mul_f32 v[62:63], v[62:63], v[194:195]
	v_pk_mul_f32 v[56:57], v[56:57], v[196:197]
	v_pk_mul_f32 v[58:59], v[58:59], v[198:199]
	v_pk_mul_f32 v[60:61], v[52:53], v[60:61]
	v_pk_mul_f32 v[62:63], v[54:55], v[62:63]
	v_pk_mul_f32 v[56:57], v[48:49], v[56:57]
	v_pk_mul_f32 v[58:59], v[50:51], v[58:59]
	v_cvt_pk_bf16_f32 v208, v60, v61
	v_cvt_pk_bf16_f32 v209, v62, v63
	v_cvt_pk_bf16_f32 v210, v56, v57
	v_cvt_pk_bf16_f32 v211, v58, v59
	s_mov_b64 s[100:101], 0xb0000
	v_lshl_add_u64 v[216:217], v[232:233], 0, s[100:101]
	global_store_dwordx4 v[216:217], v[208:211], off
	s_waitcnt lgkmcnt(2)
	v_pk_mul_f32 v[44:45], v[44:45], v[182:183] op_sel_hi:[1,0]
	v_pk_mul_f32 v[46:47], v[46:47], v[182:183] op_sel_hi:[1,0]
	v_pk_mul_f32 v[40:41], v[40:41], v[182:183] op_sel_hi:[1,0]
	v_pk_mul_f32 v[42:43], v[42:43], v[182:183] op_sel_hi:[1,0]
	v_pk_mul_f32 v[36:37], v[36:37], v[182:183] op_sel_hi:[1,0]
	v_pk_mul_f32 v[38:39], v[38:39], v[182:183] op_sel_hi:[1,0]
	v_pk_mul_f32 v[32:33], v[32:33], v[182:183] op_sel_hi:[1,0]
	v_pk_mul_f32 v[34:35], v[34:35], v[182:183] op_sel_hi:[1,0]
	v_pk_mul_f32 v[200:201], v[44:45], v[188:189] op_sel_hi:[1,0]
	v_pk_mul_f32 v[202:203], v[46:47], v[188:189] op_sel_hi:[1,0]
	v_pk_mul_f32 v[204:205], v[40:41], v[188:189] op_sel_hi:[1,0]
	v_pk_mul_f32 v[206:207], v[42:43], v[188:189] op_sel_hi:[1,0]
	v_exp_f32_e32 v200, v200
	v_exp_f32_e32 v201, v201
	v_exp_f32_e32 v202, v202
	v_exp_f32_e32 v203, v203
	v_exp_f32_e32 v204, v204
	v_exp_f32_e32 v205, v205
	v_exp_f32_e32 v206, v206
	v_exp_f32_e32 v207, v207
	v_add_f32_e32 v200, 1.0, v200
	v_add_f32_e32 v201, 1.0, v201
	v_add_f32_e32 v202, 1.0, v202
	v_add_f32_e32 v203, 1.0, v203
	v_add_f32_e32 v204, 1.0, v204
	v_add_f32_e32 v205, 1.0, v205
	v_add_f32_e32 v206, 1.0, v206
	v_add_f32_e32 v207, 1.0, v207
	v_rcp_f32_e32 v200, v200
	v_rcp_f32_e32 v201, v201
	v_rcp_f32_e32 v202, v202
	v_rcp_f32_e32 v203, v203
	v_rcp_f32_e32 v204, v204
	v_rcp_f32_e32 v205, v205
	v_rcp_f32_e32 v206, v206
	v_rcp_f32_e32 v207, v207
	v_pk_mul_f32 v[44:45], v[44:45], v[200:201]
	v_pk_mul_f32 v[46:47], v[46:47], v[202:203]
	v_pk_mul_f32 v[40:41], v[40:41], v[204:205]
	v_pk_mul_f32 v[42:43], v[42:43], v[206:207]
	v_pk_mul_f32 v[44:45], v[36:37], v[44:45]
	v_pk_mul_f32 v[46:47], v[38:39], v[46:47]
	v_pk_mul_f32 v[40:41], v[32:33], v[40:41]
	v_pk_mul_f32 v[42:43], v[34:35], v[42:43]
	v_cvt_pk_bf16_f32 v212, v44, v45
	v_cvt_pk_bf16_f32 v213, v46, v47
	v_cvt_pk_bf16_f32 v214, v40, v41
	v_cvt_pk_bf16_f32 v215, v42, v43
	s_mov_b64 s[100:101], 0xc6000
	v_lshl_add_u64 v[216:217], v[232:233], 0, s[100:101]
	global_store_dwordx4 v[216:217], v[212:215], off
	s_waitcnt lgkmcnt(1)
	v_pk_mul_f32 v[28:29], v[28:29], v[184:185] op_sel_hi:[1,0]
	v_pk_mul_f32 v[30:31], v[30:31], v[184:185] op_sel_hi:[1,0]
	v_pk_mul_f32 v[24:25], v[24:25], v[184:185] op_sel_hi:[1,0]
	v_pk_mul_f32 v[26:27], v[26:27], v[184:185] op_sel_hi:[1,0]
	v_pk_mul_f32 v[20:21], v[20:21], v[184:185] op_sel_hi:[1,0]
	v_pk_mul_f32 v[22:23], v[22:23], v[184:185] op_sel_hi:[1,0]
	v_pk_mul_f32 v[16:17], v[16:17], v[184:185] op_sel_hi:[1,0]
	v_pk_mul_f32 v[18:19], v[18:19], v[184:185] op_sel_hi:[1,0]
	v_pk_mul_f32 v[192:193], v[28:29], v[188:189] op_sel_hi:[1,0]
	v_pk_mul_f32 v[194:195], v[30:31], v[188:189] op_sel_hi:[1,0]
	v_pk_mul_f32 v[196:197], v[24:25], v[188:189] op_sel_hi:[1,0]
	v_pk_mul_f32 v[198:199], v[26:27], v[188:189] op_sel_hi:[1,0]
	v_exp_f32_e32 v192, v192
	v_exp_f32_e32 v193, v193
	v_exp_f32_e32 v194, v194
	v_exp_f32_e32 v195, v195
	v_exp_f32_e32 v196, v196
	v_exp_f32_e32 v197, v197
	v_exp_f32_e32 v198, v198
	v_exp_f32_e32 v199, v199
	v_add_f32_e32 v192, 1.0, v192
	v_add_f32_e32 v193, 1.0, v193
	v_add_f32_e32 v194, 1.0, v194
	v_add_f32_e32 v195, 1.0, v195
	v_add_f32_e32 v196, 1.0, v196
	v_add_f32_e32 v197, 1.0, v197
	v_add_f32_e32 v198, 1.0, v198
	v_add_f32_e32 v199, 1.0, v199
	v_rcp_f32_e32 v192, v192
	v_rcp_f32_e32 v193, v193
	v_rcp_f32_e32 v194, v194
	v_rcp_f32_e32 v195, v195
	v_rcp_f32_e32 v196, v196
	v_rcp_f32_e32 v197, v197
	v_rcp_f32_e32 v198, v198
	v_rcp_f32_e32 v199, v199
	v_pk_mul_f32 v[28:29], v[28:29], v[192:193]
	v_pk_mul_f32 v[30:31], v[30:31], v[194:195]
	v_pk_mul_f32 v[24:25], v[24:25], v[196:197]
	v_pk_mul_f32 v[26:27], v[26:27], v[198:199]
	v_pk_mul_f32 v[28:29], v[20:21], v[28:29]
	v_pk_mul_f32 v[30:31], v[22:23], v[30:31]
	v_pk_mul_f32 v[24:25], v[16:17], v[24:25]
	v_pk_mul_f32 v[26:27], v[18:19], v[26:27]
	v_cvt_pk_bf16_f32 v208, v28, v29
	v_cvt_pk_bf16_f32 v209, v30, v31
	v_cvt_pk_bf16_f32 v210, v24, v25
	v_cvt_pk_bf16_f32 v211, v26, v27
	s_mov_b64 s[100:101], 0xdc000
	v_lshl_add_u64 v[216:217], v[232:233], 0, s[100:101]
	global_store_dwordx4 v[216:217], v[208:211], off
	s_waitcnt lgkmcnt(0)
	v_pk_mul_f32 v[12:13], v[12:13], v[186:187] op_sel_hi:[1,0]
	v_pk_mul_f32 v[14:15], v[14:15], v[186:187] op_sel_hi:[1,0]
	v_pk_mul_f32 v[8:9], v[8:9], v[186:187] op_sel_hi:[1,0]
	v_pk_mul_f32 v[10:11], v[10:11], v[186:187] op_sel_hi:[1,0]
	v_pk_mul_f32 v[4:5], v[4:5], v[186:187] op_sel_hi:[1,0]
	v_pk_mul_f32 v[6:7], v[6:7], v[186:187] op_sel_hi:[1,0]
	v_pk_mul_f32 v[0:1], v[0:1], v[186:187] op_sel_hi:[1,0]
	v_pk_mul_f32 v[2:3], v[2:3], v[186:187] op_sel_hi:[1,0]
	v_pk_mul_f32 v[200:201], v[12:13], v[188:189] op_sel_hi:[1,0]
	v_pk_mul_f32 v[202:203], v[14:15], v[188:189] op_sel_hi:[1,0]
	v_pk_mul_f32 v[204:205], v[8:9], v[188:189] op_sel_hi:[1,0]
	v_pk_mul_f32 v[206:207], v[10:11], v[188:189] op_sel_hi:[1,0]
	v_exp_f32_e32 v200, v200
	v_exp_f32_e32 v201, v201
	v_exp_f32_e32 v202, v202
	v_exp_f32_e32 v203, v203
	v_exp_f32_e32 v204, v204
	v_exp_f32_e32 v205, v205
	v_exp_f32_e32 v206, v206
	v_exp_f32_e32 v207, v207
	v_add_f32_e32 v200, 1.0, v200
	v_add_f32_e32 v201, 1.0, v201
	v_add_f32_e32 v202, 1.0, v202
	v_add_f32_e32 v203, 1.0, v203
	v_add_f32_e32 v204, 1.0, v204
	v_add_f32_e32 v205, 1.0, v205
	v_add_f32_e32 v206, 1.0, v206
	v_add_f32_e32 v207, 1.0, v207
	v_rcp_f32_e32 v200, v200
	v_rcp_f32_e32 v201, v201
	v_rcp_f32_e32 v202, v202
	v_rcp_f32_e32 v203, v203
	v_rcp_f32_e32 v204, v204
	v_rcp_f32_e32 v205, v205
	v_rcp_f32_e32 v206, v206
	v_rcp_f32_e32 v207, v207
	v_pk_mul_f32 v[12:13], v[12:13], v[200:201]
	v_pk_mul_f32 v[14:15], v[14:15], v[202:203]
	v_pk_mul_f32 v[8:9], v[8:9], v[204:205]
	v_pk_mul_f32 v[10:11], v[10:11], v[206:207]
	v_pk_mul_f32 v[12:13], v[4:5], v[12:13]
	v_pk_mul_f32 v[14:15], v[6:7], v[14:15]
	v_pk_mul_f32 v[8:9], v[0:1], v[8:9]
	v_pk_mul_f32 v[10:11], v[2:3], v[10:11]
	v_cvt_pk_bf16_f32 v212, v12, v13
	v_cvt_pk_bf16_f32 v213, v14, v15
	v_cvt_pk_bf16_f32 v214, v8, v9
	v_cvt_pk_bf16_f32 v215, v10, v11
	s_mov_b64 s[100:101], 0xf2000
	v_lshl_add_u64 v[216:217], v[232:233], 0, s[100:101]
	global_store_dwordx4 v[216:217], v[212:215], off
	s_andn2_b64 vcc, exec, s[4:5]
	s_mov_b64 s[4:5], -1
	s_cbranch_vccnz .LBB0_1055
	s_andn2_b64 vcc, exec, s[0:1]
	s_cbranch_vccnz .LBB0_1054
	s_barrier
	s_branch .LBB0_1054

.LBB0_1134:
	s_add_i32 s58, s58, 1
	s_mul_i32 s0, s58, s53
	s_mul_hi_u32 s1, s58, s54
	s_add_i32 s1, s1, s0
	s_mul_i32 s0, s58, s54
	s_add_u32 s6, s0, s2
	s_addc_u32 s7, s1, s55
	v_cmp_gt_i64_e32 vcc, s[6:7], v[146:147]
	v_cmp_lt_i64_e64 s[0:1], s[6:7], v[144:145]
	s_cbranch_vccnz .LBB0_1140
	s_and_b32 s100, s6, 7
	s_mul_i32 s100, s100, 0x40
	s_lshr_b32 s101, s6, 3
	s_add_i32 s100, s100, s101
	s_mul_hi_u32 s101, s100, 0x8000000
	s_mul_i32 s59, s101, 0x20
	s_sub_i32 s59, s100, s59
	s_and_b32 s100, s59, 7
	s_lshl_b32 s62, s101, 3
	s_add_i32 s62, s62, s100
	s_lshr_b32 s59, s59, 3

.LBB0_1144:
	s_add_u32 s30, s30, 0xb0080
	s_addc_u32 s31, s31, 0
	s_add_u32 s13, s36, 0x100
	s_addc_u32 s63, s37, 0
	s_mov_b32 s64, -2
	s_waitcnt lgkmcnt(0)
	ds_read_b128 v[148:151], v154
	ds_read_b128 v[160:163], v154 offset:1024
	ds_read_b128 v[164:167], v154 offset:2048
	ds_read_b128 v[168:171], v154 offset:3072
	ds_read_b128 v[172:175], v155
	ds_read_b128 v[176:179], v155 offset:1024
	ds_read_b128 v[180:183], v155 offset:2048
	ds_read_b128 v[184:187], v155 offset:3072
	s_add_u32 s34, s30, 0xfff50080
	s_addc_u32 s35, s31, -1
	s_cmp_eq_u32 s64, 40
	s_cselect_b32 s39, s1, s35
	s_cselect_b32 s38, s0, s34
	s_cselect_b32 s37, s29, s63
	s_cselect_b32 s36, s28, s13
	v_lshl_add_u64 v[220:221], s[30:31], 0, v[140:141]
	s_add_i32 m0, s42, 0xc000
	ds_read_b128 v[188:191], v157
	ds_read_b128 v[192:195], v157 offset:1024
	ds_read_b128 v[196:199], v157 offset:2048
	ds_read_b128 v[200:203], v157 offset:3072
	ds_read_b128 v[204:207], v157 offset:4096
	ds_read_b128 v[208:211], v157 offset:5120
	ds_read_b128 v[212:215], v157 offset:6144
	ds_read_b128 v[216:219], v157 offset:7168
	global_load_lds_dwordx4 v[220:221], off
	v_lshl_add_u64 v[220:221], s[30:31], 0, v[142:143]
	s_add_i32 m0, s42, 0xe000
	s_nop 0
	global_load_lds_dwordx4 v[220:221], off
	s_waitcnt vmcnt(8)
	s_waitcnt lgkmcnt(0)
	s_barrier
	s_setprio 1
	s_waitcnt lgkmcnt(0)
	v_mfma_f32_16x16x32_bf16 v[124:127], v[148:151], v[188:191], 0
	v_mfma_f32_16x16x32_bf16 v[120:123], v[164:167], v[188:191], 0
	v_mfma_f32_16x16x32_bf16 v[108:111], v[148:151], v[196:199], 0
	v_mfma_f32_16x16x32_bf16 v[104:107], v[164:167], v[196:199], 0
	v_mfma_f32_16x16x32_bf16 v[92:95], v[148:151], v[204:207], 0
	v_mfma_f32_16x16x32_bf16 v[88:91], v[164:167], v[204:207], 0
	v_mfma_f32_16x16x32_bf16 v[76:79], v[148:151], v[212:215], 0
	v_mfma_f32_16x16x32_bf16 v[72:75], v[164:167], v[212:215], 0
	v_mfma_f32_16x16x32_bf16 v[124:127], v[160:163], v[192:195], v[124:127]
	v_mfma_f32_16x16x32_bf16 v[120:123], v[168:171], v[192:195], v[120:123]
	v_mfma_f32_16x16x32_bf16 v[108:111], v[160:163], v[200:203], v[108:111]
	v_mfma_f32_16x16x32_bf16 v[104:107], v[168:171], v[200:203], v[104:107]
	v_mfma_f32_16x16x32_bf16 v[92:95], v[160:163], v[208:211], v[92:95]
	v_mfma_f32_16x16x32_bf16 v[88:91], v[168:171], v[208:211], v[88:91]
	v_mfma_f32_16x16x32_bf16 v[76:79], v[160:163], v[216:219], v[76:79]
	v_mfma_f32_16x16x32_bf16 v[72:75], v[168:171], v[216:219], v[72:75]
	s_setprio 0
	s_setprio 1
	v_mfma_f32_16x16x32_bf16 v[116:119], v[172:175], v[188:191], 0
	v_mfma_f32_16x16x32_bf16 v[112:115], v[180:183], v[188:191], 0
	v_mfma_f32_16x16x32_bf16 v[100:103], v[172:175], v[196:199], 0
	v_mfma_f32_16x16x32_bf16 v[96:99], v[180:183], v[196:199], 0
	v_mfma_f32_16x16x32_bf16 v[84:87], v[172:175], v[204:207], 0
	v_mfma_f32_16x16x32_bf16 v[80:83], v[180:183], v[204:207], 0
	v_mfma_f32_16x16x32_bf16 v[68:71], v[172:175], v[212:215], 0
	v_mfma_f32_16x16x32_bf16 v[64:67], v[180:183], v[212:215], 0
	v_mfma_f32_16x16x32_bf16 v[116:119], v[176:179], v[192:195], v[116:119]
	v_mfma_f32_16x16x32_bf16 v[112:115], v[184:187], v[192:195], v[112:115]
	v_mfma_f32_16x16x32_bf16 v[100:103], v[176:179], v[200:203], v[100:103]
	v_mfma_f32_16x16x32_bf16 v[96:99], v[184:187], v[200:203], v[96:99]
	v_mfma_f32_16x16x32_bf16 v[84:87], v[176:179], v[208:211], v[84:87]
	v_mfma_f32_16x16x32_bf16 v[80:83], v[184:187], v[208:211], v[80:83]
	v_mfma_f32_16x16x32_bf16 v[68:71], v[176:179], v[216:219], v[68:71]
	v_mfma_f32_16x16x32_bf16 v[64:67], v[184:187], v[216:219], v[64:67]
	s_setprio 0
	s_barrier
	s_add_i32 s34, s56, s41
	v_lshl_add_u64 v[220:221], s[36:37], 0, v[134:135]
	s_mov_b32 m0, s34
	ds_read_b128 v[188:191], v157 offset:16384
	ds_read_b128 v[192:195], v157 offset:17408
	ds_read_b128 v[196:199], v157 offset:18432
	ds_read_b128 v[200:203], v157 offset:19456
	ds_read_b128 v[204:207], v157 offset:20480
	ds_read_b128 v[208:211], v157 offset:21504
	ds_read_b128 v[212:215], v157 offset:22528
	ds_read_b128 v[216:219], v157 offset:23552
	global_load_lds_dwordx4 v[220:221], off
	s_add_i32 m0, s34, 0x2000
	s_add_u32 s34, s36, 0xb0000
	v_lshl_add_u64 v[222:223], s[36:37], 0, v[138:139]
	s_addc_u32 s35, s37, 0
	s_add_i32 s65, s57, s41
	global_load_lds_dwordx4 v[222:223], off
	v_lshl_add_u64 v[224:225], s[34:35], 0, v[134:135]
	s_mov_b32 m0, s65
	v_lshl_add_u64 v[226:227], s[38:39], 0, v[136:137]
	global_load_lds_dwordx4 v[224:225], off
	v_lshl_add_u64 v[224:225], s[34:35], 0, v[138:139]
	s_add_i32 m0, s65, 0x2000
	s_nop 0
	global_load_lds_dwordx4 v[224:225], off
	v_lshl_add_u64 v[224:225], s[38:39], 0, v[132:133]
	s_mov_b32 m0, s42
	s_nop 0
	global_load_lds_dwordx4 v[224:225], off
	s_mov_b32 m0, s43
	s_nop 0
	global_load_lds_dwordx4 v[226:227], off
	s_waitcnt vmcnt(8)
	s_waitcnt lgkmcnt(0)
	s_barrier
	s_setprio 1
	s_waitcnt lgkmcnt(0)
	v_mfma_f32_16x16x32_bf16 v[60:63], v[148:151], v[188:191], 0
	v_mfma_f32_16x16x32_bf16 v[56:59], v[164:167], v[188:191], 0
	v_mfma_f32_16x16x32_bf16 v[44:47], v[148:151], v[196:199], 0
	v_mfma_f32_16x16x32_bf16 v[40:43], v[164:167], v[196:199], 0
	v_mfma_f32_16x16x32_bf16 v[28:31], v[148:151], v[204:207], 0
	v_mfma_f32_16x16x32_bf16 v[24:27], v[164:167], v[204:207], 0
	v_mfma_f32_16x16x32_bf16 v[12:15], v[148:151], v[212:215], 0
	v_mfma_f32_16x16x32_bf16 v[8:11], v[164:167], v[212:215], 0
	v_mfma_f32_16x16x32_bf16 v[60:63], v[160:163], v[192:195], v[60:63]
	v_mfma_f32_16x16x32_bf16 v[56:59], v[168:171], v[192:195], v[56:59]
	v_mfma_f32_16x16x32_bf16 v[44:47], v[160:163], v[200:203], v[44:47]
	v_mfma_f32_16x16x32_bf16 v[40:43], v[168:171], v[200:203], v[40:43]
	v_mfma_f32_16x16x32_bf16 v[28:31], v[160:163], v[208:211], v[28:31]
	v_mfma_f32_16x16x32_bf16 v[24:27], v[168:171], v[208:211], v[24:27]
	v_mfma_f32_16x16x32_bf16 v[12:15], v[160:163], v[216:219], v[12:15]
	v_mfma_f32_16x16x32_bf16 v[8:11], v[168:171], v[216:219], v[8:11]
	s_setprio 0
	s_setprio 1
	v_mfma_f32_16x16x32_bf16 v[52:55], v[172:175], v[188:191], 0
	v_mfma_f32_16x16x32_bf16 v[48:51], v[180:183], v[188:191], 0
	v_mfma_f32_16x16x32_bf16 v[36:39], v[172:175], v[196:199], 0
	v_mfma_f32_16x16x32_bf16 v[32:35], v[180:183], v[196:199], 0
	v_mfma_f32_16x16x32_bf16 v[20:23], v[172:175], v[204:207], 0
	v_mfma_f32_16x16x32_bf16 v[16:19], v[180:183], v[204:207], 0
	v_mfma_f32_16x16x32_bf16 v[4:7], v[172:175], v[212:215], 0
	v_mfma_f32_16x16x32_bf16 v[0:3], v[180:183], v[212:215], 0
	v_mfma_f32_16x16x32_bf16 v[52:55], v[176:179], v[192:195], v[52:55]
	v_mfma_f32_16x16x32_bf16 v[48:51], v[184:187], v[192:195], v[48:51]
	v_mfma_f32_16x16x32_bf16 v[36:39], v[176:179], v[200:203], v[36:39]
	v_mfma_f32_16x16x32_bf16 v[32:35], v[184:187], v[200:203], v[32:35]
	v_mfma_f32_16x16x32_bf16 v[20:23], v[176:179], v[208:211], v[20:23]
	v_mfma_f32_16x16x32_bf16 v[16:19], v[184:187], v[208:211], v[16:19]
	v_mfma_f32_16x16x32_bf16 v[4:7], v[176:179], v[216:219], v[4:7]
	v_mfma_f32_16x16x32_bf16 v[0:3], v[184:187], v[216:219], v[0:3]
	s_setprio 0
	s_barrier
	s_add_i32 s65, 0, 0x18000
	v_add_u32_e32 v159, s65, v152
	s_add_i32 s66, 0, 0x1c000
	ds_read_b128 v[148:151], v159
	ds_read_b128 v[160:163], v159 offset:1024
	ds_read_b128 v[164:167], v159 offset:2048
	ds_read_b128 v[168:171], v159 offset:3072
	v_add_u32_e32 v159, s66, v152
	ds_read_b128 v[172:175], v159
	ds_read_b128 v[176:179], v159 offset:1024
	ds_read_b128 v[180:183], v159 offset:2048
	ds_read_b128 v[184:187], v159 offset:3072
	s_add_u32 s34, s38, 0xb0000
	s_addc_u32 s35, s39, 0
	s_mov_b32 m0, s48
	v_lshl_add_u64 v[228:229], s[34:35], 0, v[132:133]
	ds_read_b128 v[188:191], v157 offset:32768
	ds_read_b128 v[192:195], v157 offset:33792
	ds_read_b128 v[196:199], v157 offset:34816
	ds_read_b128 v[200:203], v157 offset:35840
	ds_read_b128 v[204:207], v157 offset:36864
	ds_read_b128 v[208:211], v157 offset:37888
	ds_read_b128 v[212:215], v157 offset:38912
	ds_read_b128 v[216:219], v157 offset:39936
	global_load_lds_dwordx4 v[228:229], off
	v_lshl_add_u64 v[228:229], s[34:35], 0, v[136:137]
	s_mov_b32 m0, s49
	s_nop 0
	global_load_lds_dwordx4 v[228:229], off
	s_waitcnt vmcnt(8)
	s_waitcnt lgkmcnt(0)
	s_barrier
	s_setprio 1
	s_waitcnt lgkmcnt(0)
	v_mfma_f32_16x16x32_bf16 v[124:127], v[148:151], v[188:191], v[124:127]
	v_mfma_f32_16x16x32_bf16 v[120:123], v[164:167], v[188:191], v[120:123]
	v_mfma_f32_16x16x32_bf16 v[108:111], v[148:151], v[196:199], v[108:111]
	v_mfma_f32_16x16x32_bf16 v[104:107], v[164:167], v[196:199], v[104:107]
	v_mfma_f32_16x16x32_bf16 v[92:95], v[148:151], v[204:207], v[92:95]
	v_mfma_f32_16x16x32_bf16 v[88:91], v[164:167], v[204:207], v[88:91]
	v_mfma_f32_16x16x32_bf16 v[76:79], v[148:151], v[212:215], v[76:79]
	v_mfma_f32_16x16x32_bf16 v[72:75], v[164:167], v[212:215], v[72:75]
	v_mfma_f32_16x16x32_bf16 v[124:127], v[160:163], v[192:195], v[124:127]
	v_mfma_f32_16x16x32_bf16 v[120:123], v[168:171], v[192:195], v[120:123]
	v_mfma_f32_16x16x32_bf16 v[108:111], v[160:163], v[200:203], v[108:111]
	v_mfma_f32_16x16x32_bf16 v[104:107], v[168:171], v[200:203], v[104:107]
	v_mfma_f32_16x16x32_bf16 v[92:95], v[160:163], v[208:211], v[92:95]
	v_mfma_f32_16x16x32_bf16 v[88:91], v[168:171], v[208:211], v[88:91]
	v_mfma_f32_16x16x32_bf16 v[76:79], v[160:163], v[216:219], v[76:79]
	v_mfma_f32_16x16x32_bf16 v[72:75], v[168:171], v[216:219], v[72:75]
	s_setprio 0
	s_setprio 1
	v_mfma_f32_16x16x32_bf16 v[116:119], v[172:175], v[188:191], v[116:119]
	v_mfma_f32_16x16x32_bf16 v[112:115], v[180:183], v[188:191], v[112:115]
	v_mfma_f32_16x16x32_bf16 v[100:103], v[172:175], v[196:199], v[100:103]
	v_mfma_f32_16x16x32_bf16 v[96:99], v[180:183], v[196:199], v[96:99]
	v_mfma_f32_16x16x32_bf16 v[84:87], v[172:175], v[204:207], v[84:87]
	v_mfma_f32_16x16x32_bf16 v[80:83], v[180:183], v[204:207], v[80:83]
	v_mfma_f32_16x16x32_bf16 v[68:71], v[172:175], v[212:215], v[68:71]
	v_mfma_f32_16x16x32_bf16 v[64:67], v[180:183], v[212:215], v[64:67]
	v_mfma_f32_16x16x32_bf16 v[116:119], v[176:179], v[192:195], v[116:119]
	v_mfma_f32_16x16x32_bf16 v[112:115], v[184:187], v[192:195], v[112:115]
	v_mfma_f32_16x16x32_bf16 v[100:103], v[176:179], v[200:203], v[100:103]
	v_mfma_f32_16x16x32_bf16 v[96:99], v[184:187], v[200:203], v[96:99]
	v_mfma_f32_16x16x32_bf16 v[84:87], v[176:179], v[208:211], v[84:87]
	v_mfma_f32_16x16x32_bf16 v[80:83], v[184:187], v[208:211], v[80:83]
	v_mfma_f32_16x16x32_bf16 v[68:71], v[176:179], v[216:219], v[68:71]
	v_mfma_f32_16x16x32_bf16 v[64:67], v[184:187], v[216:219], v[64:67]
	s_setprio 0
	s_barrier
	s_add_i32 s34, s65, s41
	v_lshl_add_u64 v[220:221], v[220:221], 0, s[22:23]
	s_mov_b32 m0, s34
	ds_read_b128 v[188:191], v157 offset:49152
	ds_read_b128 v[192:195], v157 offset:50176
	ds_read_b128 v[196:199], v157 offset:51200
	ds_read_b128 v[200:203], v157 offset:52224
	ds_read_b128 v[204:207], v157 offset:53248
	ds_read_b128 v[208:211], v157 offset:54272
	ds_read_b128 v[212:215], v157 offset:55296
	ds_read_b128 v[216:219], v157 offset:56320
	global_load_lds_dwordx4 v[220:221], off
	s_add_i32 m0, s34, 0x2000
	s_add_u32 s34, s36, 0xb0080
	v_lshl_add_u64 v[220:221], v[222:223], 0, s[22:23]
	s_addc_u32 s35, s37, 0
	s_add_i32 s36, s66, s41
	global_load_lds_dwordx4 v[220:221], off
	v_lshl_add_u64 v[220:221], s[34:35], 0, v[134:135]
	s_mov_b32 m0, s36
	s_nop 0
	global_load_lds_dwordx4 v[220:221], off
	v_lshl_add_u64 v[220:221], s[34:35], 0, v[138:139]
	s_add_i32 m0, s36, 0x2000
	s_nop 0
	global_load_lds_dwordx4 v[220:221], off
	v_lshl_add_u64 v[220:221], v[224:225], 0, s[22:23]
	s_mov_b32 m0, s51
	s_nop 0
	global_load_lds_dwordx4 v[220:221], off
	v_lshl_add_u64 v[220:221], v[226:227], 0, s[22:23]
	s_mov_b32 m0, s52
	s_nop 0
	global_load_lds_dwordx4 v[220:221], off
	s_waitcnt vmcnt(8)
	s_waitcnt lgkmcnt(0)
	s_barrier
	s_setprio 1
	s_waitcnt lgkmcnt(0)
	v_mfma_f32_16x16x32_bf16 v[60:63], v[148:151], v[188:191], v[60:63]
	v_mfma_f32_16x16x32_bf16 v[56:59], v[164:167], v[188:191], v[56:59]
	v_mfma_f32_16x16x32_bf16 v[44:47], v[148:151], v[196:199], v[44:47]
	v_mfma_f32_16x16x32_bf16 v[40:43], v[164:167], v[196:199], v[40:43]
	v_mfma_f32_16x16x32_bf16 v[28:31], v[148:151], v[204:207], v[28:31]
	v_mfma_f32_16x16x32_bf16 v[24:27], v[164:167], v[204:207], v[24:27]
	v_mfma_f32_16x16x32_bf16 v[12:15], v[148:151], v[212:215], v[12:15]
	v_mfma_f32_16x16x32_bf16 v[8:11], v[164:167], v[212:215], v[8:11]
	v_mfma_f32_16x16x32_bf16 v[60:63], v[160:163], v[192:195], v[60:63]
	v_mfma_f32_16x16x32_bf16 v[56:59], v[168:171], v[192:195], v[56:59]
	v_mfma_f32_16x16x32_bf16 v[44:47], v[160:163], v[200:203], v[44:47]
	v_mfma_f32_16x16x32_bf16 v[40:43], v[168:171], v[200:203], v[40:43]
	v_mfma_f32_16x16x32_bf16 v[28:31], v[160:163], v[208:211], v[28:31]
	v_mfma_f32_16x16x32_bf16 v[24:27], v[168:171], v[208:211], v[24:27]
	v_mfma_f32_16x16x32_bf16 v[12:15], v[160:163], v[216:219], v[12:15]
	v_mfma_f32_16x16x32_bf16 v[8:11], v[168:171], v[216:219], v[8:11]
	s_setprio 0
	s_setprio 1
	v_mfma_f32_16x16x32_bf16 v[52:55], v[172:175], v[188:191], v[52:55]
	v_mfma_f32_16x16x32_bf16 v[48:51], v[180:183], v[188:191], v[48:51]
	v_mfma_f32_16x16x32_bf16 v[36:39], v[172:175], v[196:199], v[36:39]
	v_mfma_f32_16x16x32_bf16 v[32:35], v[180:183], v[196:199], v[32:35]
	v_mfma_f32_16x16x32_bf16 v[20:23], v[172:175], v[204:207], v[20:23]
	v_mfma_f32_16x16x32_bf16 v[16:19], v[180:183], v[204:207], v[16:19]
	v_mfma_f32_16x16x32_bf16 v[4:7], v[172:175], v[212:215], v[4:7]
	v_mfma_f32_16x16x32_bf16 v[0:3], v[180:183], v[212:215], v[0:3]
	v_mfma_f32_16x16x32_bf16 v[52:55], v[176:179], v[192:195], v[52:55]
	v_mfma_f32_16x16x32_bf16 v[48:51], v[184:187], v[192:195], v[48:51]
	v_mfma_f32_16x16x32_bf16 v[36:39], v[176:179], v[200:203], v[36:39]
	v_mfma_f32_16x16x32_bf16 v[32:35], v[184:187], v[200:203], v[32:35]
	v_mfma_f32_16x16x32_bf16 v[20:23], v[176:179], v[208:211], v[20:23]
	v_mfma_f32_16x16x32_bf16 v[16:19], v[184:187], v[208:211], v[16:19]
	v_mfma_f32_16x16x32_bf16 v[4:7], v[176:179], v[216:219], v[4:7]
	v_mfma_f32_16x16x32_bf16 v[0:3], v[184:187], v[216:219], v[0:3]
	s_setprio 0
	s_barrier
	s_add_i32 s64, s64, 2
	s_add_u32 s30, s30, 0x100
	s_addc_u32 s31, s31, 0
	s_add_u32 s13, s13, 0x100
	s_addc_u32 s63, s63, 0

.LBB0_1232:
	s_add_i32 s58, s58, 1
	s_mul_i32 s4, s58, s42
	s_mul_hi_u32 s5, s58, s43
	s_add_i32 s5, s5, s4
	s_mul_i32 s4, s58, s43
	s_add_u32 s26, s4, s2
	s_addc_u32 s27, s5, s3
	v_cmp_gt_i64_e32 vcc, s[26:27], v[146:147]
	v_cmp_lt_i64_e64 s[4:5], s[26:27], v[144:145]
	s_cbranch_vccnz .LBB0_1234
	s_and_b32 s100, s26, 7
	s_mul_i32 s100, s100, 0xc0
	s_lshr_b32 s101, s26, 3
	s_add_i32 s100, s100, s101
	s_mul_hi_u32 s101, s100, 0x2aaaaab
	s_mul_i32 s10, s101, 0x60
	s_sub_i32 s10, s100, s10
	s_and_b32 s100, s10, 7
	s_lshl_b32 s22, s101, 3
	s_add_i32 s22, s22, s100
	s_lshr_b32 s10, s10, 3
	s_mov_b32 s59, s58
.LBB0_1234:
	s_ashr_i32 s23, s22, 31
	s_lshl_b64 s[26:27], s[22:23], 19
	s_add_u32 s26, s14, s26
	s_addc_u32 s27, s15, s27
	s_and_b64 s[28:29], s[4:5], exec
	s_cselect_b32 s23, s27, s37
	s_cselect_b32 s64, s26, s36
	s_ashr_i32 s11, s10, 31
	s_lshl_b64 s[28:29], s[10:11], 19
	s_add_u32 s28, s49, s28
	s_addc_u32 s29, s50, s29
	s_and_b64 s[34:35], s[4:5], exec
	s_cselect_b32 s11, s29, s39
	s_cselect_b32 s65, s28, s38
	s_add_u32 s36, s36, 0x40080
	s_addc_u32 s37, s37, 0
	s_add_u32 s66, s38, 0x100
	s_addc_u32 s67, s39, 0
	s_mov_b32 s77, -2
	ds_read_b128 v[148:151], v155
	ds_read_b128 v[160:163], v155 offset:1024
	ds_read_b128 v[164:167], v155 offset:2048
	ds_read_b128 v[168:171], v155 offset:3072
	ds_read_b128 v[172:175], v157
	ds_read_b128 v[176:179], v157 offset:1024
	ds_read_b128 v[180:183], v157 offset:2048
	ds_read_b128 v[184:187], v157 offset:3072
	s_add_u32 s34, s36, 0xfffc0080
	s_addc_u32 s35, s37, -1
	s_cmp_eq_u32 s77, 12
	s_cselect_b32 s41, s23, s35
	s_cselect_b32 s40, s64, s34
	s_cselect_b32 s39, s11, s67
	s_cselect_b32 s38, s65, s66
	v_lshl_add_u64 v[220:221], s[36:37], 0, v[140:141]
	s_add_i32 m0, s31, 0xc000
	ds_read_b128 v[188:191], v158
	ds_read_b128 v[192:195], v158 offset:1024
	ds_read_b128 v[196:199], v158 offset:2048
	ds_read_b128 v[200:203], v158 offset:3072
	ds_read_b128 v[204:207], v158 offset:4096
	ds_read_b128 v[208:211], v158 offset:5120
	ds_read_b128 v[212:215], v158 offset:6144
	ds_read_b128 v[216:219], v158 offset:7168
	global_load_lds_dwordx4 v[220:221], off
	v_lshl_add_u64 v[220:221], s[36:37], 0, v[142:143]
	s_add_i32 m0, s31, 0xe000
	s_nop 0
	global_load_lds_dwordx4 v[220:221], off
	s_waitcnt vmcnt(8)
	s_waitcnt lgkmcnt(0)
	s_barrier
	s_setprio 1
	s_waitcnt lgkmcnt(0)
	v_mfma_f32_16x16x32_bf16 v[124:127], v[148:151], v[188:191], 0
	v_mfma_f32_16x16x32_bf16 v[120:123], v[164:167], v[188:191], 0
	v_mfma_f32_16x16x32_bf16 v[108:111], v[148:151], v[196:199], 0
	v_mfma_f32_16x16x32_bf16 v[104:107], v[164:167], v[196:199], 0
	v_mfma_f32_16x16x32_bf16 v[92:95], v[148:151], v[204:207], 0
	v_mfma_f32_16x16x32_bf16 v[88:91], v[164:167], v[204:207], 0
	v_mfma_f32_16x16x32_bf16 v[76:79], v[148:151], v[212:215], 0
	v_mfma_f32_16x16x32_bf16 v[72:75], v[164:167], v[212:215], 0
	v_mfma_f32_16x16x32_bf16 v[124:127], v[160:163], v[192:195], v[124:127]
	v_mfma_f32_16x16x32_bf16 v[120:123], v[168:171], v[192:195], v[120:123]
	v_mfma_f32_16x16x32_bf16 v[108:111], v[160:163], v[200:203], v[108:111]
	v_mfma_f32_16x16x32_bf16 v[104:107], v[168:171], v[200:203], v[104:107]
	v_mfma_f32_16x16x32_bf16 v[92:95], v[160:163], v[208:211], v[92:95]
	v_mfma_f32_16x16x32_bf16 v[88:91], v[168:171], v[208:211], v[88:91]
	v_mfma_f32_16x16x32_bf16 v[76:79], v[160:163], v[216:219], v[76:79]
	v_mfma_f32_16x16x32_bf16 v[72:75], v[168:171], v[216:219], v[72:75]
	s_setprio 0
	s_setprio 1
	v_mfma_f32_16x16x32_bf16 v[116:119], v[172:175], v[188:191], 0
	v_mfma_f32_16x16x32_bf16 v[112:115], v[180:183], v[188:191], 0
	v_mfma_f32_16x16x32_bf16 v[100:103], v[172:175], v[196:199], 0
	v_mfma_f32_16x16x32_bf16 v[96:99], v[180:183], v[196:199], 0
	v_mfma_f32_16x16x32_bf16 v[84:87], v[172:175], v[204:207], 0
	v_mfma_f32_16x16x32_bf16 v[80:83], v[180:183], v[204:207], 0
	v_mfma_f32_16x16x32_bf16 v[68:71], v[172:175], v[212:215], 0
	v_mfma_f32_16x16x32_bf16 v[64:67], v[180:183], v[212:215], 0
	v_mfma_f32_16x16x32_bf16 v[116:119], v[176:179], v[192:195], v[116:119]
	v_mfma_f32_16x16x32_bf16 v[112:115], v[184:187], v[192:195], v[112:115]
	v_mfma_f32_16x16x32_bf16 v[100:103], v[176:179], v[200:203], v[100:103]
	v_mfma_f32_16x16x32_bf16 v[96:99], v[184:187], v[200:203], v[96:99]
	v_mfma_f32_16x16x32_bf16 v[84:87], v[176:179], v[208:211], v[84:87]
	v_mfma_f32_16x16x32_bf16 v[80:83], v[184:187], v[208:211], v[80:83]
	v_mfma_f32_16x16x32_bf16 v[68:71], v[176:179], v[216:219], v[68:71]
	v_mfma_f32_16x16x32_bf16 v[64:67], v[184:187], v[216:219], v[64:67]
	s_setprio 0
	s_barrier
	s_add_i32 s34, s55, s48
	v_lshl_add_u64 v[220:221], s[38:39], 0, v[136:137]
	s_mov_b32 m0, s34
	ds_read_b128 v[188:191], v158 offset:16384
	ds_read_b128 v[192:195], v158 offset:17408
	ds_read_b128 v[196:199], v158 offset:18432
	ds_read_b128 v[200:203], v158 offset:19456
	ds_read_b128 v[204:207], v158 offset:20480
	ds_read_b128 v[208:211], v158 offset:21504
	ds_read_b128 v[212:215], v158 offset:22528
	ds_read_b128 v[216:219], v158 offset:23552
	global_load_lds_dwordx4 v[220:221], off
	s_add_i32 m0, s34, 0x2000
	s_add_u32 s34, s38, 0x40000
	v_lshl_add_u64 v[222:223], s[38:39], 0, v[132:133]
	s_addc_u32 s35, s39, 0
	s_add_i32 s79, s56, s48
	global_load_lds_dwordx4 v[222:223], off
	v_lshl_add_u64 v[224:225], s[34:35], 0, v[136:137]
	s_mov_b32 m0, s79
	v_lshl_add_u64 v[226:227], s[40:41], 0, v[134:135]
	global_load_lds_dwordx4 v[224:225], off
	v_lshl_add_u64 v[224:225], s[34:35], 0, v[132:133]
	s_add_i32 m0, s79, 0x2000
	s_nop 0
	global_load_lds_dwordx4 v[224:225], off
	v_lshl_add_u64 v[224:225], s[40:41], 0, v[138:139]
	s_mov_b32 m0, s31
	s_nop 0
	global_load_lds_dwordx4 v[224:225], off
	s_mov_b32 m0, s52
	s_nop 0
	global_load_lds_dwordx4 v[226:227], off
	s_waitcnt vmcnt(8)
	s_waitcnt lgkmcnt(0)
	s_barrier
	s_setprio 1
	s_waitcnt lgkmcnt(0)
	v_mfma_f32_16x16x32_bf16 v[60:63], v[148:151], v[188:191], 0
	v_mfma_f32_16x16x32_bf16 v[56:59], v[164:167], v[188:191], 0
	v_mfma_f32_16x16x32_bf16 v[44:47], v[148:151], v[196:199], 0
	v_mfma_f32_16x16x32_bf16 v[40:43], v[164:167], v[196:199], 0
	v_mfma_f32_16x16x32_bf16 v[28:31], v[148:151], v[204:207], 0
	v_mfma_f32_16x16x32_bf16 v[24:27], v[164:167], v[204:207], 0
	v_mfma_f32_16x16x32_bf16 v[12:15], v[148:151], v[212:215], 0
	v_mfma_f32_16x16x32_bf16 v[8:11], v[164:167], v[212:215], 0
	v_mfma_f32_16x16x32_bf16 v[60:63], v[160:163], v[192:195], v[60:63]
	v_mfma_f32_16x16x32_bf16 v[56:59], v[168:171], v[192:195], v[56:59]
	v_mfma_f32_16x16x32_bf16 v[44:47], v[160:163], v[200:203], v[44:47]
	v_mfma_f32_16x16x32_bf16 v[40:43], v[168:171], v[200:203], v[40:43]
	v_mfma_f32_16x16x32_bf16 v[28:31], v[160:163], v[208:211], v[28:31]
	v_mfma_f32_16x16x32_bf16 v[24:27], v[168:171], v[208:211], v[24:27]
	v_mfma_f32_16x16x32_bf16 v[12:15], v[160:163], v[216:219], v[12:15]
	v_mfma_f32_16x16x32_bf16 v[8:11], v[168:171], v[216:219], v[8:11]
	s_setprio 0
	s_setprio 1
	v_mfma_f32_16x16x32_bf16 v[52:55], v[172:175], v[188:191], 0
	v_mfma_f32_16x16x32_bf16 v[48:51], v[180:183], v[188:191], 0
	v_mfma_f32_16x16x32_bf16 v[36:39], v[172:175], v[196:199], 0
	v_mfma_f32_16x16x32_bf16 v[32:35], v[180:183], v[196:199], 0
	v_mfma_f32_16x16x32_bf16 v[20:23], v[172:175], v[204:207], 0
	v_mfma_f32_16x16x32_bf16 v[16:19], v[180:183], v[204:207], 0
	v_mfma_f32_16x16x32_bf16 v[4:7], v[172:175], v[212:215], 0
	v_mfma_f32_16x16x32_bf16 v[0:3], v[180:183], v[212:215], 0
	v_mfma_f32_16x16x32_bf16 v[52:55], v[176:179], v[192:195], v[52:55]
	v_mfma_f32_16x16x32_bf16 v[48:51], v[184:187], v[192:195], v[48:51]
	v_mfma_f32_16x16x32_bf16 v[36:39], v[176:179], v[200:203], v[36:39]
	v_mfma_f32_16x16x32_bf16 v[32:35], v[184:187], v[200:203], v[32:35]
	v_mfma_f32_16x16x32_bf16 v[20:23], v[176:179], v[208:211], v[20:23]
	v_mfma_f32_16x16x32_bf16 v[16:19], v[184:187], v[208:211], v[16:19]
	v_mfma_f32_16x16x32_bf16 v[4:7], v[176:179], v[216:219], v[4:7]
	v_mfma_f32_16x16x32_bf16 v[0:3], v[184:187], v[216:219], v[0:3]
	s_setprio 0
	s_barrier
	s_add_i32 s79, 0, 0x18000
	v_add_u32_e32 v159, s79, v152
	s_add_i32 s81, 0, 0x1c000
	ds_read_b128 v[148:151], v159
	ds_read_b128 v[160:163], v159 offset:1024
	ds_read_b128 v[164:167], v159 offset:2048
	ds_read_b128 v[168:171], v159 offset:3072
	v_add_u32_e32 v159, s81, v152
	ds_read_b128 v[172:175], v159
	ds_read_b128 v[176:179], v159 offset:1024
	ds_read_b128 v[180:183], v159 offset:2048
	ds_read_b128 v[184:187], v159 offset:3072
	s_add_u32 s34, s40, 0x40000
	s_addc_u32 s35, s41, 0
	s_mov_b32 m0, s53
	v_lshl_add_u64 v[228:229], s[34:35], 0, v[138:139]
	ds_read_b128 v[188:191], v158 offset:32768
	ds_read_b128 v[192:195], v158 offset:33792
	ds_read_b128 v[196:199], v158 offset:34816
	ds_read_b128 v[200:203], v158 offset:35840
	ds_read_b128 v[204:207], v158 offset:36864
	ds_read_b128 v[208:211], v158 offset:37888
	ds_read_b128 v[212:215], v158 offset:38912
	ds_read_b128 v[216:219], v158 offset:39936
	global_load_lds_dwordx4 v[228:229], off
	v_lshl_add_u64 v[228:229], s[34:35], 0, v[134:135]
	s_mov_b32 m0, s54
	s_nop 0
	global_load_lds_dwordx4 v[228:229], off
	s_waitcnt vmcnt(8)
	s_waitcnt lgkmcnt(0)
	s_barrier
	s_setprio 1
	s_waitcnt lgkmcnt(0)
	v_mfma_f32_16x16x32_bf16 v[124:127], v[148:151], v[188:191], v[124:127]
	v_mfma_f32_16x16x32_bf16 v[120:123], v[164:167], v[188:191], v[120:123]
	v_mfma_f32_16x16x32_bf16 v[108:111], v[148:151], v[196:199], v[108:111]
	v_mfma_f32_16x16x32_bf16 v[104:107], v[164:167], v[196:199], v[104:107]
	v_mfma_f32_16x16x32_bf16 v[92:95], v[148:151], v[204:207], v[92:95]
	v_mfma_f32_16x16x32_bf16 v[88:91], v[164:167], v[204:207], v[88:91]
	v_mfma_f32_16x16x32_bf16 v[76:79], v[148:151], v[212:215], v[76:79]
	v_mfma_f32_16x16x32_bf16 v[72:75], v[164:167], v[212:215], v[72:75]
	v_mfma_f32_16x16x32_bf16 v[124:127], v[160:163], v[192:195], v[124:127]
	v_mfma_f32_16x16x32_bf16 v[120:123], v[168:171], v[192:195], v[120:123]
	v_mfma_f32_16x16x32_bf16 v[108:111], v[160:163], v[200:203], v[108:111]
	v_mfma_f32_16x16x32_bf16 v[104:107], v[168:171], v[200:203], v[104:107]
	v_mfma_f32_16x16x32_bf16 v[92:95], v[160:163], v[208:211], v[92:95]
	v_mfma_f32_16x16x32_bf16 v[88:91], v[168:171], v[208:211], v[88:91]
	v_mfma_f32_16x16x32_bf16 v[76:79], v[160:163], v[216:219], v[76:79]
	v_mfma_f32_16x16x32_bf16 v[72:75], v[168:171], v[216:219], v[72:75]
	s_setprio 0
	s_setprio 1
	v_mfma_f32_16x16x32_bf16 v[116:119], v[172:175], v[188:191], v[116:119]
	v_mfma_f32_16x16x32_bf16 v[112:115], v[180:183], v[188:191], v[112:115]
	v_mfma_f32_16x16x32_bf16 v[100:103], v[172:175], v[196:199], v[100:103]
	v_mfma_f32_16x16x32_bf16 v[96:99], v[180:183], v[196:199], v[96:99]
	v_mfma_f32_16x16x32_bf16 v[84:87], v[172:175], v[204:207], v[84:87]
	v_mfma_f32_16x16x32_bf16 v[80:83], v[180:183], v[204:207], v[80:83]
	v_mfma_f32_16x16x32_bf16 v[68:71], v[172:175], v[212:215], v[68:71]
	v_mfma_f32_16x16x32_bf16 v[64:67], v[180:183], v[212:215], v[64:67]
	v_mfma_f32_16x16x32_bf16 v[116:119], v[176:179], v[192:195], v[116:119]
	v_mfma_f32_16x16x32_bf16 v[112:115], v[184:187], v[192:195], v[112:115]
	v_mfma_f32_16x16x32_bf16 v[100:103], v[176:179], v[200:203], v[100:103]
	v_mfma_f32_16x16x32_bf16 v[96:99], v[184:187], v[200:203], v[96:99]
	v_mfma_f32_16x16x32_bf16 v[84:87], v[176:179], v[208:211], v[84:87]
	v_mfma_f32_16x16x32_bf16 v[80:83], v[184:187], v[208:211], v[80:83]
	v_mfma_f32_16x16x32_bf16 v[68:71], v[176:179], v[216:219], v[68:71]
	v_mfma_f32_16x16x32_bf16 v[64:67], v[184:187], v[216:219], v[64:67]
	s_setprio 0
	s_barrier
	s_add_i32 s34, s79, s48
	v_lshl_add_u64 v[220:221], v[220:221], 0, s[6:7]
	s_mov_b32 m0, s34
	ds_read_b128 v[188:191], v158 offset:49152
	ds_read_b128 v[192:195], v158 offset:50176
	ds_read_b128 v[196:199], v158 offset:51200
	ds_read_b128 v[200:203], v158 offset:52224
	ds_read_b128 v[204:207], v158 offset:53248
	ds_read_b128 v[208:211], v158 offset:54272
	ds_read_b128 v[212:215], v158 offset:55296
	ds_read_b128 v[216:219], v158 offset:56320
	global_load_lds_dwordx4 v[220:221], off
	s_add_i32 m0, s34, 0x2000
	s_add_u32 s34, s38, 0x40080
	v_lshl_add_u64 v[220:221], v[222:223], 0, s[6:7]
	s_addc_u32 s35, s39, 0
	s_add_i32 s38, s81, s48
	global_load_lds_dwordx4 v[220:221], off
	v_lshl_add_u64 v[220:221], s[34:35], 0, v[136:137]
	s_mov_b32 m0, s38
	s_nop 0
	global_load_lds_dwordx4 v[220:221], off
	v_lshl_add_u64 v[220:221], s[34:35], 0, v[132:133]
	s_add_i32 m0, s38, 0x2000
	s_nop 0
	global_load_lds_dwordx4 v[220:221], off
	v_lshl_add_u64 v[220:221], v[224:225], 0, s[6:7]
	s_mov_b32 m0, s12
	s_nop 0
	global_load_lds_dwordx4 v[220:221], off
	v_lshl_add_u64 v[220:221], v[226:227], 0, s[6:7]
	s_mov_b32 m0, s13
	s_nop 0
	global_load_lds_dwordx4 v[220:221], off
	s_waitcnt vmcnt(8)
	s_waitcnt lgkmcnt(0)
	s_barrier
	s_setprio 1
	s_waitcnt lgkmcnt(0)
	v_mfma_f32_16x16x32_bf16 v[60:63], v[148:151], v[188:191], v[60:63]
	v_mfma_f32_16x16x32_bf16 v[56:59], v[164:167], v[188:191], v[56:59]
	v_mfma_f32_16x16x32_bf16 v[44:47], v[148:151], v[196:199], v[44:47]
	v_mfma_f32_16x16x32_bf16 v[40:43], v[164:167], v[196:199], v[40:43]
	v_mfma_f32_16x16x32_bf16 v[28:31], v[148:151], v[204:207], v[28:31]
	v_mfma_f32_16x16x32_bf16 v[24:27], v[164:167], v[204:207], v[24:27]
	v_mfma_f32_16x16x32_bf16 v[12:15], v[148:151], v[212:215], v[12:15]
	v_mfma_f32_16x16x32_bf16 v[8:11], v[164:167], v[212:215], v[8:11]
	v_mfma_f32_16x16x32_bf16 v[60:63], v[160:163], v[192:195], v[60:63]
	v_mfma_f32_16x16x32_bf16 v[56:59], v[168:171], v[192:195], v[56:59]
	v_mfma_f32_16x16x32_bf16 v[44:47], v[160:163], v[200:203], v[44:47]
	v_mfma_f32_16x16x32_bf16 v[40:43], v[168:171], v[200:203], v[40:43]
	v_mfma_f32_16x16x32_bf16 v[28:31], v[160:163], v[208:211], v[28:31]
	v_mfma_f32_16x16x32_bf16 v[24:27], v[168:171], v[208:211], v[24:27]
	v_mfma_f32_16x16x32_bf16 v[12:15], v[160:163], v[216:219], v[12:15]
	v_mfma_f32_16x16x32_bf16 v[8:11], v[168:171], v[216:219], v[8:11]
	s_setprio 0
	s_setprio 1
	v_mfma_f32_16x16x32_bf16 v[52:55], v[172:175], v[188:191], v[52:55]
	v_mfma_f32_16x16x32_bf16 v[48:51], v[180:183], v[188:191], v[48:51]
	v_mfma_f32_16x16x32_bf16 v[36:39], v[172:175], v[196:199], v[36:39]
	v_mfma_f32_16x16x32_bf16 v[32:35], v[180:183], v[196:199], v[32:35]
	v_mfma_f32_16x16x32_bf16 v[20:23], v[172:175], v[204:207], v[20:23]
	v_mfma_f32_16x16x32_bf16 v[16:19], v[180:183], v[204:207], v[16:19]
	v_mfma_f32_16x16x32_bf16 v[4:7], v[172:175], v[212:215], v[4:7]
	v_mfma_f32_16x16x32_bf16 v[0:3], v[180:183], v[212:215], v[0:3]
	v_mfma_f32_16x16x32_bf16 v[52:55], v[176:179], v[192:195], v[52:55]
	v_mfma_f32_16x16x32_bf16 v[48:51], v[184:187], v[192:195], v[48:51]
	v_mfma_f32_16x16x32_bf16 v[36:39], v[176:179], v[200:203], v[36:39]
	v_mfma_f32_16x16x32_bf16 v[32:35], v[184:187], v[200:203], v[32:35]
	v_mfma_f32_16x16x32_bf16 v[20:23], v[176:179], v[208:211], v[20:23]
	v_mfma_f32_16x16x32_bf16 v[16:19], v[184:187], v[208:211], v[16:19]
	v_mfma_f32_16x16x32_bf16 v[4:7], v[176:179], v[216:219], v[4:7]
	v_mfma_f32_16x16x32_bf16 v[0:3], v[184:187], v[216:219], v[0:3]
	s_setprio 0
	s_barrier
	s_add_i32 s77, s77, 2
	s_add_u32 s36, s36, 0x100
	s_addc_u32 s37, s37, 0
	s_add_u32 s66, s66, 0x100
	s_addc_u32 s67, s67, 0

.LBB0_1550:
	s_add_i32 s60, s60, 1
	s_mul_i32 s6, s60, s55
	s_mul_hi_u32 s7, s60, s56
	s_add_i32 s7, s7, s6
	s_mul_i32 s6, s60, s56
	s_add_u32 s30, s6, s2
	s_addc_u32 s31, s7, s57
	v_cmp_gt_i64_e32 vcc, s[30:31], v[144:145]
	v_cmp_lt_i64_e64 s[6:7], s[30:31], v[142:143]
	s_cbranch_vccnz .LBB0_1556
	s_and_b32 s100, s30, 7
	s_mul_i32 s100, s100, 0x40
	s_lshr_b32 s101, s30, 3
	s_add_i32 s100, s100, s101
	s_mul_hi_u32 s101, s100, 0x8000000
	s_mul_i32 s26, s101, 0x20
	s_sub_i32 s26, s100, s26
	s_and_b32 s100, s26, 7
	s_lshl_b32 s28, s101, 3
	s_add_i32 s28, s28, s100
	s_lshr_b32 s26, s26, 3
.LBB0_1556:
	s_ashr_i32 s29, s28, 31
	s_lshl_b64 s[12:13], s[28:29], 19
	s_add_u32 s30, s20, s12
	s_addc_u32 s31, s21, s13
	s_and_b64 s[12:13], s[6:7], exec
	s_cselect_b32 s12, s31, s41
	s_cselect_b32 s13, s30, s40
	s_ashr_i32 s27, s26, 31
	s_lshl_b64 s[34:35], s[26:27], 19
	s_add_u32 s36, s3, s34
	s_addc_u32 s37, s46, s35
	s_and_b64 s[34:35], s[6:7], exec
	s_cselect_b32 s27, s37, s43
	s_cselect_b32 s29, s36, s42
	s_add_u32 s40, s40, 0x40080
	s_addc_u32 s41, s41, 0
	s_add_u32 s39, s42, 0x100
	s_addc_u32 s61, s43, 0
	s_mov_b32 s62, -2
	s_waitcnt lgkmcnt(0)
	ds_read_b128 v[146:149], v153
	ds_read_b128 v[158:161], v153 offset:1024
	ds_read_b128 v[162:165], v153 offset:2048
	ds_read_b128 v[166:169], v153 offset:3072
	ds_read_b128 v[170:173], v154
	ds_read_b128 v[174:177], v154 offset:1024
	ds_read_b128 v[178:181], v154 offset:2048
	ds_read_b128 v[182:185], v154 offset:3072
	s_add_u32 s34, s40, 0xfffc0080
	s_addc_u32 s35, s41, -1
	s_cmp_eq_u32 s62, 12
	s_cselect_b32 s45, s12, s35
	s_cselect_b32 s44, s13, s34
	s_cselect_b32 s43, s27, s61
	s_cselect_b32 s42, s29, s39
	v_lshl_add_u64 v[218:219], s[40:41], 0, v[138:139]
	s_add_i32 m0, s48, 0xc000
	ds_read_b128 v[186:189], v155
	ds_read_b128 v[190:193], v155 offset:1024
	ds_read_b128 v[194:197], v155 offset:2048
	ds_read_b128 v[198:201], v155 offset:3072
	ds_read_b128 v[202:205], v155 offset:4096
	ds_read_b128 v[206:209], v155 offset:5120
	ds_read_b128 v[210:213], v155 offset:6144
	ds_read_b128 v[214:217], v155 offset:7168
	global_load_lds_dwordx4 v[218:219], off
	v_lshl_add_u64 v[218:219], s[40:41], 0, v[140:141]
	s_add_i32 m0, s48, 0xe000
	s_nop 0
	global_load_lds_dwordx4 v[218:219], off
	s_waitcnt vmcnt(8)
	s_waitcnt lgkmcnt(0)
	s_barrier
	s_setprio 1
	s_waitcnt lgkmcnt(0)
	v_mfma_f32_16x16x32_bf16 v[124:127], v[146:149], v[186:189], 0
	v_mfma_f32_16x16x32_bf16 v[120:123], v[162:165], v[186:189], 0
	v_mfma_f32_16x16x32_bf16 v[108:111], v[146:149], v[194:197], 0
	v_mfma_f32_16x16x32_bf16 v[104:107], v[162:165], v[194:197], 0
	v_mfma_f32_16x16x32_bf16 v[92:95], v[146:149], v[202:205], 0
	v_mfma_f32_16x16x32_bf16 v[88:91], v[162:165], v[202:205], 0
	v_mfma_f32_16x16x32_bf16 v[76:79], v[146:149], v[210:213], 0
	v_mfma_f32_16x16x32_bf16 v[72:75], v[162:165], v[210:213], 0
	v_mfma_f32_16x16x32_bf16 v[124:127], v[158:161], v[190:193], v[124:127]
	v_mfma_f32_16x16x32_bf16 v[120:123], v[166:169], v[190:193], v[120:123]
	v_mfma_f32_16x16x32_bf16 v[108:111], v[158:161], v[198:201], v[108:111]
	v_mfma_f32_16x16x32_bf16 v[104:107], v[166:169], v[198:201], v[104:107]
	v_mfma_f32_16x16x32_bf16 v[92:95], v[158:161], v[206:209], v[92:95]
	v_mfma_f32_16x16x32_bf16 v[88:91], v[166:169], v[206:209], v[88:91]
	v_mfma_f32_16x16x32_bf16 v[76:79], v[158:161], v[214:217], v[76:79]
	v_mfma_f32_16x16x32_bf16 v[72:75], v[166:169], v[214:217], v[72:75]
	s_setprio 0
	s_setprio 1
	v_mfma_f32_16x16x32_bf16 v[116:119], v[170:173], v[186:189], 0
	v_mfma_f32_16x16x32_bf16 v[112:115], v[178:181], v[186:189], 0
	v_mfma_f32_16x16x32_bf16 v[100:103], v[170:173], v[194:197], 0
	v_mfma_f32_16x16x32_bf16 v[96:99], v[178:181], v[194:197], 0
	v_mfma_f32_16x16x32_bf16 v[84:87], v[170:173], v[202:205], 0
	v_mfma_f32_16x16x32_bf16 v[80:83], v[178:181], v[202:205], 0
	v_mfma_f32_16x16x32_bf16 v[68:71], v[170:173], v[210:213], 0
	v_mfma_f32_16x16x32_bf16 v[64:67], v[178:181], v[210:213], 0
	v_mfma_f32_16x16x32_bf16 v[116:119], v[174:177], v[190:193], v[116:119]
	v_mfma_f32_16x16x32_bf16 v[112:115], v[182:185], v[190:193], v[112:115]
	v_mfma_f32_16x16x32_bf16 v[100:103], v[174:177], v[198:201], v[100:103]
	v_mfma_f32_16x16x32_bf16 v[96:99], v[182:185], v[198:201], v[96:99]
	v_mfma_f32_16x16x32_bf16 v[84:87], v[174:177], v[206:209], v[84:87]
	v_mfma_f32_16x16x32_bf16 v[80:83], v[182:185], v[206:209], v[80:83]
	v_mfma_f32_16x16x32_bf16 v[68:71], v[174:177], v[214:217], v[68:71]
	v_mfma_f32_16x16x32_bf16 v[64:67], v[182:185], v[214:217], v[64:67]
	s_setprio 0
	s_barrier
	s_add_i32 s34, s58, s47
	v_lshl_add_u64 v[218:219], s[42:43], 0, v[132:133]
	s_mov_b32 m0, s34
	ds_read_b128 v[186:189], v155 offset:16384
	ds_read_b128 v[190:193], v155 offset:17408
	ds_read_b128 v[194:197], v155 offset:18432
	ds_read_b128 v[198:201], v155 offset:19456
	ds_read_b128 v[202:205], v155 offset:20480
	ds_read_b128 v[206:209], v155 offset:21504
	ds_read_b128 v[210:213], v155 offset:22528
	ds_read_b128 v[214:217], v155 offset:23552
	global_load_lds_dwordx4 v[218:219], off
	s_add_i32 m0, s34, 0x2000
	s_add_u32 s34, s42, 0x40000
	v_lshl_add_u64 v[220:221], s[42:43], 0, v[136:137]
	s_addc_u32 s35, s43, 0
	s_add_i32 s63, s59, s47
	global_load_lds_dwordx4 v[220:221], off
	v_lshl_add_u64 v[222:223], s[34:35], 0, v[132:133]
	s_mov_b32 m0, s63
	v_lshl_add_u64 v[224:225], s[44:45], 0, v[134:135]
	global_load_lds_dwordx4 v[222:223], off
	v_lshl_add_u64 v[222:223], s[34:35], 0, v[136:137]
	s_add_i32 m0, s63, 0x2000
	s_nop 0
	global_load_lds_dwordx4 v[222:223], off
	v_lshl_add_u64 v[222:223], s[44:45], 0, v[130:131]
	s_mov_b32 m0, s48
	s_nop 0
	global_load_lds_dwordx4 v[222:223], off
	s_mov_b32 m0, s49
	s_nop 0
	global_load_lds_dwordx4 v[224:225], off
	s_waitcnt vmcnt(8)
	s_waitcnt lgkmcnt(0)
	s_barrier
	s_setprio 1
	s_waitcnt lgkmcnt(0)
	v_mfma_f32_16x16x32_bf16 v[60:63], v[146:149], v[186:189], 0
	v_mfma_f32_16x16x32_bf16 v[56:59], v[162:165], v[186:189], 0
	v_mfma_f32_16x16x32_bf16 v[44:47], v[146:149], v[194:197], 0
	v_mfma_f32_16x16x32_bf16 v[40:43], v[162:165], v[194:197], 0
	v_mfma_f32_16x16x32_bf16 v[28:31], v[146:149], v[202:205], 0
	v_mfma_f32_16x16x32_bf16 v[24:27], v[162:165], v[202:205], 0
	v_mfma_f32_16x16x32_bf16 v[12:15], v[146:149], v[210:213], 0
	v_mfma_f32_16x16x32_bf16 v[8:11], v[162:165], v[210:213], 0
	v_mfma_f32_16x16x32_bf16 v[60:63], v[158:161], v[190:193], v[60:63]
	v_mfma_f32_16x16x32_bf16 v[56:59], v[166:169], v[190:193], v[56:59]
	v_mfma_f32_16x16x32_bf16 v[44:47], v[158:161], v[198:201], v[44:47]
	v_mfma_f32_16x16x32_bf16 v[40:43], v[166:169], v[198:201], v[40:43]
	v_mfma_f32_16x16x32_bf16 v[28:31], v[158:161], v[206:209], v[28:31]
	v_mfma_f32_16x16x32_bf16 v[24:27], v[166:169], v[206:209], v[24:27]
	v_mfma_f32_16x16x32_bf16 v[12:15], v[158:161], v[214:217], v[12:15]
	v_mfma_f32_16x16x32_bf16 v[8:11], v[166:169], v[214:217], v[8:11]
	s_setprio 0
	s_setprio 1
	v_mfma_f32_16x16x32_bf16 v[52:55], v[170:173], v[186:189], 0
	v_mfma_f32_16x16x32_bf16 v[48:51], v[178:181], v[186:189], 0
	v_mfma_f32_16x16x32_bf16 v[36:39], v[170:173], v[194:197], 0
	v_mfma_f32_16x16x32_bf16 v[32:35], v[178:181], v[194:197], 0
	v_mfma_f32_16x16x32_bf16 v[20:23], v[170:173], v[202:205], 0
	v_mfma_f32_16x16x32_bf16 v[16:19], v[178:181], v[202:205], 0
	v_mfma_f32_16x16x32_bf16 v[4:7], v[170:173], v[210:213], 0
	v_mfma_f32_16x16x32_bf16 v[0:3], v[178:181], v[210:213], 0
	v_mfma_f32_16x16x32_bf16 v[52:55], v[174:177], v[190:193], v[52:55]
	v_mfma_f32_16x16x32_bf16 v[48:51], v[182:185], v[190:193], v[48:51]
	v_mfma_f32_16x16x32_bf16 v[36:39], v[174:177], v[198:201], v[36:39]
	v_mfma_f32_16x16x32_bf16 v[32:35], v[182:185], v[198:201], v[32:35]
	v_mfma_f32_16x16x32_bf16 v[20:23], v[174:177], v[206:209], v[20:23]
	v_mfma_f32_16x16x32_bf16 v[16:19], v[182:185], v[206:209], v[16:19]
	v_mfma_f32_16x16x32_bf16 v[4:7], v[174:177], v[214:217], v[4:7]
	v_mfma_f32_16x16x32_bf16 v[0:3], v[182:185], v[214:217], v[0:3]
	s_setprio 0
	s_barrier
	s_add_i32 s63, 0, 0x18000
	s_add_i32 s64, 0, 0x1c000
	v_add_u32_e32 v166, s63, v151
	v_add_u32_e32 v182, s64, v151
	ds_read_b128 v[146:149], v166
	ds_read_b128 v[158:161], v166 offset:1024
	ds_read_b128 v[162:165], v166 offset:2048
	ds_read_b128 v[166:169], v166 offset:3072
	ds_read_b128 v[170:173], v182
	ds_read_b128 v[174:177], v182 offset:1024
	ds_read_b128 v[178:181], v182 offset:2048
	ds_read_b128 v[182:185], v182 offset:3072
	s_add_u32 s34, s44, 0x40000
	s_addc_u32 s35, s45, 0
	s_mov_b32 m0, s50
	v_lshl_add_u64 v[226:227], s[34:35], 0, v[130:131]
	ds_read_b128 v[186:189], v155 offset:32768
	ds_read_b128 v[190:193], v155 offset:33792
	ds_read_b128 v[194:197], v155 offset:34816
	ds_read_b128 v[198:201], v155 offset:35840
	ds_read_b128 v[202:205], v155 offset:36864
	ds_read_b128 v[206:209], v155 offset:37888
	ds_read_b128 v[210:213], v155 offset:38912
	ds_read_b128 v[214:217], v155 offset:39936
	global_load_lds_dwordx4 v[226:227], off
	v_lshl_add_u64 v[226:227], s[34:35], 0, v[134:135]
	s_mov_b32 m0, s51
	s_nop 0
	global_load_lds_dwordx4 v[226:227], off
	s_waitcnt vmcnt(8)
	s_waitcnt lgkmcnt(0)
	s_barrier
	s_setprio 1
	s_waitcnt lgkmcnt(0)
	v_mfma_f32_16x16x32_bf16 v[124:127], v[146:149], v[186:189], v[124:127]
	v_mfma_f32_16x16x32_bf16 v[120:123], v[162:165], v[186:189], v[120:123]
	v_mfma_f32_16x16x32_bf16 v[108:111], v[146:149], v[194:197], v[108:111]
	v_mfma_f32_16x16x32_bf16 v[104:107], v[162:165], v[194:197], v[104:107]
	v_mfma_f32_16x16x32_bf16 v[92:95], v[146:149], v[202:205], v[92:95]
	v_mfma_f32_16x16x32_bf16 v[88:91], v[162:165], v[202:205], v[88:91]
	v_mfma_f32_16x16x32_bf16 v[76:79], v[146:149], v[210:213], v[76:79]
	v_mfma_f32_16x16x32_bf16 v[72:75], v[162:165], v[210:213], v[72:75]
	v_mfma_f32_16x16x32_bf16 v[124:127], v[158:161], v[190:193], v[124:127]
	v_mfma_f32_16x16x32_bf16 v[120:123], v[166:169], v[190:193], v[120:123]
	v_mfma_f32_16x16x32_bf16 v[108:111], v[158:161], v[198:201], v[108:111]
	v_mfma_f32_16x16x32_bf16 v[104:107], v[166:169], v[198:201], v[104:107]
	v_mfma_f32_16x16x32_bf16 v[92:95], v[158:161], v[206:209], v[92:95]
	v_mfma_f32_16x16x32_bf16 v[88:91], v[166:169], v[206:209], v[88:91]
	v_mfma_f32_16x16x32_bf16 v[76:79], v[158:161], v[214:217], v[76:79]
	v_mfma_f32_16x16x32_bf16 v[72:75], v[166:169], v[214:217], v[72:75]
	s_setprio 0
	s_setprio 1
	v_mfma_f32_16x16x32_bf16 v[116:119], v[170:173], v[186:189], v[116:119]
	v_mfma_f32_16x16x32_bf16 v[112:115], v[178:181], v[186:189], v[112:115]
	v_mfma_f32_16x16x32_bf16 v[100:103], v[170:173], v[194:197], v[100:103]
	v_mfma_f32_16x16x32_bf16 v[96:99], v[178:181], v[194:197], v[96:99]
	v_mfma_f32_16x16x32_bf16 v[84:87], v[170:173], v[202:205], v[84:87]
	v_mfma_f32_16x16x32_bf16 v[80:83], v[178:181], v[202:205], v[80:83]
	v_mfma_f32_16x16x32_bf16 v[68:71], v[170:173], v[210:213], v[68:71]
	v_mfma_f32_16x16x32_bf16 v[64:67], v[178:181], v[210:213], v[64:67]
	v_mfma_f32_16x16x32_bf16 v[116:119], v[174:177], v[190:193], v[116:119]
	v_mfma_f32_16x16x32_bf16 v[112:115], v[182:185], v[190:193], v[112:115]
	v_mfma_f32_16x16x32_bf16 v[100:103], v[174:177], v[198:201], v[100:103]
	v_mfma_f32_16x16x32_bf16 v[96:99], v[182:185], v[198:201], v[96:99]
	v_mfma_f32_16x16x32_bf16 v[84:87], v[174:177], v[206:209], v[84:87]
	v_mfma_f32_16x16x32_bf16 v[80:83], v[182:185], v[206:209], v[80:83]
	v_mfma_f32_16x16x32_bf16 v[68:71], v[174:177], v[214:217], v[68:71]
	v_mfma_f32_16x16x32_bf16 v[64:67], v[182:185], v[214:217], v[64:67]
	s_setprio 0
	s_barrier
	s_add_i32 s34, s63, s47
	v_lshl_add_u64 v[218:219], v[218:219], 0, s[10:11]
	s_mov_b32 m0, s34
	ds_read_b128 v[186:189], v155 offset:49152
	ds_read_b128 v[190:193], v155 offset:50176
	ds_read_b128 v[194:197], v155 offset:51200
	ds_read_b128 v[198:201], v155 offset:52224
	ds_read_b128 v[202:205], v155 offset:53248
	ds_read_b128 v[206:209], v155 offset:54272
	ds_read_b128 v[210:213], v155 offset:55296
	ds_read_b128 v[214:217], v155 offset:56320
	global_load_lds_dwordx4 v[218:219], off
	s_add_i32 m0, s34, 0x2000
	s_add_u32 s34, s42, 0x40080
	v_lshl_add_u64 v[218:219], v[220:221], 0, s[10:11]
	s_addc_u32 s35, s43, 0
	s_add_i32 s42, s64, s47
	global_load_lds_dwordx4 v[218:219], off
	v_lshl_add_u64 v[218:219], s[34:35], 0, v[132:133]
	s_mov_b32 m0, s42
	s_nop 0
	global_load_lds_dwordx4 v[218:219], off
	v_lshl_add_u64 v[218:219], s[34:35], 0, v[136:137]
	s_add_i32 m0, s42, 0x2000
	s_nop 0
	global_load_lds_dwordx4 v[218:219], off
	v_lshl_add_u64 v[218:219], v[222:223], 0, s[10:11]
	s_mov_b32 m0, s53
	s_nop 0
	global_load_lds_dwordx4 v[218:219], off
	v_lshl_add_u64 v[218:219], v[224:225], 0, s[10:11]
	s_mov_b32 m0, s54
	s_nop 0
	global_load_lds_dwordx4 v[218:219], off
	s_waitcnt vmcnt(8)
	s_waitcnt lgkmcnt(0)
	s_barrier
	s_setprio 1
	s_waitcnt lgkmcnt(0)
	v_mfma_f32_16x16x32_bf16 v[60:63], v[146:149], v[186:189], v[60:63]
	v_mfma_f32_16x16x32_bf16 v[56:59], v[162:165], v[186:189], v[56:59]
	v_mfma_f32_16x16x32_bf16 v[44:47], v[146:149], v[194:197], v[44:47]
	v_mfma_f32_16x16x32_bf16 v[40:43], v[162:165], v[194:197], v[40:43]
	v_mfma_f32_16x16x32_bf16 v[28:31], v[146:149], v[202:205], v[28:31]
	v_mfma_f32_16x16x32_bf16 v[24:27], v[162:165], v[202:205], v[24:27]
	v_mfma_f32_16x16x32_bf16 v[12:15], v[146:149], v[210:213], v[12:15]
	v_mfma_f32_16x16x32_bf16 v[8:11], v[162:165], v[210:213], v[8:11]
	v_mfma_f32_16x16x32_bf16 v[60:63], v[158:161], v[190:193], v[60:63]
	v_mfma_f32_16x16x32_bf16 v[56:59], v[166:169], v[190:193], v[56:59]
	v_mfma_f32_16x16x32_bf16 v[44:47], v[158:161], v[198:201], v[44:47]
	v_mfma_f32_16x16x32_bf16 v[40:43], v[166:169], v[198:201], v[40:43]
	v_mfma_f32_16x16x32_bf16 v[28:31], v[158:161], v[206:209], v[28:31]
	v_mfma_f32_16x16x32_bf16 v[24:27], v[166:169], v[206:209], v[24:27]
	v_mfma_f32_16x16x32_bf16 v[12:15], v[158:161], v[214:217], v[12:15]
	v_mfma_f32_16x16x32_bf16 v[8:11], v[166:169], v[214:217], v[8:11]
	s_setprio 0
	s_setprio 1
	v_mfma_f32_16x16x32_bf16 v[52:55], v[170:173], v[186:189], v[52:55]
	v_mfma_f32_16x16x32_bf16 v[48:51], v[178:181], v[186:189], v[48:51]
	v_mfma_f32_16x16x32_bf16 v[36:39], v[170:173], v[194:197], v[36:39]
	v_mfma_f32_16x16x32_bf16 v[32:35], v[178:181], v[194:197], v[32:35]
	v_mfma_f32_16x16x32_bf16 v[20:23], v[170:173], v[202:205], v[20:23]
	v_mfma_f32_16x16x32_bf16 v[16:19], v[178:181], v[202:205], v[16:19]
	v_mfma_f32_16x16x32_bf16 v[4:7], v[170:173], v[210:213], v[4:7]
	v_mfma_f32_16x16x32_bf16 v[0:3], v[178:181], v[210:213], v[0:3]
	v_mfma_f32_16x16x32_bf16 v[52:55], v[174:177], v[190:193], v[52:55]
	v_mfma_f32_16x16x32_bf16 v[48:51], v[182:185], v[190:193], v[48:51]
	v_mfma_f32_16x16x32_bf16 v[36:39], v[174:177], v[198:201], v[36:39]
	v_mfma_f32_16x16x32_bf16 v[32:35], v[182:185], v[198:201], v[32:35]
	v_mfma_f32_16x16x32_bf16 v[20:23], v[174:177], v[206:209], v[20:23]
	v_mfma_f32_16x16x32_bf16 v[16:19], v[182:185], v[206:209], v[16:19]
	v_mfma_f32_16x16x32_bf16 v[4:7], v[174:177], v[214:217], v[4:7]
	v_mfma_f32_16x16x32_bf16 v[0:3], v[182:185], v[214:217], v[0:3]
	s_setprio 0
	s_barrier
	s_add_i32 s62, s62, 2
	s_add_u32 s40, s40, 0x100
	s_addc_u32 s41, s41, 0
	s_add_u32 s39, s39, 0x100
	s_addc_u32 s61, s61, 0

.LBB0_1644:
	s_add_i32 s56, s56, 1
	s_mul_i32 s4, s56, s42
	s_mul_hi_u32 s5, s56, s43
	s_add_i32 s5, s5, s4
	s_mul_i32 s4, s56, s43
	s_add_u32 s26, s4, s2
	s_addc_u32 s27, s5, s3
	v_cmp_gt_i64_e32 vcc, s[26:27], v[144:145]
	v_cmp_lt_i64_e64 s[4:5], s[26:27], v[142:143]
	s_cbranch_vccnz .LBB0_1646
	s_and_b32 s100, s26, 7
	s_mul_i32 s100, s100, 0x160
	s_lshr_b32 s101, s26, 3
	s_add_i32 s100, s100, s101
	s_mul_hi_u32 s101, s100, 0x1745d18
	s_mul_i32 s10, s101, 0xb0
	s_sub_i32 s10, s100, s10
	s_and_b32 s100, s10, 7
	s_lshl_b32 s22, s101, 3
	s_add_i32 s22, s22, s100
	s_lshr_b32 s10, s10, 3
	s_mov_b32 s57, s56
.LBB0_1646:
	s_ashr_i32 s23, s22, 31
	s_lshl_b64 s[26:27], s[22:23], 19
	s_add_u32 s26, s14, s26
	s_addc_u32 s27, s15, s27
	s_and_b64 s[28:29], s[4:5], exec
	s_cselect_b32 s23, s27, s37
	s_cselect_b32 s58, s26, s36
	s_ashr_i32 s11, s10, 31
	s_lshl_b64 s[28:29], s[10:11], 19
	s_add_u32 s28, s45, s28
	s_addc_u32 s29, s46, s29
	s_and_b64 s[34:35], s[4:5], exec
	s_cselect_b32 s11, s29, s39
	s_cselect_b32 s59, s28, s38
	s_add_u32 s36, s36, 0x40080
	s_addc_u32 s37, s37, 0
	s_add_u32 s60, s38, 0x100
	s_addc_u32 s61, s39, 0
	s_mov_b32 s62, -2
	ds_read_b128 v[146:149], v154
	ds_read_b128 v[158:161], v154 offset:1024
	ds_read_b128 v[162:165], v154 offset:2048
	ds_read_b128 v[166:169], v154 offset:3072
	ds_read_b128 v[170:173], v155
	ds_read_b128 v[174:177], v155 offset:1024
	ds_read_b128 v[178:181], v155 offset:2048
	ds_read_b128 v[182:185], v155 offset:3072
	s_add_u32 s34, s36, 0xfffc0080
	s_addc_u32 s35, s37, -1
	s_cmp_eq_u32 s62, 12
	s_cselect_b32 s41, s23, s35
	s_cselect_b32 s40, s58, s34
	s_cselect_b32 s39, s11, s61
	s_cselect_b32 s38, s59, s60
	v_lshl_add_u64 v[218:219], s[36:37], 0, v[138:139]
	s_add_i32 m0, s31, 0xc000
	ds_read_b128 v[186:189], v157
	ds_read_b128 v[190:193], v157 offset:1024
	ds_read_b128 v[194:197], v157 offset:2048
	ds_read_b128 v[198:201], v157 offset:3072
	ds_read_b128 v[202:205], v157 offset:4096
	ds_read_b128 v[206:209], v157 offset:5120
	ds_read_b128 v[210:213], v157 offset:6144
	ds_read_b128 v[214:217], v157 offset:7168
	global_load_lds_dwordx4 v[218:219], off
	v_lshl_add_u64 v[218:219], s[36:37], 0, v[140:141]
	s_add_i32 m0, s31, 0xe000
	s_nop 0
	global_load_lds_dwordx4 v[218:219], off
	s_waitcnt vmcnt(8)
	s_waitcnt lgkmcnt(0)
	s_barrier
	s_setprio 1
	s_waitcnt lgkmcnt(0)
	v_mfma_f32_16x16x32_bf16 v[124:127], v[146:149], v[186:189], 0
	v_mfma_f32_16x16x32_bf16 v[120:123], v[162:165], v[186:189], 0
	v_mfma_f32_16x16x32_bf16 v[108:111], v[146:149], v[194:197], 0
	v_mfma_f32_16x16x32_bf16 v[104:107], v[162:165], v[194:197], 0
	v_mfma_f32_16x16x32_bf16 v[92:95], v[146:149], v[202:205], 0
	v_mfma_f32_16x16x32_bf16 v[88:91], v[162:165], v[202:205], 0
	v_mfma_f32_16x16x32_bf16 v[76:79], v[146:149], v[210:213], 0
	v_mfma_f32_16x16x32_bf16 v[72:75], v[162:165], v[210:213], 0
	v_mfma_f32_16x16x32_bf16 v[124:127], v[158:161], v[190:193], v[124:127]
	v_mfma_f32_16x16x32_bf16 v[120:123], v[166:169], v[190:193], v[120:123]
	v_mfma_f32_16x16x32_bf16 v[108:111], v[158:161], v[198:201], v[108:111]
	v_mfma_f32_16x16x32_bf16 v[104:107], v[166:169], v[198:201], v[104:107]
	v_mfma_f32_16x16x32_bf16 v[92:95], v[158:161], v[206:209], v[92:95]
	v_mfma_f32_16x16x32_bf16 v[88:91], v[166:169], v[206:209], v[88:91]
	v_mfma_f32_16x16x32_bf16 v[76:79], v[158:161], v[214:217], v[76:79]
	v_mfma_f32_16x16x32_bf16 v[72:75], v[166:169], v[214:217], v[72:75]
	s_setprio 0
	s_setprio 1
	v_mfma_f32_16x16x32_bf16 v[116:119], v[170:173], v[186:189], 0
	v_mfma_f32_16x16x32_bf16 v[112:115], v[178:181], v[186:189], 0
	v_mfma_f32_16x16x32_bf16 v[100:103], v[170:173], v[194:197], 0
	v_mfma_f32_16x16x32_bf16 v[96:99], v[178:181], v[194:197], 0
	v_mfma_f32_16x16x32_bf16 v[84:87], v[170:173], v[202:205], 0
	v_mfma_f32_16x16x32_bf16 v[80:83], v[178:181], v[202:205], 0
	v_mfma_f32_16x16x32_bf16 v[68:71], v[170:173], v[210:213], 0
	v_mfma_f32_16x16x32_bf16 v[64:67], v[178:181], v[210:213], 0
	v_mfma_f32_16x16x32_bf16 v[116:119], v[174:177], v[190:193], v[116:119]
	v_mfma_f32_16x16x32_bf16 v[112:115], v[182:185], v[190:193], v[112:115]
	v_mfma_f32_16x16x32_bf16 v[100:103], v[174:177], v[198:201], v[100:103]
	v_mfma_f32_16x16x32_bf16 v[96:99], v[182:185], v[198:201], v[96:99]
	v_mfma_f32_16x16x32_bf16 v[84:87], v[174:177], v[206:209], v[84:87]
	v_mfma_f32_16x16x32_bf16 v[80:83], v[182:185], v[206:209], v[80:83]
	v_mfma_f32_16x16x32_bf16 v[68:71], v[174:177], v[214:217], v[68:71]
	v_mfma_f32_16x16x32_bf16 v[64:67], v[182:185], v[214:217], v[64:67]
	s_setprio 0
	s_barrier
	s_add_i32 s34, s53, s44
	v_lshl_add_u64 v[218:219], s[38:39], 0, v[134:135]
	s_mov_b32 m0, s34
	ds_read_b128 v[186:189], v157 offset:16384
	ds_read_b128 v[190:193], v157 offset:17408
	ds_read_b128 v[194:197], v157 offset:18432
	ds_read_b128 v[198:201], v157 offset:19456
	ds_read_b128 v[202:205], v157 offset:20480
	ds_read_b128 v[206:209], v157 offset:21504
	ds_read_b128 v[210:213], v157 offset:22528
	ds_read_b128 v[214:217], v157 offset:23552
	global_load_lds_dwordx4 v[218:219], off
	s_add_i32 m0, s34, 0x2000
	s_add_u32 s34, s38, 0x40000
	v_lshl_add_u64 v[220:221], s[38:39], 0, v[130:131]
	s_addc_u32 s35, s39, 0
	s_add_i32 s63, s54, s44
	global_load_lds_dwordx4 v[220:221], off
	v_lshl_add_u64 v[222:223], s[34:35], 0, v[134:135]
	s_mov_b32 m0, s63
	v_lshl_add_u64 v[224:225], s[40:41], 0, v[132:133]
	global_load_lds_dwordx4 v[222:223], off
	v_lshl_add_u64 v[222:223], s[34:35], 0, v[130:131]
	s_add_i32 m0, s63, 0x2000
	s_nop 0
	global_load_lds_dwordx4 v[222:223], off
	v_lshl_add_u64 v[222:223], s[40:41], 0, v[136:137]
	s_mov_b32 m0, s31
	s_nop 0
	global_load_lds_dwordx4 v[222:223], off
	s_mov_b32 m0, s48
	s_nop 0
	global_load_lds_dwordx4 v[224:225], off
	s_waitcnt vmcnt(8)
	s_waitcnt lgkmcnt(0)
	s_barrier
	s_setprio 1
	s_waitcnt lgkmcnt(0)
	v_mfma_f32_16x16x32_bf16 v[60:63], v[146:149], v[186:189], 0
	v_mfma_f32_16x16x32_bf16 v[56:59], v[162:165], v[186:189], 0
	v_mfma_f32_16x16x32_bf16 v[44:47], v[146:149], v[194:197], 0
	v_mfma_f32_16x16x32_bf16 v[40:43], v[162:165], v[194:197], 0
	v_mfma_f32_16x16x32_bf16 v[28:31], v[146:149], v[202:205], 0
	v_mfma_f32_16x16x32_bf16 v[24:27], v[162:165], v[202:205], 0
	v_mfma_f32_16x16x32_bf16 v[12:15], v[146:149], v[210:213], 0
	v_mfma_f32_16x16x32_bf16 v[8:11], v[162:165], v[210:213], 0
	v_mfma_f32_16x16x32_bf16 v[60:63], v[158:161], v[190:193], v[60:63]
	v_mfma_f32_16x16x32_bf16 v[56:59], v[166:169], v[190:193], v[56:59]
	v_mfma_f32_16x16x32_bf16 v[44:47], v[158:161], v[198:201], v[44:47]
	v_mfma_f32_16x16x32_bf16 v[40:43], v[166:169], v[198:201], v[40:43]
	v_mfma_f32_16x16x32_bf16 v[28:31], v[158:161], v[206:209], v[28:31]
	v_mfma_f32_16x16x32_bf16 v[24:27], v[166:169], v[206:209], v[24:27]
	v_mfma_f32_16x16x32_bf16 v[12:15], v[158:161], v[214:217], v[12:15]
	v_mfma_f32_16x16x32_bf16 v[8:11], v[166:169], v[214:217], v[8:11]
	s_setprio 0
	s_setprio 1
	v_mfma_f32_16x16x32_bf16 v[52:55], v[170:173], v[186:189], 0
	v_mfma_f32_16x16x32_bf16 v[48:51], v[178:181], v[186:189], 0
	v_mfma_f32_16x16x32_bf16 v[36:39], v[170:173], v[194:197], 0
	v_mfma_f32_16x16x32_bf16 v[32:35], v[178:181], v[194:197], 0
	v_mfma_f32_16x16x32_bf16 v[20:23], v[170:173], v[202:205], 0
	v_mfma_f32_16x16x32_bf16 v[16:19], v[178:181], v[202:205], 0
	v_mfma_f32_16x16x32_bf16 v[4:7], v[170:173], v[210:213], 0
	v_mfma_f32_16x16x32_bf16 v[0:3], v[178:181], v[210:213], 0
	v_mfma_f32_16x16x32_bf16 v[52:55], v[174:177], v[190:193], v[52:55]
	v_mfma_f32_16x16x32_bf16 v[48:51], v[182:185], v[190:193], v[48:51]
	v_mfma_f32_16x16x32_bf16 v[36:39], v[174:177], v[198:201], v[36:39]
	v_mfma_f32_16x16x32_bf16 v[32:35], v[182:185], v[198:201], v[32:35]
	v_mfma_f32_16x16x32_bf16 v[20:23], v[174:177], v[206:209], v[20:23]
	v_mfma_f32_16x16x32_bf16 v[16:19], v[182:185], v[206:209], v[16:19]
	v_mfma_f32_16x16x32_bf16 v[4:7], v[174:177], v[214:217], v[4:7]
	v_mfma_f32_16x16x32_bf16 v[0:3], v[182:185], v[214:217], v[0:3]
	s_setprio 0
	s_barrier
	s_add_i32 s63, 0, 0x18000
	s_add_i32 s64, 0, 0x1c000
	v_add_u32_e32 v166, s63, v151
	v_add_u32_e32 v182, s64, v151
	ds_read_b128 v[146:149], v166
	ds_read_b128 v[158:161], v166 offset:1024
	ds_read_b128 v[162:165], v166 offset:2048
	ds_read_b128 v[166:169], v166 offset:3072
	ds_read_b128 v[170:173], v182
	ds_read_b128 v[174:177], v182 offset:1024
	ds_read_b128 v[178:181], v182 offset:2048
	ds_read_b128 v[182:185], v182 offset:3072
	s_add_u32 s34, s40, 0x40000
	s_addc_u32 s35, s41, 0
	s_mov_b32 m0, s49
	v_lshl_add_u64 v[226:227], s[34:35], 0, v[136:137]
	ds_read_b128 v[186:189], v157 offset:32768
	ds_read_b128 v[190:193], v157 offset:33792
	ds_read_b128 v[194:197], v157 offset:34816
	ds_read_b128 v[198:201], v157 offset:35840
	ds_read_b128 v[202:205], v157 offset:36864
	ds_read_b128 v[206:209], v157 offset:37888
	ds_read_b128 v[210:213], v157 offset:38912
	ds_read_b128 v[214:217], v157 offset:39936
	global_load_lds_dwordx4 v[226:227], off
	v_lshl_add_u64 v[226:227], s[34:35], 0, v[132:133]
	s_mov_b32 m0, s50
	s_nop 0
	global_load_lds_dwordx4 v[226:227], off
	s_waitcnt vmcnt(8)
	s_waitcnt lgkmcnt(0)
	s_barrier
	s_setprio 1
	s_waitcnt lgkmcnt(0)
	v_mfma_f32_16x16x32_bf16 v[124:127], v[146:149], v[186:189], v[124:127]
	v_mfma_f32_16x16x32_bf16 v[120:123], v[162:165], v[186:189], v[120:123]
	v_mfma_f32_16x16x32_bf16 v[108:111], v[146:149], v[194:197], v[108:111]
	v_mfma_f32_16x16x32_bf16 v[104:107], v[162:165], v[194:197], v[104:107]
	v_mfma_f32_16x16x32_bf16 v[92:95], v[146:149], v[202:205], v[92:95]
	v_mfma_f32_16x16x32_bf16 v[88:91], v[162:165], v[202:205], v[88:91]
	v_mfma_f32_16x16x32_bf16 v[76:79], v[146:149], v[210:213], v[76:79]
	v_mfma_f32_16x16x32_bf16 v[72:75], v[162:165], v[210:213], v[72:75]
	v_mfma_f32_16x16x32_bf16 v[124:127], v[158:161], v[190:193], v[124:127]
	v_mfma_f32_16x16x32_bf16 v[120:123], v[166:169], v[190:193], v[120:123]
	v_mfma_f32_16x16x32_bf16 v[108:111], v[158:161], v[198:201], v[108:111]
	v_mfma_f32_16x16x32_bf16 v[104:107], v[166:169], v[198:201], v[104:107]
	v_mfma_f32_16x16x32_bf16 v[92:95], v[158:161], v[206:209], v[92:95]
	v_mfma_f32_16x16x32_bf16 v[88:91], v[166:169], v[206:209], v[88:91]
	v_mfma_f32_16x16x32_bf16 v[76:79], v[158:161], v[214:217], v[76:79]
	v_mfma_f32_16x16x32_bf16 v[72:75], v[166:169], v[214:217], v[72:75]
	s_setprio 0
	s_setprio 1
	v_mfma_f32_16x16x32_bf16 v[116:119], v[170:173], v[186:189], v[116:119]
	v_mfma_f32_16x16x32_bf16 v[112:115], v[178:181], v[186:189], v[112:115]
	v_mfma_f32_16x16x32_bf16 v[100:103], v[170:173], v[194:197], v[100:103]
	v_mfma_f32_16x16x32_bf16 v[96:99], v[178:181], v[194:197], v[96:99]
	v_mfma_f32_16x16x32_bf16 v[84:87], v[170:173], v[202:205], v[84:87]
	v_mfma_f32_16x16x32_bf16 v[80:83], v[178:181], v[202:205], v[80:83]
	v_mfma_f32_16x16x32_bf16 v[68:71], v[170:173], v[210:213], v[68:71]
	v_mfma_f32_16x16x32_bf16 v[64:67], v[178:181], v[210:213], v[64:67]
	v_mfma_f32_16x16x32_bf16 v[116:119], v[174:177], v[190:193], v[116:119]
	v_mfma_f32_16x16x32_bf16 v[112:115], v[182:185], v[190:193], v[112:115]
	v_mfma_f32_16x16x32_bf16 v[100:103], v[174:177], v[198:201], v[100:103]
	v_mfma_f32_16x16x32_bf16 v[96:99], v[182:185], v[198:201], v[96:99]
	v_mfma_f32_16x16x32_bf16 v[84:87], v[174:177], v[206:209], v[84:87]
	v_mfma_f32_16x16x32_bf16 v[80:83], v[182:185], v[206:209], v[80:83]
	v_mfma_f32_16x16x32_bf16 v[68:71], v[174:177], v[214:217], v[68:71]
	v_mfma_f32_16x16x32_bf16 v[64:67], v[182:185], v[214:217], v[64:67]
	s_setprio 0
	s_barrier
	s_add_i32 s34, s63, s44
	v_lshl_add_u64 v[218:219], v[218:219], 0, s[6:7]
	s_mov_b32 m0, s34
	ds_read_b128 v[186:189], v157 offset:49152
	ds_read_b128 v[190:193], v157 offset:50176
	ds_read_b128 v[194:197], v157 offset:51200
	ds_read_b128 v[198:201], v157 offset:52224
	ds_read_b128 v[202:205], v157 offset:53248
	ds_read_b128 v[206:209], v157 offset:54272
	ds_read_b128 v[210:213], v157 offset:55296
	ds_read_b128 v[214:217], v157 offset:56320
	global_load_lds_dwordx4 v[218:219], off
	s_add_i32 m0, s34, 0x2000
	s_add_u32 s34, s38, 0x40080
	v_lshl_add_u64 v[218:219], v[220:221], 0, s[6:7]
	s_addc_u32 s35, s39, 0
	s_add_i32 s38, s64, s44
	global_load_lds_dwordx4 v[218:219], off
	v_lshl_add_u64 v[218:219], s[34:35], 0, v[134:135]
	s_mov_b32 m0, s38
	s_nop 0
	global_load_lds_dwordx4 v[218:219], off
	v_lshl_add_u64 v[218:219], s[34:35], 0, v[130:131]
	s_add_i32 m0, s38, 0x2000
	s_nop 0
	global_load_lds_dwordx4 v[218:219], off
	v_lshl_add_u64 v[218:219], v[222:223], 0, s[6:7]
	s_mov_b32 m0, s51
	s_nop 0
	global_load_lds_dwordx4 v[218:219], off
	v_lshl_add_u64 v[218:219], v[224:225], 0, s[6:7]
	s_mov_b32 m0, s52
	s_nop 0
	global_load_lds_dwordx4 v[218:219], off
	s_waitcnt vmcnt(8)
	s_waitcnt lgkmcnt(0)
	s_barrier
	s_setprio 1
	s_waitcnt lgkmcnt(0)
	v_mfma_f32_16x16x32_bf16 v[60:63], v[146:149], v[186:189], v[60:63]
	v_mfma_f32_16x16x32_bf16 v[56:59], v[162:165], v[186:189], v[56:59]
	v_mfma_f32_16x16x32_bf16 v[44:47], v[146:149], v[194:197], v[44:47]
	v_mfma_f32_16x16x32_bf16 v[40:43], v[162:165], v[194:197], v[40:43]
	v_mfma_f32_16x16x32_bf16 v[28:31], v[146:149], v[202:205], v[28:31]
	v_mfma_f32_16x16x32_bf16 v[24:27], v[162:165], v[202:205], v[24:27]
	v_mfma_f32_16x16x32_bf16 v[12:15], v[146:149], v[210:213], v[12:15]
	v_mfma_f32_16x16x32_bf16 v[8:11], v[162:165], v[210:213], v[8:11]
	v_mfma_f32_16x16x32_bf16 v[60:63], v[158:161], v[190:193], v[60:63]
	v_mfma_f32_16x16x32_bf16 v[56:59], v[166:169], v[190:193], v[56:59]
	v_mfma_f32_16x16x32_bf16 v[44:47], v[158:161], v[198:201], v[44:47]
	v_mfma_f32_16x16x32_bf16 v[40:43], v[166:169], v[198:201], v[40:43]
	v_mfma_f32_16x16x32_bf16 v[28:31], v[158:161], v[206:209], v[28:31]
	v_mfma_f32_16x16x32_bf16 v[24:27], v[166:169], v[206:209], v[24:27]
	v_mfma_f32_16x16x32_bf16 v[12:15], v[158:161], v[214:217], v[12:15]
	v_mfma_f32_16x16x32_bf16 v[8:11], v[166:169], v[214:217], v[8:11]
	s_setprio 0
	s_setprio 1
	v_mfma_f32_16x16x32_bf16 v[52:55], v[170:173], v[186:189], v[52:55]
	v_mfma_f32_16x16x32_bf16 v[48:51], v[178:181], v[186:189], v[48:51]
	v_mfma_f32_16x16x32_bf16 v[36:39], v[170:173], v[194:197], v[36:39]
	v_mfma_f32_16x16x32_bf16 v[32:35], v[178:181], v[194:197], v[32:35]
	v_mfma_f32_16x16x32_bf16 v[20:23], v[170:173], v[202:205], v[20:23]
	v_mfma_f32_16x16x32_bf16 v[16:19], v[178:181], v[202:205], v[16:19]
	v_mfma_f32_16x16x32_bf16 v[4:7], v[170:173], v[210:213], v[4:7]
	v_mfma_f32_16x16x32_bf16 v[0:3], v[178:181], v[210:213], v[0:3]
	v_mfma_f32_16x16x32_bf16 v[52:55], v[174:177], v[190:193], v[52:55]
	v_mfma_f32_16x16x32_bf16 v[48:51], v[182:185], v[190:193], v[48:51]
	v_mfma_f32_16x16x32_bf16 v[36:39], v[174:177], v[198:201], v[36:39]
	v_mfma_f32_16x16x32_bf16 v[32:35], v[182:185], v[198:201], v[32:35]
	v_mfma_f32_16x16x32_bf16 v[20:23], v[174:177], v[206:209], v[20:23]
	v_mfma_f32_16x16x32_bf16 v[16:19], v[182:185], v[206:209], v[16:19]
	v_mfma_f32_16x16x32_bf16 v[4:7], v[174:177], v[214:217], v[4:7]
	v_mfma_f32_16x16x32_bf16 v[0:3], v[182:185], v[214:217], v[0:3]
	s_setprio 0
	s_barrier
	s_add_i32 s62, s62, 2
	s_add_u32 s36, s36, 0x100
	s_addc_u32 s37, s37, 0
	s_add_u32 s60, s60, 0x100
	s_addc_u32 s61, s61, 0

.LBB0_1650:
	v_lshl_add_u32 v159, s12, 10, v152
	v_lshl_or_b32 v148, s13, 7, v153
	v_lshl_add_u32 v158, s30, 8, v150
	v_ashrrev_i32_e32 v149, 31, v148
	v_mov_b64_e32 v[146:147], s[16:17]
	v_mad_i64_i32 v[162:163], s[12:13], v158, s55, v[146:147]
	v_lshlrev_b64 v[148:149], 1, v[148:149]
	v_lshl_add_u64 v[162:163], v[162:163], 0, v[148:149]
	v_mov_b32_e32 v232, v162
	v_mov_b32_e32 v233, v163
	ds_read_b32 v172, v159
	ds_read_b32 v174, v159 offset:64
	ds_read_b32 v176, v159 offset:128
	ds_read_b32 v178, v159 offset:192
	ds_read_b32 v180, v159 offset:512
	ds_read_b32 v182, v159 offset:576
	ds_read_b32 v184, v159 offset:640
	ds_read_b32 v186, v159 offset:704
	v_mov_b32_e32 v188, 0xbfb8aa3b
	s_waitcnt lgkmcnt(7)
	v_pk_mul_f32 v[124:125], v[124:125], v[172:173] op_sel_hi:[1,0]
	v_pk_mul_f32 v[126:127], v[126:127], v[172:173] op_sel_hi:[1,0]
	v_pk_mul_f32 v[120:121], v[120:121], v[172:173] op_sel_hi:[1,0]
	v_pk_mul_f32 v[122:123], v[122:123], v[172:173] op_sel_hi:[1,0]
	v_pk_mul_f32 v[116:117], v[116:117], v[172:173] op_sel_hi:[1,0]
	v_pk_mul_f32 v[118:119], v[118:119], v[172:173] op_sel_hi:[1,0]
	v_pk_mul_f32 v[112:113], v[112:113], v[172:173] op_sel_hi:[1,0]
	v_pk_mul_f32 v[114:115], v[114:115], v[172:173] op_sel_hi:[1,0]
	v_pk_mul_f32 v[192:193], v[124:125], v[188:189] op_sel_hi:[1,0]
	v_pk_mul_f32 v[194:195], v[126:127], v[188:189] op_sel_hi:[1,0]
	v_pk_mul_f32 v[196:197], v[120:121], v[188:189] op_sel_hi:[1,0]
	v_pk_mul_f32 v[198:199], v[122:123], v[188:189] op_sel_hi:[1,0]
	v_exp_f32_e32 v192, v192
	v_exp_f32_e32 v193, v193
	v_exp_f32_e32 v194, v194
	v_exp_f32_e32 v195, v195
	v_exp_f32_e32 v196, v196
	v_exp_f32_e32 v197, v197
	v_exp_f32_e32 v198, v198
	v_exp_f32_e32 v199, v199
	v_add_f32_e32 v192, 1.0, v192
	v_add_f32_e32 v193, 1.0, v193
	v_add_f32_e32 v194, 1.0, v194
	v_add_f32_e32 v195, 1.0, v195
	v_add_f32_e32 v196, 1.0, v196
	v_add_f32_e32 v197, 1.0, v197
	v_add_f32_e32 v198, 1.0, v198
	v_add_f32_e32 v199, 1.0, v199
	v_rcp_f32_e32 v192, v192
	v_rcp_f32_e32 v193, v193
	v_rcp_f32_e32 v194, v194
	v_rcp_f32_e32 v195, v195
	v_rcp_f32_e32 v196, v196
	v_rcp_f32_e32 v197, v197
	v_rcp_f32_e32 v198, v198
	v_rcp_f32_e32 v199, v199
	v_pk_mul_f32 v[124:125], v[124:125], v[192:193]
	v_pk_mul_f32 v[126:127], v[126:127], v[194:195]
	v_pk_mul_f32 v[120:121], v[120:121], v[196:197]
	v_pk_mul_f32 v[122:123], v[122:123], v[198:199]
	v_pk_mul_f32 v[124:125], v[116:117], v[124:125]
	v_pk_mul_f32 v[126:127], v[118:119], v[126:127]
	v_pk_mul_f32 v[120:121], v[112:113], v[120:121]
	v_pk_mul_f32 v[122:123], v[114:115], v[122:123]
	v_cvt_pk_bf16_f32 v208, v124, v125
	v_cvt_pk_bf16_f32 v209, v126, v127
	v_cvt_pk_bf16_f32 v210, v120, v121
	v_cvt_pk_bf16_f32 v211, v122, v123
	global_store_dwordx4 v[232:233], v[208:211], off
	s_waitcnt lgkmcnt(6)
	v_pk_mul_f32 v[108:109], v[108:109], v[174:175] op_sel_hi:[1,0]
	v_pk_mul_f32 v[110:111], v[110:111], v[174:175] op_sel_hi:[1,0]
	v_pk_mul_f32 v[104:105], v[104:105], v[174:175] op_sel_hi:[1,0]
	v_pk_mul_f32 v[106:107], v[106:107], v[174:175] op_sel_hi:[1,0]
	v_pk_mul_f32 v[100:101], v[100:101], v[174:175] op_sel_hi:[1,0]
	v_pk_mul_f32 v[102:103], v[102:103], v[174:175] op_sel_hi:[1,0]
	v_pk_mul_f32 v[96:97], v[96:97], v[174:175] op_sel_hi:[1,0]
	v_pk_mul_f32 v[98:99], v[98:99], v[174:175] op_sel_hi:[1,0]
	v_pk_mul_f32 v[200:201], v[108:109], v[188:189] op_sel_hi:[1,0]
	v_pk_mul_f32 v[202:203], v[110:111], v[188:189] op_sel_hi:[1,0]
	v_pk_mul_f32 v[204:205], v[104:105], v[188:189] op_sel_hi:[1,0]
	v_pk_mul_f32 v[206:207], v[106:107], v[188:189] op_sel_hi:[1,0]
	v_exp_f32_e32 v200, v200
	v_exp_f32_e32 v201, v201
	v_exp_f32_e32 v202, v202
	v_exp_f32_e32 v203, v203
	v_exp_f32_e32 v204, v204
	v_exp_f32_e32 v205, v205
	v_exp_f32_e32 v206, v206
	v_exp_f32_e32 v207, v207
	v_add_f32_e32 v200, 1.0, v200
	v_add_f32_e32 v201, 1.0, v201
	v_add_f32_e32 v202, 1.0, v202
	v_add_f32_e32 v203, 1.0, v203
	v_add_f32_e32 v204, 1.0, v204
	v_add_f32_e32 v205, 1.0, v205
	v_add_f32_e32 v206, 1.0, v206
	v_add_f32_e32 v207, 1.0, v207
	v_rcp_f32_e32 v200, v200
	v_rcp_f32_e32 v201, v201
	v_rcp_f32_e32 v202, v202
	v_rcp_f32_e32 v203, v203
	v_rcp_f32_e32 v204, v204
	v_rcp_f32_e32 v205, v205
	v_rcp_f32_e32 v206, v206
	v_rcp_f32_e32 v207, v207
	v_pk_mul_f32 v[108:109], v[108:109], v[200:201]
	v_pk_mul_f32 v[110:111], v[110:111], v[202:203]
	v_pk_mul_f32 v[104:105], v[104:105], v[204:205]
	v_pk_mul_f32 v[106:107], v[106:107], v[206:207]
	v_pk_mul_f32 v[108:109], v[100:101], v[108:109]
	v_pk_mul_f32 v[110:111], v[102:103], v[110:111]
	v_pk_mul_f32 v[104:105], v[96:97], v[104:105]
	v_pk_mul_f32 v[106:107], v[98:99], v[106:107]
	v_cvt_pk_bf16_f32 v212, v108, v109
	v_cvt_pk_bf16_f32 v213, v110, v111
	v_cvt_pk_bf16_f32 v214, v104, v105
	v_cvt_pk_bf16_f32 v215, v106, v107
	s_mov_b64 s[100:101], 0x16000
	v_lshl_add_u64 v[216:217], v[232:233], 0, s[100:101]
	global_store_dwordx4 v[216:217], v[212:215], off
	s_waitcnt lgkmcnt(5)
	v_pk_mul_f32 v[92:93], v[92:93], v[176:177] op_sel_hi:[1,0]
	v_pk_mul_f32 v[94:95], v[94:95], v[176:177] op_sel_hi:[1,0]
	v_pk_mul_f32 v[88:89], v[88:89], v[176:177] op_sel_hi:[1,0]
	v_pk_mul_f32 v[90:91], v[90:91], v[176:177] op_sel_hi:[1,0]
	v_pk_mul_f32 v[84:85], v[84:85], v[176:177] op_sel_hi:[1,0]
	v_pk_mul_f32 v[86:87], v[86:87], v[176:177] op_sel_hi:[1,0]
	v_pk_mul_f32 v[80:81], v[80:81], v[176:177] op_sel_hi:[1,0]
	v_pk_mul_f32 v[82:83], v[82:83], v[176:177] op_sel_hi:[1,0]
	v_pk_mul_f32 v[192:193], v[92:93], v[188:189] op_sel_hi:[1,0]
	v_pk_mul_f32 v[194:195], v[94:95], v[188:189] op_sel_hi:[1,0]
	v_pk_mul_f32 v[196:197], v[88:89], v[188:189] op_sel_hi:[1,0]
	v_pk_mul_f32 v[198:199], v[90:91], v[188:189] op_sel_hi:[1,0]
	v_exp_f32_e32 v192, v192
	v_exp_f32_e32 v193, v193
	v_exp_f32_e32 v194, v194
	v_exp_f32_e32 v195, v195
	v_exp_f32_e32 v196, v196
	v_exp_f32_e32 v197, v197
	v_exp_f32_e32 v198, v198
	v_exp_f32_e32 v199, v199
	v_add_f32_e32 v192, 1.0, v192
	v_add_f32_e32 v193, 1.0, v193
	v_add_f32_e32 v194, 1.0, v194
	v_add_f32_e32 v195, 1.0, v195
	v_add_f32_e32 v196, 1.0, v196
	v_add_f32_e32 v197, 1.0, v197
	v_add_f32_e32 v198, 1.0, v198
	v_add_f32_e32 v199, 1.0, v199
	v_rcp_f32_e32 v192, v192
	v_rcp_f32_e32 v193, v193
	v_rcp_f32_e32 v194, v194
	v_rcp_f32_e32 v195, v195
	v_rcp_f32_e32 v196, v196
	v_rcp_f32_e32 v197, v197
	v_rcp_f32_e32 v198, v198
	v_rcp_f32_e32 v199, v199
	v_pk_mul_f32 v[92:93], v[92:93], v[192:193]
	v_pk_mul_f32 v[94:95], v[94:95], v[194:195]
	v_pk_mul_f32 v[88:89], v[88:89], v[196:197]
	v_pk_mul_f32 v[90:91], v[90:91], v[198:199]
	v_pk_mul_f32 v[92:93], v[84:85], v[92:93]
	v_pk_mul_f32 v[94:95], v[86:87], v[94:95]
	v_pk_mul_f32 v[88:89], v[80:81], v[88:89]
	v_pk_mul_f32 v[90:91], v[82:83], v[90:91]
	v_cvt_pk_bf16_f32 v208, v92, v93
	v_cvt_pk_bf16_f32 v209, v94, v95
	v_cvt_pk_bf16_f32 v210, v88, v89
	v_cvt_pk_bf16_f32 v211, v90, v91
	s_mov_b64 s[100:101], 0x2c000
	v_lshl_add_u64 v[216:217], v[232:233], 0, s[100:101]
	global_store_dwordx4 v[216:217], v[208:211], off
	s_waitcnt lgkmcnt(4)
	v_pk_mul_f32 v[76:77], v[76:77], v[178:179] op_sel_hi:[1,0]
	v_pk_mul_f32 v[78:79], v[78:79], v[178:179] op_sel_hi:[1,0]
	v_pk_mul_f32 v[72:73], v[72:73], v[178:179] op_sel_hi:[1,0]
	v_pk_mul_f32 v[74:75], v[74:75], v[178:179] op_sel_hi:[1,0]
	v_pk_mul_f32 v[68:69], v[68:69], v[178:179] op_sel_hi:[1,0]
	v_pk_mul_f32 v[70:71], v[70:71], v[178:179] op_sel_hi:[1,0]
	v_pk_mul_f32 v[64:65], v[64:65], v[178:179] op_sel_hi:[1,0]
	v_pk_mul_f32 v[66:67], v[66:67], v[178:179] op_sel_hi:[1,0]
	v_pk_mul_f32 v[200:201], v[76:77], v[188:189] op_sel_hi:[1,0]
	v_pk_mul_f32 v[202:203], v[78:79], v[188:189] op_sel_hi:[1,0]
	v_pk_mul_f32 v[204:205], v[72:73], v[188:189] op_sel_hi:[1,0]
	v_pk_mul_f32 v[206:207], v[74:75], v[188:189] op_sel_hi:[1,0]
	v_exp_f32_e32 v200, v200
	v_exp_f32_e32 v201, v201
	v_exp_f32_e32 v202, v202
	v_exp_f32_e32 v203, v203
	v_exp_f32_e32 v204, v204
	v_exp_f32_e32 v205, v205
	v_exp_f32_e32 v206, v206
	v_exp_f32_e32 v207, v207
	v_add_f32_e32 v200, 1.0, v200
	v_add_f32_e32 v201, 1.0, v201
	v_add_f32_e32 v202, 1.0, v202
	v_add_f32_e32 v203, 1.0, v203
	v_add_f32_e32 v204, 1.0, v204
	v_add_f32_e32 v205, 1.0, v205
	v_add_f32_e32 v206, 1.0, v206
	v_add_f32_e32 v207, 1.0, v207
	v_rcp_f32_e32 v200, v200
	v_rcp_f32_e32 v201, v201
	v_rcp_f32_e32 v202, v202
	v_rcp_f32_e32 v203, v203
	v_rcp_f32_e32 v204, v204
	v_rcp_f32_e32 v205, v205
	v_rcp_f32_e32 v206, v206
	v_rcp_f32_e32 v207, v207
	v_pk_mul_f32 v[76:77], v[76:77], v[200:201]
	v_pk_mul_f32 v[78:79], v[78:79], v[202:203]
	v_pk_mul_f32 v[72:73], v[72:73], v[204:205]
	v_pk_mul_f32 v[74:75], v[74:75], v[206:207]
	v_pk_mul_f32 v[76:77], v[68:69], v[76:77]
	v_pk_mul_f32 v[78:79], v[70:71], v[78:79]
	v_pk_mul_f32 v[72:73], v[64:65], v[72:73]
	v_pk_mul_f32 v[74:75], v[66:67], v[74:75]
	v_cvt_pk_bf16_f32 v212, v76, v77
	v_cvt_pk_bf16_f32 v213, v78, v79
	v_cvt_pk_bf16_f32 v214, v72, v73
	v_cvt_pk_bf16_f32 v215, v74, v75
	s_mov_b64 s[100:101], 0x42000
	v_lshl_add_u64 v[216:217], v[232:233], 0, s[100:101]
	global_store_dwordx4 v[216:217], v[212:215], off
	s_waitcnt lgkmcnt(3)
	v_pk_mul_f32 v[60:61], v[60:61], v[180:181] op_sel_hi:[1,0]
	v_pk_mul_f32 v[62:63], v[62:63], v[180:181] op_sel_hi:[1,0]
	v_pk_mul_f32 v[56:57], v[56:57], v[180:181] op_sel_hi:[1,0]
	v_pk_mul_f32 v[58:59], v[58:59], v[180:181] op_sel_hi:[1,0]
	v_pk_mul_f32 v[52:53], v[52:53], v[180:181] op_sel_hi:[1,0]
	v_pk_mul_f32 v[54:55], v[54:55], v[180:181] op_sel_hi:[1,0]
	v_pk_mul_f32 v[48:49], v[48:49], v[180:181] op_sel_hi:[1,0]
	v_pk_mul_f32 v[50:51], v[50:51], v[180:181] op_sel_hi:[1,0]
	v_pk_mul_f32 v[192:193], v[60:61], v[188:189] op_sel_hi:[1,0]
	v_pk_mul_f32 v[194:195], v[62:63], v[188:189] op_sel_hi:[1,0]
	v_pk_mul_f32 v[196:197], v[56:57], v[188:189] op_sel_hi:[1,0]
	v_pk_mul_f32 v[198:199], v[58:59], v[188:189] op_sel_hi:[1,0]
	v_exp_f32_e32 v192, v192
	v_exp_f32_e32 v193, v193
	v_exp_f32_e32 v194, v194
	v_exp_f32_e32 v195, v195
	v_exp_f32_e32 v196, v196
	v_exp_f32_e32 v197, v197
	v_exp_f32_e32 v198, v198
	v_exp_f32_e32 v199, v199
	v_add_f32_e32 v192, 1.0, v192
	v_add_f32_e32 v193, 1.0, v193
	v_add_f32_e32 v194, 1.0, v194
	v_add_f32_e32 v195, 1.0, v195
	v_add_f32_e32 v196, 1.0, v196
	v_add_f32_e32 v197, 1.0, v197
	v_add_f32_e32 v198, 1.0, v198
	v_add_f32_e32 v199, 1.0, v199
	v_rcp_f32_e32 v192, v192
	v_rcp_f32_e32 v193, v193
	v_rcp_f32_e32 v194, v194
	v_rcp_f32_e32 v195, v195
	v_rcp_f32_e32 v196, v196
	v_rcp_f32_e32 v197, v197
	v_rcp_f32_e32 v198, v198
	v_rcp_f32_e32 v199, v199
	v_pk_mul_f32 v[60:61], v[60:61], v[192:193]
	v_pk_mul_f32 v[62:63], v[62:63], v[194:195]
	v_pk_mul_f32 v[56:57], v[56:57], v[196:197]
	v_pk_mul_f32 v[58:59], v[58:59], v[198:199]
	v_pk_mul_f32 v[60:61], v[52:53], v[60:61]
	v_pk_mul_f32 v[62:63], v[54:55], v[62:63]
	v_pk_mul_f32 v[56:57], v[48:49], v[56:57]
	v_pk_mul_f32 v[58:59], v[50:51], v[58:59]
	v_cvt_pk_bf16_f32 v208, v60, v61
	v_cvt_pk_bf16_f32 v209, v62, v63
	v_cvt_pk_bf16_f32 v210, v56, v57
	v_cvt_pk_bf16_f32 v211, v58, v59
	s_mov_b64 s[100:101], 0xb0000
	v_lshl_add_u64 v[216:217], v[232:233], 0, s[100:101]
	global_store_dwordx4 v[216:217], v[208:211], off
	s_waitcnt lgkmcnt(2)
	v_pk_mul_f32 v[44:45], v[44:45], v[182:183] op_sel_hi:[1,0]
	v_pk_mul_f32 v[46:47], v[46:47], v[182:183] op_sel_hi:[1,0]
	v_pk_mul_f32 v[40:41], v[40:41], v[182:183] op_sel_hi:[1,0]
	v_pk_mul_f32 v[42:43], v[42:43], v[182:183] op_sel_hi:[1,0]
	v_pk_mul_f32 v[36:37], v[36:37], v[182:183] op_sel_hi:[1,0]
	v_pk_mul_f32 v[38:39], v[38:39], v[182:183] op_sel_hi:[1,0]
	v_pk_mul_f32 v[32:33], v[32:33], v[182:183] op_sel_hi:[1,0]
	v_pk_mul_f32 v[34:35], v[34:35], v[182:183] op_sel_hi:[1,0]
	v_pk_mul_f32 v[200:201], v[44:45], v[188:189] op_sel_hi:[1,0]
	v_pk_mul_f32 v[202:203], v[46:47], v[188:189] op_sel_hi:[1,0]
	v_pk_mul_f32 v[204:205], v[40:41], v[188:189] op_sel_hi:[1,0]
	v_pk_mul_f32 v[206:207], v[42:43], v[188:189] op_sel_hi:[1,0]
	v_exp_f32_e32 v200, v200
	v_exp_f32_e32 v201, v201
	v_exp_f32_e32 v202, v202
	v_exp_f32_e32 v203, v203
	v_exp_f32_e32 v204, v204
	v_exp_f32_e32 v205, v205
	v_exp_f32_e32 v206, v206
	v_exp_f32_e32 v207, v207
	v_add_f32_e32 v200, 1.0, v200
	v_add_f32_e32 v201, 1.0, v201
	v_add_f32_e32 v202, 1.0, v202
	v_add_f32_e32 v203, 1.0, v203
	v_add_f32_e32 v204, 1.0, v204
	v_add_f32_e32 v205, 1.0, v205
	v_add_f32_e32 v206, 1.0, v206
	v_add_f32_e32 v207, 1.0, v207
	v_rcp_f32_e32 v200, v200
	v_rcp_f32_e32 v201, v201
	v_rcp_f32_e32 v202, v202
	v_rcp_f32_e32 v203, v203
	v_rcp_f32_e32 v204, v204
	v_rcp_f32_e32 v205, v205
	v_rcp_f32_e32 v206, v206
	v_rcp_f32_e32 v207, v207
	v_pk_mul_f32 v[44:45], v[44:45], v[200:201]
	v_pk_mul_f32 v[46:47], v[46:47], v[202:203]
	v_pk_mul_f32 v[40:41], v[40:41], v[204:205]
	v_pk_mul_f32 v[42:43], v[42:43], v[206:207]
	v_pk_mul_f32 v[44:45], v[36:37], v[44:45]
	v_pk_mul_f32 v[46:47], v[38:39], v[46:47]
	v_pk_mul_f32 v[40:41], v[32:33], v[40:41]
	v_pk_mul_f32 v[42:43], v[34:35], v[42:43]
	v_cvt_pk_bf16_f32 v212, v44, v45
	v_cvt_pk_bf16_f32 v213, v46, v47
	v_cvt_pk_bf16_f32 v214, v40, v41
	v_cvt_pk_bf16_f32 v215, v42, v43
	s_mov_b64 s[100:101], 0xc6000
	v_lshl_add_u64 v[216:217], v[232:233], 0, s[100:101]
	global_store_dwordx4 v[216:217], v[212:215], off
	s_waitcnt lgkmcnt(1)
	v_pk_mul_f32 v[28:29], v[28:29], v[184:185] op_sel_hi:[1,0]
	v_pk_mul_f32 v[30:31], v[30:31], v[184:185] op_sel_hi:[1,0]
	v_pk_mul_f32 v[24:25], v[24:25], v[184:185] op_sel_hi:[1,0]
	v_pk_mul_f32 v[26:27], v[26:27], v[184:185] op_sel_hi:[1,0]
	v_pk_mul_f32 v[20:21], v[20:21], v[184:185] op_sel_hi:[1,0]
	v_pk_mul_f32 v[22:23], v[22:23], v[184:185] op_sel_hi:[1,0]
	v_pk_mul_f32 v[16:17], v[16:17], v[184:185] op_sel_hi:[1,0]
	v_pk_mul_f32 v[18:19], v[18:19], v[184:185] op_sel_hi:[1,0]
	v_pk_mul_f32 v[192:193], v[28:29], v[188:189] op_sel_hi:[1,0]
	v_pk_mul_f32 v[194:195], v[30:31], v[188:189] op_sel_hi:[1,0]
	v_pk_mul_f32 v[196:197], v[24:25], v[188:189] op_sel_hi:[1,0]
	v_pk_mul_f32 v[198:199], v[26:27], v[188:189] op_sel_hi:[1,0]
	v_exp_f32_e32 v192, v192
	v_exp_f32_e32 v193, v193
	v_exp_f32_e32 v194, v194
	v_exp_f32_e32 v195, v195
	v_exp_f32_e32 v196, v196
	v_exp_f32_e32 v197, v197
	v_exp_f32_e32 v198, v198
	v_exp_f32_e32 v199, v199
	v_add_f32_e32 v192, 1.0, v192
	v_add_f32_e32 v193, 1.0, v193
	v_add_f32_e32 v194, 1.0, v194
	v_add_f32_e32 v195, 1.0, v195
	v_add_f32_e32 v196, 1.0, v196
	v_add_f32_e32 v197, 1.0, v197
	v_add_f32_e32 v198, 1.0, v198
	v_add_f32_e32 v199, 1.0, v199
	v_rcp_f32_e32 v192, v192
	v_rcp_f32_e32 v193, v193
	v_rcp_f32_e32 v194, v194
	v_rcp_f32_e32 v195, v195
	v_rcp_f32_e32 v196, v196
	v_rcp_f32_e32 v197, v197
	v_rcp_f32_e32 v198, v198
	v_rcp_f32_e32 v199, v199
	v_pk_mul_f32 v[28:29], v[28:29], v[192:193]
	v_pk_mul_f32 v[30:31], v[30:31], v[194:195]
	v_pk_mul_f32 v[24:25], v[24:25], v[196:197]
	v_pk_mul_f32 v[26:27], v[26:27], v[198:199]
	v_pk_mul_f32 v[28:29], v[20:21], v[28:29]
	v_pk_mul_f32 v[30:31], v[22:23], v[30:31]
	v_pk_mul_f32 v[24:25], v[16:17], v[24:25]
	v_pk_mul_f32 v[26:27], v[18:19], v[26:27]
	v_cvt_pk_bf16_f32 v208, v28, v29
	v_cvt_pk_bf16_f32 v209, v30, v31
	v_cvt_pk_bf16_f32 v210, v24, v25
	v_cvt_pk_bf16_f32 v211, v26, v27
	s_mov_b64 s[100:101], 0xdc000
	v_lshl_add_u64 v[216:217], v[232:233], 0, s[100:101]
	global_store_dwordx4 v[216:217], v[208:211], off
	s_waitcnt lgkmcnt(0)
	v_pk_mul_f32 v[12:13], v[12:13], v[186:187] op_sel_hi:[1,0]
	v_pk_mul_f32 v[14:15], v[14:15], v[186:187] op_sel_hi:[1,0]
	v_pk_mul_f32 v[8:9], v[8:9], v[186:187] op_sel_hi:[1,0]
	v_pk_mul_f32 v[10:11], v[10:11], v[186:187] op_sel_hi:[1,0]
	v_pk_mul_f32 v[4:5], v[4:5], v[186:187] op_sel_hi:[1,0]
	v_pk_mul_f32 v[6:7], v[6:7], v[186:187] op_sel_hi:[1,0]
	v_pk_mul_f32 v[0:1], v[0:1], v[186:187] op_sel_hi:[1,0]
	v_pk_mul_f32 v[2:3], v[2:3], v[186:187] op_sel_hi:[1,0]
	v_pk_mul_f32 v[200:201], v[12:13], v[188:189] op_sel_hi:[1,0]
	v_pk_mul_f32 v[202:203], v[14:15], v[188:189] op_sel_hi:[1,0]
	v_pk_mul_f32 v[204:205], v[8:9], v[188:189] op_sel_hi:[1,0]
	v_pk_mul_f32 v[206:207], v[10:11], v[188:189] op_sel_hi:[1,0]
	v_exp_f32_e32 v200, v200
	v_exp_f32_e32 v201, v201
	v_exp_f32_e32 v202, v202
	v_exp_f32_e32 v203, v203
	v_exp_f32_e32 v204, v204
	v_exp_f32_e32 v205, v205
	v_exp_f32_e32 v206, v206
	v_exp_f32_e32 v207, v207
	v_add_f32_e32 v200, 1.0, v200
	v_add_f32_e32 v201, 1.0, v201
	v_add_f32_e32 v202, 1.0, v202
	v_add_f32_e32 v203, 1.0, v203
	v_add_f32_e32 v204, 1.0, v204
	v_add_f32_e32 v205, 1.0, v205
	v_add_f32_e32 v206, 1.0, v206
	v_add_f32_e32 v207, 1.0, v207
	v_rcp_f32_e32 v200, v200
	v_rcp_f32_e32 v201, v201
	v_rcp_f32_e32 v202, v202
	v_rcp_f32_e32 v203, v203
	v_rcp_f32_e32 v204, v204
	v_rcp_f32_e32 v205, v205
	v_rcp_f32_e32 v206, v206
	v_rcp_f32_e32 v207, v207
	v_pk_mul_f32 v[12:13], v[12:13], v[200:201]
	v_pk_mul_f32 v[14:15], v[14:15], v[202:203]
	v_pk_mul_f32 v[8:9], v[8:9], v[204:205]
	v_pk_mul_f32 v[10:11], v[10:11], v[206:207]
	v_pk_mul_f32 v[12:13], v[4:5], v[12:13]
	v_pk_mul_f32 v[14:15], v[6:7], v[14:15]
	v_pk_mul_f32 v[8:9], v[0:1], v[8:9]
	v_pk_mul_f32 v[10:11], v[2:3], v[10:11]
	v_cvt_pk_bf16_f32 v212, v12, v13
	v_cvt_pk_bf16_f32 v213, v14, v15
	v_cvt_pk_bf16_f32 v214, v8, v9
	v_cvt_pk_bf16_f32 v215, v10, v11
	s_mov_b64 s[100:101], 0xf2000
	v_lshl_add_u64 v[216:217], v[232:233], 0, s[100:101]
	global_store_dwordx4 v[216:217], v[212:215], off
	s_andn2_b64 vcc, exec, s[4:5]
	s_mov_b64 s[4:5], -1
	s_cbranch_vccnz .LBB0_1643
	s_andn2_b64 vcc, exec, s[0:1]
	s_cbranch_vccnz .LBB0_1642
	s_barrier
	s_branch .LBB0_1642

.LBB0_1722:
	s_add_i32 s54, s54, 1
	s_mul_i32 s0, s54, s49
	s_mul_hi_u32 s1, s54, s50
	s_add_i32 s1, s1, s0
	s_mul_i32 s0, s54, s50
	s_add_u32 s6, s0, s2
	s_addc_u32 s7, s1, s51
	v_cmp_gt_i64_e32 vcc, s[6:7], v[144:145]
	v_cmp_lt_i64_e64 s[0:1], s[6:7], v[142:143]
	s_cbranch_vccnz .LBB0_1728
	s_and_b32 s100, s6, 7
	s_mul_i32 s100, s100, 0x40
	s_lshr_b32 s101, s6, 3
	s_add_i32 s100, s100, s101
	s_mul_hi_u32 s101, s100, 0x8000000
	s_mul_i32 s55, s101, 0x20
	s_sub_i32 s55, s100, s55
	s_and_b32 s100, s55, 7
	s_lshl_b32 s56, s101, 3
	s_add_i32 s56, s56, s100
	s_lshr_b32 s55, s55, 3

.LBB0_1732:
	s_add_u32 s30, s30, 0xb0080
	s_addc_u32 s31, s31, 0
	s_add_u32 s13, s36, 0x100
	s_addc_u32 s57, s37, 0
	s_mov_b32 s58, -2
	s_waitcnt lgkmcnt(0)
	ds_read_b128 v[146:149], v153
	ds_read_b128 v[158:161], v153 offset:1024
	ds_read_b128 v[162:165], v153 offset:2048
	ds_read_b128 v[166:169], v153 offset:3072
	ds_read_b128 v[170:173], v154
	ds_read_b128 v[174:177], v154 offset:1024
	ds_read_b128 v[178:181], v154 offset:2048
	ds_read_b128 v[182:185], v154 offset:3072
	s_add_u32 s34, s30, 0xfff50080
	s_addc_u32 s35, s31, -1
	s_cmp_eq_u32 s58, 40
	s_cselect_b32 s39, s1, s35
	s_cselect_b32 s38, s0, s34
	s_cselect_b32 s37, s29, s57
	s_cselect_b32 s36, s28, s13
	v_lshl_add_u64 v[218:219], s[30:31], 0, v[138:139]
	s_add_i32 m0, s42, 0xc000
	ds_read_b128 v[186:189], v155
	ds_read_b128 v[190:193], v155 offset:1024
	ds_read_b128 v[194:197], v155 offset:2048
	ds_read_b128 v[198:201], v155 offset:3072
	ds_read_b128 v[202:205], v155 offset:4096
	ds_read_b128 v[206:209], v155 offset:5120
	ds_read_b128 v[210:213], v155 offset:6144
	ds_read_b128 v[214:217], v155 offset:7168
	global_load_lds_dwordx4 v[218:219], off
	v_lshl_add_u64 v[218:219], s[30:31], 0, v[140:141]
	s_add_i32 m0, s42, 0xe000
	s_nop 0
	global_load_lds_dwordx4 v[218:219], off
	s_waitcnt vmcnt(8)
	s_waitcnt lgkmcnt(0)
	s_barrier
	s_setprio 1
	s_waitcnt lgkmcnt(0)
	v_mfma_f32_16x16x32_bf16 v[124:127], v[146:149], v[186:189], 0
	v_mfma_f32_16x16x32_bf16 v[120:123], v[162:165], v[186:189], 0
	v_mfma_f32_16x16x32_bf16 v[108:111], v[146:149], v[194:197], 0
	v_mfma_f32_16x16x32_bf16 v[104:107], v[162:165], v[194:197], 0
	v_mfma_f32_16x16x32_bf16 v[92:95], v[146:149], v[202:205], 0
	v_mfma_f32_16x16x32_bf16 v[88:91], v[162:165], v[202:205], 0
	v_mfma_f32_16x16x32_bf16 v[76:79], v[146:149], v[210:213], 0
	v_mfma_f32_16x16x32_bf16 v[72:75], v[162:165], v[210:213], 0
	v_mfma_f32_16x16x32_bf16 v[124:127], v[158:161], v[190:193], v[124:127]
	v_mfma_f32_16x16x32_bf16 v[120:123], v[166:169], v[190:193], v[120:123]
	v_mfma_f32_16x16x32_bf16 v[108:111], v[158:161], v[198:201], v[108:111]
	v_mfma_f32_16x16x32_bf16 v[104:107], v[166:169], v[198:201], v[104:107]
	v_mfma_f32_16x16x32_bf16 v[92:95], v[158:161], v[206:209], v[92:95]
	v_mfma_f32_16x16x32_bf16 v[88:91], v[166:169], v[206:209], v[88:91]
	v_mfma_f32_16x16x32_bf16 v[76:79], v[158:161], v[214:217], v[76:79]
	v_mfma_f32_16x16x32_bf16 v[72:75], v[166:169], v[214:217], v[72:75]
	s_setprio 0
	s_setprio 1
	v_mfma_f32_16x16x32_bf16 v[116:119], v[170:173], v[186:189], 0
	v_mfma_f32_16x16x32_bf16 v[112:115], v[178:181], v[186:189], 0
	v_mfma_f32_16x16x32_bf16 v[100:103], v[170:173], v[194:197], 0
	v_mfma_f32_16x16x32_bf16 v[96:99], v[178:181], v[194:197], 0
	v_mfma_f32_16x16x32_bf16 v[84:87], v[170:173], v[202:205], 0
	v_mfma_f32_16x16x32_bf16 v[80:83], v[178:181], v[202:205], 0
	v_mfma_f32_16x16x32_bf16 v[68:71], v[170:173], v[210:213], 0
	v_mfma_f32_16x16x32_bf16 v[64:67], v[178:181], v[210:213], 0
	v_mfma_f32_16x16x32_bf16 v[116:119], v[174:177], v[190:193], v[116:119]
	v_mfma_f32_16x16x32_bf16 v[112:115], v[182:185], v[190:193], v[112:115]
	v_mfma_f32_16x16x32_bf16 v[100:103], v[174:177], v[198:201], v[100:103]
	v_mfma_f32_16x16x32_bf16 v[96:99], v[182:185], v[198:201], v[96:99]
	v_mfma_f32_16x16x32_bf16 v[84:87], v[174:177], v[206:209], v[84:87]
	v_mfma_f32_16x16x32_bf16 v[80:83], v[182:185], v[206:209], v[80:83]
	v_mfma_f32_16x16x32_bf16 v[68:71], v[174:177], v[214:217], v[68:71]
	v_mfma_f32_16x16x32_bf16 v[64:67], v[182:185], v[214:217], v[64:67]
	s_setprio 0
	s_barrier
	s_add_i32 s34, s52, s41
	v_lshl_add_u64 v[218:219], s[36:37], 0, v[132:133]
	s_mov_b32 m0, s34
	ds_read_b128 v[186:189], v155 offset:16384
	ds_read_b128 v[190:193], v155 offset:17408
	ds_read_b128 v[194:197], v155 offset:18432
	ds_read_b128 v[198:201], v155 offset:19456
	ds_read_b128 v[202:205], v155 offset:20480
	ds_read_b128 v[206:209], v155 offset:21504
	ds_read_b128 v[210:213], v155 offset:22528
	ds_read_b128 v[214:217], v155 offset:23552
	global_load_lds_dwordx4 v[218:219], off
	s_add_i32 m0, s34, 0x2000
	s_add_u32 s34, s36, 0xb0000
	v_lshl_add_u64 v[220:221], s[36:37], 0, v[136:137]
	s_addc_u32 s35, s37, 0
	s_add_i32 s59, s53, s41
	global_load_lds_dwordx4 v[220:221], off
	v_lshl_add_u64 v[222:223], s[34:35], 0, v[132:133]
	s_mov_b32 m0, s59
	v_lshl_add_u64 v[224:225], s[38:39], 0, v[134:135]
	global_load_lds_dwordx4 v[222:223], off
	v_lshl_add_u64 v[222:223], s[34:35], 0, v[136:137]
	s_add_i32 m0, s59, 0x2000
	s_nop 0
	global_load_lds_dwordx4 v[222:223], off
	v_lshl_add_u64 v[222:223], s[38:39], 0, v[130:131]
	s_mov_b32 m0, s42
	s_nop 0
	global_load_lds_dwordx4 v[222:223], off
	s_mov_b32 m0, s43
	s_nop 0
	global_load_lds_dwordx4 v[224:225], off
	s_waitcnt vmcnt(8)
	s_waitcnt lgkmcnt(0)
	s_barrier
	s_setprio 1
	s_waitcnt lgkmcnt(0)
	v_mfma_f32_16x16x32_bf16 v[60:63], v[146:149], v[186:189], 0
	v_mfma_f32_16x16x32_bf16 v[56:59], v[162:165], v[186:189], 0
	v_mfma_f32_16x16x32_bf16 v[44:47], v[146:149], v[194:197], 0
	v_mfma_f32_16x16x32_bf16 v[40:43], v[162:165], v[194:197], 0
	v_mfma_f32_16x16x32_bf16 v[28:31], v[146:149], v[202:205], 0
	v_mfma_f32_16x16x32_bf16 v[24:27], v[162:165], v[202:205], 0
	v_mfma_f32_16x16x32_bf16 v[12:15], v[146:149], v[210:213], 0
	v_mfma_f32_16x16x32_bf16 v[8:11], v[162:165], v[210:213], 0
	v_mfma_f32_16x16x32_bf16 v[60:63], v[158:161], v[190:193], v[60:63]
	v_mfma_f32_16x16x32_bf16 v[56:59], v[166:169], v[190:193], v[56:59]
	v_mfma_f32_16x16x32_bf16 v[44:47], v[158:161], v[198:201], v[44:47]
	v_mfma_f32_16x16x32_bf16 v[40:43], v[166:169], v[198:201], v[40:43]
	v_mfma_f32_16x16x32_bf16 v[28:31], v[158:161], v[206:209], v[28:31]
	v_mfma_f32_16x16x32_bf16 v[24:27], v[166:169], v[206:209], v[24:27]
	v_mfma_f32_16x16x32_bf16 v[12:15], v[158:161], v[214:217], v[12:15]
	v_mfma_f32_16x16x32_bf16 v[8:11], v[166:169], v[214:217], v[8:11]
	s_setprio 0
	s_setprio 1
	v_mfma_f32_16x16x32_bf16 v[52:55], v[170:173], v[186:189], 0
	v_mfma_f32_16x16x32_bf16 v[48:51], v[178:181], v[186:189], 0
	v_mfma_f32_16x16x32_bf16 v[36:39], v[170:173], v[194:197], 0
	v_mfma_f32_16x16x32_bf16 v[32:35], v[178:181], v[194:197], 0
	v_mfma_f32_16x16x32_bf16 v[20:23], v[170:173], v[202:205], 0
	v_mfma_f32_16x16x32_bf16 v[16:19], v[178:181], v[202:205], 0
	v_mfma_f32_16x16x32_bf16 v[4:7], v[170:173], v[210:213], 0
	v_mfma_f32_16x16x32_bf16 v[0:3], v[178:181], v[210:213], 0
	v_mfma_f32_16x16x32_bf16 v[52:55], v[174:177], v[190:193], v[52:55]
	v_mfma_f32_16x16x32_bf16 v[48:51], v[182:185], v[190:193], v[48:51]
	v_mfma_f32_16x16x32_bf16 v[36:39], v[174:177], v[198:201], v[36:39]
	v_mfma_f32_16x16x32_bf16 v[32:35], v[182:185], v[198:201], v[32:35]
	v_mfma_f32_16x16x32_bf16 v[20:23], v[174:177], v[206:209], v[20:23]
	v_mfma_f32_16x16x32_bf16 v[16:19], v[182:185], v[206:209], v[16:19]
	v_mfma_f32_16x16x32_bf16 v[4:7], v[174:177], v[214:217], v[4:7]
	v_mfma_f32_16x16x32_bf16 v[0:3], v[182:185], v[214:217], v[0:3]
	s_setprio 0
	s_barrier
	s_add_i32 s59, 0, 0x18000
	s_add_i32 s60, 0, 0x1c000
	v_add_u32_e32 v166, s59, v151
	v_add_u32_e32 v182, s60, v151
	ds_read_b128 v[146:149], v166
	ds_read_b128 v[158:161], v166 offset:1024
	ds_read_b128 v[162:165], v166 offset:2048
	ds_read_b128 v[166:169], v166 offset:3072
	ds_read_b128 v[170:173], v182
	ds_read_b128 v[174:177], v182 offset:1024
	ds_read_b128 v[178:181], v182 offset:2048
	ds_read_b128 v[182:185], v182 offset:3072
	s_add_u32 s34, s38, 0xb0000
	s_addc_u32 s35, s39, 0
	s_mov_b32 m0, s44
	v_lshl_add_u64 v[226:227], s[34:35], 0, v[130:131]
	ds_read_b128 v[186:189], v155 offset:32768
	ds_read_b128 v[190:193], v155 offset:33792
	ds_read_b128 v[194:197], v155 offset:34816
	ds_read_b128 v[198:201], v155 offset:35840
	ds_read_b128 v[202:205], v155 offset:36864
	ds_read_b128 v[206:209], v155 offset:37888
	ds_read_b128 v[210:213], v155 offset:38912
	ds_read_b128 v[214:217], v155 offset:39936
	global_load_lds_dwordx4 v[226:227], off
	v_lshl_add_u64 v[226:227], s[34:35], 0, v[134:135]
	s_mov_b32 m0, s45
	s_nop 0
	global_load_lds_dwordx4 v[226:227], off
	s_waitcnt vmcnt(8)
	s_waitcnt lgkmcnt(0)
	s_barrier
	s_setprio 1
	s_waitcnt lgkmcnt(0)
	v_mfma_f32_16x16x32_bf16 v[124:127], v[146:149], v[186:189], v[124:127]
	v_mfma_f32_16x16x32_bf16 v[120:123], v[162:165], v[186:189], v[120:123]
	v_mfma_f32_16x16x32_bf16 v[108:111], v[146:149], v[194:197], v[108:111]
	v_mfma_f32_16x16x32_bf16 v[104:107], v[162:165], v[194:197], v[104:107]
	v_mfma_f32_16x16x32_bf16 v[92:95], v[146:149], v[202:205], v[92:95]
	v_mfma_f32_16x16x32_bf16 v[88:91], v[162:165], v[202:205], v[88:91]
	v_mfma_f32_16x16x32_bf16 v[76:79], v[146:149], v[210:213], v[76:79]
	v_mfma_f32_16x16x32_bf16 v[72:75], v[162:165], v[210:213], v[72:75]
	v_mfma_f32_16x16x32_bf16 v[124:127], v[158:161], v[190:193], v[124:127]
	v_mfma_f32_16x16x32_bf16 v[120:123], v[166:169], v[190:193], v[120:123]
	v_mfma_f32_16x16x32_bf16 v[108:111], v[158:161], v[198:201], v[108:111]
	v_mfma_f32_16x16x32_bf16 v[104:107], v[166:169], v[198:201], v[104:107]
	v_mfma_f32_16x16x32_bf16 v[92:95], v[158:161], v[206:209], v[92:95]
	v_mfma_f32_16x16x32_bf16 v[88:91], v[166:169], v[206:209], v[88:91]
	v_mfma_f32_16x16x32_bf16 v[76:79], v[158:161], v[214:217], v[76:79]
	v_mfma_f32_16x16x32_bf16 v[72:75], v[166:169], v[214:217], v[72:75]
	s_setprio 0
	s_setprio 1
	v_mfma_f32_16x16x32_bf16 v[116:119], v[170:173], v[186:189], v[116:119]
	v_mfma_f32_16x16x32_bf16 v[112:115], v[178:181], v[186:189], v[112:115]
	v_mfma_f32_16x16x32_bf16 v[100:103], v[170:173], v[194:197], v[100:103]
	v_mfma_f32_16x16x32_bf16 v[96:99], v[178:181], v[194:197], v[96:99]
	v_mfma_f32_16x16x32_bf16 v[84:87], v[170:173], v[202:205], v[84:87]
	v_mfma_f32_16x16x32_bf16 v[80:83], v[178:181], v[202:205], v[80:83]
	v_mfma_f32_16x16x32_bf16 v[68:71], v[170:173], v[210:213], v[68:71]
	v_mfma_f32_16x16x32_bf16 v[64:67], v[178:181], v[210:213], v[64:67]
	v_mfma_f32_16x16x32_bf16 v[116:119], v[174:177], v[190:193], v[116:119]
	v_mfma_f32_16x16x32_bf16 v[112:115], v[182:185], v[190:193], v[112:115]
	v_mfma_f32_16x16x32_bf16 v[100:103], v[174:177], v[198:201], v[100:103]
	v_mfma_f32_16x16x32_bf16 v[96:99], v[182:185], v[198:201], v[96:99]
	v_mfma_f32_16x16x32_bf16 v[84:87], v[174:177], v[206:209], v[84:87]
	v_mfma_f32_16x16x32_bf16 v[80:83], v[182:185], v[206:209], v[80:83]
	v_mfma_f32_16x16x32_bf16 v[68:71], v[174:177], v[214:217], v[68:71]
	v_mfma_f32_16x16x32_bf16 v[64:67], v[182:185], v[214:217], v[64:67]
	s_setprio 0
	s_barrier
	s_add_i32 s34, s59, s41
	v_lshl_add_u64 v[218:219], v[218:219], 0, s[22:23]
	s_mov_b32 m0, s34
	ds_read_b128 v[186:189], v155 offset:49152
	ds_read_b128 v[190:193], v155 offset:50176
	ds_read_b128 v[194:197], v155 offset:51200
	ds_read_b128 v[198:201], v155 offset:52224
	ds_read_b128 v[202:205], v155 offset:53248
	ds_read_b128 v[206:209], v155 offset:54272
	ds_read_b128 v[210:213], v155 offset:55296
	ds_read_b128 v[214:217], v155 offset:56320
	global_load_lds_dwordx4 v[218:219], off
	s_add_i32 m0, s34, 0x2000
	s_add_u32 s34, s36, 0xb0080
	v_lshl_add_u64 v[218:219], v[220:221], 0, s[22:23]
	s_addc_u32 s35, s37, 0
	s_add_i32 s36, s60, s41
	global_load_lds_dwordx4 v[218:219], off
	v_lshl_add_u64 v[218:219], s[34:35], 0, v[132:133]
	s_mov_b32 m0, s36
	s_nop 0
	global_load_lds_dwordx4 v[218:219], off
	v_lshl_add_u64 v[218:219], s[34:35], 0, v[136:137]
	s_add_i32 m0, s36, 0x2000
	s_nop 0
	global_load_lds_dwordx4 v[218:219], off
	v_lshl_add_u64 v[218:219], v[222:223], 0, s[22:23]
	s_mov_b32 m0, s47
	s_nop 0
	global_load_lds_dwordx4 v[218:219], off
	v_lshl_add_u64 v[218:219], v[224:225], 0, s[22:23]
	s_mov_b32 m0, s48
	s_nop 0
	global_load_lds_dwordx4 v[218:219], off
	s_waitcnt vmcnt(8)
	s_waitcnt lgkmcnt(0)
	s_barrier
	s_setprio 1
	s_waitcnt lgkmcnt(0)
	v_mfma_f32_16x16x32_bf16 v[60:63], v[146:149], v[186:189], v[60:63]
	v_mfma_f32_16x16x32_bf16 v[56:59], v[162:165], v[186:189], v[56:59]
	v_mfma_f32_16x16x32_bf16 v[44:47], v[146:149], v[194:197], v[44:47]
	v_mfma_f32_16x16x32_bf16 v[40:43], v[162:165], v[194:197], v[40:43]
	v_mfma_f32_16x16x32_bf16 v[28:31], v[146:149], v[202:205], v[28:31]
	v_mfma_f32_16x16x32_bf16 v[24:27], v[162:165], v[202:205], v[24:27]
	v_mfma_f32_16x16x32_bf16 v[12:15], v[146:149], v[210:213], v[12:15]
	v_mfma_f32_16x16x32_bf16 v[8:11], v[162:165], v[210:213], v[8:11]
	v_mfma_f32_16x16x32_bf16 v[60:63], v[158:161], v[190:193], v[60:63]
	v_mfma_f32_16x16x32_bf16 v[56:59], v[166:169], v[190:193], v[56:59]
	v_mfma_f32_16x16x32_bf16 v[44:47], v[158:161], v[198:201], v[44:47]
	v_mfma_f32_16x16x32_bf16 v[40:43], v[166:169], v[198:201], v[40:43]
	v_mfma_f32_16x16x32_bf16 v[28:31], v[158:161], v[206:209], v[28:31]
	v_mfma_f32_16x16x32_bf16 v[24:27], v[166:169], v[206:209], v[24:27]
	v_mfma_f32_16x16x32_bf16 v[12:15], v[158:161], v[214:217], v[12:15]
	v_mfma_f32_16x16x32_bf16 v[8:11], v[166:169], v[214:217], v[8:11]
	s_setprio 0
	s_setprio 1
	v_mfma_f32_16x16x32_bf16 v[52:55], v[170:173], v[186:189], v[52:55]
	v_mfma_f32_16x16x32_bf16 v[48:51], v[178:181], v[186:189], v[48:51]
	v_mfma_f32_16x16x32_bf16 v[36:39], v[170:173], v[194:197], v[36:39]
	v_mfma_f32_16x16x32_bf16 v[32:35], v[178:181], v[194:197], v[32:35]
	v_mfma_f32_16x16x32_bf16 v[20:23], v[170:173], v[202:205], v[20:23]
	v_mfma_f32_16x16x32_bf16 v[16:19], v[178:181], v[202:205], v[16:19]
	v_mfma_f32_16x16x32_bf16 v[4:7], v[170:173], v[210:213], v[4:7]
	v_mfma_f32_16x16x32_bf16 v[0:3], v[178:181], v[210:213], v[0:3]
	v_mfma_f32_16x16x32_bf16 v[52:55], v[174:177], v[190:193], v[52:55]
	v_mfma_f32_16x16x32_bf16 v[48:51], v[182:185], v[190:193], v[48:51]
	v_mfma_f32_16x16x32_bf16 v[36:39], v[174:177], v[198:201], v[36:39]
	v_mfma_f32_16x16x32_bf16 v[32:35], v[182:185], v[198:201], v[32:35]
	v_mfma_f32_16x16x32_bf16 v[20:23], v[174:177], v[206:209], v[20:23]
	v_mfma_f32_16x16x32_bf16 v[16:19], v[182:185], v[206:209], v[16:19]
	v_mfma_f32_16x16x32_bf16 v[4:7], v[174:177], v[214:217], v[4:7]
	v_mfma_f32_16x16x32_bf16 v[0:3], v[182:185], v[214:217], v[0:3]
	s_setprio 0
	s_barrier
	s_add_i32 s58, s58, 2
	s_add_u32 s30, s30, 0x100
	s_addc_u32 s31, s31, 0
	s_add_u32 s13, s13, 0x100
	s_addc_u32 s57, s57, 0

.LBB0_1823:
	s_add_i32 s63, s63, 1
	s_mul_i32 s4, s63, s48
	s_mul_hi_u32 s5, s63, s49
	s_add_i32 s5, s5, s4
	s_mul_i32 s4, s63, s49
	s_add_u32 s38, s4, s2
	s_addc_u32 s39, s5, s3
	v_cmp_gt_i64_e32 vcc, s[38:39], v[148:149]
	v_cmp_lt_i64_e64 s[4:5], s[38:39], v[146:147]
	s_cbranch_vccnz .LBB0_1825
	s_and_b32 s100, s38, 7
	s_mul_i32 s100, s100, 0xc0
	s_lshr_b32 s101, s38, 3
	s_add_i32 s100, s100, s101
	s_mul_hi_u32 s101, s100, 0x2aaaaab
	s_mul_i32 s30, s101, 0x60
	s_sub_i32 s30, s100, s30
	s_and_b32 s100, s30, 7
	s_lshl_b32 s36, s101, 3
	s_add_i32 s36, s36, s100
	s_lshr_b32 s30, s30, 3
	s_mov_b32 s64, s63
.LBB0_1825:
	s_ashr_i32 s37, s36, 31
	s_lshl_b64 s[12:13], s[36:37], 19
	s_add_u32 s38, s14, s12
	s_addc_u32 s39, s15, s13
	s_and_b64 s[12:13], s[4:5], exec
	s_cselect_b32 s7, s39, s43
	s_cselect_b32 s8, s38, s42
	s_ashr_i32 s31, s30, 31
	s_lshl_b64 s[12:13], s[30:31], 19
	s_add_u32 s40, s51, s12
	s_addc_u32 s41, s52, s13
	s_and_b64 s[12:13], s[4:5], exec
	s_cselect_b32 s12, s41, s45
	s_cselect_b32 s13, s40, s44
	s_add_u32 s42, s42, 0x40080
	s_addc_u32 s43, s43, 0
	s_add_u32 s31, s44, 0x100
	s_addc_u32 s37, s45, 0
	s_mov_b32 s65, -2
	s_waitcnt lgkmcnt(0)
	ds_read_b128 v[150:153], v157
	ds_read_b128 v[160:163], v157 offset:1024
	ds_read_b128 v[164:167], v157 offset:2048
	ds_read_b128 v[168:171], v157 offset:3072
	ds_read_b128 v[172:175], v158
	ds_read_b128 v[176:179], v158 offset:1024
	ds_read_b128 v[180:183], v158 offset:2048
	ds_read_b128 v[184:187], v158 offset:3072
	s_add_u32 s34, s42, 0xfffc0080
	s_addc_u32 s35, s43, -1
	s_cmp_eq_u32 s65, 12
	s_cselect_b32 s47, s7, s35
	s_cselect_b32 s46, s8, s34
	s_cselect_b32 s45, s12, s37
	s_cselect_b32 s44, s13, s31
	v_lshl_add_u64 v[220:221], s[42:43], 0, v[142:143]
	s_add_i32 m0, s53, 0xc000
	ds_read_b128 v[188:191], v159
	ds_read_b128 v[192:195], v159 offset:1024
	ds_read_b128 v[196:199], v159 offset:2048
	ds_read_b128 v[200:203], v159 offset:3072
	ds_read_b128 v[204:207], v159 offset:4096
	ds_read_b128 v[208:211], v159 offset:5120
	ds_read_b128 v[212:215], v159 offset:6144
	ds_read_b128 v[216:219], v159 offset:7168
	global_load_lds_dwordx4 v[220:221], off
	v_lshl_add_u64 v[220:221], s[42:43], 0, v[144:145]
	s_add_i32 m0, s53, 0xe000
	s_nop 0
	global_load_lds_dwordx4 v[220:221], off
	s_waitcnt vmcnt(8)
	s_waitcnt lgkmcnt(0)
	s_barrier
	s_setprio 1
	s_waitcnt lgkmcnt(0)
	v_mfma_f32_16x16x32_bf16 v[124:127], v[150:153], v[188:191], 0
	v_mfma_f32_16x16x32_bf16 v[120:123], v[164:167], v[188:191], 0
	v_mfma_f32_16x16x32_bf16 v[108:111], v[150:153], v[196:199], 0
	v_mfma_f32_16x16x32_bf16 v[104:107], v[164:167], v[196:199], 0
	v_mfma_f32_16x16x32_bf16 v[92:95], v[150:153], v[204:207], 0
	v_mfma_f32_16x16x32_bf16 v[88:91], v[164:167], v[204:207], 0
	v_mfma_f32_16x16x32_bf16 v[76:79], v[150:153], v[212:215], 0
	v_mfma_f32_16x16x32_bf16 v[72:75], v[164:167], v[212:215], 0
	v_mfma_f32_16x16x32_bf16 v[124:127], v[160:163], v[192:195], v[124:127]
	v_mfma_f32_16x16x32_bf16 v[120:123], v[168:171], v[192:195], v[120:123]
	v_mfma_f32_16x16x32_bf16 v[108:111], v[160:163], v[200:203], v[108:111]
	v_mfma_f32_16x16x32_bf16 v[104:107], v[168:171], v[200:203], v[104:107]
	v_mfma_f32_16x16x32_bf16 v[92:95], v[160:163], v[208:211], v[92:95]
	v_mfma_f32_16x16x32_bf16 v[88:91], v[168:171], v[208:211], v[88:91]
	v_mfma_f32_16x16x32_bf16 v[76:79], v[160:163], v[216:219], v[76:79]
	v_mfma_f32_16x16x32_bf16 v[72:75], v[168:171], v[216:219], v[72:75]
	s_setprio 0
	s_setprio 1
	v_mfma_f32_16x16x32_bf16 v[116:119], v[172:175], v[188:191], 0
	v_mfma_f32_16x16x32_bf16 v[112:115], v[180:183], v[188:191], 0
	v_mfma_f32_16x16x32_bf16 v[100:103], v[172:175], v[196:199], 0
	v_mfma_f32_16x16x32_bf16 v[96:99], v[180:183], v[196:199], 0
	v_mfma_f32_16x16x32_bf16 v[84:87], v[172:175], v[204:207], 0
	v_mfma_f32_16x16x32_bf16 v[80:83], v[180:183], v[204:207], 0
	v_mfma_f32_16x16x32_bf16 v[68:71], v[172:175], v[212:215], 0
	v_mfma_f32_16x16x32_bf16 v[64:67], v[180:183], v[212:215], 0
	v_mfma_f32_16x16x32_bf16 v[116:119], v[176:179], v[192:195], v[116:119]
	v_mfma_f32_16x16x32_bf16 v[112:115], v[184:187], v[192:195], v[112:115]
	v_mfma_f32_16x16x32_bf16 v[100:103], v[176:179], v[200:203], v[100:103]
	v_mfma_f32_16x16x32_bf16 v[96:99], v[184:187], v[200:203], v[96:99]
	v_mfma_f32_16x16x32_bf16 v[84:87], v[176:179], v[208:211], v[84:87]
	v_mfma_f32_16x16x32_bf16 v[80:83], v[184:187], v[208:211], v[80:83]
	v_mfma_f32_16x16x32_bf16 v[68:71], v[176:179], v[216:219], v[68:71]
	v_mfma_f32_16x16x32_bf16 v[64:67], v[184:187], v[216:219], v[64:67]
	s_setprio 0
	s_barrier
	s_add_i32 s34, s61, s50
	v_lshl_add_u64 v[220:221], s[44:45], 0, v[134:135]
	s_mov_b32 m0, s34
	ds_read_b128 v[188:191], v159 offset:16384
	ds_read_b128 v[192:195], v159 offset:17408
	ds_read_b128 v[196:199], v159 offset:18432
	ds_read_b128 v[200:203], v159 offset:19456
	ds_read_b128 v[204:207], v159 offset:20480
	ds_read_b128 v[208:211], v159 offset:21504
	ds_read_b128 v[212:215], v159 offset:22528
	ds_read_b128 v[216:219], v159 offset:23552
	global_load_lds_dwordx4 v[220:221], off
	s_add_i32 m0, s34, 0x2000
	s_add_u32 s34, s44, 0x40000
	v_lshl_add_u64 v[222:223], s[44:45], 0, v[138:139]
	s_addc_u32 s35, s45, 0
	s_add_i32 s66, s62, s50
	global_load_lds_dwordx4 v[222:223], off
	v_lshl_add_u64 v[224:225], s[34:35], 0, v[134:135]
	s_mov_b32 m0, s66
	v_lshl_add_u64 v[226:227], s[46:47], 0, v[136:137]
	global_load_lds_dwordx4 v[224:225], off
	v_lshl_add_u64 v[224:225], s[34:35], 0, v[138:139]
	s_add_i32 m0, s66, 0x2000
	s_nop 0
	global_load_lds_dwordx4 v[224:225], off
	v_lshl_add_u64 v[224:225], s[46:47], 0, v[132:133]
	s_mov_b32 m0, s53
	s_nop 0
	global_load_lds_dwordx4 v[224:225], off
	s_mov_b32 m0, s54
	s_nop 0
	global_load_lds_dwordx4 v[226:227], off
	s_waitcnt vmcnt(8)
	s_waitcnt lgkmcnt(0)
	s_barrier
	s_setprio 1
	s_waitcnt lgkmcnt(0)
	v_mfma_f32_16x16x32_bf16 v[60:63], v[150:153], v[188:191], 0
	v_mfma_f32_16x16x32_bf16 v[56:59], v[164:167], v[188:191], 0
	v_mfma_f32_16x16x32_bf16 v[44:47], v[150:153], v[196:199], 0
	v_mfma_f32_16x16x32_bf16 v[40:43], v[164:167], v[196:199], 0
	v_mfma_f32_16x16x32_bf16 v[28:31], v[150:153], v[204:207], 0
	v_mfma_f32_16x16x32_bf16 v[24:27], v[164:167], v[204:207], 0
	v_mfma_f32_16x16x32_bf16 v[12:15], v[150:153], v[212:215], 0
	v_mfma_f32_16x16x32_bf16 v[8:11], v[164:167], v[212:215], 0
	v_mfma_f32_16x16x32_bf16 v[60:63], v[160:163], v[192:195], v[60:63]
	v_mfma_f32_16x16x32_bf16 v[56:59], v[168:171], v[192:195], v[56:59]
	v_mfma_f32_16x16x32_bf16 v[44:47], v[160:163], v[200:203], v[44:47]
	v_mfma_f32_16x16x32_bf16 v[40:43], v[168:171], v[200:203], v[40:43]
	v_mfma_f32_16x16x32_bf16 v[28:31], v[160:163], v[208:211], v[28:31]
	v_mfma_f32_16x16x32_bf16 v[24:27], v[168:171], v[208:211], v[24:27]
	v_mfma_f32_16x16x32_bf16 v[12:15], v[160:163], v[216:219], v[12:15]
	v_mfma_f32_16x16x32_bf16 v[8:11], v[168:171], v[216:219], v[8:11]
	s_setprio 0
	s_setprio 1
	v_mfma_f32_16x16x32_bf16 v[52:55], v[172:175], v[188:191], 0
	v_mfma_f32_16x16x32_bf16 v[48:51], v[180:183], v[188:191], 0
	v_mfma_f32_16x16x32_bf16 v[36:39], v[172:175], v[196:199], 0
	v_mfma_f32_16x16x32_bf16 v[32:35], v[180:183], v[196:199], 0
	v_mfma_f32_16x16x32_bf16 v[20:23], v[172:175], v[204:207], 0
	v_mfma_f32_16x16x32_bf16 v[16:19], v[180:183], v[204:207], 0
	v_mfma_f32_16x16x32_bf16 v[4:7], v[172:175], v[212:215], 0
	v_mfma_f32_16x16x32_bf16 v[0:3], v[180:183], v[212:215], 0
	v_mfma_f32_16x16x32_bf16 v[52:55], v[176:179], v[192:195], v[52:55]
	v_mfma_f32_16x16x32_bf16 v[48:51], v[184:187], v[192:195], v[48:51]
	v_mfma_f32_16x16x32_bf16 v[36:39], v[176:179], v[200:203], v[36:39]
	v_mfma_f32_16x16x32_bf16 v[32:35], v[184:187], v[200:203], v[32:35]
	v_mfma_f32_16x16x32_bf16 v[20:23], v[176:179], v[208:211], v[20:23]
	v_mfma_f32_16x16x32_bf16 v[16:19], v[184:187], v[208:211], v[16:19]
	v_mfma_f32_16x16x32_bf16 v[4:7], v[176:179], v[216:219], v[4:7]
	v_mfma_f32_16x16x32_bf16 v[0:3], v[184:187], v[216:219], v[0:3]
	s_setprio 0
	s_barrier
	s_add_i32 s66, 0, 0x18000
	v_add_u32_e32 v140, s66, v154
	s_add_i32 s67, 0, 0x1c000
	ds_read_b128 v[150:153], v140
	ds_read_b128 v[160:163], v140 offset:1024
	ds_read_b128 v[164:167], v140 offset:2048
	ds_read_b128 v[168:171], v140 offset:3072
	v_add_u32_e32 v140, s67, v154
	ds_read_b128 v[172:175], v140
	ds_read_b128 v[176:179], v140 offset:1024
	ds_read_b128 v[180:183], v140 offset:2048
	ds_read_b128 v[184:187], v140 offset:3072
	s_add_u32 s34, s46, 0x40000
	s_addc_u32 s35, s47, 0
	s_mov_b32 m0, s55
	v_lshl_add_u64 v[228:229], s[34:35], 0, v[132:133]
	ds_read_b128 v[188:191], v159 offset:32768
	ds_read_b128 v[192:195], v159 offset:33792
	ds_read_b128 v[196:199], v159 offset:34816
	ds_read_b128 v[200:203], v159 offset:35840
	ds_read_b128 v[204:207], v159 offset:36864
	ds_read_b128 v[208:211], v159 offset:37888
	ds_read_b128 v[212:215], v159 offset:38912
	ds_read_b128 v[216:219], v159 offset:39936
	global_load_lds_dwordx4 v[228:229], off
	v_lshl_add_u64 v[228:229], s[34:35], 0, v[136:137]
	s_mov_b32 m0, s56
	s_nop 0
	global_load_lds_dwordx4 v[228:229], off
	s_waitcnt vmcnt(8)
	s_waitcnt lgkmcnt(0)
	s_barrier
	s_setprio 1
	s_waitcnt lgkmcnt(0)
	v_mfma_f32_16x16x32_bf16 v[124:127], v[150:153], v[188:191], v[124:127]
	v_mfma_f32_16x16x32_bf16 v[120:123], v[164:167], v[188:191], v[120:123]
	v_mfma_f32_16x16x32_bf16 v[108:111], v[150:153], v[196:199], v[108:111]
	v_mfma_f32_16x16x32_bf16 v[104:107], v[164:167], v[196:199], v[104:107]
	v_mfma_f32_16x16x32_bf16 v[92:95], v[150:153], v[204:207], v[92:95]
	v_mfma_f32_16x16x32_bf16 v[88:91], v[164:167], v[204:207], v[88:91]
	v_mfma_f32_16x16x32_bf16 v[76:79], v[150:153], v[212:215], v[76:79]
	v_mfma_f32_16x16x32_bf16 v[72:75], v[164:167], v[212:215], v[72:75]
	v_mfma_f32_16x16x32_bf16 v[124:127], v[160:163], v[192:195], v[124:127]
	v_mfma_f32_16x16x32_bf16 v[120:123], v[168:171], v[192:195], v[120:123]
	v_mfma_f32_16x16x32_bf16 v[108:111], v[160:163], v[200:203], v[108:111]
	v_mfma_f32_16x16x32_bf16 v[104:107], v[168:171], v[200:203], v[104:107]
	v_mfma_f32_16x16x32_bf16 v[92:95], v[160:163], v[208:211], v[92:95]
	v_mfma_f32_16x16x32_bf16 v[88:91], v[168:171], v[208:211], v[88:91]
	v_mfma_f32_16x16x32_bf16 v[76:79], v[160:163], v[216:219], v[76:79]
	v_mfma_f32_16x16x32_bf16 v[72:75], v[168:171], v[216:219], v[72:75]
	s_setprio 0
	s_setprio 1
	v_mfma_f32_16x16x32_bf16 v[116:119], v[172:175], v[188:191], v[116:119]
	v_mfma_f32_16x16x32_bf16 v[112:115], v[180:183], v[188:191], v[112:115]
	v_mfma_f32_16x16x32_bf16 v[100:103], v[172:175], v[196:199], v[100:103]
	v_mfma_f32_16x16x32_bf16 v[96:99], v[180:183], v[196:199], v[96:99]
	v_mfma_f32_16x16x32_bf16 v[84:87], v[172:175], v[204:207], v[84:87]
	v_mfma_f32_16x16x32_bf16 v[80:83], v[180:183], v[204:207], v[80:83]
	v_mfma_f32_16x16x32_bf16 v[68:71], v[172:175], v[212:215], v[68:71]
	v_mfma_f32_16x16x32_bf16 v[64:67], v[180:183], v[212:215], v[64:67]
	v_mfma_f32_16x16x32_bf16 v[116:119], v[176:179], v[192:195], v[116:119]
	v_mfma_f32_16x16x32_bf16 v[112:115], v[184:187], v[192:195], v[112:115]
	v_mfma_f32_16x16x32_bf16 v[100:103], v[176:179], v[200:203], v[100:103]
	v_mfma_f32_16x16x32_bf16 v[96:99], v[184:187], v[200:203], v[96:99]
	v_mfma_f32_16x16x32_bf16 v[84:87], v[176:179], v[208:211], v[84:87]
	v_mfma_f32_16x16x32_bf16 v[80:83], v[184:187], v[208:211], v[80:83]
	v_mfma_f32_16x16x32_bf16 v[68:71], v[176:179], v[216:219], v[68:71]
	v_mfma_f32_16x16x32_bf16 v[64:67], v[184:187], v[216:219], v[64:67]
	s_setprio 0
	s_barrier
	s_add_i32 s34, s66, s50
	v_lshl_add_u64 v[220:221], v[220:221], 0, s[26:27]
	s_mov_b32 m0, s34
	ds_read_b128 v[188:191], v159 offset:49152
	ds_read_b128 v[192:195], v159 offset:50176
	ds_read_b128 v[196:199], v159 offset:51200
	ds_read_b128 v[200:203], v159 offset:52224
	ds_read_b128 v[204:207], v159 offset:53248
	ds_read_b128 v[208:211], v159 offset:54272
	ds_read_b128 v[212:215], v159 offset:55296
	ds_read_b128 v[216:219], v159 offset:56320
	global_load_lds_dwordx4 v[220:221], off
	s_add_i32 m0, s34, 0x2000
	s_add_u32 s34, s44, 0x40080
	v_lshl_add_u64 v[220:221], v[222:223], 0, s[26:27]
	s_addc_u32 s35, s45, 0
	s_add_i32 s44, s67, s50
	global_load_lds_dwordx4 v[220:221], off
	v_lshl_add_u64 v[220:221], s[34:35], 0, v[134:135]
	s_mov_b32 m0, s44
	s_nop 0
	global_load_lds_dwordx4 v[220:221], off
	v_lshl_add_u64 v[220:221], s[34:35], 0, v[138:139]
	s_add_i32 m0, s44, 0x2000
	s_nop 0
	global_load_lds_dwordx4 v[220:221], off
	v_lshl_add_u64 v[220:221], v[224:225], 0, s[26:27]
	s_mov_b32 m0, s58
	s_nop 0
	global_load_lds_dwordx4 v[220:221], off
	v_lshl_add_u64 v[220:221], v[226:227], 0, s[26:27]
	s_mov_b32 m0, s59
	s_nop 0
	global_load_lds_dwordx4 v[220:221], off
	s_waitcnt vmcnt(8)
	s_waitcnt lgkmcnt(0)
	s_barrier
	s_setprio 1
	s_waitcnt lgkmcnt(0)
	v_mfma_f32_16x16x32_bf16 v[60:63], v[150:153], v[188:191], v[60:63]
	v_mfma_f32_16x16x32_bf16 v[56:59], v[164:167], v[188:191], v[56:59]
	v_mfma_f32_16x16x32_bf16 v[44:47], v[150:153], v[196:199], v[44:47]
	v_mfma_f32_16x16x32_bf16 v[40:43], v[164:167], v[196:199], v[40:43]
	v_mfma_f32_16x16x32_bf16 v[28:31], v[150:153], v[204:207], v[28:31]
	v_mfma_f32_16x16x32_bf16 v[24:27], v[164:167], v[204:207], v[24:27]
	v_mfma_f32_16x16x32_bf16 v[12:15], v[150:153], v[212:215], v[12:15]
	v_mfma_f32_16x16x32_bf16 v[8:11], v[164:167], v[212:215], v[8:11]
	v_mfma_f32_16x16x32_bf16 v[60:63], v[160:163], v[192:195], v[60:63]
	v_mfma_f32_16x16x32_bf16 v[56:59], v[168:171], v[192:195], v[56:59]
	v_mfma_f32_16x16x32_bf16 v[44:47], v[160:163], v[200:203], v[44:47]
	v_mfma_f32_16x16x32_bf16 v[40:43], v[168:171], v[200:203], v[40:43]
	v_mfma_f32_16x16x32_bf16 v[28:31], v[160:163], v[208:211], v[28:31]
	v_mfma_f32_16x16x32_bf16 v[24:27], v[168:171], v[208:211], v[24:27]
	v_mfma_f32_16x16x32_bf16 v[12:15], v[160:163], v[216:219], v[12:15]
	v_mfma_f32_16x16x32_bf16 v[8:11], v[168:171], v[216:219], v[8:11]
	s_setprio 0
	s_setprio 1
	v_mfma_f32_16x16x32_bf16 v[52:55], v[172:175], v[188:191], v[52:55]
	v_mfma_f32_16x16x32_bf16 v[48:51], v[180:183], v[188:191], v[48:51]
	v_mfma_f32_16x16x32_bf16 v[36:39], v[172:175], v[196:199], v[36:39]
	v_mfma_f32_16x16x32_bf16 v[32:35], v[180:183], v[196:199], v[32:35]
	v_mfma_f32_16x16x32_bf16 v[20:23], v[172:175], v[204:207], v[20:23]
	v_mfma_f32_16x16x32_bf16 v[16:19], v[180:183], v[204:207], v[16:19]
	v_mfma_f32_16x16x32_bf16 v[4:7], v[172:175], v[212:215], v[4:7]
	v_mfma_f32_16x16x32_bf16 v[0:3], v[180:183], v[212:215], v[0:3]
	v_mfma_f32_16x16x32_bf16 v[52:55], v[176:179], v[192:195], v[52:55]
	v_mfma_f32_16x16x32_bf16 v[48:51], v[184:187], v[192:195], v[48:51]
	v_mfma_f32_16x16x32_bf16 v[36:39], v[176:179], v[200:203], v[36:39]
	v_mfma_f32_16x16x32_bf16 v[32:35], v[184:187], v[200:203], v[32:35]
	v_mfma_f32_16x16x32_bf16 v[20:23], v[176:179], v[208:211], v[20:23]
	v_mfma_f32_16x16x32_bf16 v[16:19], v[184:187], v[208:211], v[16:19]
	v_mfma_f32_16x16x32_bf16 v[4:7], v[176:179], v[216:219], v[4:7]
	v_mfma_f32_16x16x32_bf16 v[0:3], v[184:187], v[216:219], v[0:3]
	s_setprio 0
	s_barrier
	s_add_i32 s65, s65, 2
	s_add_u32 s42, s42, 0x100
	s_addc_u32 s43, s43, 0
	s_add_u32 s31, s31, 0x100
	s_addc_u32 s37, s37, 0

.LBB0_1994:
	s_add_i32 s58, s58, 1
	s_mul_i32 s6, s58, s53
	s_mul_hi_u32 s7, s58, s54
	s_add_i32 s7, s7, s6
	s_mul_i32 s6, s58, s54
	s_add_u32 s28, s6, s2
	s_addc_u32 s29, s7, s55
	v_cmp_gt_i64_e32 vcc, s[28:29], v[144:145]
	v_cmp_lt_i64_e64 s[6:7], s[28:29], v[142:143]
	s_cbranch_vccnz .LBB0_2000
	s_and_b32 s100, s28, 7
	s_mul_i32 s100, s100, 0x40
	s_lshr_b32 s101, s28, 3
	s_add_i32 s100, s100, s101
	s_mul_hi_u32 s101, s100, 0x8000000
	s_mul_i32 s24, s101, 0x20
	s_sub_i32 s24, s100, s24
	s_and_b32 s100, s24, 7
	s_lshl_b32 s26, s101, 3
	s_add_i32 s26, s26, s100
	s_lshr_b32 s24, s24, 3
.LBB0_2000:
	s_ashr_i32 s27, s26, 31
	s_lshl_b64 s[12:13], s[26:27], 19
	s_add_u32 s28, s20, s12
	s_addc_u32 s29, s21, s13
	s_and_b64 s[12:13], s[6:7], exec
	s_cselect_b32 s12, s29, s39
	s_cselect_b32 s13, s28, s38
	s_ashr_i32 s25, s24, 31
	s_lshl_b64 s[30:31], s[24:25], 19
	s_add_u32 s30, s3, s30
	s_addc_u32 s31, s44, s31
	s_and_b64 s[34:35], s[6:7], exec
	s_cselect_b32 s25, s31, s41
	s_cselect_b32 s27, s30, s40
	s_add_u32 s38, s38, 0x40080
	s_addc_u32 s39, s39, 0
	s_add_u32 s37, s40, 0x100
	s_addc_u32 s59, s41, 0
	s_mov_b32 s60, -2
	s_waitcnt lgkmcnt(0)
	ds_read_b128 v[146:149], v153
	ds_read_b128 v[158:161], v153 offset:1024
	ds_read_b128 v[162:165], v153 offset:2048
	ds_read_b128 v[166:169], v153 offset:3072
	ds_read_b128 v[170:173], v154
	ds_read_b128 v[174:177], v154 offset:1024
	ds_read_b128 v[178:181], v154 offset:2048
	ds_read_b128 v[182:185], v154 offset:3072
	s_add_u32 s34, s38, 0xfffc0080
	s_addc_u32 s35, s39, -1
	s_cmp_eq_u32 s60, 12
	s_cselect_b32 s43, s12, s35
	s_cselect_b32 s42, s13, s34
	s_cselect_b32 s41, s25, s59
	s_cselect_b32 s40, s27, s37
	v_lshl_add_u64 v[218:219], s[38:39], 0, v[138:139]
	s_add_i32 m0, s46, 0xc000
	ds_read_b128 v[186:189], v155
	ds_read_b128 v[190:193], v155 offset:1024
	ds_read_b128 v[194:197], v155 offset:2048
	ds_read_b128 v[198:201], v155 offset:3072
	ds_read_b128 v[202:205], v155 offset:4096
	ds_read_b128 v[206:209], v155 offset:5120
	ds_read_b128 v[210:213], v155 offset:6144
	ds_read_b128 v[214:217], v155 offset:7168
	global_load_lds_dwordx4 v[218:219], off
	v_lshl_add_u64 v[218:219], s[38:39], 0, v[140:141]
	s_add_i32 m0, s46, 0xe000
	s_nop 0
	global_load_lds_dwordx4 v[218:219], off
	s_waitcnt vmcnt(8)
	s_waitcnt lgkmcnt(0)
	s_barrier
	s_setprio 1
	s_waitcnt lgkmcnt(0)
	v_mfma_f32_16x16x32_bf16 v[124:127], v[146:149], v[186:189], 0
	v_mfma_f32_16x16x32_bf16 v[120:123], v[162:165], v[186:189], 0
	v_mfma_f32_16x16x32_bf16 v[108:111], v[146:149], v[194:197], 0
	v_mfma_f32_16x16x32_bf16 v[104:107], v[162:165], v[194:197], 0
	v_mfma_f32_16x16x32_bf16 v[92:95], v[146:149], v[202:205], 0
	v_mfma_f32_16x16x32_bf16 v[88:91], v[162:165], v[202:205], 0
	v_mfma_f32_16x16x32_bf16 v[76:79], v[146:149], v[210:213], 0
	v_mfma_f32_16x16x32_bf16 v[72:75], v[162:165], v[210:213], 0
	v_mfma_f32_16x16x32_bf16 v[124:127], v[158:161], v[190:193], v[124:127]
	v_mfma_f32_16x16x32_bf16 v[120:123], v[166:169], v[190:193], v[120:123]
	v_mfma_f32_16x16x32_bf16 v[108:111], v[158:161], v[198:201], v[108:111]
	v_mfma_f32_16x16x32_bf16 v[104:107], v[166:169], v[198:201], v[104:107]
	v_mfma_f32_16x16x32_bf16 v[92:95], v[158:161], v[206:209], v[92:95]
	v_mfma_f32_16x16x32_bf16 v[88:91], v[166:169], v[206:209], v[88:91]
	v_mfma_f32_16x16x32_bf16 v[76:79], v[158:161], v[214:217], v[76:79]
	v_mfma_f32_16x16x32_bf16 v[72:75], v[166:169], v[214:217], v[72:75]
	s_setprio 0
	s_setprio 1
	v_mfma_f32_16x16x32_bf16 v[116:119], v[170:173], v[186:189], 0
	v_mfma_f32_16x16x32_bf16 v[112:115], v[178:181], v[186:189], 0
	v_mfma_f32_16x16x32_bf16 v[100:103], v[170:173], v[194:197], 0
	v_mfma_f32_16x16x32_bf16 v[96:99], v[178:181], v[194:197], 0
	v_mfma_f32_16x16x32_bf16 v[84:87], v[170:173], v[202:205], 0
	v_mfma_f32_16x16x32_bf16 v[80:83], v[178:181], v[202:205], 0
	v_mfma_f32_16x16x32_bf16 v[68:71], v[170:173], v[210:213], 0
	v_mfma_f32_16x16x32_bf16 v[64:67], v[178:181], v[210:213], 0
	v_mfma_f32_16x16x32_bf16 v[116:119], v[174:177], v[190:193], v[116:119]
	v_mfma_f32_16x16x32_bf16 v[112:115], v[182:185], v[190:193], v[112:115]
	v_mfma_f32_16x16x32_bf16 v[100:103], v[174:177], v[198:201], v[100:103]
	v_mfma_f32_16x16x32_bf16 v[96:99], v[182:185], v[198:201], v[96:99]
	v_mfma_f32_16x16x32_bf16 v[84:87], v[174:177], v[206:209], v[84:87]
	v_mfma_f32_16x16x32_bf16 v[80:83], v[182:185], v[206:209], v[80:83]
	v_mfma_f32_16x16x32_bf16 v[68:71], v[174:177], v[214:217], v[68:71]
	v_mfma_f32_16x16x32_bf16 v[64:67], v[182:185], v[214:217], v[64:67]
	s_setprio 0
	s_barrier
	s_add_i32 s34, s56, s45
	v_lshl_add_u64 v[218:219], s[40:41], 0, v[132:133]
	s_mov_b32 m0, s34
	ds_read_b128 v[186:189], v155 offset:16384
	ds_read_b128 v[190:193], v155 offset:17408
	ds_read_b128 v[194:197], v155 offset:18432
	ds_read_b128 v[198:201], v155 offset:19456
	ds_read_b128 v[202:205], v155 offset:20480
	ds_read_b128 v[206:209], v155 offset:21504
	ds_read_b128 v[210:213], v155 offset:22528
	ds_read_b128 v[214:217], v155 offset:23552
	global_load_lds_dwordx4 v[218:219], off
	s_add_i32 m0, s34, 0x2000
	s_add_u32 s34, s40, 0x40000
	v_lshl_add_u64 v[220:221], s[40:41], 0, v[136:137]
	s_addc_u32 s35, s41, 0
	s_add_i32 s61, s57, s45
	global_load_lds_dwordx4 v[220:221], off
	v_lshl_add_u64 v[222:223], s[34:35], 0, v[132:133]
	s_mov_b32 m0, s61
	v_lshl_add_u64 v[224:225], s[42:43], 0, v[134:135]
	global_load_lds_dwordx4 v[222:223], off
	v_lshl_add_u64 v[222:223], s[34:35], 0, v[136:137]
	s_add_i32 m0, s61, 0x2000
	s_nop 0
	global_load_lds_dwordx4 v[222:223], off
	v_lshl_add_u64 v[222:223], s[42:43], 0, v[130:131]
	s_mov_b32 m0, s46
	s_nop 0
	global_load_lds_dwordx4 v[222:223], off
	s_mov_b32 m0, s47
	s_nop 0
	global_load_lds_dwordx4 v[224:225], off
	s_waitcnt vmcnt(8)
	s_waitcnt lgkmcnt(0)
	s_barrier
	s_setprio 1
	s_waitcnt lgkmcnt(0)
	v_mfma_f32_16x16x32_bf16 v[60:63], v[146:149], v[186:189], 0
	v_mfma_f32_16x16x32_bf16 v[56:59], v[162:165], v[186:189], 0
	v_mfma_f32_16x16x32_bf16 v[44:47], v[146:149], v[194:197], 0
	v_mfma_f32_16x16x32_bf16 v[40:43], v[162:165], v[194:197], 0
	v_mfma_f32_16x16x32_bf16 v[28:31], v[146:149], v[202:205], 0
	v_mfma_f32_16x16x32_bf16 v[24:27], v[162:165], v[202:205], 0
	v_mfma_f32_16x16x32_bf16 v[12:15], v[146:149], v[210:213], 0
	v_mfma_f32_16x16x32_bf16 v[8:11], v[162:165], v[210:213], 0
	v_mfma_f32_16x16x32_bf16 v[60:63], v[158:161], v[190:193], v[60:63]
	v_mfma_f32_16x16x32_bf16 v[56:59], v[166:169], v[190:193], v[56:59]
	v_mfma_f32_16x16x32_bf16 v[44:47], v[158:161], v[198:201], v[44:47]
	v_mfma_f32_16x16x32_bf16 v[40:43], v[166:169], v[198:201], v[40:43]
	v_mfma_f32_16x16x32_bf16 v[28:31], v[158:161], v[206:209], v[28:31]
	v_mfma_f32_16x16x32_bf16 v[24:27], v[166:169], v[206:209], v[24:27]
	v_mfma_f32_16x16x32_bf16 v[12:15], v[158:161], v[214:217], v[12:15]
	v_mfma_f32_16x16x32_bf16 v[8:11], v[166:169], v[214:217], v[8:11]
	s_setprio 0
	s_setprio 1
	v_mfma_f32_16x16x32_bf16 v[52:55], v[170:173], v[186:189], 0
	v_mfma_f32_16x16x32_bf16 v[48:51], v[178:181], v[186:189], 0
	v_mfma_f32_16x16x32_bf16 v[36:39], v[170:173], v[194:197], 0
	v_mfma_f32_16x16x32_bf16 v[32:35], v[178:181], v[194:197], 0
	v_mfma_f32_16x16x32_bf16 v[20:23], v[170:173], v[202:205], 0
	v_mfma_f32_16x16x32_bf16 v[16:19], v[178:181], v[202:205], 0
	v_mfma_f32_16x16x32_bf16 v[4:7], v[170:173], v[210:213], 0
	v_mfma_f32_16x16x32_bf16 v[0:3], v[178:181], v[210:213], 0
	v_mfma_f32_16x16x32_bf16 v[52:55], v[174:177], v[190:193], v[52:55]
	v_mfma_f32_16x16x32_bf16 v[48:51], v[182:185], v[190:193], v[48:51]
	v_mfma_f32_16x16x32_bf16 v[36:39], v[174:177], v[198:201], v[36:39]
	v_mfma_f32_16x16x32_bf16 v[32:35], v[182:185], v[198:201], v[32:35]
	v_mfma_f32_16x16x32_bf16 v[20:23], v[174:177], v[206:209], v[20:23]
	v_mfma_f32_16x16x32_bf16 v[16:19], v[182:185], v[206:209], v[16:19]
	v_mfma_f32_16x16x32_bf16 v[4:7], v[174:177], v[214:217], v[4:7]
	v_mfma_f32_16x16x32_bf16 v[0:3], v[182:185], v[214:217], v[0:3]
	s_setprio 0
	s_barrier
	s_add_i32 s61, 0, 0x18000
	v_add_u32_e32 v157, s61, v151
	s_add_i32 s62, 0, 0x1c000
	ds_read_b128 v[146:149], v157
	ds_read_b128 v[158:161], v157 offset:1024
	ds_read_b128 v[162:165], v157 offset:2048
	ds_read_b128 v[166:169], v157 offset:3072
	v_add_u32_e32 v157, s62, v151
	ds_read_b128 v[170:173], v157
	ds_read_b128 v[174:177], v157 offset:1024
	ds_read_b128 v[178:181], v157 offset:2048
	ds_read_b128 v[182:185], v157 offset:3072
	s_add_u32 s34, s42, 0x40000
	s_addc_u32 s35, s43, 0
	s_mov_b32 m0, s48
	v_lshl_add_u64 v[226:227], s[34:35], 0, v[130:131]
	ds_read_b128 v[186:189], v155 offset:32768
	ds_read_b128 v[190:193], v155 offset:33792
	ds_read_b128 v[194:197], v155 offset:34816
	ds_read_b128 v[198:201], v155 offset:35840
	ds_read_b128 v[202:205], v155 offset:36864
	ds_read_b128 v[206:209], v155 offset:37888
	ds_read_b128 v[210:213], v155 offset:38912
	ds_read_b128 v[214:217], v155 offset:39936
	global_load_lds_dwordx4 v[226:227], off
	v_lshl_add_u64 v[226:227], s[34:35], 0, v[134:135]
	s_mov_b32 m0, s49
	s_nop 0
	global_load_lds_dwordx4 v[226:227], off
	s_waitcnt vmcnt(8)
	s_waitcnt lgkmcnt(0)
	s_barrier
	s_setprio 1
	s_waitcnt lgkmcnt(0)
	v_mfma_f32_16x16x32_bf16 v[124:127], v[146:149], v[186:189], v[124:127]
	v_mfma_f32_16x16x32_bf16 v[120:123], v[162:165], v[186:189], v[120:123]
	v_mfma_f32_16x16x32_bf16 v[108:111], v[146:149], v[194:197], v[108:111]
	v_mfma_f32_16x16x32_bf16 v[104:107], v[162:165], v[194:197], v[104:107]
	v_mfma_f32_16x16x32_bf16 v[92:95], v[146:149], v[202:205], v[92:95]
	v_mfma_f32_16x16x32_bf16 v[88:91], v[162:165], v[202:205], v[88:91]
	v_mfma_f32_16x16x32_bf16 v[76:79], v[146:149], v[210:213], v[76:79]
	v_mfma_f32_16x16x32_bf16 v[72:75], v[162:165], v[210:213], v[72:75]
	v_mfma_f32_16x16x32_bf16 v[124:127], v[158:161], v[190:193], v[124:127]
	v_mfma_f32_16x16x32_bf16 v[120:123], v[166:169], v[190:193], v[120:123]
	v_mfma_f32_16x16x32_bf16 v[108:111], v[158:161], v[198:201], v[108:111]
	v_mfma_f32_16x16x32_bf16 v[104:107], v[166:169], v[198:201], v[104:107]
	v_mfma_f32_16x16x32_bf16 v[92:95], v[158:161], v[206:209], v[92:95]
	v_mfma_f32_16x16x32_bf16 v[88:91], v[166:169], v[206:209], v[88:91]
	v_mfma_f32_16x16x32_bf16 v[76:79], v[158:161], v[214:217], v[76:79]
	v_mfma_f32_16x16x32_bf16 v[72:75], v[166:169], v[214:217], v[72:75]
	s_setprio 0
	s_setprio 1
	v_mfma_f32_16x16x32_bf16 v[116:119], v[170:173], v[186:189], v[116:119]
	v_mfma_f32_16x16x32_bf16 v[112:115], v[178:181], v[186:189], v[112:115]
	v_mfma_f32_16x16x32_bf16 v[100:103], v[170:173], v[194:197], v[100:103]
	v_mfma_f32_16x16x32_bf16 v[96:99], v[178:181], v[194:197], v[96:99]
	v_mfma_f32_16x16x32_bf16 v[84:87], v[170:173], v[202:205], v[84:87]
	v_mfma_f32_16x16x32_bf16 v[80:83], v[178:181], v[202:205], v[80:83]
	v_mfma_f32_16x16x32_bf16 v[68:71], v[170:173], v[210:213], v[68:71]
	v_mfma_f32_16x16x32_bf16 v[64:67], v[178:181], v[210:213], v[64:67]
	v_mfma_f32_16x16x32_bf16 v[116:119], v[174:177], v[190:193], v[116:119]
	v_mfma_f32_16x16x32_bf16 v[112:115], v[182:185], v[190:193], v[112:115]
	v_mfma_f32_16x16x32_bf16 v[100:103], v[174:177], v[198:201], v[100:103]
	v_mfma_f32_16x16x32_bf16 v[96:99], v[182:185], v[198:201], v[96:99]
	v_mfma_f32_16x16x32_bf16 v[84:87], v[174:177], v[206:209], v[84:87]
	v_mfma_f32_16x16x32_bf16 v[80:83], v[182:185], v[206:209], v[80:83]
	v_mfma_f32_16x16x32_bf16 v[68:71], v[174:177], v[214:217], v[68:71]
	v_mfma_f32_16x16x32_bf16 v[64:67], v[182:185], v[214:217], v[64:67]
	s_setprio 0
	s_barrier
	s_add_i32 s34, s61, s45
	v_lshl_add_u64 v[218:219], v[218:219], 0, s[10:11]
	s_mov_b32 m0, s34
	ds_read_b128 v[186:189], v155 offset:49152
	ds_read_b128 v[190:193], v155 offset:50176
	ds_read_b128 v[194:197], v155 offset:51200
	ds_read_b128 v[198:201], v155 offset:52224
	ds_read_b128 v[202:205], v155 offset:53248
	ds_read_b128 v[206:209], v155 offset:54272
	ds_read_b128 v[210:213], v155 offset:55296
	ds_read_b128 v[214:217], v155 offset:56320
	global_load_lds_dwordx4 v[218:219], off
	s_add_i32 m0, s34, 0x2000
	s_add_u32 s34, s40, 0x40080
	v_lshl_add_u64 v[218:219], v[220:221], 0, s[10:11]
	s_addc_u32 s35, s41, 0
	s_add_i32 s40, s62, s45
	global_load_lds_dwordx4 v[218:219], off
	v_lshl_add_u64 v[218:219], s[34:35], 0, v[132:133]
	s_mov_b32 m0, s40
	s_nop 0
	global_load_lds_dwordx4 v[218:219], off
	v_lshl_add_u64 v[218:219], s[34:35], 0, v[136:137]
	s_add_i32 m0, s40, 0x2000
	s_nop 0
	global_load_lds_dwordx4 v[218:219], off
	v_lshl_add_u64 v[218:219], v[222:223], 0, s[10:11]
	s_mov_b32 m0, s51
	s_nop 0
	global_load_lds_dwordx4 v[218:219], off
	v_lshl_add_u64 v[218:219], v[224:225], 0, s[10:11]
	s_mov_b32 m0, s52
	s_nop 0
	global_load_lds_dwordx4 v[218:219], off
	s_waitcnt vmcnt(8)
	s_waitcnt lgkmcnt(0)
	s_barrier
	s_setprio 1
	s_waitcnt lgkmcnt(0)
	v_mfma_f32_16x16x32_bf16 v[60:63], v[146:149], v[186:189], v[60:63]
	v_mfma_f32_16x16x32_bf16 v[56:59], v[162:165], v[186:189], v[56:59]
	v_mfma_f32_16x16x32_bf16 v[44:47], v[146:149], v[194:197], v[44:47]
	v_mfma_f32_16x16x32_bf16 v[40:43], v[162:165], v[194:197], v[40:43]
	v_mfma_f32_16x16x32_bf16 v[28:31], v[146:149], v[202:205], v[28:31]
	v_mfma_f32_16x16x32_bf16 v[24:27], v[162:165], v[202:205], v[24:27]
	v_mfma_f32_16x16x32_bf16 v[12:15], v[146:149], v[210:213], v[12:15]
	v_mfma_f32_16x16x32_bf16 v[8:11], v[162:165], v[210:213], v[8:11]
	v_mfma_f32_16x16x32_bf16 v[60:63], v[158:161], v[190:193], v[60:63]
	v_mfma_f32_16x16x32_bf16 v[56:59], v[166:169], v[190:193], v[56:59]
	v_mfma_f32_16x16x32_bf16 v[44:47], v[158:161], v[198:201], v[44:47]
	v_mfma_f32_16x16x32_bf16 v[40:43], v[166:169], v[198:201], v[40:43]
	v_mfma_f32_16x16x32_bf16 v[28:31], v[158:161], v[206:209], v[28:31]
	v_mfma_f32_16x16x32_bf16 v[24:27], v[166:169], v[206:209], v[24:27]
	v_mfma_f32_16x16x32_bf16 v[12:15], v[158:161], v[214:217], v[12:15]
	v_mfma_f32_16x16x32_bf16 v[8:11], v[166:169], v[214:217], v[8:11]
	s_setprio 0
	s_setprio 1
	v_mfma_f32_16x16x32_bf16 v[52:55], v[170:173], v[186:189], v[52:55]
	v_mfma_f32_16x16x32_bf16 v[48:51], v[178:181], v[186:189], v[48:51]
	v_mfma_f32_16x16x32_bf16 v[36:39], v[170:173], v[194:197], v[36:39]
	v_mfma_f32_16x16x32_bf16 v[32:35], v[178:181], v[194:197], v[32:35]
	v_mfma_f32_16x16x32_bf16 v[20:23], v[170:173], v[202:205], v[20:23]
	v_mfma_f32_16x16x32_bf16 v[16:19], v[178:181], v[202:205], v[16:19]
	v_mfma_f32_16x16x32_bf16 v[4:7], v[170:173], v[210:213], v[4:7]
	v_mfma_f32_16x16x32_bf16 v[0:3], v[178:181], v[210:213], v[0:3]
	v_mfma_f32_16x16x32_bf16 v[52:55], v[174:177], v[190:193], v[52:55]
	v_mfma_f32_16x16x32_bf16 v[48:51], v[182:185], v[190:193], v[48:51]
	v_mfma_f32_16x16x32_bf16 v[36:39], v[174:177], v[198:201], v[36:39]
	v_mfma_f32_16x16x32_bf16 v[32:35], v[182:185], v[198:201], v[32:35]
	v_mfma_f32_16x16x32_bf16 v[20:23], v[174:177], v[206:209], v[20:23]
	v_mfma_f32_16x16x32_bf16 v[16:19], v[182:185], v[206:209], v[16:19]
	v_mfma_f32_16x16x32_bf16 v[4:7], v[174:177], v[214:217], v[4:7]
	v_mfma_f32_16x16x32_bf16 v[0:3], v[182:185], v[214:217], v[0:3]
	s_setprio 0
	s_barrier
	s_add_i32 s60, s60, 2
	s_add_u32 s38, s38, 0x100
	s_addc_u32 s39, s39, 0
	s_add_u32 s37, s37, 0x100
	s_addc_u32 s59, s59, 0

.LBB0_2088:
	s_add_i32 s50, s50, 1
	s_mul_i32 s4, s50, s36
	s_mul_hi_u32 s5, s50, s37
	s_add_i32 s5, s5, s4
	s_mul_i32 s4, s50, s37
	s_add_u32 s20, s4, s2
	s_addc_u32 s21, s5, s3
	v_cmp_gt_i64_e32 vcc, s[20:21], v[144:145]
	v_cmp_lt_i64_e64 s[4:5], s[20:21], v[142:143]
	s_cbranch_vccnz .LBB0_2090
	s_and_b32 s100, s20, 7
	s_mul_i32 s100, s100, 0x160
	s_lshr_b32 s101, s20, 3
	s_add_i32 s100, s100, s101
	s_mul_hi_u32 s101, s100, 0x1745d18
	s_mul_i32 s10, s101, 0xb0
	s_sub_i32 s10, s100, s10
	s_and_b32 s100, s10, 7
	s_lshl_b32 s18, s101, 3
	s_add_i32 s18, s18, s100
	s_lshr_b32 s10, s10, 3
	s_mov_b32 s51, s50
.LBB0_2090:
	s_ashr_i32 s19, s18, 31
	s_lshl_b64 s[20:21], s[18:19], 19
	s_add_u32 s20, s14, s20
	s_addc_u32 s21, s15, s21
	s_and_b64 s[22:23], s[4:5], exec
	s_cselect_b32 s19, s21, s27
	s_cselect_b32 s52, s20, s26
	s_ashr_i32 s11, s10, 31
	s_lshl_b64 s[22:23], s[10:11], 19
	s_add_u32 s22, s39, s22
	s_addc_u32 s23, s40, s23
	s_and_b64 s[30:31], s[4:5], exec
	s_cselect_b32 s11, s23, s29
	s_cselect_b32 s53, s22, s28
	s_add_u32 s26, s26, 0x40080
	s_addc_u32 s27, s27, 0
	s_add_u32 s54, s28, 0x100
	s_addc_u32 s55, s29, 0
	s_mov_b32 s56, -2
	ds_read_b128 v[146:149], v153
	ds_read_b128 v[156:159], v153 offset:1024
	ds_read_b128 v[160:163], v153 offset:2048
	ds_read_b128 v[164:167], v153 offset:3072
	ds_read_b128 v[168:171], v154
	ds_read_b128 v[172:175], v154 offset:1024
	ds_read_b128 v[176:179], v154 offset:2048
	ds_read_b128 v[180:183], v154 offset:3072
	s_add_u32 s28, s26, 0xfffc0080
	s_addc_u32 s29, s27, -1
	s_cmp_eq_u32 s56, 12
	s_cselect_b32 s31, s19, s29
	s_cselect_b32 s30, s52, s28
	s_cselect_b32 s29, s11, s55
	s_cselect_b32 s28, s53, s54
	v_lshl_add_u64 v[216:217], s[26:27], 0, v[138:139]
	s_add_i32 m0, s25, 0xc000
	ds_read_b128 v[184:187], v155
	ds_read_b128 v[188:191], v155 offset:1024
	ds_read_b128 v[192:195], v155 offset:2048
	ds_read_b128 v[196:199], v155 offset:3072
	ds_read_b128 v[200:203], v155 offset:4096
	ds_read_b128 v[204:207], v155 offset:5120
	ds_read_b128 v[208:211], v155 offset:6144
	ds_read_b128 v[212:215], v155 offset:7168
	global_load_lds_dwordx4 v[216:217], off
	v_lshl_add_u64 v[216:217], s[26:27], 0, v[140:141]
	s_add_i32 m0, s25, 0xe000
	s_nop 0
	global_load_lds_dwordx4 v[216:217], off
	s_waitcnt vmcnt(8)
	s_waitcnt lgkmcnt(0)
	s_barrier
	s_setprio 1
	s_waitcnt lgkmcnt(0)
	v_mfma_f32_16x16x32_bf16 v[124:127], v[146:149], v[184:187], 0
	v_mfma_f32_16x16x32_bf16 v[120:123], v[160:163], v[184:187], 0
	v_mfma_f32_16x16x32_bf16 v[108:111], v[146:149], v[192:195], 0
	v_mfma_f32_16x16x32_bf16 v[104:107], v[160:163], v[192:195], 0
	v_mfma_f32_16x16x32_bf16 v[92:95], v[146:149], v[200:203], 0
	v_mfma_f32_16x16x32_bf16 v[88:91], v[160:163], v[200:203], 0
	v_mfma_f32_16x16x32_bf16 v[76:79], v[146:149], v[208:211], 0
	v_mfma_f32_16x16x32_bf16 v[72:75], v[160:163], v[208:211], 0
	v_mfma_f32_16x16x32_bf16 v[124:127], v[156:159], v[188:191], v[124:127]
	v_mfma_f32_16x16x32_bf16 v[120:123], v[164:167], v[188:191], v[120:123]
	v_mfma_f32_16x16x32_bf16 v[108:111], v[156:159], v[196:199], v[108:111]
	v_mfma_f32_16x16x32_bf16 v[104:107], v[164:167], v[196:199], v[104:107]
	v_mfma_f32_16x16x32_bf16 v[92:95], v[156:159], v[204:207], v[92:95]
	v_mfma_f32_16x16x32_bf16 v[88:91], v[164:167], v[204:207], v[88:91]
	v_mfma_f32_16x16x32_bf16 v[76:79], v[156:159], v[212:215], v[76:79]
	v_mfma_f32_16x16x32_bf16 v[72:75], v[164:167], v[212:215], v[72:75]
	s_setprio 0
	s_setprio 1
	v_mfma_f32_16x16x32_bf16 v[116:119], v[168:171], v[184:187], 0
	v_mfma_f32_16x16x32_bf16 v[112:115], v[176:179], v[184:187], 0
	v_mfma_f32_16x16x32_bf16 v[100:103], v[168:171], v[192:195], 0
	v_mfma_f32_16x16x32_bf16 v[96:99], v[176:179], v[192:195], 0
	v_mfma_f32_16x16x32_bf16 v[84:87], v[168:171], v[200:203], 0
	v_mfma_f32_16x16x32_bf16 v[80:83], v[176:179], v[200:203], 0
	v_mfma_f32_16x16x32_bf16 v[68:71], v[168:171], v[208:211], 0
	v_mfma_f32_16x16x32_bf16 v[64:67], v[176:179], v[208:211], 0
	v_mfma_f32_16x16x32_bf16 v[116:119], v[172:175], v[188:191], v[116:119]
	v_mfma_f32_16x16x32_bf16 v[112:115], v[180:183], v[188:191], v[112:115]
	v_mfma_f32_16x16x32_bf16 v[100:103], v[172:175], v[196:199], v[100:103]
	v_mfma_f32_16x16x32_bf16 v[96:99], v[180:183], v[196:199], v[96:99]
	v_mfma_f32_16x16x32_bf16 v[84:87], v[172:175], v[204:207], v[84:87]
	v_mfma_f32_16x16x32_bf16 v[80:83], v[180:183], v[204:207], v[80:83]
	v_mfma_f32_16x16x32_bf16 v[68:71], v[172:175], v[212:215], v[68:71]
	v_mfma_f32_16x16x32_bf16 v[64:67], v[180:183], v[212:215], v[64:67]
	s_setprio 0
	s_barrier
	s_add_i32 s34, s47, s38
	v_lshl_add_u64 v[216:217], s[28:29], 0, v[134:135]
	s_mov_b32 m0, s34
	ds_read_b128 v[184:187], v155 offset:16384
	ds_read_b128 v[188:191], v155 offset:17408
	ds_read_b128 v[192:195], v155 offset:18432
	ds_read_b128 v[196:199], v155 offset:19456
	ds_read_b128 v[200:203], v155 offset:20480
	ds_read_b128 v[204:207], v155 offset:21504
	ds_read_b128 v[208:211], v155 offset:22528
	ds_read_b128 v[212:215], v155 offset:23552
	global_load_lds_dwordx4 v[216:217], off
	s_add_i32 m0, s34, 0x2000
	s_add_u32 s34, s28, 0x40000
	v_lshl_add_u64 v[218:219], s[28:29], 0, v[130:131]
	s_addc_u32 s35, s29, 0
	s_add_i32 s57, s48, s38
	global_load_lds_dwordx4 v[218:219], off
	v_lshl_add_u64 v[220:221], s[34:35], 0, v[134:135]
	s_mov_b32 m0, s57
	v_lshl_add_u64 v[222:223], s[30:31], 0, v[132:133]
	global_load_lds_dwordx4 v[220:221], off
	v_lshl_add_u64 v[220:221], s[34:35], 0, v[130:131]
	s_add_i32 m0, s57, 0x2000
	s_nop 0
	global_load_lds_dwordx4 v[220:221], off
	v_lshl_add_u64 v[220:221], s[30:31], 0, v[136:137]
	s_mov_b32 m0, s25
	s_nop 0
	global_load_lds_dwordx4 v[220:221], off
	s_mov_b32 m0, s42
	s_nop 0
	global_load_lds_dwordx4 v[222:223], off
	s_waitcnt vmcnt(8)
	s_waitcnt lgkmcnt(0)
	s_barrier
	s_setprio 1
	s_waitcnt lgkmcnt(0)
	v_mfma_f32_16x16x32_bf16 v[60:63], v[146:149], v[184:187], 0
	v_mfma_f32_16x16x32_bf16 v[56:59], v[160:163], v[184:187], 0
	v_mfma_f32_16x16x32_bf16 v[44:47], v[146:149], v[192:195], 0
	v_mfma_f32_16x16x32_bf16 v[40:43], v[160:163], v[192:195], 0
	v_mfma_f32_16x16x32_bf16 v[28:31], v[146:149], v[200:203], 0
	v_mfma_f32_16x16x32_bf16 v[24:27], v[160:163], v[200:203], 0
	v_mfma_f32_16x16x32_bf16 v[12:15], v[146:149], v[208:211], 0
	v_mfma_f32_16x16x32_bf16 v[8:11], v[160:163], v[208:211], 0
	v_mfma_f32_16x16x32_bf16 v[60:63], v[156:159], v[188:191], v[60:63]
	v_mfma_f32_16x16x32_bf16 v[56:59], v[164:167], v[188:191], v[56:59]
	v_mfma_f32_16x16x32_bf16 v[44:47], v[156:159], v[196:199], v[44:47]
	v_mfma_f32_16x16x32_bf16 v[40:43], v[164:167], v[196:199], v[40:43]
	v_mfma_f32_16x16x32_bf16 v[28:31], v[156:159], v[204:207], v[28:31]
	v_mfma_f32_16x16x32_bf16 v[24:27], v[164:167], v[204:207], v[24:27]
	v_mfma_f32_16x16x32_bf16 v[12:15], v[156:159], v[212:215], v[12:15]
	v_mfma_f32_16x16x32_bf16 v[8:11], v[164:167], v[212:215], v[8:11]
	s_setprio 0
	s_setprio 1
	v_mfma_f32_16x16x32_bf16 v[52:55], v[168:171], v[184:187], 0
	v_mfma_f32_16x16x32_bf16 v[48:51], v[176:179], v[184:187], 0
	v_mfma_f32_16x16x32_bf16 v[36:39], v[168:171], v[192:195], 0
	v_mfma_f32_16x16x32_bf16 v[32:35], v[176:179], v[192:195], 0
	v_mfma_f32_16x16x32_bf16 v[20:23], v[168:171], v[200:203], 0
	v_mfma_f32_16x16x32_bf16 v[16:19], v[176:179], v[200:203], 0
	v_mfma_f32_16x16x32_bf16 v[4:7], v[168:171], v[208:211], 0
	v_mfma_f32_16x16x32_bf16 v[0:3], v[176:179], v[208:211], 0
	v_mfma_f32_16x16x32_bf16 v[52:55], v[172:175], v[188:191], v[52:55]
	v_mfma_f32_16x16x32_bf16 v[48:51], v[180:183], v[188:191], v[48:51]
	v_mfma_f32_16x16x32_bf16 v[36:39], v[172:175], v[196:199], v[36:39]
	v_mfma_f32_16x16x32_bf16 v[32:35], v[180:183], v[196:199], v[32:35]
	v_mfma_f32_16x16x32_bf16 v[20:23], v[172:175], v[204:207], v[20:23]
	v_mfma_f32_16x16x32_bf16 v[16:19], v[180:183], v[204:207], v[16:19]
	v_mfma_f32_16x16x32_bf16 v[4:7], v[172:175], v[212:215], v[4:7]
	v_mfma_f32_16x16x32_bf16 v[0:3], v[180:183], v[212:215], v[0:3]
	s_setprio 0
	s_barrier
	s_add_i32 s34, 0, 0x18000
	s_add_i32 s35, 0, 0x1c000
	v_add_u32_e32 v164, s34, v150
	v_add_u32_e32 v180, s35, v150
	ds_read_b128 v[146:149], v164
	ds_read_b128 v[156:159], v164 offset:1024
	ds_read_b128 v[160:163], v164 offset:2048
	ds_read_b128 v[164:167], v164 offset:3072
	ds_read_b128 v[168:171], v180
	ds_read_b128 v[172:175], v180 offset:1024
	ds_read_b128 v[176:179], v180 offset:2048
	ds_read_b128 v[180:183], v180 offset:3072
	s_add_u32 s30, s30, 0x40000
	s_addc_u32 s31, s31, 0
	s_mov_b32 m0, s43
	v_lshl_add_u64 v[224:225], s[30:31], 0, v[136:137]
	ds_read_b128 v[184:187], v155 offset:32768
	ds_read_b128 v[188:191], v155 offset:33792
	ds_read_b128 v[192:195], v155 offset:34816
	ds_read_b128 v[196:199], v155 offset:35840
	ds_read_b128 v[200:203], v155 offset:36864
	ds_read_b128 v[204:207], v155 offset:37888
	ds_read_b128 v[208:211], v155 offset:38912
	ds_read_b128 v[212:215], v155 offset:39936
	global_load_lds_dwordx4 v[224:225], off
	v_lshl_add_u64 v[224:225], s[30:31], 0, v[132:133]
	s_mov_b32 m0, s44
	s_nop 0
	global_load_lds_dwordx4 v[224:225], off
	s_waitcnt vmcnt(8)
	s_waitcnt lgkmcnt(0)
	s_barrier
	s_setprio 1
	s_waitcnt lgkmcnt(0)
	v_mfma_f32_16x16x32_bf16 v[124:127], v[146:149], v[184:187], v[124:127]
	v_mfma_f32_16x16x32_bf16 v[120:123], v[160:163], v[184:187], v[120:123]
	v_mfma_f32_16x16x32_bf16 v[108:111], v[146:149], v[192:195], v[108:111]
	v_mfma_f32_16x16x32_bf16 v[104:107], v[160:163], v[192:195], v[104:107]
	v_mfma_f32_16x16x32_bf16 v[92:95], v[146:149], v[200:203], v[92:95]
	v_mfma_f32_16x16x32_bf16 v[88:91], v[160:163], v[200:203], v[88:91]
	v_mfma_f32_16x16x32_bf16 v[76:79], v[146:149], v[208:211], v[76:79]
	v_mfma_f32_16x16x32_bf16 v[72:75], v[160:163], v[208:211], v[72:75]
	v_mfma_f32_16x16x32_bf16 v[124:127], v[156:159], v[188:191], v[124:127]
	v_mfma_f32_16x16x32_bf16 v[120:123], v[164:167], v[188:191], v[120:123]
	v_mfma_f32_16x16x32_bf16 v[108:111], v[156:159], v[196:199], v[108:111]
	v_mfma_f32_16x16x32_bf16 v[104:107], v[164:167], v[196:199], v[104:107]
	v_mfma_f32_16x16x32_bf16 v[92:95], v[156:159], v[204:207], v[92:95]
	v_mfma_f32_16x16x32_bf16 v[88:91], v[164:167], v[204:207], v[88:91]
	v_mfma_f32_16x16x32_bf16 v[76:79], v[156:159], v[212:215], v[76:79]
	v_mfma_f32_16x16x32_bf16 v[72:75], v[164:167], v[212:215], v[72:75]
	s_setprio 0
	s_setprio 1
	v_mfma_f32_16x16x32_bf16 v[116:119], v[168:171], v[184:187], v[116:119]
	v_mfma_f32_16x16x32_bf16 v[112:115], v[176:179], v[184:187], v[112:115]
	v_mfma_f32_16x16x32_bf16 v[100:103], v[168:171], v[192:195], v[100:103]
	v_mfma_f32_16x16x32_bf16 v[96:99], v[176:179], v[192:195], v[96:99]
	v_mfma_f32_16x16x32_bf16 v[84:87], v[168:171], v[200:203], v[84:87]
	v_mfma_f32_16x16x32_bf16 v[80:83], v[176:179], v[200:203], v[80:83]
	v_mfma_f32_16x16x32_bf16 v[68:71], v[168:171], v[208:211], v[68:71]
	v_mfma_f32_16x16x32_bf16 v[64:67], v[176:179], v[208:211], v[64:67]
	v_mfma_f32_16x16x32_bf16 v[116:119], v[172:175], v[188:191], v[116:119]
	v_mfma_f32_16x16x32_bf16 v[112:115], v[180:183], v[188:191], v[112:115]
	v_mfma_f32_16x16x32_bf16 v[100:103], v[172:175], v[196:199], v[100:103]
	v_mfma_f32_16x16x32_bf16 v[96:99], v[180:183], v[196:199], v[96:99]
	v_mfma_f32_16x16x32_bf16 v[84:87], v[172:175], v[204:207], v[84:87]
	v_mfma_f32_16x16x32_bf16 v[80:83], v[180:183], v[204:207], v[80:83]
	v_mfma_f32_16x16x32_bf16 v[68:71], v[172:175], v[212:215], v[68:71]
	v_mfma_f32_16x16x32_bf16 v[64:67], v[180:183], v[212:215], v[64:67]
	s_setprio 0
	s_barrier
	s_add_i32 s30, s34, s38
	v_lshl_add_u64 v[216:217], v[216:217], 0, s[6:7]
	s_mov_b32 m0, s30
	ds_read_b128 v[184:187], v155 offset:49152
	ds_read_b128 v[188:191], v155 offset:50176
	ds_read_b128 v[192:195], v155 offset:51200
	ds_read_b128 v[196:199], v155 offset:52224
	ds_read_b128 v[200:203], v155 offset:53248
	ds_read_b128 v[204:207], v155 offset:54272
	ds_read_b128 v[208:211], v155 offset:55296
	ds_read_b128 v[212:215], v155 offset:56320
	global_load_lds_dwordx4 v[216:217], off
	s_add_i32 m0, s30, 0x2000
	s_add_u32 s28, s28, 0x40080
	v_lshl_add_u64 v[216:217], v[218:219], 0, s[6:7]
	s_addc_u32 s29, s29, 0
	s_add_i32 s30, s35, s38
	global_load_lds_dwordx4 v[216:217], off
	v_lshl_add_u64 v[216:217], s[28:29], 0, v[134:135]
	s_mov_b32 m0, s30
	s_nop 0
	global_load_lds_dwordx4 v[216:217], off
	v_lshl_add_u64 v[216:217], s[28:29], 0, v[130:131]
	s_add_i32 m0, s30, 0x2000
	s_nop 0
	global_load_lds_dwordx4 v[216:217], off
	v_lshl_add_u64 v[216:217], v[220:221], 0, s[6:7]
	s_mov_b32 m0, s45
	s_nop 0
	global_load_lds_dwordx4 v[216:217], off
	v_lshl_add_u64 v[216:217], v[222:223], 0, s[6:7]
	s_mov_b32 m0, s46
	s_nop 0
	global_load_lds_dwordx4 v[216:217], off
	s_waitcnt vmcnt(8)
	s_waitcnt lgkmcnt(0)
	s_barrier
	s_setprio 1
	s_waitcnt lgkmcnt(0)
	v_mfma_f32_16x16x32_bf16 v[60:63], v[146:149], v[184:187], v[60:63]
	v_mfma_f32_16x16x32_bf16 v[56:59], v[160:163], v[184:187], v[56:59]
	v_mfma_f32_16x16x32_bf16 v[44:47], v[146:149], v[192:195], v[44:47]
	v_mfma_f32_16x16x32_bf16 v[40:43], v[160:163], v[192:195], v[40:43]
	v_mfma_f32_16x16x32_bf16 v[28:31], v[146:149], v[200:203], v[28:31]
	v_mfma_f32_16x16x32_bf16 v[24:27], v[160:163], v[200:203], v[24:27]
	v_mfma_f32_16x16x32_bf16 v[12:15], v[146:149], v[208:211], v[12:15]
	v_mfma_f32_16x16x32_bf16 v[8:11], v[160:163], v[208:211], v[8:11]
	v_mfma_f32_16x16x32_bf16 v[60:63], v[156:159], v[188:191], v[60:63]
	v_mfma_f32_16x16x32_bf16 v[56:59], v[164:167], v[188:191], v[56:59]
	v_mfma_f32_16x16x32_bf16 v[44:47], v[156:159], v[196:199], v[44:47]
	v_mfma_f32_16x16x32_bf16 v[40:43], v[164:167], v[196:199], v[40:43]
	v_mfma_f32_16x16x32_bf16 v[28:31], v[156:159], v[204:207], v[28:31]
	v_mfma_f32_16x16x32_bf16 v[24:27], v[164:167], v[204:207], v[24:27]
	v_mfma_f32_16x16x32_bf16 v[12:15], v[156:159], v[212:215], v[12:15]
	v_mfma_f32_16x16x32_bf16 v[8:11], v[164:167], v[212:215], v[8:11]
	s_setprio 0
	s_setprio 1
	v_mfma_f32_16x16x32_bf16 v[52:55], v[168:171], v[184:187], v[52:55]
	v_mfma_f32_16x16x32_bf16 v[48:51], v[176:179], v[184:187], v[48:51]
	v_mfma_f32_16x16x32_bf16 v[36:39], v[168:171], v[192:195], v[36:39]
	v_mfma_f32_16x16x32_bf16 v[32:35], v[176:179], v[192:195], v[32:35]
	v_mfma_f32_16x16x32_bf16 v[20:23], v[168:171], v[200:203], v[20:23]
	v_mfma_f32_16x16x32_bf16 v[16:19], v[176:179], v[200:203], v[16:19]
	v_mfma_f32_16x16x32_bf16 v[4:7], v[168:171], v[208:211], v[4:7]
	v_mfma_f32_16x16x32_bf16 v[0:3], v[176:179], v[208:211], v[0:3]
	v_mfma_f32_16x16x32_bf16 v[52:55], v[172:175], v[188:191], v[52:55]
	v_mfma_f32_16x16x32_bf16 v[48:51], v[180:183], v[188:191], v[48:51]
	v_mfma_f32_16x16x32_bf16 v[36:39], v[172:175], v[196:199], v[36:39]
	v_mfma_f32_16x16x32_bf16 v[32:35], v[180:183], v[196:199], v[32:35]
	v_mfma_f32_16x16x32_bf16 v[20:23], v[172:175], v[204:207], v[20:23]
	v_mfma_f32_16x16x32_bf16 v[16:19], v[180:183], v[204:207], v[16:19]
	v_mfma_f32_16x16x32_bf16 v[4:7], v[172:175], v[212:215], v[4:7]
	v_mfma_f32_16x16x32_bf16 v[0:3], v[180:183], v[212:215], v[0:3]
	s_setprio 0
	s_barrier
	s_add_i32 s56, s56, 2
	s_add_u32 s26, s26, 0x100
	s_addc_u32 s27, s27, 0
	s_add_u32 s54, s54, 0x100
	s_addc_u32 s55, s55, 0

.LBB0_2094:
	v_lshl_add_u32 v157, s12, 10, v151
	v_lshl_or_b32 v148, s13, 7, v152
	v_lshl_add_u32 v156, s24, 8, v129
	v_ashrrev_i32_e32 v149, 31, v148
	v_mov_b64_e32 v[146:147], s[16:17]
	v_mad_i64_i32 v[160:161], s[12:13], v156, s49, v[146:147]
	v_lshlrev_b64 v[148:149], 1, v[148:149]
	v_lshl_add_u64 v[160:161], v[160:161], 0, v[148:149]
	v_mov_b32_e32 v232, v160
	v_mov_b32_e32 v233, v161
	ds_read_b32 v172, v157
	ds_read_b32 v174, v157 offset:64
	ds_read_b32 v176, v157 offset:128
	ds_read_b32 v178, v157 offset:192
	ds_read_b32 v180, v157 offset:512
	ds_read_b32 v182, v157 offset:576
	ds_read_b32 v184, v157 offset:640
	ds_read_b32 v186, v157 offset:704
	v_mov_b32_e32 v188, 0xbfb8aa3b
	s_waitcnt lgkmcnt(7)
	v_pk_mul_f32 v[124:125], v[124:125], v[172:173] op_sel_hi:[1,0]
	v_pk_mul_f32 v[126:127], v[126:127], v[172:173] op_sel_hi:[1,0]
	v_pk_mul_f32 v[120:121], v[120:121], v[172:173] op_sel_hi:[1,0]
	v_pk_mul_f32 v[122:123], v[122:123], v[172:173] op_sel_hi:[1,0]
	v_pk_mul_f32 v[116:117], v[116:117], v[172:173] op_sel_hi:[1,0]
	v_pk_mul_f32 v[118:119], v[118:119], v[172:173] op_sel_hi:[1,0]
	v_pk_mul_f32 v[112:113], v[112:113], v[172:173] op_sel_hi:[1,0]
	v_pk_mul_f32 v[114:115], v[114:115], v[172:173] op_sel_hi:[1,0]
	v_pk_mul_f32 v[192:193], v[124:125], v[188:189] op_sel_hi:[1,0]
	v_pk_mul_f32 v[194:195], v[126:127], v[188:189] op_sel_hi:[1,0]
	v_pk_mul_f32 v[196:197], v[120:121], v[188:189] op_sel_hi:[1,0]
	v_pk_mul_f32 v[198:199], v[122:123], v[188:189] op_sel_hi:[1,0]
	v_exp_f32_e32 v192, v192
	v_exp_f32_e32 v193, v193
	v_exp_f32_e32 v194, v194
	v_exp_f32_e32 v195, v195
	v_exp_f32_e32 v196, v196
	v_exp_f32_e32 v197, v197
	v_exp_f32_e32 v198, v198
	v_exp_f32_e32 v199, v199
	v_add_f32_e32 v192, 1.0, v192
	v_add_f32_e32 v193, 1.0, v193
	v_add_f32_e32 v194, 1.0, v194
	v_add_f32_e32 v195, 1.0, v195
	v_add_f32_e32 v196, 1.0, v196
	v_add_f32_e32 v197, 1.0, v197
	v_add_f32_e32 v198, 1.0, v198
	v_add_f32_e32 v199, 1.0, v199
	v_rcp_f32_e32 v192, v192
	v_rcp_f32_e32 v193, v193
	v_rcp_f32_e32 v194, v194
	v_rcp_f32_e32 v195, v195
	v_rcp_f32_e32 v196, v196
	v_rcp_f32_e32 v197, v197
	v_rcp_f32_e32 v198, v198
	v_rcp_f32_e32 v199, v199
	v_pk_mul_f32 v[124:125], v[124:125], v[192:193]
	v_pk_mul_f32 v[126:127], v[126:127], v[194:195]
	v_pk_mul_f32 v[120:121], v[120:121], v[196:197]
	v_pk_mul_f32 v[122:123], v[122:123], v[198:199]
	v_pk_mul_f32 v[124:125], v[116:117], v[124:125]
	v_pk_mul_f32 v[126:127], v[118:119], v[126:127]
	v_pk_mul_f32 v[120:121], v[112:113], v[120:121]
	v_pk_mul_f32 v[122:123], v[114:115], v[122:123]
	v_cvt_pk_bf16_f32 v208, v124, v125
	v_cvt_pk_bf16_f32 v209, v126, v127
	v_cvt_pk_bf16_f32 v210, v120, v121
	v_cvt_pk_bf16_f32 v211, v122, v123
	global_store_dwordx4 v[232:233], v[208:211], off
	s_waitcnt lgkmcnt(6)
	v_pk_mul_f32 v[108:109], v[108:109], v[174:175] op_sel_hi:[1,0]
	v_pk_mul_f32 v[110:111], v[110:111], v[174:175] op_sel_hi:[1,0]
	v_pk_mul_f32 v[104:105], v[104:105], v[174:175] op_sel_hi:[1,0]
	v_pk_mul_f32 v[106:107], v[106:107], v[174:175] op_sel_hi:[1,0]
	v_pk_mul_f32 v[100:101], v[100:101], v[174:175] op_sel_hi:[1,0]
	v_pk_mul_f32 v[102:103], v[102:103], v[174:175] op_sel_hi:[1,0]
	v_pk_mul_f32 v[96:97], v[96:97], v[174:175] op_sel_hi:[1,0]
	v_pk_mul_f32 v[98:99], v[98:99], v[174:175] op_sel_hi:[1,0]
	v_pk_mul_f32 v[200:201], v[108:109], v[188:189] op_sel_hi:[1,0]
	v_pk_mul_f32 v[202:203], v[110:111], v[188:189] op_sel_hi:[1,0]
	v_pk_mul_f32 v[204:205], v[104:105], v[188:189] op_sel_hi:[1,0]
	v_pk_mul_f32 v[206:207], v[106:107], v[188:189] op_sel_hi:[1,0]
	v_exp_f32_e32 v200, v200
	v_exp_f32_e32 v201, v201
	v_exp_f32_e32 v202, v202
	v_exp_f32_e32 v203, v203
	v_exp_f32_e32 v204, v204
	v_exp_f32_e32 v205, v205
	v_exp_f32_e32 v206, v206
	v_exp_f32_e32 v207, v207
	v_add_f32_e32 v200, 1.0, v200
	v_add_f32_e32 v201, 1.0, v201
	v_add_f32_e32 v202, 1.0, v202
	v_add_f32_e32 v203, 1.0, v203
	v_add_f32_e32 v204, 1.0, v204
	v_add_f32_e32 v205, 1.0, v205
	v_add_f32_e32 v206, 1.0, v206
	v_add_f32_e32 v207, 1.0, v207
	v_rcp_f32_e32 v200, v200
	v_rcp_f32_e32 v201, v201
	v_rcp_f32_e32 v202, v202
	v_rcp_f32_e32 v203, v203
	v_rcp_f32_e32 v204, v204
	v_rcp_f32_e32 v205, v205
	v_rcp_f32_e32 v206, v206
	v_rcp_f32_e32 v207, v207
	v_pk_mul_f32 v[108:109], v[108:109], v[200:201]
	v_pk_mul_f32 v[110:111], v[110:111], v[202:203]
	v_pk_mul_f32 v[104:105], v[104:105], v[204:205]
	v_pk_mul_f32 v[106:107], v[106:107], v[206:207]
	v_pk_mul_f32 v[108:109], v[100:101], v[108:109]
	v_pk_mul_f32 v[110:111], v[102:103], v[110:111]
	v_pk_mul_f32 v[104:105], v[96:97], v[104:105]
	v_pk_mul_f32 v[106:107], v[98:99], v[106:107]
	v_cvt_pk_bf16_f32 v212, v108, v109
	v_cvt_pk_bf16_f32 v213, v110, v111
	v_cvt_pk_bf16_f32 v214, v104, v105
	v_cvt_pk_bf16_f32 v215, v106, v107
	s_mov_b64 s[100:101], 0x16000
	v_lshl_add_u64 v[216:217], v[232:233], 0, s[100:101]
	global_store_dwordx4 v[216:217], v[212:215], off
	s_waitcnt lgkmcnt(5)
	v_pk_mul_f32 v[92:93], v[92:93], v[176:177] op_sel_hi:[1,0]
	v_pk_mul_f32 v[94:95], v[94:95], v[176:177] op_sel_hi:[1,0]
	v_pk_mul_f32 v[88:89], v[88:89], v[176:177] op_sel_hi:[1,0]
	v_pk_mul_f32 v[90:91], v[90:91], v[176:177] op_sel_hi:[1,0]
	v_pk_mul_f32 v[84:85], v[84:85], v[176:177] op_sel_hi:[1,0]
	v_pk_mul_f32 v[86:87], v[86:87], v[176:177] op_sel_hi:[1,0]
	v_pk_mul_f32 v[80:81], v[80:81], v[176:177] op_sel_hi:[1,0]
	v_pk_mul_f32 v[82:83], v[82:83], v[176:177] op_sel_hi:[1,0]
	v_pk_mul_f32 v[192:193], v[92:93], v[188:189] op_sel_hi:[1,0]
	v_pk_mul_f32 v[194:195], v[94:95], v[188:189] op_sel_hi:[1,0]
	v_pk_mul_f32 v[196:197], v[88:89], v[188:189] op_sel_hi:[1,0]
	v_pk_mul_f32 v[198:199], v[90:91], v[188:189] op_sel_hi:[1,0]
	v_exp_f32_e32 v192, v192
	v_exp_f32_e32 v193, v193
	v_exp_f32_e32 v194, v194
	v_exp_f32_e32 v195, v195
	v_exp_f32_e32 v196, v196
	v_exp_f32_e32 v197, v197
	v_exp_f32_e32 v198, v198
	v_exp_f32_e32 v199, v199
	v_add_f32_e32 v192, 1.0, v192
	v_add_f32_e32 v193, 1.0, v193
	v_add_f32_e32 v194, 1.0, v194
	v_add_f32_e32 v195, 1.0, v195
	v_add_f32_e32 v196, 1.0, v196
	v_add_f32_e32 v197, 1.0, v197
	v_add_f32_e32 v198, 1.0, v198
	v_add_f32_e32 v199, 1.0, v199
	v_rcp_f32_e32 v192, v192
	v_rcp_f32_e32 v193, v193
	v_rcp_f32_e32 v194, v194
	v_rcp_f32_e32 v195, v195
	v_rcp_f32_e32 v196, v196
	v_rcp_f32_e32 v197, v197
	v_rcp_f32_e32 v198, v198
	v_rcp_f32_e32 v199, v199
	v_pk_mul_f32 v[92:93], v[92:93], v[192:193]
	v_pk_mul_f32 v[94:95], v[94:95], v[194:195]
	v_pk_mul_f32 v[88:89], v[88:89], v[196:197]
	v_pk_mul_f32 v[90:91], v[90:91], v[198:199]
	v_pk_mul_f32 v[92:93], v[84:85], v[92:93]
	v_pk_mul_f32 v[94:95], v[86:87], v[94:95]
	v_pk_mul_f32 v[88:89], v[80:81], v[88:89]
	v_pk_mul_f32 v[90:91], v[82:83], v[90:91]
	v_cvt_pk_bf16_f32 v208, v92, v93
	v_cvt_pk_bf16_f32 v209, v94, v95
	v_cvt_pk_bf16_f32 v210, v88, v89
	v_cvt_pk_bf16_f32 v211, v90, v91
	s_mov_b64 s[100:101], 0x2c000
	v_lshl_add_u64 v[216:217], v[232:233], 0, s[100:101]
	global_store_dwordx4 v[216:217], v[208:211], off
	s_waitcnt lgkmcnt(4)
	v_pk_mul_f32 v[76:77], v[76:77], v[178:179] op_sel_hi:[1,0]
	v_pk_mul_f32 v[78:79], v[78:79], v[178:179] op_sel_hi:[1,0]
	v_pk_mul_f32 v[72:73], v[72:73], v[178:179] op_sel_hi:[1,0]
	v_pk_mul_f32 v[74:75], v[74:75], v[178:179] op_sel_hi:[1,0]
	v_pk_mul_f32 v[68:69], v[68:69], v[178:179] op_sel_hi:[1,0]
	v_pk_mul_f32 v[70:71], v[70:71], v[178:179] op_sel_hi:[1,0]
	v_pk_mul_f32 v[64:65], v[64:65], v[178:179] op_sel_hi:[1,0]
	v_pk_mul_f32 v[66:67], v[66:67], v[178:179] op_sel_hi:[1,0]
	v_pk_mul_f32 v[200:201], v[76:77], v[188:189] op_sel_hi:[1,0]
	v_pk_mul_f32 v[202:203], v[78:79], v[188:189] op_sel_hi:[1,0]
	v_pk_mul_f32 v[204:205], v[72:73], v[188:189] op_sel_hi:[1,0]
	v_pk_mul_f32 v[206:207], v[74:75], v[188:189] op_sel_hi:[1,0]
	v_exp_f32_e32 v200, v200
	v_exp_f32_e32 v201, v201
	v_exp_f32_e32 v202, v202
	v_exp_f32_e32 v203, v203
	v_exp_f32_e32 v204, v204
	v_exp_f32_e32 v205, v205
	v_exp_f32_e32 v206, v206
	v_exp_f32_e32 v207, v207
	v_add_f32_e32 v200, 1.0, v200
	v_add_f32_e32 v201, 1.0, v201
	v_add_f32_e32 v202, 1.0, v202
	v_add_f32_e32 v203, 1.0, v203
	v_add_f32_e32 v204, 1.0, v204
	v_add_f32_e32 v205, 1.0, v205
	v_add_f32_e32 v206, 1.0, v206
	v_add_f32_e32 v207, 1.0, v207
	v_rcp_f32_e32 v200, v200
	v_rcp_f32_e32 v201, v201
	v_rcp_f32_e32 v202, v202
	v_rcp_f32_e32 v203, v203
	v_rcp_f32_e32 v204, v204
	v_rcp_f32_e32 v205, v205
	v_rcp_f32_e32 v206, v206
	v_rcp_f32_e32 v207, v207
	v_pk_mul_f32 v[76:77], v[76:77], v[200:201]
	v_pk_mul_f32 v[78:79], v[78:79], v[202:203]
	v_pk_mul_f32 v[72:73], v[72:73], v[204:205]
	v_pk_mul_f32 v[74:75], v[74:75], v[206:207]
	v_pk_mul_f32 v[76:77], v[68:69], v[76:77]
	v_pk_mul_f32 v[78:79], v[70:71], v[78:79]
	v_pk_mul_f32 v[72:73], v[64:65], v[72:73]
	v_pk_mul_f32 v[74:75], v[66:67], v[74:75]
	v_cvt_pk_bf16_f32 v212, v76, v77
	v_cvt_pk_bf16_f32 v213, v78, v79
	v_cvt_pk_bf16_f32 v214, v72, v73
	v_cvt_pk_bf16_f32 v215, v74, v75
	s_mov_b64 s[100:101], 0x42000
	v_lshl_add_u64 v[216:217], v[232:233], 0, s[100:101]
	global_store_dwordx4 v[216:217], v[212:215], off
	s_waitcnt lgkmcnt(3)
	v_pk_mul_f32 v[60:61], v[60:61], v[180:181] op_sel_hi:[1,0]
	v_pk_mul_f32 v[62:63], v[62:63], v[180:181] op_sel_hi:[1,0]
	v_pk_mul_f32 v[56:57], v[56:57], v[180:181] op_sel_hi:[1,0]
	v_pk_mul_f32 v[58:59], v[58:59], v[180:181] op_sel_hi:[1,0]
	v_pk_mul_f32 v[52:53], v[52:53], v[180:181] op_sel_hi:[1,0]
	v_pk_mul_f32 v[54:55], v[54:55], v[180:181] op_sel_hi:[1,0]
	v_pk_mul_f32 v[48:49], v[48:49], v[180:181] op_sel_hi:[1,0]
	v_pk_mul_f32 v[50:51], v[50:51], v[180:181] op_sel_hi:[1,0]
	v_pk_mul_f32 v[192:193], v[60:61], v[188:189] op_sel_hi:[1,0]
	v_pk_mul_f32 v[194:195], v[62:63], v[188:189] op_sel_hi:[1,0]
	v_pk_mul_f32 v[196:197], v[56:57], v[188:189] op_sel_hi:[1,0]
	v_pk_mul_f32 v[198:199], v[58:59], v[188:189] op_sel_hi:[1,0]
	v_exp_f32_e32 v192, v192
	v_exp_f32_e32 v193, v193
	v_exp_f32_e32 v194, v194
	v_exp_f32_e32 v195, v195
	v_exp_f32_e32 v196, v196
	v_exp_f32_e32 v197, v197
	v_exp_f32_e32 v198, v198
	v_exp_f32_e32 v199, v199
	v_add_f32_e32 v192, 1.0, v192
	v_add_f32_e32 v193, 1.0, v193
	v_add_f32_e32 v194, 1.0, v194
	v_add_f32_e32 v195, 1.0, v195
	v_add_f32_e32 v196, 1.0, v196
	v_add_f32_e32 v197, 1.0, v197
	v_add_f32_e32 v198, 1.0, v198
	v_add_f32_e32 v199, 1.0, v199
	v_rcp_f32_e32 v192, v192
	v_rcp_f32_e32 v193, v193
	v_rcp_f32_e32 v194, v194
	v_rcp_f32_e32 v195, v195
	v_rcp_f32_e32 v196, v196
	v_rcp_f32_e32 v197, v197
	v_rcp_f32_e32 v198, v198
	v_rcp_f32_e32 v199, v199
	v_pk_mul_f32 v[60:61], v[60:61], v[192:193]
	v_pk_mul_f32 v[62:63], v[62:63], v[194:195]
	v_pk_mul_f32 v[56:57], v[56:57], v[196:197]
	v_pk_mul_f32 v[58:59], v[58:59], v[198:199]
	v_pk_mul_f32 v[60:61], v[52:53], v[60:61]
	v_pk_mul_f32 v[62:63], v[54:55], v[62:63]
	v_pk_mul_f32 v[56:57], v[48:49], v[56:57]
	v_pk_mul_f32 v[58:59], v[50:51], v[58:59]
	v_cvt_pk_bf16_f32 v208, v60, v61
	v_cvt_pk_bf16_f32 v209, v62, v63
	v_cvt_pk_bf16_f32 v210, v56, v57
	v_cvt_pk_bf16_f32 v211, v58, v59
	s_mov_b64 s[100:101], 0xb0000
	v_lshl_add_u64 v[216:217], v[232:233], 0, s[100:101]
	global_store_dwordx4 v[216:217], v[208:211], off
	s_waitcnt lgkmcnt(2)
	v_pk_mul_f32 v[44:45], v[44:45], v[182:183] op_sel_hi:[1,0]
	v_pk_mul_f32 v[46:47], v[46:47], v[182:183] op_sel_hi:[1,0]
	v_pk_mul_f32 v[40:41], v[40:41], v[182:183] op_sel_hi:[1,0]
	v_pk_mul_f32 v[42:43], v[42:43], v[182:183] op_sel_hi:[1,0]
	v_pk_mul_f32 v[36:37], v[36:37], v[182:183] op_sel_hi:[1,0]
	v_pk_mul_f32 v[38:39], v[38:39], v[182:183] op_sel_hi:[1,0]
	v_pk_mul_f32 v[32:33], v[32:33], v[182:183] op_sel_hi:[1,0]
	v_pk_mul_f32 v[34:35], v[34:35], v[182:183] op_sel_hi:[1,0]
	v_pk_mul_f32 v[200:201], v[44:45], v[188:189] op_sel_hi:[1,0]
	v_pk_mul_f32 v[202:203], v[46:47], v[188:189] op_sel_hi:[1,0]
	v_pk_mul_f32 v[204:205], v[40:41], v[188:189] op_sel_hi:[1,0]
	v_pk_mul_f32 v[206:207], v[42:43], v[188:189] op_sel_hi:[1,0]
	v_exp_f32_e32 v200, v200
	v_exp_f32_e32 v201, v201
	v_exp_f32_e32 v202, v202
	v_exp_f32_e32 v203, v203
	v_exp_f32_e32 v204, v204
	v_exp_f32_e32 v205, v205
	v_exp_f32_e32 v206, v206
	v_exp_f32_e32 v207, v207
	v_add_f32_e32 v200, 1.0, v200
	v_add_f32_e32 v201, 1.0, v201
	v_add_f32_e32 v202, 1.0, v202
	v_add_f32_e32 v203, 1.0, v203
	v_add_f32_e32 v204, 1.0, v204
	v_add_f32_e32 v205, 1.0, v205
	v_add_f32_e32 v206, 1.0, v206
	v_add_f32_e32 v207, 1.0, v207
	v_rcp_f32_e32 v200, v200
	v_rcp_f32_e32 v201, v201
	v_rcp_f32_e32 v202, v202
	v_rcp_f32_e32 v203, v203
	v_rcp_f32_e32 v204, v204
	v_rcp_f32_e32 v205, v205
	v_rcp_f32_e32 v206, v206
	v_rcp_f32_e32 v207, v207
	v_pk_mul_f32 v[44:45], v[44:45], v[200:201]
	v_pk_mul_f32 v[46:47], v[46:47], v[202:203]
	v_pk_mul_f32 v[40:41], v[40:41], v[204:205]
	v_pk_mul_f32 v[42:43], v[42:43], v[206:207]
	v_pk_mul_f32 v[44:45], v[36:37], v[44:45]
	v_pk_mul_f32 v[46:47], v[38:39], v[46:47]
	v_pk_mul_f32 v[40:41], v[32:33], v[40:41]
	v_pk_mul_f32 v[42:43], v[34:35], v[42:43]
	v_cvt_pk_bf16_f32 v212, v44, v45
	v_cvt_pk_bf16_f32 v213, v46, v47
	v_cvt_pk_bf16_f32 v214, v40, v41
	v_cvt_pk_bf16_f32 v215, v42, v43
	s_mov_b64 s[100:101], 0xc6000
	v_lshl_add_u64 v[216:217], v[232:233], 0, s[100:101]
	global_store_dwordx4 v[216:217], v[212:215], off
	s_waitcnt lgkmcnt(1)
	v_pk_mul_f32 v[28:29], v[28:29], v[184:185] op_sel_hi:[1,0]
	v_pk_mul_f32 v[30:31], v[30:31], v[184:185] op_sel_hi:[1,0]
	v_pk_mul_f32 v[24:25], v[24:25], v[184:185] op_sel_hi:[1,0]
	v_pk_mul_f32 v[26:27], v[26:27], v[184:185] op_sel_hi:[1,0]
	v_pk_mul_f32 v[20:21], v[20:21], v[184:185] op_sel_hi:[1,0]
	v_pk_mul_f32 v[22:23], v[22:23], v[184:185] op_sel_hi:[1,0]
	v_pk_mul_f32 v[16:17], v[16:17], v[184:185] op_sel_hi:[1,0]
	v_pk_mul_f32 v[18:19], v[18:19], v[184:185] op_sel_hi:[1,0]
	v_pk_mul_f32 v[192:193], v[28:29], v[188:189] op_sel_hi:[1,0]
	v_pk_mul_f32 v[194:195], v[30:31], v[188:189] op_sel_hi:[1,0]
	v_pk_mul_f32 v[196:197], v[24:25], v[188:189] op_sel_hi:[1,0]
	v_pk_mul_f32 v[198:199], v[26:27], v[188:189] op_sel_hi:[1,0]
	v_exp_f32_e32 v192, v192
	v_exp_f32_e32 v193, v193
	v_exp_f32_e32 v194, v194
	v_exp_f32_e32 v195, v195
	v_exp_f32_e32 v196, v196
	v_exp_f32_e32 v197, v197
	v_exp_f32_e32 v198, v198
	v_exp_f32_e32 v199, v199
	v_add_f32_e32 v192, 1.0, v192
	v_add_f32_e32 v193, 1.0, v193
	v_add_f32_e32 v194, 1.0, v194
	v_add_f32_e32 v195, 1.0, v195
	v_add_f32_e32 v196, 1.0, v196
	v_add_f32_e32 v197, 1.0, v197
	v_add_f32_e32 v198, 1.0, v198
	v_add_f32_e32 v199, 1.0, v199
	v_rcp_f32_e32 v192, v192
	v_rcp_f32_e32 v193, v193
	v_rcp_f32_e32 v194, v194
	v_rcp_f32_e32 v195, v195
	v_rcp_f32_e32 v196, v196
	v_rcp_f32_e32 v197, v197
	v_rcp_f32_e32 v198, v198
	v_rcp_f32_e32 v199, v199
	v_pk_mul_f32 v[28:29], v[28:29], v[192:193]
	v_pk_mul_f32 v[30:31], v[30:31], v[194:195]
	v_pk_mul_f32 v[24:25], v[24:25], v[196:197]
	v_pk_mul_f32 v[26:27], v[26:27], v[198:199]
	v_pk_mul_f32 v[28:29], v[20:21], v[28:29]
	v_pk_mul_f32 v[30:31], v[22:23], v[30:31]
	v_pk_mul_f32 v[24:25], v[16:17], v[24:25]
	v_pk_mul_f32 v[26:27], v[18:19], v[26:27]
	v_cvt_pk_bf16_f32 v208, v28, v29
	v_cvt_pk_bf16_f32 v209, v30, v31
	v_cvt_pk_bf16_f32 v210, v24, v25
	v_cvt_pk_bf16_f32 v211, v26, v27
	s_mov_b64 s[100:101], 0xdc000
	v_lshl_add_u64 v[216:217], v[232:233], 0, s[100:101]
	global_store_dwordx4 v[216:217], v[208:211], off
	s_waitcnt lgkmcnt(0)
	v_pk_mul_f32 v[12:13], v[12:13], v[186:187] op_sel_hi:[1,0]
	v_pk_mul_f32 v[14:15], v[14:15], v[186:187] op_sel_hi:[1,0]
	v_pk_mul_f32 v[8:9], v[8:9], v[186:187] op_sel_hi:[1,0]
	v_pk_mul_f32 v[10:11], v[10:11], v[186:187] op_sel_hi:[1,0]
	v_pk_mul_f32 v[4:5], v[4:5], v[186:187] op_sel_hi:[1,0]
	v_pk_mul_f32 v[6:7], v[6:7], v[186:187] op_sel_hi:[1,0]
	v_pk_mul_f32 v[0:1], v[0:1], v[186:187] op_sel_hi:[1,0]
	v_pk_mul_f32 v[2:3], v[2:3], v[186:187] op_sel_hi:[1,0]
	v_pk_mul_f32 v[200:201], v[12:13], v[188:189] op_sel_hi:[1,0]
	v_pk_mul_f32 v[202:203], v[14:15], v[188:189] op_sel_hi:[1,0]
	v_pk_mul_f32 v[204:205], v[8:9], v[188:189] op_sel_hi:[1,0]
	v_pk_mul_f32 v[206:207], v[10:11], v[188:189] op_sel_hi:[1,0]
	v_exp_f32_e32 v200, v200
	v_exp_f32_e32 v201, v201
	v_exp_f32_e32 v202, v202
	v_exp_f32_e32 v203, v203
	v_exp_f32_e32 v204, v204
	v_exp_f32_e32 v205, v205
	v_exp_f32_e32 v206, v206
	v_exp_f32_e32 v207, v207
	v_add_f32_e32 v200, 1.0, v200
	v_add_f32_e32 v201, 1.0, v201
	v_add_f32_e32 v202, 1.0, v202
	v_add_f32_e32 v203, 1.0, v203
	v_add_f32_e32 v204, 1.0, v204
	v_add_f32_e32 v205, 1.0, v205
	v_add_f32_e32 v206, 1.0, v206
	v_add_f32_e32 v207, 1.0, v207
	v_rcp_f32_e32 v200, v200
	v_rcp_f32_e32 v201, v201
	v_rcp_f32_e32 v202, v202
	v_rcp_f32_e32 v203, v203
	v_rcp_f32_e32 v204, v204
	v_rcp_f32_e32 v205, v205
	v_rcp_f32_e32 v206, v206
	v_rcp_f32_e32 v207, v207
	v_pk_mul_f32 v[12:13], v[12:13], v[200:201]
	v_pk_mul_f32 v[14:15], v[14:15], v[202:203]
	v_pk_mul_f32 v[8:9], v[8:9], v[204:205]
	v_pk_mul_f32 v[10:11], v[10:11], v[206:207]
	v_pk_mul_f32 v[12:13], v[4:5], v[12:13]
	v_pk_mul_f32 v[14:15], v[6:7], v[14:15]
	v_pk_mul_f32 v[8:9], v[0:1], v[8:9]
	v_pk_mul_f32 v[10:11], v[2:3], v[10:11]
	v_cvt_pk_bf16_f32 v212, v12, v13
	v_cvt_pk_bf16_f32 v213, v14, v15
	v_cvt_pk_bf16_f32 v214, v8, v9
	v_cvt_pk_bf16_f32 v215, v10, v11
	s_mov_b64 s[100:101], 0xf2000
	v_lshl_add_u64 v[216:217], v[232:233], 0, s[100:101]
	global_store_dwordx4 v[216:217], v[212:215], off
	s_andn2_b64 vcc, exec, s[4:5]
	s_mov_b64 s[4:5], -1
	s_cbranch_vccnz .LBB0_2087
	s_andn2_b64 vcc, exec, s[0:1]
	s_cbranch_vccnz .LBB0_2086
	s_barrier
	s_branch .LBB0_2086

.LBB0_2163:
	s_add_i32 s45, s45, 1
	s_mul_i32 s0, s45, s48
	s_mul_hi_u32 s1, s45, s49
	s_add_i32 s1, s1, s0
	s_mul_i32 s0, s45, s49
	s_add_u32 s4, s0, s2
	s_addc_u32 s5, s1, s3
	v_cmp_gt_i64_e32 vcc, s[4:5], v[142:143]
	v_cmp_lt_i64_e64 s[0:1], s[4:5], v[140:141]
	s_cbranch_vccnz .LBB0_2169
	s_and_b32 s100, s4, 7
	s_mul_i32 s100, s100, 0x40
	s_lshr_b32 s101, s4, 3
	s_add_i32 s100, s100, s101
	s_mul_hi_u32 s101, s100, 0x8000000
	s_mul_i32 s52, s101, 0x20
	s_sub_i32 s52, s100, s52
	s_and_b32 s100, s52, 7
	s_lshl_b32 s53, s101, 3
	s_add_i32 s53, s53, s100
	s_lshr_b32 s52, s52, 3

.LBB0_2173:
	s_add_u32 s28, s28, 0xb0080
	s_addc_u32 s29, s29, 0
	s_add_u32 s54, s30, 0x100
	s_addc_u32 s55, s31, 0
	s_mov_b32 s56, -2
	ds_read_b128 v[144:147], v153
	ds_read_b128 v[156:159], v153 offset:1024
	ds_read_b128 v[160:163], v153 offset:2048
	ds_read_b128 v[164:167], v153 offset:3072
	ds_read_b128 v[168:171], v154
	ds_read_b128 v[172:175], v154 offset:1024
	ds_read_b128 v[176:179], v154 offset:2048
	ds_read_b128 v[180:183], v154 offset:3072
	s_add_u32 s30, s28, 0xfff50080
	s_addc_u32 s31, s29, -1
	s_cmp_eq_u32 s56, 40
	s_cselect_b32 s37, s1, s31
	s_cselect_b32 s36, s0, s30
	s_cselect_b32 s31, s27, s55
	s_cselect_b32 s30, s26, s54
	v_lshl_add_u64 v[148:149], s[28:29], 0, v[128:129]
	s_add_i32 m0, s41, 0xc000
	ds_read_b128 v[184:187], v155
	ds_read_b128 v[188:191], v155 offset:1024
	ds_read_b128 v[192:195], v155 offset:2048
	ds_read_b128 v[196:199], v155 offset:3072
	ds_read_b128 v[200:203], v155 offset:4096
	ds_read_b128 v[204:207], v155 offset:5120
	ds_read_b128 v[208:211], v155 offset:6144
	ds_read_b128 v[212:215], v155 offset:7168
	global_load_lds_dwordx4 v[148:149], off
	v_lshl_add_u64 v[148:149], s[28:29], 0, v[138:139]
	s_add_i32 m0, s41, 0xe000
	s_nop 0
	global_load_lds_dwordx4 v[148:149], off
	s_waitcnt vmcnt(8)
	s_waitcnt lgkmcnt(0)
	s_barrier
	s_setprio 1
	s_waitcnt lgkmcnt(0)
	v_mfma_f32_16x16x32_bf16 v[124:127], v[144:147], v[184:187], 0
	v_mfma_f32_16x16x32_bf16 v[120:123], v[160:163], v[184:187], 0
	v_mfma_f32_16x16x32_bf16 v[108:111], v[144:147], v[192:195], 0
	v_mfma_f32_16x16x32_bf16 v[104:107], v[160:163], v[192:195], 0
	v_mfma_f32_16x16x32_bf16 v[92:95], v[144:147], v[200:203], 0
	v_mfma_f32_16x16x32_bf16 v[88:91], v[160:163], v[200:203], 0
	v_mfma_f32_16x16x32_bf16 v[76:79], v[144:147], v[208:211], 0
	v_mfma_f32_16x16x32_bf16 v[72:75], v[160:163], v[208:211], 0
	v_mfma_f32_16x16x32_bf16 v[124:127], v[156:159], v[188:191], v[124:127]
	v_mfma_f32_16x16x32_bf16 v[120:123], v[164:167], v[188:191], v[120:123]
	v_mfma_f32_16x16x32_bf16 v[108:111], v[156:159], v[196:199], v[108:111]
	v_mfma_f32_16x16x32_bf16 v[104:107], v[164:167], v[196:199], v[104:107]
	v_mfma_f32_16x16x32_bf16 v[92:95], v[156:159], v[204:207], v[92:95]
	v_mfma_f32_16x16x32_bf16 v[88:91], v[164:167], v[204:207], v[88:91]
	v_mfma_f32_16x16x32_bf16 v[76:79], v[156:159], v[212:215], v[76:79]
	v_mfma_f32_16x16x32_bf16 v[72:75], v[164:167], v[212:215], v[72:75]
	s_setprio 0
	s_setprio 1
	v_mfma_f32_16x16x32_bf16 v[116:119], v[168:171], v[184:187], 0
	v_mfma_f32_16x16x32_bf16 v[112:115], v[176:179], v[184:187], 0
	v_mfma_f32_16x16x32_bf16 v[100:103], v[168:171], v[192:195], 0
	v_mfma_f32_16x16x32_bf16 v[96:99], v[176:179], v[192:195], 0
	v_mfma_f32_16x16x32_bf16 v[84:87], v[168:171], v[200:203], 0
	v_mfma_f32_16x16x32_bf16 v[80:83], v[176:179], v[200:203], 0
	v_mfma_f32_16x16x32_bf16 v[68:71], v[168:171], v[208:211], 0
	v_mfma_f32_16x16x32_bf16 v[64:67], v[176:179], v[208:211], 0
	v_mfma_f32_16x16x32_bf16 v[116:119], v[172:175], v[188:191], v[116:119]
	v_mfma_f32_16x16x32_bf16 v[112:115], v[180:183], v[188:191], v[112:115]
	v_mfma_f32_16x16x32_bf16 v[100:103], v[172:175], v[196:199], v[100:103]
	v_mfma_f32_16x16x32_bf16 v[96:99], v[180:183], v[196:199], v[96:99]
	v_mfma_f32_16x16x32_bf16 v[84:87], v[172:175], v[204:207], v[84:87]
	v_mfma_f32_16x16x32_bf16 v[80:83], v[180:183], v[204:207], v[80:83]
	v_mfma_f32_16x16x32_bf16 v[68:71], v[172:175], v[212:215], v[68:71]
	v_mfma_f32_16x16x32_bf16 v[64:67], v[180:183], v[212:215], v[64:67]
	s_setprio 0
	s_barrier
	s_add_i32 s34, s50, s40
	v_lshl_add_u64 v[148:149], s[30:31], 0, v[132:133]
	s_mov_b32 m0, s34
	ds_read_b128 v[184:187], v155 offset:16384
	ds_read_b128 v[188:191], v155 offset:17408
	ds_read_b128 v[192:195], v155 offset:18432
	ds_read_b128 v[196:199], v155 offset:19456
	ds_read_b128 v[200:203], v155 offset:20480
	ds_read_b128 v[204:207], v155 offset:21504
	ds_read_b128 v[208:211], v155 offset:22528
	ds_read_b128 v[212:215], v155 offset:23552
	global_load_lds_dwordx4 v[148:149], off
	s_add_i32 m0, s34, 0x2000
	s_add_u32 s34, s30, 0xb0000
	v_lshl_add_u64 v[216:217], s[30:31], 0, v[136:137]
	s_addc_u32 s35, s31, 0
	s_add_i32 s57, s51, s40
	global_load_lds_dwordx4 v[216:217], off
	v_lshl_add_u64 v[218:219], s[34:35], 0, v[132:133]
	s_mov_b32 m0, s57
	v_lshl_add_u64 v[220:221], s[36:37], 0, v[134:135]
	global_load_lds_dwordx4 v[218:219], off
	v_lshl_add_u64 v[218:219], s[34:35], 0, v[136:137]
	s_add_i32 m0, s57, 0x2000
	s_nop 0
	global_load_lds_dwordx4 v[218:219], off
	v_lshl_add_u64 v[218:219], s[36:37], 0, v[130:131]
	s_mov_b32 m0, s41
	s_nop 0
	global_load_lds_dwordx4 v[218:219], off
	s_mov_b32 m0, s42
	s_nop 0
	global_load_lds_dwordx4 v[220:221], off
	s_waitcnt vmcnt(8)
	s_waitcnt lgkmcnt(0)
	s_barrier
	s_setprio 1
	s_waitcnt lgkmcnt(0)
	v_mfma_f32_16x16x32_bf16 v[60:63], v[144:147], v[184:187], 0
	v_mfma_f32_16x16x32_bf16 v[56:59], v[160:163], v[184:187], 0
	v_mfma_f32_16x16x32_bf16 v[44:47], v[144:147], v[192:195], 0
	v_mfma_f32_16x16x32_bf16 v[40:43], v[160:163], v[192:195], 0
	v_mfma_f32_16x16x32_bf16 v[28:31], v[144:147], v[200:203], 0
	v_mfma_f32_16x16x32_bf16 v[24:27], v[160:163], v[200:203], 0
	v_mfma_f32_16x16x32_bf16 v[12:15], v[144:147], v[208:211], 0
	v_mfma_f32_16x16x32_bf16 v[8:11], v[160:163], v[208:211], 0
	v_mfma_f32_16x16x32_bf16 v[60:63], v[156:159], v[188:191], v[60:63]
	v_mfma_f32_16x16x32_bf16 v[56:59], v[164:167], v[188:191], v[56:59]
	v_mfma_f32_16x16x32_bf16 v[44:47], v[156:159], v[196:199], v[44:47]
	v_mfma_f32_16x16x32_bf16 v[40:43], v[164:167], v[196:199], v[40:43]
	v_mfma_f32_16x16x32_bf16 v[28:31], v[156:159], v[204:207], v[28:31]
	v_mfma_f32_16x16x32_bf16 v[24:27], v[164:167], v[204:207], v[24:27]
	v_mfma_f32_16x16x32_bf16 v[12:15], v[156:159], v[212:215], v[12:15]
	v_mfma_f32_16x16x32_bf16 v[8:11], v[164:167], v[212:215], v[8:11]
	s_setprio 0
	s_setprio 1
	v_mfma_f32_16x16x32_bf16 v[52:55], v[168:171], v[184:187], 0
	v_mfma_f32_16x16x32_bf16 v[48:51], v[176:179], v[184:187], 0
	v_mfma_f32_16x16x32_bf16 v[36:39], v[168:171], v[192:195], 0
	v_mfma_f32_16x16x32_bf16 v[32:35], v[176:179], v[192:195], 0
	v_mfma_f32_16x16x32_bf16 v[20:23], v[168:171], v[200:203], 0
	v_mfma_f32_16x16x32_bf16 v[16:19], v[176:179], v[200:203], 0
	v_mfma_f32_16x16x32_bf16 v[4:7], v[168:171], v[208:211], 0
	v_mfma_f32_16x16x32_bf16 v[0:3], v[176:179], v[208:211], 0
	v_mfma_f32_16x16x32_bf16 v[52:55], v[172:175], v[188:191], v[52:55]
	v_mfma_f32_16x16x32_bf16 v[48:51], v[180:183], v[188:191], v[48:51]
	v_mfma_f32_16x16x32_bf16 v[36:39], v[172:175], v[196:199], v[36:39]
	v_mfma_f32_16x16x32_bf16 v[32:35], v[180:183], v[196:199], v[32:35]
	v_mfma_f32_16x16x32_bf16 v[20:23], v[172:175], v[204:207], v[20:23]
	v_mfma_f32_16x16x32_bf16 v[16:19], v[180:183], v[204:207], v[16:19]
	v_mfma_f32_16x16x32_bf16 v[4:7], v[172:175], v[212:215], v[4:7]
	v_mfma_f32_16x16x32_bf16 v[0:3], v[180:183], v[212:215], v[0:3]
	s_setprio 0
	s_barrier
	s_add_i32 s57, 0, 0x18000
	s_add_i32 s58, 0, 0x1c000
	v_add_u32_e32 v164, s57, v151
	v_add_u32_e32 v180, s58, v151
	ds_read_b128 v[144:147], v164
	ds_read_b128 v[156:159], v164 offset:1024
	ds_read_b128 v[160:163], v164 offset:2048
	ds_read_b128 v[164:167], v164 offset:3072
	ds_read_b128 v[168:171], v180
	ds_read_b128 v[172:175], v180 offset:1024
	ds_read_b128 v[176:179], v180 offset:2048
	ds_read_b128 v[180:183], v180 offset:3072
	s_add_u32 s34, s36, 0xb0000
	s_addc_u32 s35, s37, 0
	s_mov_b32 m0, s43
	v_lshl_add_u64 v[222:223], s[34:35], 0, v[130:131]
	ds_read_b128 v[184:187], v155 offset:32768
	ds_read_b128 v[188:191], v155 offset:33792
	ds_read_b128 v[192:195], v155 offset:34816
	ds_read_b128 v[196:199], v155 offset:35840
	ds_read_b128 v[200:203], v155 offset:36864
	ds_read_b128 v[204:207], v155 offset:37888
	ds_read_b128 v[208:211], v155 offset:38912
	ds_read_b128 v[212:215], v155 offset:39936
	global_load_lds_dwordx4 v[222:223], off
	v_lshl_add_u64 v[222:223], s[34:35], 0, v[134:135]
	s_mov_b32 m0, s44
	s_nop 0
	global_load_lds_dwordx4 v[222:223], off
	s_waitcnt vmcnt(8)
	s_waitcnt lgkmcnt(0)
	s_barrier
	s_setprio 1
	s_waitcnt lgkmcnt(0)
	v_mfma_f32_16x16x32_bf16 v[124:127], v[144:147], v[184:187], v[124:127]
	v_mfma_f32_16x16x32_bf16 v[120:123], v[160:163], v[184:187], v[120:123]
	v_mfma_f32_16x16x32_bf16 v[108:111], v[144:147], v[192:195], v[108:111]
	v_mfma_f32_16x16x32_bf16 v[104:107], v[160:163], v[192:195], v[104:107]
	v_mfma_f32_16x16x32_bf16 v[92:95], v[144:147], v[200:203], v[92:95]
	v_mfma_f32_16x16x32_bf16 v[88:91], v[160:163], v[200:203], v[88:91]
	v_mfma_f32_16x16x32_bf16 v[76:79], v[144:147], v[208:211], v[76:79]
	v_mfma_f32_16x16x32_bf16 v[72:75], v[160:163], v[208:211], v[72:75]
	v_mfma_f32_16x16x32_bf16 v[124:127], v[156:159], v[188:191], v[124:127]
	v_mfma_f32_16x16x32_bf16 v[120:123], v[164:167], v[188:191], v[120:123]
	v_mfma_f32_16x16x32_bf16 v[108:111], v[156:159], v[196:199], v[108:111]
	v_mfma_f32_16x16x32_bf16 v[104:107], v[164:167], v[196:199], v[104:107]
	v_mfma_f32_16x16x32_bf16 v[92:95], v[156:159], v[204:207], v[92:95]
	v_mfma_f32_16x16x32_bf16 v[88:91], v[164:167], v[204:207], v[88:91]
	v_mfma_f32_16x16x32_bf16 v[76:79], v[156:159], v[212:215], v[76:79]
	v_mfma_f32_16x16x32_bf16 v[72:75], v[164:167], v[212:215], v[72:75]
	s_setprio 0
	s_setprio 1
	v_mfma_f32_16x16x32_bf16 v[116:119], v[168:171], v[184:187], v[116:119]
	v_mfma_f32_16x16x32_bf16 v[112:115], v[176:179], v[184:187], v[112:115]
	v_mfma_f32_16x16x32_bf16 v[100:103], v[168:171], v[192:195], v[100:103]
	v_mfma_f32_16x16x32_bf16 v[96:99], v[176:179], v[192:195], v[96:99]
	v_mfma_f32_16x16x32_bf16 v[84:87], v[168:171], v[200:203], v[84:87]
	v_mfma_f32_16x16x32_bf16 v[80:83], v[176:179], v[200:203], v[80:83]
	v_mfma_f32_16x16x32_bf16 v[68:71], v[168:171], v[208:211], v[68:71]
	v_mfma_f32_16x16x32_bf16 v[64:67], v[176:179], v[208:211], v[64:67]
	v_mfma_f32_16x16x32_bf16 v[116:119], v[172:175], v[188:191], v[116:119]
	v_mfma_f32_16x16x32_bf16 v[112:115], v[180:183], v[188:191], v[112:115]
	v_mfma_f32_16x16x32_bf16 v[100:103], v[172:175], v[196:199], v[100:103]
	v_mfma_f32_16x16x32_bf16 v[96:99], v[180:183], v[196:199], v[96:99]
	v_mfma_f32_16x16x32_bf16 v[84:87], v[172:175], v[204:207], v[84:87]
	v_mfma_f32_16x16x32_bf16 v[80:83], v[180:183], v[204:207], v[80:83]
	v_mfma_f32_16x16x32_bf16 v[68:71], v[172:175], v[212:215], v[68:71]
	v_mfma_f32_16x16x32_bf16 v[64:67], v[180:183], v[212:215], v[64:67]
	s_setprio 0
	s_barrier
	s_add_i32 s34, s57, s40
	v_lshl_add_u64 v[148:149], v[148:149], 0, s[8:9]
	s_mov_b32 m0, s34
	ds_read_b128 v[184:187], v155 offset:49152
	ds_read_b128 v[188:191], v155 offset:50176
	ds_read_b128 v[192:195], v155 offset:51200
	ds_read_b128 v[196:199], v155 offset:52224
	ds_read_b128 v[200:203], v155 offset:53248
	ds_read_b128 v[204:207], v155 offset:54272
	ds_read_b128 v[208:211], v155 offset:55296
	ds_read_b128 v[212:215], v155 offset:56320
	global_load_lds_dwordx4 v[148:149], off
	s_add_i32 m0, s34, 0x2000
	s_add_u32 s30, s30, 0xb0080
	v_lshl_add_u64 v[148:149], v[216:217], 0, s[8:9]
	s_addc_u32 s31, s31, 0
	s_add_i32 s34, s58, s40
	global_load_lds_dwordx4 v[148:149], off
	v_lshl_add_u64 v[148:149], s[30:31], 0, v[132:133]
	s_mov_b32 m0, s34
	s_nop 0
	global_load_lds_dwordx4 v[148:149], off
	v_lshl_add_u64 v[148:149], s[30:31], 0, v[136:137]
	s_add_i32 m0, s34, 0x2000
	s_nop 0
	global_load_lds_dwordx4 v[148:149], off
	v_lshl_add_u64 v[148:149], v[218:219], 0, s[8:9]
	s_mov_b32 m0, s46
	s_nop 0
	global_load_lds_dwordx4 v[148:149], off
	v_lshl_add_u64 v[148:149], v[220:221], 0, s[8:9]
	s_mov_b32 m0, s47
	s_nop 0
	global_load_lds_dwordx4 v[148:149], off
	s_waitcnt vmcnt(8)
	s_waitcnt lgkmcnt(0)
	s_barrier
	s_setprio 1
	s_waitcnt lgkmcnt(0)
	v_mfma_f32_16x16x32_bf16 v[60:63], v[144:147], v[184:187], v[60:63]
	v_mfma_f32_16x16x32_bf16 v[56:59], v[160:163], v[184:187], v[56:59]
	v_mfma_f32_16x16x32_bf16 v[44:47], v[144:147], v[192:195], v[44:47]
	v_mfma_f32_16x16x32_bf16 v[40:43], v[160:163], v[192:195], v[40:43]
	v_mfma_f32_16x16x32_bf16 v[28:31], v[144:147], v[200:203], v[28:31]
	v_mfma_f32_16x16x32_bf16 v[24:27], v[160:163], v[200:203], v[24:27]
	v_mfma_f32_16x16x32_bf16 v[12:15], v[144:147], v[208:211], v[12:15]
	v_mfma_f32_16x16x32_bf16 v[8:11], v[160:163], v[208:211], v[8:11]
	v_mfma_f32_16x16x32_bf16 v[60:63], v[156:159], v[188:191], v[60:63]
	v_mfma_f32_16x16x32_bf16 v[56:59], v[164:167], v[188:191], v[56:59]
	v_mfma_f32_16x16x32_bf16 v[44:47], v[156:159], v[196:199], v[44:47]
	v_mfma_f32_16x16x32_bf16 v[40:43], v[164:167], v[196:199], v[40:43]
	v_mfma_f32_16x16x32_bf16 v[28:31], v[156:159], v[204:207], v[28:31]
	v_mfma_f32_16x16x32_bf16 v[24:27], v[164:167], v[204:207], v[24:27]
	v_mfma_f32_16x16x32_bf16 v[12:15], v[156:159], v[212:215], v[12:15]
	v_mfma_f32_16x16x32_bf16 v[8:11], v[164:167], v[212:215], v[8:11]
	s_setprio 0
	s_setprio 1
	v_mfma_f32_16x16x32_bf16 v[52:55], v[168:171], v[184:187], v[52:55]
	v_mfma_f32_16x16x32_bf16 v[48:51], v[176:179], v[184:187], v[48:51]
	v_mfma_f32_16x16x32_bf16 v[36:39], v[168:171], v[192:195], v[36:39]
	v_mfma_f32_16x16x32_bf16 v[32:35], v[176:179], v[192:195], v[32:35]
	v_mfma_f32_16x16x32_bf16 v[20:23], v[168:171], v[200:203], v[20:23]
	v_mfma_f32_16x16x32_bf16 v[16:19], v[176:179], v[200:203], v[16:19]
	v_mfma_f32_16x16x32_bf16 v[4:7], v[168:171], v[208:211], v[4:7]
	v_mfma_f32_16x16x32_bf16 v[0:3], v[176:179], v[208:211], v[0:3]
	v_mfma_f32_16x16x32_bf16 v[52:55], v[172:175], v[188:191], v[52:55]
	v_mfma_f32_16x16x32_bf16 v[48:51], v[180:183], v[188:191], v[48:51]
	v_mfma_f32_16x16x32_bf16 v[36:39], v[172:175], v[196:199], v[36:39]
	v_mfma_f32_16x16x32_bf16 v[32:35], v[180:183], v[196:199], v[32:35]
	v_mfma_f32_16x16x32_bf16 v[20:23], v[172:175], v[204:207], v[20:23]
	v_mfma_f32_16x16x32_bf16 v[16:19], v[180:183], v[204:207], v[16:19]
	v_mfma_f32_16x16x32_bf16 v[4:7], v[172:175], v[212:215], v[4:7]
	v_mfma_f32_16x16x32_bf16 v[0:3], v[180:183], v[212:215], v[0:3]
	s_setprio 0
	s_barrier
	s_add_i32 s56, s56, 2
	s_add_u32 s28, s28, 0x100
	s_addc_u32 s29, s29, 0
	s_add_u32 s54, s54, 0x100
	s_addc_u32 s55, s55, 0
